# the ten GEMM K-loop heads aligned to 64 bytes (s_nop fill)
# baseline (speedup 1.0000x reference)
; #define PG8_STAGE(bufoff, gbase, voff) do { _Pragma("unroll") for (int _i = 0; _i < 2; ++_i) \
;     __builtin_amdgcn_global_load_lds((const unsigned*)((const char*)(gbase) + (voff)[_i]), (LAS unsigned*)(lds + (bufoff) + ldsw + _i * 8192), 16, 0, 0); } while (0)
; #define PG8_LDA(dst, b, h) do { _Pragma("unroll") for (int m = 0; m < 4; ++m) _Pragma("unroll") for (int k = 0; k < 2; ++k) dst[m][k] = *(const LAS bf16x8*)(lds + PG8_SA(b, h) + aoff + m * 2048 + k * 1024); } while (0)
; #define PG8_LDB(dst, b, h) do { _Pragma("unroll") for (int n = 0; n < 2; ++n) _Pragma("unroll") for (int k = 0; k < 2; ++k) dst[n][k] = *(const LAS bf16x8*)(lds + PG8_SB(b, h) + boff + n * 2048 + k * 1024); } while (0)
; #define PG8_MMA(ai, bj, At, Bt) do { __builtin_amdgcn_s_setprio(1); _Pragma("unroll") for (int m = 0; m < 4; ++m) _Pragma("unroll") for (int n = 0; n < 2; ++n) _Pragma("unroll") for (int k = 0; k < 2; ++k) \
;     acc[ai][bj][m][n] = __builtin_amdgcn_mfma_f32_16x16x32_bf16(Bt[n][k], At[m][k], acc[ai][bj][m][n], 0, 0, 0); __builtin_amdgcn_s_setprio(0); } while (0)
; #define PG8_WAIT_V(n) asm volatile("s_waitcnt vmcnt(" #n ")" ::: "memory")
; #define PG8_WAIT_L(n) asm volatile("s_waitcnt lgkmcnt(" #n ")" ::: "memory")
; #define PG8_BAR __builtin_amdgcn_s_barrier()
; #define PG8_SCHED __builtin_amdgcn_sched_barrier(0)
; template <class Epi>
; __device__ __forceinline__ void gemm_phase(LAS unsigned char* lds, const Gemm g, const StaticOrder& S, const Epi& E, int wv0) {
;     ...
;     for (int t = 0; t < nt; t += 2) {
;       const bool last = (t == nt - 2);
;       const char* a1 = cA + (size_t)(t + 1) * kstep;
;       const char* a2 = last ? nA : cA + (size_t)(t + 2) * kstep; const char* b2 = last ? nB : cB + (size_t)(t + 2) * kstep;
;       const char* a3 = a2 + kstep; const char* b3 = b2 + kstep;
;       PG8_LDB(B0, 0, 0); PG8_SCHED; PG8_LDA(At, 0, 0); PG8_STAGE(PG8_SA(1, 1), a1 + hstepA, voffA);
;       PG8_WAIT_L(8); PG8_BAR; PG8_WAIT_L(0); PG8_MMA(0, 0, At, B0); PG8_BAR; PG8_SCHED;
;       PG8_LDB(B1, 0, 1); PG8_STAGE(PG8_SB(0, 0), b2, voffB);
;       PG8_BAR; PG8_WAIT_L(0); PG8_MMA(0, 1, At, B1); PG8_BAR;
;       PG8_LDA(At, 0, 1); PG8_STAGE(PG8_SA(0, 0), a2, voffA);
;       PG8_BAR; PG8_WAIT_L(0); PG8_MMA(1, 0, At, B0); PG8_BAR; PG8_SCHED;
;       PG8_STAGE(PG8_SB(0, 1), b2 + hstepB, voffB);
;       PG8_WAIT_V(6); PG8_BAR; PG8_MMA(1, 1, At, B1); PG8_BAR;
.Lgprio0:
	.p2alignl 6, 3212836864
.LBB0_153:
	s_add_u32 s0, s8, 0xfff80080
	s_addc_u32 s24, s9, -1
	s_add_i32 s49, 0, 0x10000
	v_add_u32_e32 v96, s49, v196
	s_waitcnt vmcnt(6)
	ds_read_b128 v[88:91], v96
	ds_read_b128 v[92:95], v96 offset:1024
	ds_read_b128 v[106:109], v96 offset:2048
	ds_read_b128 v[110:113], v96 offset:3072
	s_cmp_eq_u32 s29, 28
	s_cselect_b32 s27, s1, s24
	s_cselect_b32 s26, s5, s0
	s_cselect_b32 s25, s7, s28
	s_cselect_b32 s24, s17, s19
	v_lshl_add_u64 v[190:191], s[8:9], 0, v[170:171]
	s_add_i32 m0, s39, 0xc000
	ds_read_b128 v[122:125], v197
	ds_read_b128 v[126:129], v197 offset:1024
	ds_read_b128 v[138:141], v197 offset:2048
	ds_read_b128 v[142:145], v197 offset:3072
	ds_read_b128 v[174:177], v197 offset:4096
	ds_read_b128 v[178:181], v197 offset:5120
	ds_read_b128 v[182:185], v197 offset:6144
	ds_read_b128 v[186:189], v197 offset:7168
	global_load_lds_dwordx4 v[190:191], off
	v_lshl_add_u64 v[190:191], s[8:9], 0, v[172:173]
	s_add_i32 m0, s39, 0xe000
	s_nop 0
	global_load_lds_dwordx4 v[190:191], off
	s_waitcnt lgkmcnt(8)
	s_barrier
	s_waitcnt lgkmcnt(0)
	s_waitcnt lgkmcnt(0)
	v_mfma_f32_16x16x32_bf16 v[68:71], v[88:91], v[122:125], v[68:71]
	v_mfma_f32_16x16x32_bf16 v[64:67], v[106:109], v[122:125], v[64:67]
	v_mfma_f32_16x16x32_bf16 v[158:161], v[88:91], v[138:141], v[158:161]
	v_mfma_f32_16x16x32_bf16 v[154:157], v[106:109], v[138:141], v[154:157]
	v_mfma_f32_16x16x32_bf16 v[150:153], v[88:91], v[174:177], v[150:153]
	v_mfma_f32_16x16x32_bf16 v[146:149], v[106:109], v[174:177], v[146:149]
	v_mfma_f32_16x16x32_bf16 v[134:137], v[88:91], v[182:185], v[134:137]
	v_mfma_f32_16x16x32_bf16 v[130:133], v[106:109], v[182:185], v[130:133]
	v_mfma_f32_16x16x32_bf16 v[68:71], v[92:95], v[126:129], v[68:71]
	v_mfma_f32_16x16x32_bf16 v[64:67], v[110:113], v[126:129], v[64:67]
	v_mfma_f32_16x16x32_bf16 v[158:161], v[92:95], v[142:145], v[158:161]
	v_mfma_f32_16x16x32_bf16 v[154:157], v[110:113], v[142:145], v[154:157]
	v_mfma_f32_16x16x32_bf16 v[150:153], v[92:95], v[178:181], v[150:153]
	v_mfma_f32_16x16x32_bf16 v[146:149], v[110:113], v[178:181], v[146:149]
	v_mfma_f32_16x16x32_bf16 v[134:137], v[92:95], v[186:189], v[134:137]
	v_mfma_f32_16x16x32_bf16 v[130:133], v[110:113], v[186:189], v[130:133]
	s_barrier
	s_add_i32 s0, 0, 0x14000
	s_add_i32 s49, s49, s38
	v_add_u32_e32 v96, s0, v196
	v_lshl_add_u64 v[210:211], s[24:25], 0, v[164:165]
	s_mov_b32 m0, s49
	ds_read_b128 v[190:193], v96
	ds_read_b128 v[198:201], v96 offset:1024
	ds_read_b128 v[202:205], v96 offset:2048
	ds_read_b128 v[206:209], v96 offset:3072
	global_load_lds_dwordx4 v[210:211], off
	v_lshl_add_u64 v[212:213], s[24:25], 0, v[168:169]
	s_add_i32 m0, s49, 0x2000
	s_nop 0
	global_load_lds_dwordx4 v[212:213], off
	s_barrier
	s_waitcnt lgkmcnt(0)
	s_waitcnt lgkmcnt(0)
	v_mfma_f32_16x16x32_bf16 v[56:59], v[190:193], v[122:125], v[56:59]
	v_mfma_f32_16x16x32_bf16 v[60:63], v[202:205], v[122:125], v[60:63]
	v_mfma_f32_16x16x32_bf16 v[48:51], v[190:193], v[138:141], v[48:51]
	v_mfma_f32_16x16x32_bf16 v[52:55], v[202:205], v[138:141], v[52:55]
	v_mfma_f32_16x16x32_bf16 v[40:43], v[190:193], v[174:177], v[40:43]
	v_mfma_f32_16x16x32_bf16 v[44:47], v[202:205], v[174:177], v[44:47]
	v_mfma_f32_16x16x32_bf16 v[32:35], v[190:193], v[182:185], v[32:35]
	v_mfma_f32_16x16x32_bf16 v[36:39], v[202:205], v[182:185], v[36:39]
	v_mfma_f32_16x16x32_bf16 v[56:59], v[198:201], v[126:129], v[56:59]
	v_mfma_f32_16x16x32_bf16 v[60:63], v[206:209], v[126:129], v[60:63]
	v_mfma_f32_16x16x32_bf16 v[48:51], v[198:201], v[142:145], v[48:51]
	v_mfma_f32_16x16x32_bf16 v[52:55], v[206:209], v[142:145], v[52:55]
	v_mfma_f32_16x16x32_bf16 v[40:43], v[198:201], v[178:181], v[40:43]
	v_mfma_f32_16x16x32_bf16 v[44:47], v[206:209], v[178:181], v[44:47]
	v_mfma_f32_16x16x32_bf16 v[32:35], v[198:201], v[186:189], v[32:35]
	v_mfma_f32_16x16x32_bf16 v[36:39], v[206:209], v[186:189], v[36:39]
	s_mov_b32 m0, s39
	v_lshl_add_u64 v[214:215], s[26:27], 0, v[162:163]
	s_barrier
	ds_read_b128 v[122:125], v197 offset:16384
	ds_read_b128 v[126:129], v197 offset:17408
	ds_read_b128 v[138:141], v197 offset:18432
	ds_read_b128 v[142:145], v197 offset:19456
	ds_read_b128 v[174:177], v197 offset:20480
	ds_read_b128 v[178:181], v197 offset:21504
	ds_read_b128 v[182:185], v197 offset:22528
	ds_read_b128 v[186:189], v197 offset:23552
	global_load_lds_dwordx4 v[214:215], off
	v_lshl_add_u64 v[216:217], s[26:27], 0, v[166:167]
	s_mov_b32 m0, s40
	s_nop 0
	global_load_lds_dwordx4 v[216:217], off
	s_barrier
	s_waitcnt lgkmcnt(0)
	s_waitcnt lgkmcnt(0)
	v_mfma_f32_16x16x32_bf16 v[118:121], v[88:91], v[122:125], v[118:121]
	v_mfma_f32_16x16x32_bf16 v[114:117], v[106:109], v[122:125], v[114:117]
	v_mfma_f32_16x16x32_bf16 v[102:105], v[88:91], v[138:141], v[102:105]
	v_mfma_f32_16x16x32_bf16 v[98:101], v[106:109], v[138:141], v[98:101]
	v_mfma_f32_16x16x32_bf16 v[84:87], v[88:91], v[174:177], v[84:87]
	v_mfma_f32_16x16x32_bf16 v[80:83], v[106:109], v[174:177], v[80:83]
	v_mfma_f32_16x16x32_bf16 v[76:79], v[88:91], v[182:185], v[76:79]
	v_mfma_f32_16x16x32_bf16 v[72:75], v[106:109], v[182:185], v[72:75]
	v_mfma_f32_16x16x32_bf16 v[118:121], v[92:95], v[126:129], v[118:121]
	v_mfma_f32_16x16x32_bf16 v[114:117], v[110:113], v[126:129], v[114:117]
	v_mfma_f32_16x16x32_bf16 v[102:105], v[92:95], v[142:145], v[102:105]
	v_mfma_f32_16x16x32_bf16 v[98:101], v[110:113], v[142:145], v[98:101]
	v_mfma_f32_16x16x32_bf16 v[84:87], v[92:95], v[178:181], v[84:87]
	v_mfma_f32_16x16x32_bf16 v[80:83], v[110:113], v[178:181], v[80:83]
	v_mfma_f32_16x16x32_bf16 v[76:79], v[92:95], v[186:189], v[76:79]
	v_mfma_f32_16x16x32_bf16 v[72:75], v[110:113], v[186:189], v[72:75]
	s_barrier
; #define PG8_STAGE(bufoff, gbase, voff) do { _Pragma("unroll") for (int _i = 0; _i < 2; ++_i) \
;     __builtin_amdgcn_global_load_lds((const unsigned*)((const char*)(gbase) + (voff)[_i]), (LAS unsigned*)(lds + (bufoff) + ldsw + _i * 8192), 16, 0, 0); } while (0)
; #define PG8_LDA(dst, b, h) do { _Pragma("unroll") for (int m = 0; m < 4; ++m) _Pragma("unroll") for (int k = 0; k < 2; ++k) dst[m][k] = *(const LAS bf16x8*)(lds + PG8_SA(b, h) + aoff + m * 2048 + k * 1024); } while (0)
; #define PG8_LDB(dst, b, h) do { _Pragma("unroll") for (int n = 0; n < 2; ++n) _Pragma("unroll") for (int k = 0; k < 2; ++k) dst[n][k] = *(const LAS bf16x8*)(lds + PG8_SB(b, h) + boff + n * 2048 + k * 1024); } while (0)
; #define PG8_MMA(ai, bj, At, Bt) do { __builtin_amdgcn_s_setprio(1); _Pragma("unroll") for (int m = 0; m < 4; ++m) _Pragma("unroll") for (int n = 0; n < 2; ++n) _Pragma("unroll") for (int k = 0; k < 2; ++k) \
;     acc[ai][bj][m][n] = __builtin_amdgcn_mfma_f32_16x16x32_bf16(Bt[n][k], At[m][k], acc[ai][bj][m][n], 0, 0, 0); __builtin_amdgcn_s_setprio(0); } while (0)
; #define PG8_WAIT_V(n) asm volatile("s_waitcnt vmcnt(" #n ")" ::: "memory")
; #define PG8_WAIT_L(n) asm volatile("s_waitcnt lgkmcnt(" #n ")" ::: "memory")
; #define PG8_BAR __builtin_amdgcn_s_barrier()
; #define PG8_SCHED __builtin_amdgcn_sched_barrier(0)
; template <class Epi>
; __device__ __forceinline__ void gemm_phase(LAS unsigned char* lds, const Gemm g, const StaticOrder& S, const Epi& E, int wv0) {
;     ...
;       PG8_STAGE(PG8_SB(0, 1), b2 + hstepB, voffB);
;       PG8_WAIT_V(6); PG8_BAR; PG8_MMA(1, 1, At, B1); PG8_BAR;
;       PG8_LDB(B0, 1, 0); PG8_SCHED; PG8_LDA(At, 1, 0); PG8_STAGE(PG8_SA(0, 1), a2 + hstepA, voffA);
;       PG8_WAIT_L(8); PG8_BAR; PG8_WAIT_L(0); PG8_MMA(0, 0, At, B0); PG8_BAR; PG8_SCHED;
;       PG8_LDB(B1, 1, 1); PG8_STAGE(PG8_SB(1, 0), b3, voffB);
;       PG8_BAR; PG8_WAIT_L(0); PG8_MMA(0, 1, At, B1); PG8_BAR;
;       PG8_LDA(At, 1, 1); PG8_STAGE(PG8_SA(1, 0), a3, voffA);
	s_add_u32 s50, s24, 0x80000
	s_addc_u32 s51, s25, 0
	s_add_i32 s0, s0, s38
	v_lshl_add_u64 v[88:89], s[50:51], 0, v[164:165]
	s_mov_b32 m0, s0
	s_nop 0
	global_load_lds_dwordx4 v[88:89], off
	v_lshl_add_u64 v[88:89], s[50:51], 0, v[168:169]
	s_add_i32 m0, s0, 0x2000
	s_nop 0
	global_load_lds_dwordx4 v[88:89], off
	s_waitcnt vmcnt(6)
	s_barrier
	v_mfma_f32_16x16x32_bf16 v[24:27], v[190:193], v[122:125], v[24:27]
	v_mfma_f32_16x16x32_bf16 v[28:31], v[202:205], v[122:125], v[28:31]
	v_mfma_f32_16x16x32_bf16 v[16:19], v[190:193], v[138:141], v[16:19]
	v_mfma_f32_16x16x32_bf16 v[20:23], v[202:205], v[138:141], v[20:23]
	v_mfma_f32_16x16x32_bf16 v[8:11], v[190:193], v[174:177], v[8:11]
	v_mfma_f32_16x16x32_bf16 v[12:15], v[202:205], v[174:177], v[12:15]
	v_mfma_f32_16x16x32_bf16 v[0:3], v[190:193], v[182:185], v[0:3]
	v_mfma_f32_16x16x32_bf16 v[4:7], v[202:205], v[182:185], v[4:7]
	v_mfma_f32_16x16x32_bf16 v[24:27], v[198:201], v[126:129], v[24:27]
	v_mfma_f32_16x16x32_bf16 v[28:31], v[206:209], v[126:129], v[28:31]
	v_mfma_f32_16x16x32_bf16 v[16:19], v[198:201], v[142:145], v[16:19]
	v_mfma_f32_16x16x32_bf16 v[20:23], v[206:209], v[142:145], v[20:23]
	v_mfma_f32_16x16x32_bf16 v[8:11], v[198:201], v[178:181], v[8:11]
	v_mfma_f32_16x16x32_bf16 v[12:15], v[206:209], v[178:181], v[12:15]
	v_mfma_f32_16x16x32_bf16 v[0:3], v[198:201], v[186:189], v[0:3]
	v_mfma_f32_16x16x32_bf16 v[4:7], v[206:209], v[186:189], v[4:7]
	s_add_i32 s0, 0, 0x18000
	v_add_u32_e32 v96, s0, v196
	s_barrier
	ds_read_b128 v[88:91], v96
	ds_read_b128 v[92:95], v96 offset:1024
	ds_read_b128 v[106:109], v96 offset:2048
	ds_read_b128 v[110:113], v96 offset:3072
	s_add_u32 s26, s26, 0x80000
	s_addc_u32 s27, s27, 0
	s_mov_b32 m0, s41
	v_lshl_add_u64 v[190:191], s[26:27], 0, v[162:163]
	ds_read_b128 v[122:125], v197 offset:32768
	ds_read_b128 v[126:129], v197 offset:33792
	ds_read_b128 v[138:141], v197 offset:34816
	ds_read_b128 v[142:145], v197 offset:35840
	ds_read_b128 v[174:177], v197 offset:36864
	ds_read_b128 v[178:181], v197 offset:37888
	ds_read_b128 v[182:185], v197 offset:38912
	ds_read_b128 v[186:189], v197 offset:39936
	global_load_lds_dwordx4 v[190:191], off
	v_lshl_add_u64 v[190:191], s[26:27], 0, v[166:167]
	s_mov_b32 m0, s42
	s_nop 0
	global_load_lds_dwordx4 v[190:191], off
	s_waitcnt lgkmcnt(8)
	s_barrier
	s_waitcnt lgkmcnt(0)
	s_waitcnt lgkmcnt(0)
	v_mfma_f32_16x16x32_bf16 v[68:71], v[88:91], v[122:125], v[68:71]
	v_mfma_f32_16x16x32_bf16 v[64:67], v[106:109], v[122:125], v[64:67]
	v_mfma_f32_16x16x32_bf16 v[158:161], v[88:91], v[138:141], v[158:161]
	v_mfma_f32_16x16x32_bf16 v[154:157], v[106:109], v[138:141], v[154:157]
	v_mfma_f32_16x16x32_bf16 v[150:153], v[88:91], v[174:177], v[150:153]
	v_mfma_f32_16x16x32_bf16 v[146:149], v[106:109], v[174:177], v[146:149]
	v_mfma_f32_16x16x32_bf16 v[134:137], v[88:91], v[182:185], v[134:137]
	v_mfma_f32_16x16x32_bf16 v[130:133], v[106:109], v[182:185], v[130:133]
	v_mfma_f32_16x16x32_bf16 v[68:71], v[92:95], v[126:129], v[68:71]
	v_mfma_f32_16x16x32_bf16 v[64:67], v[110:113], v[126:129], v[64:67]
	v_mfma_f32_16x16x32_bf16 v[158:161], v[92:95], v[142:145], v[158:161]
	v_mfma_f32_16x16x32_bf16 v[154:157], v[110:113], v[142:145], v[154:157]
	v_mfma_f32_16x16x32_bf16 v[150:153], v[92:95], v[178:181], v[150:153]
	v_mfma_f32_16x16x32_bf16 v[146:149], v[110:113], v[178:181], v[146:149]
	v_mfma_f32_16x16x32_bf16 v[134:137], v[92:95], v[186:189], v[134:137]
	v_mfma_f32_16x16x32_bf16 v[130:133], v[110:113], v[186:189], v[130:133]
	s_barrier
	s_add_i32 s26, 0, 0x1c000
	s_add_i32 s0, s0, s38
	v_add_u32_e32 v96, s26, v196
	v_lshl_add_u64 v[210:211], v[210:211], 0, s[72:73]
	s_mov_b32 m0, s0
	ds_read_b128 v[190:193], v96
	ds_read_b128 v[198:201], v96 offset:1024
	ds_read_b128 v[202:205], v96 offset:2048
	ds_read_b128 v[206:209], v96 offset:3072
	global_load_lds_dwordx4 v[210:211], off
	v_lshl_add_u64 v[210:211], v[212:213], 0, s[72:73]
	s_add_i32 m0, s0, 0x2000
	s_nop 0
	global_load_lds_dwordx4 v[210:211], off
	s_barrier
; #define PG8_STAGE(bufoff, gbase, voff) do { _Pragma("unroll") for (int _i = 0; _i < 2; ++_i) \
;     __builtin_amdgcn_global_load_lds((const unsigned*)((const char*)(gbase) + (voff)[_i]), (LAS unsigned*)(lds + (bufoff) + ldsw + _i * 8192), 16, 0, 0); } while (0)
; #define PG8_LDA(dst, b, h) do { _Pragma("unroll") for (int m = 0; m < 4; ++m) _Pragma("unroll") for (int k = 0; k < 2; ++k) dst[m][k] = *(const LAS bf16x8*)(lds + PG8_SA(b, h) + aoff + m * 2048 + k * 1024); } while (0)
; #define PG8_MMA(ai, bj, At, Bt) do { __builtin_amdgcn_s_setprio(1); _Pragma("unroll") for (int m = 0; m < 4; ++m) _Pragma("unroll") for (int n = 0; n < 2; ++n) _Pragma("unroll") for (int k = 0; k < 2; ++k) \
;     acc[ai][bj][m][n] = __builtin_amdgcn_mfma_f32_16x16x32_bf16(Bt[n][k], At[m][k], acc[ai][bj][m][n], 0, 0, 0); __builtin_amdgcn_s_setprio(0); } while (0)
; #define PG8_WAIT_V(n) asm volatile("s_waitcnt vmcnt(" #n ")" ::: "memory")
; #define PG8_WAIT_L(n) asm volatile("s_waitcnt lgkmcnt(" #n ")" ::: "memory")
; #define PG8_BAR __builtin_amdgcn_s_barrier()
; #define PG8_SCHED __builtin_amdgcn_sched_barrier(0)
; template <class Epi>
; __device__ __forceinline__ void gemm_phase(LAS unsigned char* lds, const Gemm g, const StaticOrder& S, const Epi& E, int wv0) {
;     ...
;       PG8_BAR; PG8_WAIT_L(0); PG8_MMA(0, 1, At, B1); PG8_BAR;
;       PG8_LDA(At, 1, 1); PG8_STAGE(PG8_SA(1, 0), a3, voffA);
;       PG8_BAR; PG8_WAIT_L(0); PG8_MMA(1, 0, At, B0); PG8_BAR; PG8_SCHED;
;       PG8_STAGE(PG8_SB(1, 1), b3 + hstepB, voffB);
;       PG8_WAIT_V(6); PG8_BAR; PG8_MMA(1, 1, At, B1); PG8_BAR;
;     }
;     E(acc, cur, wr, wc, fr, fq);
;     if (!has_next) break;
;   __device__ __forceinline__ void preload(EpiPre& q, int row, int col) const {
;     if (MODE == E_GATE || MODE == E_UKV) return;
;     if (MODE == E_MAIN) {
;       if (col >= C_KR && col < C_HU) { const float* cs = e.f0 + ((size_t)row * 32 + ((col - C_KR) >> 1)) * 2; q.a0 = *(const f32x4*)cs; q.a1 = *(const f32x4*)(cs + 4); }
	s_waitcnt lgkmcnt(0)
	s_waitcnt lgkmcnt(0)
	v_mfma_f32_16x16x32_bf16 v[56:59], v[190:193], v[122:125], v[56:59]
	v_mfma_f32_16x16x32_bf16 v[60:63], v[202:205], v[122:125], v[60:63]
	v_mfma_f32_16x16x32_bf16 v[48:51], v[190:193], v[138:141], v[48:51]
	v_mfma_f32_16x16x32_bf16 v[52:55], v[202:205], v[138:141], v[52:55]
	v_mfma_f32_16x16x32_bf16 v[40:43], v[190:193], v[174:177], v[40:43]
	v_mfma_f32_16x16x32_bf16 v[44:47], v[202:205], v[174:177], v[44:47]
	v_mfma_f32_16x16x32_bf16 v[32:35], v[190:193], v[182:185], v[32:35]
	v_mfma_f32_16x16x32_bf16 v[36:39], v[202:205], v[182:185], v[36:39]
	v_mfma_f32_16x16x32_bf16 v[56:59], v[198:201], v[126:129], v[56:59]
	v_mfma_f32_16x16x32_bf16 v[60:63], v[206:209], v[126:129], v[60:63]
	v_mfma_f32_16x16x32_bf16 v[48:51], v[198:201], v[142:145], v[48:51]
	v_mfma_f32_16x16x32_bf16 v[52:55], v[206:209], v[142:145], v[52:55]
	v_mfma_f32_16x16x32_bf16 v[40:43], v[198:201], v[178:181], v[40:43]
	v_mfma_f32_16x16x32_bf16 v[44:47], v[206:209], v[178:181], v[44:47]
	v_mfma_f32_16x16x32_bf16 v[32:35], v[198:201], v[186:189], v[32:35]
	v_mfma_f32_16x16x32_bf16 v[36:39], v[206:209], v[186:189], v[36:39]
	s_mov_b32 m0, s44
	v_lshl_add_u64 v[210:211], v[214:215], 0, s[72:73]
	s_barrier
	ds_read_b128 v[122:125], v197 offset:49152
	ds_read_b128 v[126:129], v197 offset:50176
	ds_read_b128 v[138:141], v197 offset:51200
	ds_read_b128 v[142:145], v197 offset:52224
	ds_read_b128 v[174:177], v197 offset:53248
	ds_read_b128 v[178:181], v197 offset:54272
	ds_read_b128 v[182:185], v197 offset:55296
	ds_read_b128 v[186:189], v197 offset:56320
	global_load_lds_dwordx4 v[210:211], off
	v_lshl_add_u64 v[210:211], v[216:217], 0, s[72:73]
	s_mov_b32 m0, s45
	s_nop 0
	global_load_lds_dwordx4 v[210:211], off
	s_barrier
	s_waitcnt lgkmcnt(0)
	s_waitcnt lgkmcnt(0)
	v_mfma_f32_16x16x32_bf16 v[118:121], v[88:91], v[122:125], v[118:121]
	v_mfma_f32_16x16x32_bf16 v[114:117], v[106:109], v[122:125], v[114:117]
	v_mfma_f32_16x16x32_bf16 v[102:105], v[88:91], v[138:141], v[102:105]
	v_mfma_f32_16x16x32_bf16 v[98:101], v[106:109], v[138:141], v[98:101]
	v_mfma_f32_16x16x32_bf16 v[84:87], v[88:91], v[174:177], v[84:87]
	v_mfma_f32_16x16x32_bf16 v[80:83], v[106:109], v[174:177], v[80:83]
	v_mfma_f32_16x16x32_bf16 v[76:79], v[88:91], v[182:185], v[76:79]
	v_mfma_f32_16x16x32_bf16 v[72:75], v[106:109], v[182:185], v[72:75]
	v_mfma_f32_16x16x32_bf16 v[118:121], v[92:95], v[126:129], v[118:121]
	v_mfma_f32_16x16x32_bf16 v[114:117], v[110:113], v[126:129], v[114:117]
	v_mfma_f32_16x16x32_bf16 v[102:105], v[92:95], v[142:145], v[102:105]
	v_mfma_f32_16x16x32_bf16 v[98:101], v[110:113], v[142:145], v[98:101]
	v_mfma_f32_16x16x32_bf16 v[84:87], v[92:95], v[178:181], v[84:87]
	v_mfma_f32_16x16x32_bf16 v[80:83], v[110:113], v[178:181], v[80:83]
	v_mfma_f32_16x16x32_bf16 v[76:79], v[92:95], v[186:189], v[76:79]
	v_mfma_f32_16x16x32_bf16 v[72:75], v[110:113], v[186:189], v[72:75]
	s_barrier
	s_add_u32 s24, s24, 0x80080
	s_addc_u32 s25, s25, 0
	s_add_i32 s0, s26, s38
	v_lshl_add_u64 v[88:89], s[24:25], 0, v[164:165]
	s_mov_b32 m0, s0
	s_nop 0
	global_load_lds_dwordx4 v[88:89], off
	v_lshl_add_u64 v[88:89], s[24:25], 0, v[168:169]
	s_add_i32 m0, s0, 0x2000
	s_nop 0
	global_load_lds_dwordx4 v[88:89], off
	s_waitcnt vmcnt(6)
	s_barrier
	v_mfma_f32_16x16x32_bf16 v[24:27], v[190:193], v[122:125], v[24:27]
	v_mfma_f32_16x16x32_bf16 v[28:31], v[202:205], v[122:125], v[28:31]
	v_mfma_f32_16x16x32_bf16 v[16:19], v[190:193], v[138:141], v[16:19]
	v_mfma_f32_16x16x32_bf16 v[20:23], v[202:205], v[138:141], v[20:23]
	v_mfma_f32_16x16x32_bf16 v[8:11], v[190:193], v[174:177], v[8:11]
	v_mfma_f32_16x16x32_bf16 v[12:15], v[202:205], v[174:177], v[12:15]
	v_mfma_f32_16x16x32_bf16 v[0:3], v[190:193], v[182:185], v[0:3]
	v_mfma_f32_16x16x32_bf16 v[4:7], v[202:205], v[182:185], v[4:7]
	v_mfma_f32_16x16x32_bf16 v[24:27], v[198:201], v[126:129], v[24:27]
	v_mfma_f32_16x16x32_bf16 v[28:31], v[206:209], v[126:129], v[28:31]
	v_mfma_f32_16x16x32_bf16 v[16:19], v[198:201], v[142:145], v[16:19]
	v_mfma_f32_16x16x32_bf16 v[20:23], v[206:209], v[142:145], v[20:23]
	v_mfma_f32_16x16x32_bf16 v[8:11], v[198:201], v[178:181], v[8:11]
	v_mfma_f32_16x16x32_bf16 v[12:15], v[206:209], v[178:181], v[12:15]
	v_mfma_f32_16x16x32_bf16 v[0:3], v[198:201], v[186:189], v[0:3]
	v_mfma_f32_16x16x32_bf16 v[4:7], v[206:209], v[186:189], v[4:7]
	s_add_i32 s29, s29, 2
	s_add_u32 s8, s8, 0x100
	s_addc_u32 s9, s9, 0
	s_add_u32 s19, s19, 0x100
	s_addc_u32 s28, s28, 0
	s_cmp_gt_u32 s29, 29
	s_barrier
	s_cbranch_scc0 .LBB0_153
	s_setprio 0
	s_lshl_b32 s0, s4, 8
	s_or_b32 s17, s0, s43
	s_and_b32 s0, s17, 0xffffff40
	v_bitop3_b32 v88, s17, 56, v195 bitop3:0xc8
	v_lshlrev_b32_e32 v96, 2, v88
	s_cmpk_eq_i32 s0, 0x500
	v_lshl_add_u32 v176, s6, 8, v194
	s_cselect_b64 s[4:5], -1, 0
	s_cmpk_lg_i32 s0, 0x500
	v_lshl_add_u64 v[178:179], s[14:15], 0, v[96:97]
	s_cbranch_scc1 .LBB0_156
	v_ashrrev_i32_e32 v177, 31, v176
	v_lshlrev_b64 v[88:89], 8, v[176:177]
	v_lshl_add_u64 v[88:89], v[178:179], 0, v[88:89]
	global_load_dwordx4 v[138:141], v[88:89], off offset:16
	global_load_dwordx4 v[142:145], v[88:89], off

; #define PG8_STAGE(bufoff, gbase, voff) do { _Pragma("unroll") for (int _i = 0; _i < 2; ++_i) \
;     __builtin_amdgcn_global_load_lds((const unsigned*)((const char*)(gbase) + (voff)[_i]), (LAS unsigned*)(lds + (bufoff) + ldsw + _i * 8192), 16, 0, 0); } while (0)
; #define PG8_LDA(dst, b, h) do { _Pragma("unroll") for (int m = 0; m < 4; ++m) _Pragma("unroll") for (int k = 0; k < 2; ++k) dst[m][k] = *(const LAS bf16x8*)(lds + PG8_SA(b, h) + aoff + m * 2048 + k * 1024); } while (0)
; #define PG8_LDB(dst, b, h) do { _Pragma("unroll") for (int n = 0; n < 2; ++n) _Pragma("unroll") for (int k = 0; k < 2; ++k) dst[n][k] = *(const LAS bf16x8*)(lds + PG8_SB(b, h) + boff + n * 2048 + k * 1024); } while (0)
; #define PG8_MMA(ai, bj, At, Bt) do { __builtin_amdgcn_s_setprio(1); _Pragma("unroll") for (int m = 0; m < 4; ++m) _Pragma("unroll") for (int n = 0; n < 2; ++n) _Pragma("unroll") for (int k = 0; k < 2; ++k) \
;     acc[ai][bj][m][n] = __builtin_amdgcn_mfma_f32_16x16x32_bf16(Bt[n][k], At[m][k], acc[ai][bj][m][n], 0, 0, 0); __builtin_amdgcn_s_setprio(0); } while (0)
; #define PG8_WAIT_L(n) asm volatile("s_waitcnt lgkmcnt(" #n ")" ::: "memory")
; #define PG8_BAR __builtin_amdgcn_s_barrier()
; #define PG8_SCHED __builtin_amdgcn_sched_barrier(0)
; template <class Epi>
; __device__ __forceinline__ void gemm_phase(LAS unsigned char* lds, const Gemm g, const StaticOrder& S, const Epi& E, int wv0) {
;     ...
;     for (int t = 0; t < nt; t += 2) {
;       const bool last = (t == nt - 2);
;       const char* a1 = cA + (size_t)(t + 1) * kstep;
;       const char* a2 = last ? nA : cA + (size_t)(t + 2) * kstep; const char* b2 = last ? nB : cB + (size_t)(t + 2) * kstep;
;       const char* a3 = a2 + kstep; const char* b3 = b2 + kstep;
;       PG8_LDB(B0, 0, 0); PG8_SCHED; PG8_LDA(At, 0, 0); PG8_STAGE(PG8_SA(1, 1), a1 + hstepA, voffA);
;       PG8_WAIT_L(8); PG8_BAR; PG8_WAIT_L(0); PG8_MMA(0, 0, At, B0); PG8_BAR; PG8_SCHED;
;       PG8_LDB(B1, 0, 1); PG8_STAGE(PG8_SB(0, 0), b2, voffB);
;       PG8_BAR; PG8_WAIT_L(0); PG8_MMA(0, 1, At, B1); PG8_BAR;
;       PG8_LDA(At, 0, 1); PG8_STAGE(PG8_SA(0, 0), a2, voffA);
;       PG8_BAR; PG8_WAIT_L(0); PG8_MMA(1, 0, At, B0); PG8_BAR; PG8_SCHED;
.LBB0_671:
	s_add_u32 s4, s18, 0x100
	s_addc_u32 s5, s19, 0
	s_add_i32 s0, 0, 0x10000
	s_waitcnt vmcnt(6)
	v_add_u32_e32 v80, s0, v253
	ds_read_b128 v[72:75], v80
	ds_read_b128 v[76:79], v80 offset:1024
	ds_read_b128 v[90:93], v80 offset:2048
	ds_read_b128 v[98:101], v80 offset:3072
	s_cmp_eq_u32 s46, 4
	s_cselect_b32 s23, s13, s5
	s_cselect_b32 s22, s12, s4
	s_cselect_b32 s21, s11, s45
	s_cselect_b32 s20, s17, s44
	v_lshl_add_u64 v[80:81], s[18:19], 0, v[230:231]
	s_add_i32 m0, s34, 0xc000
	ds_read_b128 v[110:113], v244
	ds_read_b128 v[114:117], v244 offset:1024
	ds_read_b128 v[118:121], v244 offset:2048
	ds_read_b128 v[122:125], v244 offset:3072
	ds_read_b128 v[136:139], v244 offset:4096
	ds_read_b128 v[140:143], v244 offset:5120
	ds_read_b128 v[144:147], v244 offset:6144
	ds_read_b128 v[148:151], v244 offset:7168
	global_load_lds_dwordx4 v[80:81], off
	v_lshl_add_u64 v[80:81], s[18:19], 0, v[232:233]
	s_add_i32 m0, s34, 0xe000
	s_nop 0
	global_load_lds_dwordx4 v[80:81], off
	s_waitcnt lgkmcnt(8)
	s_barrier
	s_waitcnt lgkmcnt(0)
	s_waitcnt lgkmcnt(0)
	v_mfma_f32_16x16x32_bf16 v[132:135], v[72:75], v[136:139], v[132:135]
	v_mfma_f32_16x16x32_bf16 v[126:129], v[90:93], v[136:139], v[128:131]
	v_mfma_f32_16x16x32_bf16 v[86:89], v[72:75], v[144:147], v[86:89]
	v_mfma_f32_16x16x32_bf16 v[80:83], v[90:93], v[144:147], v[82:85]
	v_mfma_f32_16x16x32_bf16 v[152:155], v[72:75], v[110:113], v[202:205]
	v_mfma_f32_16x16x32_bf16 v[156:159], v[90:93], v[110:113], v[198:201]
	v_mfma_f32_16x16x32_bf16 v[170:173], v[72:75], v[118:121], v[186:189]
	v_mfma_f32_16x16x32_bf16 v[174:177], v[90:93], v[118:121], v[182:185]
	v_mfma_f32_16x16x32_bf16 v[132:135], v[76:79], v[140:143], v[132:135]
	v_mfma_f32_16x16x32_bf16 v[126:129], v[98:101], v[140:143], v[126:129]
	v_mfma_f32_16x16x32_bf16 v[86:89], v[76:79], v[148:151], v[86:89]
	v_mfma_f32_16x16x32_bf16 v[80:83], v[98:101], v[148:151], v[80:83]
	v_mfma_f32_16x16x32_bf16 v[152:155], v[76:79], v[114:117], v[152:155]
	v_mfma_f32_16x16x32_bf16 v[156:159], v[98:101], v[114:117], v[156:159]
	v_mfma_f32_16x16x32_bf16 v[170:173], v[76:79], v[122:125], v[170:173]
	v_mfma_f32_16x16x32_bf16 v[174:177], v[98:101], v[122:125], v[174:177]
	s_barrier
	s_add_i32 s47, 0, 0x14000
	s_add_i32 s0, s0, s31
	v_add_u32_e32 v84, s47, v253
	v_lshl_add_u64 v[214:215], s[20:21], 0, v[224:225]
	s_mov_b32 m0, s0
	ds_read_b128 v[178:181], v84
	ds_read_b128 v[182:185], v84 offset:1024
	ds_read_b128 v[186:189], v84 offset:2048
	ds_read_b128 v[198:201], v84 offset:3072
	global_load_lds_dwordx4 v[214:215], off
	v_lshl_add_u64 v[216:217], s[20:21], 0, v[228:229]
	s_add_i32 m0, s0, 0x2000
	s_nop 0
	global_load_lds_dwordx4 v[216:217], off
	s_barrier
	s_waitcnt lgkmcnt(0)
	s_waitcnt lgkmcnt(0)
	v_mfma_f32_16x16x32_bf16 v[194:197], v[178:181], v[110:113], v[194:197]
	v_mfma_f32_16x16x32_bf16 v[110:113], v[186:189], v[110:113], v[190:193]
	v_mfma_f32_16x16x32_bf16 v[106:109], v[178:181], v[136:139], v[106:109]
	v_mfma_f32_16x16x32_bf16 v[102:105], v[186:189], v[136:139], v[102:105]
	v_mfma_f32_16x16x32_bf16 v[68:71], v[178:181], v[144:147], v[68:71]
	v_mfma_f32_16x16x32_bf16 v[64:67], v[186:189], v[144:147], v[64:67]
	v_mfma_f32_16x16x32_bf16 v[194:197], v[182:185], v[114:117], v[194:197]
	v_mfma_f32_16x16x32_bf16 v[110:113], v[198:201], v[114:117], v[110:113]
	v_mfma_f32_16x16x32_bf16 v[114:117], v[178:181], v[118:121], v[166:169]
	v_mfma_f32_16x16x32_bf16 v[118:121], v[186:189], v[118:121], v[162:165]
	v_mfma_f32_16x16x32_bf16 v[106:109], v[182:185], v[140:143], v[106:109]
	v_mfma_f32_16x16x32_bf16 v[102:105], v[198:201], v[140:143], v[102:105]
	v_mfma_f32_16x16x32_bf16 v[68:71], v[182:185], v[148:151], v[68:71]
	v_mfma_f32_16x16x32_bf16 v[64:67], v[198:201], v[148:151], v[64:67]
	v_mfma_f32_16x16x32_bf16 v[114:117], v[182:185], v[122:125], v[114:117]
	v_mfma_f32_16x16x32_bf16 v[118:121], v[198:201], v[122:125], v[118:121]
	s_mov_b32 m0, s34
	v_lshl_add_u64 v[218:219], s[22:23], 0, v[94:95]
	s_barrier
	ds_read_b128 v[122:125], v244 offset:16384
	ds_read_b128 v[136:139], v244 offset:17408
	ds_read_b128 v[140:143], v244 offset:18432
	ds_read_b128 v[144:147], v244 offset:19456
	ds_read_b128 v[148:151], v244 offset:20480
	ds_read_b128 v[160:163], v244 offset:21504
	ds_read_b128 v[164:167], v244 offset:22528
	ds_read_b128 v[190:193], v244 offset:23552
	global_load_lds_dwordx4 v[218:219], off
	v_lshl_add_u64 v[220:221], s[22:23], 0, v[226:227]
	s_mov_b32 m0, s35
	s_nop 0
	global_load_lds_dwordx4 v[220:221], off
	s_barrier
	s_waitcnt lgkmcnt(0)
	s_waitcnt lgkmcnt(0)
	v_mfma_f32_16x16x32_bf16 v[60:63], v[72:75], v[122:125], v[60:63]
	v_mfma_f32_16x16x32_bf16 v[56:59], v[90:93], v[122:125], v[56:59]
	v_mfma_f32_16x16x32_bf16 v[44:47], v[72:75], v[140:143], v[44:47]
	v_mfma_f32_16x16x32_bf16 v[40:43], v[90:93], v[140:143], v[40:43]
	v_mfma_f32_16x16x32_bf16 v[28:31], v[72:75], v[148:151], v[28:31]
	v_mfma_f32_16x16x32_bf16 v[24:27], v[90:93], v[148:151], v[24:27]
	v_mfma_f32_16x16x32_bf16 v[12:15], v[72:75], v[164:167], v[12:15]
	v_mfma_f32_16x16x32_bf16 v[8:11], v[90:93], v[164:167], v[8:11]
	v_mfma_f32_16x16x32_bf16 v[60:63], v[76:79], v[136:139], v[60:63]
	v_mfma_f32_16x16x32_bf16 v[56:59], v[98:101], v[136:139], v[56:59]
	v_mfma_f32_16x16x32_bf16 v[44:47], v[76:79], v[144:147], v[44:47]
	v_mfma_f32_16x16x32_bf16 v[40:43], v[98:101], v[144:147], v[40:43]
	v_mfma_f32_16x16x32_bf16 v[28:31], v[76:79], v[160:163], v[28:31]
	v_mfma_f32_16x16x32_bf16 v[24:27], v[98:101], v[160:163], v[24:27]
	v_mfma_f32_16x16x32_bf16 v[12:15], v[76:79], v[190:193], v[12:15]
	v_mfma_f32_16x16x32_bf16 v[8:11], v[98:101], v[190:193], v[8:11]
	s_barrier
; #define PG8_STAGE(bufoff, gbase, voff) do { _Pragma("unroll") for (int _i = 0; _i < 2; ++_i) \
;     __builtin_amdgcn_global_load_lds((const unsigned*)((const char*)(gbase) + (voff)[_i]), (LAS unsigned*)(lds + (bufoff) + ldsw + _i * 8192), 16, 0, 0); } while (0)
; #define PG8_LDA(dst, b, h) do { _Pragma("unroll") for (int m = 0; m < 4; ++m) _Pragma("unroll") for (int k = 0; k < 2; ++k) dst[m][k] = *(const LAS bf16x8*)(lds + PG8_SA(b, h) + aoff + m * 2048 + k * 1024); } while (0)
; #define PG8_LDB(dst, b, h) do { _Pragma("unroll") for (int n = 0; n < 2; ++n) _Pragma("unroll") for (int k = 0; k < 2; ++k) dst[n][k] = *(const LAS bf16x8*)(lds + PG8_SB(b, h) + boff + n * 2048 + k * 1024); } while (0)
; #define PG8_MMA(ai, bj, At, Bt) do { __builtin_amdgcn_s_setprio(1); _Pragma("unroll") for (int m = 0; m < 4; ++m) _Pragma("unroll") for (int n = 0; n < 2; ++n) _Pragma("unroll") for (int k = 0; k < 2; ++k) \
;     acc[ai][bj][m][n] = __builtin_amdgcn_mfma_f32_16x16x32_bf16(Bt[n][k], At[m][k], acc[ai][bj][m][n], 0, 0, 0); __builtin_amdgcn_s_setprio(0); } while (0)
; #define PG8_WAIT_V(n) asm volatile("s_waitcnt vmcnt(" #n ")" ::: "memory")
; #define PG8_WAIT_L(n) asm volatile("s_waitcnt lgkmcnt(" #n ")" ::: "memory")
; #define PG8_BAR __builtin_amdgcn_s_barrier()
; #define PG8_SCHED __builtin_amdgcn_sched_barrier(0)
; template <class Epi>
; __device__ __forceinline__ void gemm_phase(LAS unsigned char* lds, const Gemm g, const StaticOrder& S, const Epi& E, int wv0) {
;     ...
;       PG8_STAGE(PG8_SB(0, 1), b2 + hstepB, voffB);
;       PG8_WAIT_V(6); PG8_BAR; PG8_MMA(1, 1, At, B1); PG8_BAR;
;       PG8_LDB(B0, 1, 0); PG8_SCHED; PG8_LDA(At, 1, 0); PG8_STAGE(PG8_SA(0, 1), a2 + hstepA, voffA);
;       PG8_WAIT_L(8); PG8_BAR; PG8_WAIT_L(0); PG8_MMA(0, 0, At, B0); PG8_BAR; PG8_SCHED;
;       PG8_LDB(B1, 1, 1); PG8_STAGE(PG8_SB(1, 0), b3, voffB);
;       PG8_BAR; PG8_WAIT_L(0); PG8_MMA(0, 1, At, B1); PG8_BAR;
;       PG8_LDA(At, 1, 1); PG8_STAGE(PG8_SA(1, 0), a3, voffA);
	s_add_u32 s18, s20, 0x20000
	s_addc_u32 s19, s21, 0
	s_add_i32 s0, s47, s31
	v_lshl_add_u64 v[72:73], s[18:19], 0, v[224:225]
	s_mov_b32 m0, s0
	s_nop 0
	global_load_lds_dwordx4 v[72:73], off
	v_lshl_add_u64 v[72:73], s[18:19], 0, v[228:229]
	s_add_i32 m0, s0, 0x2000
	s_nop 0
	global_load_lds_dwordx4 v[72:73], off
	s_waitcnt vmcnt(6)
	s_barrier
	v_mfma_f32_16x16x32_bf16 v[52:55], v[178:181], v[122:125], v[52:55]
	v_mfma_f32_16x16x32_bf16 v[48:51], v[186:189], v[122:125], v[48:51]
	v_mfma_f32_16x16x32_bf16 v[36:39], v[178:181], v[140:143], v[36:39]
	v_mfma_f32_16x16x32_bf16 v[32:35], v[186:189], v[140:143], v[32:35]
	v_mfma_f32_16x16x32_bf16 v[20:23], v[178:181], v[148:151], v[20:23]
	v_mfma_f32_16x16x32_bf16 v[16:19], v[186:189], v[148:151], v[16:19]
	v_mfma_f32_16x16x32_bf16 v[4:7], v[178:181], v[164:167], v[4:7]
	v_mfma_f32_16x16x32_bf16 v[0:3], v[186:189], v[164:167], v[0:3]
	v_mfma_f32_16x16x32_bf16 v[52:55], v[182:185], v[136:139], v[52:55]
	v_mfma_f32_16x16x32_bf16 v[48:51], v[198:201], v[136:139], v[48:51]
	v_mfma_f32_16x16x32_bf16 v[36:39], v[182:185], v[144:147], v[36:39]
	v_mfma_f32_16x16x32_bf16 v[32:35], v[198:201], v[144:147], v[32:35]
	v_mfma_f32_16x16x32_bf16 v[20:23], v[182:185], v[160:163], v[20:23]
	v_mfma_f32_16x16x32_bf16 v[16:19], v[198:201], v[160:163], v[16:19]
	v_mfma_f32_16x16x32_bf16 v[4:7], v[182:185], v[190:193], v[4:7]
	v_mfma_f32_16x16x32_bf16 v[0:3], v[198:201], v[190:193], v[0:3]
	s_add_i32 s0, 0, 0x18000
	v_add_u32_e32 v84, s0, v253
	s_barrier
	ds_read_b128 v[72:75], v84
	ds_read_b128 v[76:79], v84 offset:1024
	ds_read_b128 v[90:93], v84 offset:2048
	ds_read_b128 v[98:101], v84 offset:3072
	s_add_u32 s18, s22, 0x114000
	s_addc_u32 s19, s23, 0
	s_mov_b32 m0, s36
	v_lshl_add_u64 v[84:85], s[18:19], 0, v[94:95]
	ds_read_b128 v[122:125], v244 offset:32768
	ds_read_b128 v[136:139], v244 offset:33792
	ds_read_b128 v[140:143], v244 offset:34816
	ds_read_b128 v[144:147], v244 offset:35840
	ds_read_b128 v[148:151], v244 offset:36864
	ds_read_b128 v[178:181], v244 offset:37888
	ds_read_b128 v[206:209], v244 offset:38912
	ds_read_b128 v[210:213], v244 offset:39936
	global_load_lds_dwordx4 v[84:85], off
	v_lshl_add_u64 v[84:85], s[18:19], 0, v[226:227]
	s_mov_b32 m0, s37
	s_nop 0
	global_load_lds_dwordx4 v[84:85], off
	s_waitcnt lgkmcnt(8)
	s_barrier
	s_waitcnt lgkmcnt(0)
	s_waitcnt lgkmcnt(0)
	v_mfma_f32_16x16x32_bf16 v[152:155], v[72:75], v[122:125], v[152:155]
	v_mfma_f32_16x16x32_bf16 v[202:205], v[76:79], v[136:139], v[152:155]
	v_mfma_f32_16x16x32_bf16 v[152:155], v[90:93], v[122:125], v[156:159]
	v_mfma_f32_16x16x32_bf16 v[198:201], v[98:101], v[136:139], v[152:155]
	v_mfma_f32_16x16x32_bf16 v[152:155], v[72:75], v[140:143], v[170:173]
	v_mfma_f32_16x16x32_bf16 v[186:189], v[76:79], v[144:147], v[152:155]
	v_mfma_f32_16x16x32_bf16 v[152:155], v[90:93], v[140:143], v[174:177]
	v_mfma_f32_16x16x32_bf16 v[130:133], v[72:75], v[148:151], v[132:135]
	v_mfma_f32_16x16x32_bf16 v[126:129], v[90:93], v[148:151], v[126:129]
	v_mfma_f32_16x16x32_bf16 v[84:87], v[72:75], v[206:209], v[86:89]
	v_mfma_f32_16x16x32_bf16 v[80:83], v[90:93], v[206:209], v[80:83]
	v_mfma_f32_16x16x32_bf16 v[182:185], v[98:101], v[144:147], v[152:155]
	v_mfma_f32_16x16x32_bf16 v[132:135], v[76:79], v[178:181], v[130:133]
	v_mfma_f32_16x16x32_bf16 v[128:131], v[98:101], v[178:181], v[126:129]
	v_mfma_f32_16x16x32_bf16 v[86:89], v[76:79], v[210:213], v[84:87]
	v_mfma_f32_16x16x32_bf16 v[82:85], v[98:101], v[210:213], v[80:83]
	s_barrier
	s_add_i32 s22, 0, 0x1c000
	v_add_u32_e32 v80, s22, v253
	s_add_i32 s0, s0, s31
	ds_read_b128 v[152:155], v80
	ds_read_b128 v[156:159], v80 offset:1024
	ds_read_b128 v[170:173], v80 offset:2048
	ds_read_b128 v[174:177], v80 offset:3072
	v_lshl_add_u64 v[80:81], v[214:215], 0, s[72:73]
	s_mov_b32 m0, s0
	s_nop 0
	global_load_lds_dwordx4 v[80:81], off
	v_lshl_add_u64 v[80:81], v[216:217], 0, s[72:73]
	s_add_i32 m0, s0, 0x2000
	s_nop 0
	global_load_lds_dwordx4 v[80:81], off
	s_barrier
	s_waitcnt lgkmcnt(0)
	s_waitcnt lgkmcnt(0)
	v_mfma_f32_16x16x32_bf16 v[110:113], v[170:173], v[122:125], v[110:113]
	v_mfma_f32_16x16x32_bf16 v[190:193], v[174:177], v[136:139], v[110:113]
	v_mfma_f32_16x16x32_bf16 v[110:113], v[152:155], v[140:143], v[114:117]
	v_mfma_f32_16x16x32_bf16 v[160:163], v[152:155], v[122:125], v[194:197]
	v_mfma_f32_16x16x32_bf16 v[166:169], v[156:159], v[144:147], v[110:113]
	v_mfma_f32_16x16x32_bf16 v[110:113], v[170:173], v[140:143], v[118:121]
	v_mfma_f32_16x16x32_bf16 v[106:109], v[152:155], v[148:151], v[106:109]
	v_mfma_f32_16x16x32_bf16 v[102:105], v[170:173], v[148:151], v[102:105]
	v_mfma_f32_16x16x32_bf16 v[68:71], v[152:155], v[206:209], v[68:71]
	v_mfma_f32_16x16x32_bf16 v[64:67], v[170:173], v[206:209], v[64:67]
	v_mfma_f32_16x16x32_bf16 v[194:197], v[156:159], v[136:139], v[160:163]
	v_mfma_f32_16x16x32_bf16 v[162:165], v[174:177], v[144:147], v[110:113]
	v_mfma_f32_16x16x32_bf16 v[106:109], v[156:159], v[178:181], v[106:109]
	v_mfma_f32_16x16x32_bf16 v[102:105], v[174:177], v[178:181], v[102:105]
	v_mfma_f32_16x16x32_bf16 v[68:71], v[156:159], v[210:213], v[68:71]
	v_mfma_f32_16x16x32_bf16 v[64:67], v[174:177], v[210:213], v[64:67]
	s_mov_b32 m0, s38
	v_lshl_add_u64 v[80:81], v[218:219], 0, s[72:73]
	s_barrier
; #define PG8_STAGE(bufoff, gbase, voff) do { _Pragma("unroll") for (int _i = 0; _i < 2; ++_i) \
;     __builtin_amdgcn_global_load_lds((const unsigned*)((const char*)(gbase) + (voff)[_i]), (LAS unsigned*)(lds + (bufoff) + ldsw + _i * 8192), 16, 0, 0); } while (0)
; #define PG8_LDA(dst, b, h) do { _Pragma("unroll") for (int m = 0; m < 4; ++m) _Pragma("unroll") for (int k = 0; k < 2; ++k) dst[m][k] = *(const LAS bf16x8*)(lds + PG8_SA(b, h) + aoff + m * 2048 + k * 1024); } while (0)
; #define PG8_MMA(ai, bj, At, Bt) do { __builtin_amdgcn_s_setprio(1); _Pragma("unroll") for (int m = 0; m < 4; ++m) _Pragma("unroll") for (int n = 0; n < 2; ++n) _Pragma("unroll") for (int k = 0; k < 2; ++k) \
;     acc[ai][bj][m][n] = __builtin_amdgcn_mfma_f32_16x16x32_bf16(Bt[n][k], At[m][k], acc[ai][bj][m][n], 0, 0, 0); __builtin_amdgcn_s_setprio(0); } while (0)
; #define PG8_WAIT_V(n) asm volatile("s_waitcnt vmcnt(" #n ")" ::: "memory")
; #define PG8_WAIT_L(n) asm volatile("s_waitcnt lgkmcnt(" #n ")" ::: "memory")
; #define PG8_BAR __builtin_amdgcn_s_barrier()
; #define PG8_SCHED __builtin_amdgcn_sched_barrier(0)
; template <class Epi>
; __device__ __forceinline__ void gemm_phase(LAS unsigned char* lds, const Gemm g, const StaticOrder& S, const Epi& E, int wv0) {
;     ...
;       PG8_BAR; PG8_WAIT_L(0); PG8_MMA(0, 1, At, B1); PG8_BAR;
;       PG8_LDA(At, 1, 1); PG8_STAGE(PG8_SA(1, 0), a3, voffA);
;       PG8_BAR; PG8_WAIT_L(0); PG8_MMA(1, 0, At, B0); PG8_BAR; PG8_SCHED;
;       PG8_STAGE(PG8_SB(1, 1), b3 + hstepB, voffB);
;       PG8_WAIT_V(6); PG8_BAR; PG8_MMA(1, 1, At, B1); PG8_BAR;
;     }
;     E(acc, cur, wr, wc, fr, fq);
;   __device__ __forceinline__ void preload(EpiPre& q, int row, int col) const {
;     ...
;     } else if (MODE == E_UQ) {
;       const int c192 = col % 192;
;       if (c192 >= 128) { const float* cs = e.facc + ((size_t)row * 32 + ((c192 - 128) >> 1)) * 2; q.a0 = *(const f32x4*)cs; q.a1 = *(const f32x4*)(cs + 4); }
;   __device__ __forceinline__ void operator()(const f32x4 (&acc)[2][2][4][2], const pg8::Unit& u, int wr, int wc, int fr, int fq) const {
;     ...
;       for (int m = 0; m < 4; ++m) { hs[ai][m] = 0.f;
;         if (MODE == E_UQ) hs[ai][m] = ((const f32x4*)e.f0)[row0 + ai * 128 + m * 16].x * MLA_QSCALE;
	ds_read_b128 v[110:113], v244 offset:49152
	ds_read_b128 v[114:117], v244 offset:50176
	ds_read_b128 v[118:121], v244 offset:51200
	ds_read_b128 v[122:125], v244 offset:52224
	ds_read_b128 v[136:139], v244 offset:53248
	ds_read_b128 v[140:143], v244 offset:54272
	ds_read_b128 v[144:147], v244 offset:55296
	ds_read_b128 v[148:151], v244 offset:56320
	global_load_lds_dwordx4 v[80:81], off
	v_lshl_add_u64 v[80:81], v[220:221], 0, s[72:73]
	s_mov_b32 m0, s39
	s_nop 0
	global_load_lds_dwordx4 v[80:81], off
	s_barrier
	s_waitcnt lgkmcnt(0)
	s_waitcnt lgkmcnt(0)
	v_mfma_f32_16x16x32_bf16 v[60:63], v[72:75], v[110:113], v[60:63]
	v_mfma_f32_16x16x32_bf16 v[56:59], v[90:93], v[110:113], v[56:59]
	v_mfma_f32_16x16x32_bf16 v[44:47], v[72:75], v[118:121], v[44:47]
	v_mfma_f32_16x16x32_bf16 v[40:43], v[90:93], v[118:121], v[40:43]
	v_mfma_f32_16x16x32_bf16 v[28:31], v[72:75], v[136:139], v[28:31]
	v_mfma_f32_16x16x32_bf16 v[24:27], v[90:93], v[136:139], v[24:27]
	v_mfma_f32_16x16x32_bf16 v[12:15], v[72:75], v[144:147], v[12:15]
	v_mfma_f32_16x16x32_bf16 v[8:11], v[90:93], v[144:147], v[8:11]
	v_mfma_f32_16x16x32_bf16 v[60:63], v[76:79], v[114:117], v[60:63]
	v_mfma_f32_16x16x32_bf16 v[56:59], v[98:101], v[114:117], v[56:59]
	v_mfma_f32_16x16x32_bf16 v[44:47], v[76:79], v[122:125], v[44:47]
	v_mfma_f32_16x16x32_bf16 v[40:43], v[98:101], v[122:125], v[40:43]
	v_mfma_f32_16x16x32_bf16 v[28:31], v[76:79], v[140:143], v[28:31]
	v_mfma_f32_16x16x32_bf16 v[24:27], v[98:101], v[140:143], v[24:27]
	v_mfma_f32_16x16x32_bf16 v[12:15], v[76:79], v[148:151], v[12:15]
	v_mfma_f32_16x16x32_bf16 v[8:11], v[98:101], v[148:151], v[8:11]
	s_barrier
	s_add_u32 s18, s20, 0x20080
	s_addc_u32 s19, s21, 0
	s_add_i32 s0, s22, s31
	v_lshl_add_u64 v[72:73], s[18:19], 0, v[224:225]
	s_mov_b32 m0, s0
	s_nop 0
	global_load_lds_dwordx4 v[72:73], off
	v_lshl_add_u64 v[72:73], s[18:19], 0, v[228:229]
	s_add_i32 m0, s0, 0x2000
	s_nop 0
	global_load_lds_dwordx4 v[72:73], off
	s_waitcnt vmcnt(6)
	s_barrier
	v_mfma_f32_16x16x32_bf16 v[52:55], v[152:155], v[110:113], v[52:55]
	v_mfma_f32_16x16x32_bf16 v[48:51], v[170:173], v[110:113], v[48:51]
	v_mfma_f32_16x16x32_bf16 v[36:39], v[152:155], v[118:121], v[36:39]
	v_mfma_f32_16x16x32_bf16 v[32:35], v[170:173], v[118:121], v[32:35]
	v_mfma_f32_16x16x32_bf16 v[20:23], v[152:155], v[136:139], v[20:23]
	v_mfma_f32_16x16x32_bf16 v[16:19], v[170:173], v[136:139], v[16:19]
	v_mfma_f32_16x16x32_bf16 v[4:7], v[152:155], v[144:147], v[4:7]
	v_mfma_f32_16x16x32_bf16 v[0:3], v[170:173], v[144:147], v[0:3]
	v_mfma_f32_16x16x32_bf16 v[52:55], v[156:159], v[114:117], v[52:55]
	v_mfma_f32_16x16x32_bf16 v[48:51], v[174:177], v[114:117], v[48:51]
	v_mfma_f32_16x16x32_bf16 v[36:39], v[156:159], v[122:125], v[36:39]
	v_mfma_f32_16x16x32_bf16 v[32:35], v[174:177], v[122:125], v[32:35]
	v_mfma_f32_16x16x32_bf16 v[20:23], v[156:159], v[140:143], v[20:23]
	v_mfma_f32_16x16x32_bf16 v[16:19], v[174:177], v[140:143], v[16:19]
	v_mfma_f32_16x16x32_bf16 v[4:7], v[156:159], v[148:151], v[4:7]
	v_mfma_f32_16x16x32_bf16 v[0:3], v[174:177], v[148:151], v[0:3]
	s_add_i32 s46, s46, 2
	s_add_u32 s44, s44, 0x100
	s_addc_u32 s45, s45, 0
	s_cmp_gt_u32 s46, 5
	s_mov_b64 s[18:19], s[4:5]
	s_barrier
	s_cbranch_scc0 .LBB0_671
	s_setprio 0
	v_lshl_add_u32 v234, s1, 8, v252
	v_or_b32_e32 v238, 32, v234
	v_ashrrev_i32_e32 v239, 31, v238
	v_or_b32_e32 v236, 48, v234
	v_ashrrev_i32_e32 v235, 31, v234
	v_lshl_add_u64 v[76:77], v[238:239], 4, s[68:69]
	v_ashrrev_i32_e32 v237, 31, v236
	v_lshl_add_u64 v[72:73], v[234:235], 4, s[68:69]
	v_lshl_add_u64 v[78:79], v[236:237], 4, s[68:69]
	global_load_dwordx4 v[210:213], v[76:77], off
	global_load_dwordx4 v[206:209], v[78:79], off
	global_load_dwordx4 v[216:219], v[72:73], off
	global_load_dwordx4 v[178:181], v[72:73], off offset:2048
	global_load_dwordx4 v[144:147], v[72:73], off offset:2304
	global_load_dwordx4 v[110:113], v[72:73], off offset:2560
	v_or_b32_e32 v240, 16, v234
	v_ashrrev_i32_e32 v241, 31, v240
	v_lshl_add_u64 v[74:75], v[240:241], 4, s[68:69]
	global_load_dwordx4 v[212:215], v[74:75], off
	s_nop 0
	global_load_dwordx4 v[72:75], v[72:73], off offset:2816
	s_waitcnt vmcnt(0)
	v_lshl_or_b32 v180, s16, 8, v254
	v_mul_hi_i32 v73, v180, s71
	v_lshrrev_b32_e32 v74, 31, v73
	v_lshrrev_b32_e32 v73, 5, v73
	v_add_u32_e32 v73, v73, v74
	v_mul_lo_u32 v73, v73, s59
	v_sub_u32_e32 v96, v180, v73
	v_lshlrev_b64 v[74:75], 8, v[234:235]
	v_cmp_lt_i32_e64 s[4:5], s67, v96
	v_lshl_add_u64 v[74:75], s[8:9], 0, v[74:75]
	s_and_saveexec_b64 s[16:17], s[4:5]
	s_cbranch_execz .LBB0_674
	v_lshl_add_u64 v[76:77], v[96:97], 2, v[74:75]
	global_load_dwordx4 v[170:173], v[76:77], off offset:-496
	global_load_dwordx4 v[174:177], v[76:77], off offset:-512

; #define PG8_STAGE(bufoff, gbase, voff) do { _Pragma("unroll") for (int _i = 0; _i < 2; ++_i) \
;     __builtin_amdgcn_global_load_lds((const unsigned*)((const char*)(gbase) + (voff)[_i]), (LAS unsigned*)(lds + (bufoff) + ldsw + _i * 8192), 16, 0, 0); } while (0)
; #define PG8_LDA(dst, b, h) do { _Pragma("unroll") for (int m = 0; m < 4; ++m) _Pragma("unroll") for (int k = 0; k < 2; ++k) dst[m][k] = *(const LAS bf16x8*)(lds + PG8_SA(b, h) + aoff + m * 2048 + k * 1024); } while (0)
; #define PG8_LDB(dst, b, h) do { _Pragma("unroll") for (int n = 0; n < 2; ++n) _Pragma("unroll") for (int k = 0; k < 2; ++k) dst[n][k] = *(const LAS bf16x8*)(lds + PG8_SB(b, h) + boff + n * 2048 + k * 1024); } while (0)
; #define PG8_MMA(ai, bj, At, Bt) do { __builtin_amdgcn_s_setprio(1); _Pragma("unroll") for (int m = 0; m < 4; ++m) _Pragma("unroll") for (int n = 0; n < 2; ++n) _Pragma("unroll") for (int k = 0; k < 2; ++k) \
;     acc[ai][bj][m][n] = __builtin_amdgcn_mfma_f32_16x16x32_bf16(Bt[n][k], At[m][k], acc[ai][bj][m][n], 0, 0, 0); __builtin_amdgcn_s_setprio(0); } while (0)
; #define PG8_WAIT_V(n) asm volatile("s_waitcnt vmcnt(" #n ")" ::: "memory")
; #define PG8_WAIT_L(n) asm volatile("s_waitcnt lgkmcnt(" #n ")" ::: "memory")
; #define PG8_BAR __builtin_amdgcn_s_barrier()
; #define PG8_SCHED __builtin_amdgcn_sched_barrier(0)
; template <class Epi>
; __device__ __forceinline__ void gemm_phase(LAS unsigned char* lds, const Gemm g, const StaticOrder& S, const Epi& E, int wv0) {
;     ...
;       PG8_LDB(B0, 0, 0); PG8_SCHED; PG8_LDA(At, 0, 0); PG8_STAGE(PG8_SA(1, 1), a1 + hstepA, voffA);
;       PG8_WAIT_L(8); PG8_BAR; PG8_WAIT_L(0); PG8_MMA(0, 0, At, B0); PG8_BAR; PG8_SCHED;
;       PG8_LDB(B1, 0, 1); PG8_STAGE(PG8_SB(0, 0), b2, voffB);
;       PG8_BAR; PG8_WAIT_L(0); PG8_MMA(0, 1, At, B1); PG8_BAR;
;       PG8_LDA(At, 0, 1); PG8_STAGE(PG8_SA(0, 0), a2, voffA);
;       PG8_BAR; PG8_WAIT_L(0); PG8_MMA(1, 0, At, B0); PG8_BAR; PG8_SCHED;
;       PG8_STAGE(PG8_SB(0, 1), b2 + hstepB, voffB);
;       PG8_WAIT_V(6); PG8_BAR; PG8_MMA(1, 1, At, B1); PG8_BAR;
.LBB0_756:
	s_add_u32 s4, s14, 0x100
	s_addc_u32 s5, s15, 0
	s_add_i32 s0, 0, 0x10000
	v_add_u32_e32 v156, s0, v149
	ds_read_b128 v[140:143], v156
	ds_read_b128 v[144:147], v156 offset:1024
	ds_read_b128 v[152:155], v156 offset:2048
	ds_read_b128 v[156:159], v156 offset:3072
	s_cmp_eq_u32 s44, 4
	s_cselect_b32 s19, s11, s5
	s_cselect_b32 s18, s10, s4
	s_cselect_b32 s17, s9, s43
	s_cselect_b32 s16, s41, s42
	v_lshl_add_u64 v[192:193], s[14:15], 0, v[136:137]
	s_add_i32 m0, s29, 0xc000
	ds_read_b128 v[160:163], v151
	ds_read_b128 v[164:167], v151 offset:1024
	ds_read_b128 v[168:171], v151 offset:2048
	ds_read_b128 v[172:175], v151 offset:3072
	ds_read_b128 v[176:179], v151 offset:4096
	ds_read_b128 v[180:183], v151 offset:5120
	ds_read_b128 v[184:187], v151 offset:6144
	ds_read_b128 v[188:191], v151 offset:7168
	global_load_lds_dwordx4 v[192:193], off
	v_lshl_add_u64 v[192:193], s[14:15], 0, v[138:139]
	s_add_i32 m0, s29, 0xe000
	s_nop 0
	global_load_lds_dwordx4 v[192:193], off
	s_waitcnt lgkmcnt(8)
	s_barrier
	s_waitcnt lgkmcnt(0)
	s_waitcnt lgkmcnt(0)
	v_mfma_f32_16x16x32_bf16 v[126:129], v[140:143], v[160:163], v[126:129]
	v_mfma_f32_16x16x32_bf16 v[122:125], v[152:155], v[160:163], v[122:125]
	v_mfma_f32_16x16x32_bf16 v[118:121], v[140:143], v[168:171], v[118:121]
	v_mfma_f32_16x16x32_bf16 v[114:117], v[152:155], v[168:171], v[114:117]
	v_mfma_f32_16x16x32_bf16 v[106:109], v[140:143], v[176:179], v[106:109]
	v_mfma_f32_16x16x32_bf16 v[98:101], v[152:155], v[176:179], v[98:101]
	v_mfma_f32_16x16x32_bf16 v[76:79], v[140:143], v[184:187], v[76:79]
	v_mfma_f32_16x16x32_bf16 v[72:75], v[152:155], v[184:187], v[72:75]
	v_mfma_f32_16x16x32_bf16 v[126:129], v[144:147], v[164:167], v[126:129]
	v_mfma_f32_16x16x32_bf16 v[122:125], v[156:159], v[164:167], v[122:125]
	v_mfma_f32_16x16x32_bf16 v[118:121], v[144:147], v[172:175], v[118:121]
	v_mfma_f32_16x16x32_bf16 v[114:117], v[156:159], v[172:175], v[114:117]
	v_mfma_f32_16x16x32_bf16 v[106:109], v[144:147], v[180:183], v[106:109]
	v_mfma_f32_16x16x32_bf16 v[98:101], v[156:159], v[180:183], v[98:101]
	v_mfma_f32_16x16x32_bf16 v[76:79], v[144:147], v[188:191], v[76:79]
	v_mfma_f32_16x16x32_bf16 v[72:75], v[156:159], v[188:191], v[72:75]
	s_barrier
	s_add_i32 s45, 0, 0x14000
	s_add_i32 s0, s0, s28
	v_add_u32_e32 v204, s45, v149
	v_lshl_add_u64 v[208:209], s[16:17], 0, v[96:97]
	s_mov_b32 m0, s0
	ds_read_b128 v[192:195], v204
	ds_read_b128 v[196:199], v204 offset:1024
	ds_read_b128 v[200:203], v204 offset:2048
	ds_read_b128 v[204:207], v204 offset:3072
	global_load_lds_dwordx4 v[208:209], off
	v_lshl_add_u64 v[210:211], s[16:17], 0, v[134:135]
	s_add_i32 m0, s0, 0x2000
	s_nop 0
	global_load_lds_dwordx4 v[210:211], off
	s_barrier
	s_waitcnt lgkmcnt(0)
	s_waitcnt lgkmcnt(0)
	v_mfma_f32_16x16x32_bf16 v[110:113], v[192:195], v[160:163], v[110:113]
	v_mfma_f32_16x16x32_bf16 v[102:105], v[200:203], v[160:163], v[102:105]
	v_mfma_f32_16x16x32_bf16 v[92:95], v[192:195], v[168:171], v[92:95]
	v_mfma_f32_16x16x32_bf16 v[88:91], v[200:203], v[168:171], v[88:91]
	v_mfma_f32_16x16x32_bf16 v[84:87], v[192:195], v[176:179], v[84:87]
	v_mfma_f32_16x16x32_bf16 v[80:83], v[200:203], v[176:179], v[80:83]
	v_mfma_f32_16x16x32_bf16 v[68:71], v[192:195], v[184:187], v[68:71]
	v_mfma_f32_16x16x32_bf16 v[64:67], v[200:203], v[184:187], v[64:67]
	v_mfma_f32_16x16x32_bf16 v[110:113], v[196:199], v[164:167], v[110:113]
	v_mfma_f32_16x16x32_bf16 v[102:105], v[204:207], v[164:167], v[102:105]
	v_mfma_f32_16x16x32_bf16 v[92:95], v[196:199], v[172:175], v[92:95]
	v_mfma_f32_16x16x32_bf16 v[88:91], v[204:207], v[172:175], v[88:91]
	v_mfma_f32_16x16x32_bf16 v[84:87], v[196:199], v[180:183], v[84:87]
	v_mfma_f32_16x16x32_bf16 v[80:83], v[204:207], v[180:183], v[80:83]
	v_mfma_f32_16x16x32_bf16 v[68:71], v[196:199], v[188:191], v[68:71]
	v_mfma_f32_16x16x32_bf16 v[64:67], v[204:207], v[188:191], v[64:67]
	s_mov_b32 m0, s29
	v_lshl_add_u64 v[212:213], s[18:19], 0, v[130:131]
	s_barrier
	ds_read_b128 v[160:163], v151 offset:16384
	ds_read_b128 v[164:167], v151 offset:17408
	ds_read_b128 v[168:171], v151 offset:18432
	ds_read_b128 v[172:175], v151 offset:19456
	ds_read_b128 v[176:179], v151 offset:20480
	ds_read_b128 v[180:183], v151 offset:21504
	ds_read_b128 v[184:187], v151 offset:22528
	ds_read_b128 v[188:191], v151 offset:23552
	global_load_lds_dwordx4 v[212:213], off
	v_lshl_add_u64 v[214:215], s[18:19], 0, v[132:133]
	s_mov_b32 m0, s30
	s_nop 0
	global_load_lds_dwordx4 v[214:215], off
	s_barrier
	s_waitcnt lgkmcnt(0)
	s_waitcnt lgkmcnt(0)
	v_mfma_f32_16x16x32_bf16 v[60:63], v[140:143], v[160:163], v[60:63]
	v_mfma_f32_16x16x32_bf16 v[56:59], v[152:155], v[160:163], v[56:59]
	v_mfma_f32_16x16x32_bf16 v[52:55], v[140:143], v[168:171], v[52:55]
	v_mfma_f32_16x16x32_bf16 v[44:47], v[152:155], v[168:171], v[44:47]
	v_mfma_f32_16x16x32_bf16 v[36:39], v[140:143], v[176:179], v[36:39]
	v_mfma_f32_16x16x32_bf16 v[28:31], v[152:155], v[176:179], v[28:31]
	v_mfma_f32_16x16x32_bf16 v[20:23], v[140:143], v[184:187], v[20:23]
	v_mfma_f32_16x16x32_bf16 v[12:15], v[152:155], v[184:187], v[12:15]
	v_mfma_f32_16x16x32_bf16 v[60:63], v[144:147], v[164:167], v[60:63]
	v_mfma_f32_16x16x32_bf16 v[56:59], v[156:159], v[164:167], v[56:59]
	v_mfma_f32_16x16x32_bf16 v[52:55], v[144:147], v[172:175], v[52:55]
	v_mfma_f32_16x16x32_bf16 v[44:47], v[156:159], v[172:175], v[44:47]
	v_mfma_f32_16x16x32_bf16 v[36:39], v[144:147], v[180:183], v[36:39]
	v_mfma_f32_16x16x32_bf16 v[28:31], v[156:159], v[180:183], v[28:31]
	v_mfma_f32_16x16x32_bf16 v[20:23], v[144:147], v[188:191], v[20:23]
	v_mfma_f32_16x16x32_bf16 v[12:15], v[156:159], v[188:191], v[12:15]
	s_barrier
; #define PG8_STAGE(bufoff, gbase, voff) do { _Pragma("unroll") for (int _i = 0; _i < 2; ++_i) \
;     __builtin_amdgcn_global_load_lds((const unsigned*)((const char*)(gbase) + (voff)[_i]), (LAS unsigned*)(lds + (bufoff) + ldsw + _i * 8192), 16, 0, 0); } while (0)
; #define PG8_LDA(dst, b, h) do { _Pragma("unroll") for (int m = 0; m < 4; ++m) _Pragma("unroll") for (int k = 0; k < 2; ++k) dst[m][k] = *(const LAS bf16x8*)(lds + PG8_SA(b, h) + aoff + m * 2048 + k * 1024); } while (0)
; #define PG8_LDB(dst, b, h) do { _Pragma("unroll") for (int n = 0; n < 2; ++n) _Pragma("unroll") for (int k = 0; k < 2; ++k) dst[n][k] = *(const LAS bf16x8*)(lds + PG8_SB(b, h) + boff + n * 2048 + k * 1024); } while (0)
; #define PG8_MMA(ai, bj, At, Bt) do { __builtin_amdgcn_s_setprio(1); _Pragma("unroll") for (int m = 0; m < 4; ++m) _Pragma("unroll") for (int n = 0; n < 2; ++n) _Pragma("unroll") for (int k = 0; k < 2; ++k) \
;     acc[ai][bj][m][n] = __builtin_amdgcn_mfma_f32_16x16x32_bf16(Bt[n][k], At[m][k], acc[ai][bj][m][n], 0, 0, 0); __builtin_amdgcn_s_setprio(0); } while (0)
; #define PG8_WAIT_V(n) asm volatile("s_waitcnt vmcnt(" #n ")" ::: "memory")
; #define PG8_WAIT_L(n) asm volatile("s_waitcnt lgkmcnt(" #n ")" ::: "memory")
; #define PG8_BAR __builtin_amdgcn_s_barrier()
; #define PG8_SCHED __builtin_amdgcn_sched_barrier(0)
; template <class Epi>
; __device__ __forceinline__ void gemm_phase(LAS unsigned char* lds, const Gemm g, const StaticOrder& S, const Epi& E, int wv0) {
;     ...
;       PG8_STAGE(PG8_SB(0, 1), b2 + hstepB, voffB);
;       PG8_WAIT_V(6); PG8_BAR; PG8_MMA(1, 1, At, B1); PG8_BAR;
;       PG8_LDB(B0, 1, 0); PG8_SCHED; PG8_LDA(At, 1, 0); PG8_STAGE(PG8_SA(0, 1), a2 + hstepA, voffA);
;       PG8_WAIT_L(8); PG8_BAR; PG8_WAIT_L(0); PG8_MMA(0, 0, At, B0); PG8_BAR; PG8_SCHED;
;       PG8_LDB(B1, 1, 1); PG8_STAGE(PG8_SB(1, 0), b3, voffB);
;       PG8_BAR; PG8_WAIT_L(0); PG8_MMA(0, 1, At, B1); PG8_BAR;
;       PG8_LDA(At, 1, 1); PG8_STAGE(PG8_SA(1, 0), a3, voffA);
	s_add_u32 s14, s16, 0x20000
	s_addc_u32 s15, s17, 0
	s_add_i32 s0, s45, s28
	v_lshl_add_u64 v[140:141], s[14:15], 0, v[96:97]
	s_mov_b32 m0, s0
	s_nop 0
	global_load_lds_dwordx4 v[140:141], off
	v_lshl_add_u64 v[140:141], s[14:15], 0, v[134:135]
	s_add_i32 m0, s0, 0x2000
	s_nop 0
	global_load_lds_dwordx4 v[140:141], off
	s_waitcnt vmcnt(6)
	s_barrier
	v_mfma_f32_16x16x32_bf16 v[48:51], v[192:195], v[160:163], v[48:51]
	v_mfma_f32_16x16x32_bf16 v[40:43], v[200:203], v[160:163], v[40:43]
	v_mfma_f32_16x16x32_bf16 v[32:35], v[192:195], v[168:171], v[32:35]
	v_mfma_f32_16x16x32_bf16 v[24:27], v[200:203], v[168:171], v[24:27]
	v_mfma_f32_16x16x32_bf16 v[16:19], v[192:195], v[176:179], v[16:19]
	v_mfma_f32_16x16x32_bf16 v[8:11], v[200:203], v[176:179], v[8:11]
	v_mfma_f32_16x16x32_bf16 v[4:7], v[192:195], v[184:187], v[4:7]
	v_mfma_f32_16x16x32_bf16 v[0:3], v[200:203], v[184:187], v[0:3]
	v_mfma_f32_16x16x32_bf16 v[48:51], v[196:199], v[164:167], v[48:51]
	v_mfma_f32_16x16x32_bf16 v[40:43], v[204:207], v[164:167], v[40:43]
	v_mfma_f32_16x16x32_bf16 v[32:35], v[196:199], v[172:175], v[32:35]
	v_mfma_f32_16x16x32_bf16 v[24:27], v[204:207], v[172:175], v[24:27]
	v_mfma_f32_16x16x32_bf16 v[16:19], v[196:199], v[180:183], v[16:19]
	v_mfma_f32_16x16x32_bf16 v[8:11], v[204:207], v[180:183], v[8:11]
	v_mfma_f32_16x16x32_bf16 v[4:7], v[196:199], v[188:191], v[4:7]
	v_mfma_f32_16x16x32_bf16 v[0:3], v[204:207], v[188:191], v[0:3]
	s_add_i32 s0, 0, 0x18000
	v_add_u32_e32 v156, s0, v149
	s_barrier
	ds_read_b128 v[140:143], v156
	ds_read_b128 v[144:147], v156 offset:1024
	ds_read_b128 v[152:155], v156 offset:2048
	ds_read_b128 v[156:159], v156 offset:3072
	s_add_u32 s14, s18, 0x114000
	s_addc_u32 s15, s19, 0
	s_mov_b32 m0, s31
	v_lshl_add_u64 v[192:193], s[14:15], 0, v[130:131]
	ds_read_b128 v[160:163], v151 offset:32768
	ds_read_b128 v[164:167], v151 offset:33792
	ds_read_b128 v[168:171], v151 offset:34816
	ds_read_b128 v[172:175], v151 offset:35840
	ds_read_b128 v[176:179], v151 offset:36864
	ds_read_b128 v[180:183], v151 offset:37888
	ds_read_b128 v[184:187], v151 offset:38912
	ds_read_b128 v[188:191], v151 offset:39936
	global_load_lds_dwordx4 v[192:193], off
	v_lshl_add_u64 v[192:193], s[14:15], 0, v[132:133]
	s_mov_b32 m0, s34
	s_nop 0
	global_load_lds_dwordx4 v[192:193], off
	s_waitcnt lgkmcnt(8)
	s_barrier
	s_waitcnt lgkmcnt(0)
	s_waitcnt lgkmcnt(0)
	v_mfma_f32_16x16x32_bf16 v[126:129], v[140:143], v[160:163], v[126:129]
	v_mfma_f32_16x16x32_bf16 v[122:125], v[152:155], v[160:163], v[122:125]
	v_mfma_f32_16x16x32_bf16 v[118:121], v[140:143], v[168:171], v[118:121]
	v_mfma_f32_16x16x32_bf16 v[114:117], v[152:155], v[168:171], v[114:117]
	v_mfma_f32_16x16x32_bf16 v[106:109], v[140:143], v[176:179], v[106:109]
	v_mfma_f32_16x16x32_bf16 v[98:101], v[152:155], v[176:179], v[98:101]
	v_mfma_f32_16x16x32_bf16 v[76:79], v[140:143], v[184:187], v[76:79]
	v_mfma_f32_16x16x32_bf16 v[72:75], v[152:155], v[184:187], v[72:75]
	v_mfma_f32_16x16x32_bf16 v[126:129], v[144:147], v[164:167], v[126:129]
	v_mfma_f32_16x16x32_bf16 v[122:125], v[156:159], v[164:167], v[122:125]
	v_mfma_f32_16x16x32_bf16 v[118:121], v[144:147], v[172:175], v[118:121]
	v_mfma_f32_16x16x32_bf16 v[114:117], v[156:159], v[172:175], v[114:117]
	v_mfma_f32_16x16x32_bf16 v[106:109], v[144:147], v[180:183], v[106:109]
	v_mfma_f32_16x16x32_bf16 v[98:101], v[156:159], v[180:183], v[98:101]
	v_mfma_f32_16x16x32_bf16 v[76:79], v[144:147], v[188:191], v[76:79]
	v_mfma_f32_16x16x32_bf16 v[72:75], v[156:159], v[188:191], v[72:75]
	s_barrier
	s_add_i32 s18, 0, 0x1c000
	s_add_i32 s0, s0, s28
	v_add_u32_e32 v204, s18, v149
	v_lshl_add_u64 v[208:209], v[208:209], 0, s[72:73]
	s_mov_b32 m0, s0
	ds_read_b128 v[192:195], v204
	ds_read_b128 v[196:199], v204 offset:1024
	ds_read_b128 v[200:203], v204 offset:2048
	ds_read_b128 v[204:207], v204 offset:3072
	global_load_lds_dwordx4 v[208:209], off
	v_lshl_add_u64 v[208:209], v[210:211], 0, s[72:73]
	s_add_i32 m0, s0, 0x2000
	s_nop 0
	global_load_lds_dwordx4 v[208:209], off
	s_barrier
	s_waitcnt lgkmcnt(0)
	s_waitcnt lgkmcnt(0)
	v_mfma_f32_16x16x32_bf16 v[110:113], v[192:195], v[160:163], v[110:113]
	v_mfma_f32_16x16x32_bf16 v[102:105], v[200:203], v[160:163], v[102:105]
	v_mfma_f32_16x16x32_bf16 v[92:95], v[192:195], v[168:171], v[92:95]
	v_mfma_f32_16x16x32_bf16 v[88:91], v[200:203], v[168:171], v[88:91]
	v_mfma_f32_16x16x32_bf16 v[84:87], v[192:195], v[176:179], v[84:87]
	v_mfma_f32_16x16x32_bf16 v[80:83], v[200:203], v[176:179], v[80:83]
	v_mfma_f32_16x16x32_bf16 v[68:71], v[192:195], v[184:187], v[68:71]
	v_mfma_f32_16x16x32_bf16 v[64:67], v[200:203], v[184:187], v[64:67]
	v_mfma_f32_16x16x32_bf16 v[110:113], v[196:199], v[164:167], v[110:113]
	v_mfma_f32_16x16x32_bf16 v[102:105], v[204:207], v[164:167], v[102:105]
	v_mfma_f32_16x16x32_bf16 v[92:95], v[196:199], v[172:175], v[92:95]
	v_mfma_f32_16x16x32_bf16 v[88:91], v[204:207], v[172:175], v[88:91]
	v_mfma_f32_16x16x32_bf16 v[84:87], v[196:199], v[180:183], v[84:87]
	v_mfma_f32_16x16x32_bf16 v[80:83], v[204:207], v[180:183], v[80:83]
	v_mfma_f32_16x16x32_bf16 v[68:71], v[196:199], v[188:191], v[68:71]
	v_mfma_f32_16x16x32_bf16 v[64:67], v[204:207], v[188:191], v[64:67]
	s_mov_b32 m0, s35
	v_lshl_add_u64 v[208:209], v[212:213], 0, s[72:73]
	s_barrier
	ds_read_b128 v[160:163], v151 offset:49152
	ds_read_b128 v[164:167], v151 offset:50176
	ds_read_b128 v[168:171], v151 offset:51200
	ds_read_b128 v[172:175], v151 offset:52224
	ds_read_b128 v[176:179], v151 offset:53248
	ds_read_b128 v[180:183], v151 offset:54272
	ds_read_b128 v[184:187], v151 offset:55296
	ds_read_b128 v[188:191], v151 offset:56320
	global_load_lds_dwordx4 v[208:209], off
	v_lshl_add_u64 v[208:209], v[214:215], 0, s[72:73]
	s_mov_b32 m0, s36
	s_nop 0
	global_load_lds_dwordx4 v[208:209], off
	s_barrier
; #define PG8_STAGE(bufoff, gbase, voff) do { _Pragma("unroll") for (int _i = 0; _i < 2; ++_i) \
;     __builtin_amdgcn_global_load_lds((const unsigned*)((const char*)(gbase) + (voff)[_i]), (LAS unsigned*)(lds + (bufoff) + ldsw + _i * 8192), 16, 0, 0); } while (0)
; #define PG8_LDA(dst, b, h) do { _Pragma("unroll") for (int m = 0; m < 4; ++m) _Pragma("unroll") for (int k = 0; k < 2; ++k) dst[m][k] = *(const LAS bf16x8*)(lds + PG8_SA(b, h) + aoff + m * 2048 + k * 1024); } while (0)
; #define PG8_LDB(dst, b, h) do { _Pragma("unroll") for (int n = 0; n < 2; ++n) _Pragma("unroll") for (int k = 0; k < 2; ++k) dst[n][k] = *(const LAS bf16x8*)(lds + PG8_SB(b, h) + boff + n * 2048 + k * 1024); } while (0)
; #define PG8_MMA(ai, bj, At, Bt) do { __builtin_amdgcn_s_setprio(1); _Pragma("unroll") for (int m = 0; m < 4; ++m) _Pragma("unroll") for (int n = 0; n < 2; ++n) _Pragma("unroll") for (int k = 0; k < 2; ++k) \
;     acc[ai][bj][m][n] = __builtin_amdgcn_mfma_f32_16x16x32_bf16(Bt[n][k], At[m][k], acc[ai][bj][m][n], 0, 0, 0); __builtin_amdgcn_s_setprio(0); } while (0)
; #define PG8_BAR __builtin_amdgcn_s_barrier()
; template <class Epi>
; __device__ __forceinline__ void gemm_phase(LAS unsigned char* lds, const Gemm g, const StaticOrder& S, const Epi& E, int wv0) {
;     ...
;       PG8_WAIT_V(6); PG8_BAR; PG8_MMA(1, 1, At, B1); PG8_BAR;
;       PG8_LDB(B0, 1, 0); PG8_SCHED; PG8_LDA(At, 1, 0); PG8_STAGE(PG8_SA(0, 1), a2 + hstepA, voffA);
;       PG8_WAIT_L(8); PG8_BAR; PG8_WAIT_L(0); PG8_MMA(0, 0, At, B0); PG8_BAR; PG8_SCHED;
;       PG8_LDB(B1, 1, 1); PG8_STAGE(PG8_SB(1, 0), b3, voffB);
;       PG8_BAR; PG8_WAIT_L(0); PG8_MMA(0, 1, At, B1); PG8_BAR;
;       PG8_LDA(At, 1, 1); PG8_STAGE(PG8_SA(1, 0), a3, voffA);
;       PG8_BAR; PG8_WAIT_L(0); PG8_MMA(1, 0, At, B0); PG8_BAR; PG8_SCHED;
;       PG8_STAGE(PG8_SB(1, 1), b3 + hstepB, voffB);
;       PG8_WAIT_V(6); PG8_BAR; PG8_MMA(1, 1, At, B1); PG8_BAR;
;     }
;     E(acc, cur, wr, wc, fr, fq);
;     if (!has_next) break;
;   __device__ __forceinline__ void operator()(const f32x4 (&acc)[2][2][4][2], const pg8::Unit& u, int wr, int wc, int fr, int fq) const {
;     ...
;       for (int m = 0; m < 4; ++m) { hs[ai][m] = 0.f;
;         if (MODE == E_UQ) hs[ai][m] = ((const f32x4*)e.f0)[row0 + ai * 128 + m * 16].x * MLA_QSCALE;
;         if (MODE == E_UKV) hs[ai][m] = ((const f32x4*)e.f0)[row0 + ai * 128 + m * 16].y; }
	s_waitcnt lgkmcnt(0)
	s_waitcnt lgkmcnt(0)
	v_mfma_f32_16x16x32_bf16 v[60:63], v[140:143], v[160:163], v[60:63]
	v_mfma_f32_16x16x32_bf16 v[56:59], v[152:155], v[160:163], v[56:59]
	v_mfma_f32_16x16x32_bf16 v[52:55], v[140:143], v[168:171], v[52:55]
	v_mfma_f32_16x16x32_bf16 v[44:47], v[152:155], v[168:171], v[44:47]
	v_mfma_f32_16x16x32_bf16 v[36:39], v[140:143], v[176:179], v[36:39]
	v_mfma_f32_16x16x32_bf16 v[28:31], v[152:155], v[176:179], v[28:31]
	v_mfma_f32_16x16x32_bf16 v[20:23], v[140:143], v[184:187], v[20:23]
	v_mfma_f32_16x16x32_bf16 v[12:15], v[152:155], v[184:187], v[12:15]
	v_mfma_f32_16x16x32_bf16 v[60:63], v[144:147], v[164:167], v[60:63]
	v_mfma_f32_16x16x32_bf16 v[56:59], v[156:159], v[164:167], v[56:59]
	v_mfma_f32_16x16x32_bf16 v[52:55], v[144:147], v[172:175], v[52:55]
	v_mfma_f32_16x16x32_bf16 v[44:47], v[156:159], v[172:175], v[44:47]
	v_mfma_f32_16x16x32_bf16 v[36:39], v[144:147], v[180:183], v[36:39]
	v_mfma_f32_16x16x32_bf16 v[28:31], v[156:159], v[180:183], v[28:31]
	v_mfma_f32_16x16x32_bf16 v[20:23], v[144:147], v[188:191], v[20:23]
	v_mfma_f32_16x16x32_bf16 v[12:15], v[156:159], v[188:191], v[12:15]
	s_barrier
	s_add_u32 s14, s16, 0x20080
	s_addc_u32 s15, s17, 0
	s_add_i32 s0, s18, s28
	v_lshl_add_u64 v[140:141], s[14:15], 0, v[96:97]
	s_mov_b32 m0, s0
	s_nop 0
	global_load_lds_dwordx4 v[140:141], off
	v_lshl_add_u64 v[140:141], s[14:15], 0, v[134:135]
	s_add_i32 m0, s0, 0x2000
	s_nop 0
	global_load_lds_dwordx4 v[140:141], off
	s_waitcnt vmcnt(6)
	s_barrier
	v_mfma_f32_16x16x32_bf16 v[48:51], v[192:195], v[160:163], v[48:51]
	v_mfma_f32_16x16x32_bf16 v[40:43], v[200:203], v[160:163], v[40:43]
	v_mfma_f32_16x16x32_bf16 v[32:35], v[192:195], v[168:171], v[32:35]
	v_mfma_f32_16x16x32_bf16 v[24:27], v[200:203], v[168:171], v[24:27]
	v_mfma_f32_16x16x32_bf16 v[16:19], v[192:195], v[176:179], v[16:19]
	v_mfma_f32_16x16x32_bf16 v[8:11], v[200:203], v[176:179], v[8:11]
	v_mfma_f32_16x16x32_bf16 v[4:7], v[192:195], v[184:187], v[4:7]
	v_mfma_f32_16x16x32_bf16 v[0:3], v[200:203], v[184:187], v[0:3]
	v_mfma_f32_16x16x32_bf16 v[48:51], v[196:199], v[164:167], v[48:51]
	v_mfma_f32_16x16x32_bf16 v[40:43], v[204:207], v[164:167], v[40:43]
	v_mfma_f32_16x16x32_bf16 v[32:35], v[196:199], v[172:175], v[32:35]
	v_mfma_f32_16x16x32_bf16 v[24:27], v[204:207], v[172:175], v[24:27]
	v_mfma_f32_16x16x32_bf16 v[16:19], v[196:199], v[180:183], v[16:19]
	v_mfma_f32_16x16x32_bf16 v[8:11], v[204:207], v[180:183], v[8:11]
	v_mfma_f32_16x16x32_bf16 v[4:7], v[196:199], v[188:191], v[4:7]
	v_mfma_f32_16x16x32_bf16 v[0:3], v[204:207], v[188:191], v[0:3]
	s_add_i32 s44, s44, 2
	s_add_u32 s42, s42, 0x100
	s_addc_u32 s43, s43, 0
	s_cmp_gt_u32 s44, 5
	s_mov_b64 s[14:15], s[4:5]
	s_barrier
	s_cbranch_scc0 .LBB0_756
	s_setprio 0
	v_lshl_add_u32 v140, s39, 8, v148
	v_or_b32_e32 v146, 16, v140
	v_ashrrev_i32_e32 v141, 31, v140
	v_ashrrev_i32_e32 v147, 31, v146
	v_or_b32_e32 v156, 32, v140
	v_lshl_add_u64 v[142:143], v[140:141], 4, s[68:69]
	v_lshl_add_u64 v[144:145], v[146:147], 4, s[68:69]
	v_ashrrev_i32_e32 v157, 31, v156
	v_or_b32_e32 v160, 48, v140
	global_load_dwordx2 v[152:153], v[142:143], off
	global_load_dwordx2 v[154:155], v[144:145], off
	v_lshl_add_u64 v[144:145], v[156:157], 4, s[68:69]
	v_ashrrev_i32_e32 v161, 31, v160
	global_load_dwordx2 v[158:159], v[144:145], off
	v_lshl_add_u64 v[144:145], v[160:161], 4, s[68:69]
	global_load_dwordx2 v[162:163], v[144:145], off
	v_lshl_or_b32 v144, s40, 8, v150
	v_ashrrev_i32_e32 v145, 31, v144
	v_lshlrev_b64 v[164:165], 13, v[140:141]
	v_lshlrev_b64 v[166:167], 1, v[144:145]
	global_load_dwordx2 v[168:169], v[142:143], off offset:2048
	global_load_dwordx2 v[144:145], v[142:143], off offset:2304
	global_load_dwordx2 v[140:141], v[142:143], off offset:2560
	v_lshl_add_u64 v[164:165], s[6:7], 0, v[164:165]
	global_load_dwordx2 v[142:143], v[142:143], off offset:2816
	v_lshlrev_b64 v[170:171], 13, v[146:147]
	v_lshl_add_u64 v[146:147], v[164:165], 0, v[166:167]
	v_lshl_add_u64 v[164:165], s[6:7], 0, v[170:171]
	v_lshl_add_u64 v[164:165], v[164:165], 0, v[166:167]
	v_lshlrev_b64 v[156:157], 13, v[156:157]
	v_lshl_add_u64 v[156:157], s[6:7], 0, v[156:157]
	v_lshl_add_u64 v[156:157], v[156:157], 0, v[166:167]
	s_mov_b64 s[4:5], 0x100000
	s_mov_b32 s0, 0x140000
	s_mov_b32 s40, s8
	s_mov_b32 s39, s1
	s_mov_b64 s[16:17], s[12:13]
	s_mov_b64 s[14:15], s[10:11]
	s_waitcnt vmcnt(0)
; __device__ __forceinline__ void store8bf(bf16_t* dst, const float (&v)[8]) {
;   u32x4 w; w.x = pk2(v[0], v[1]); w.y = pk2(v[2], v[3]); w.z = pk2(v[4], v[5]); w.w = pk2(v[6], v[7]);
;   *(u32x4*)dst = w;
; }
;   __device__ __forceinline__ void emit(const EpiPre& q0, int row, int col, f32x4 a, f32x4 b, const f32x4 (&hb)[2][2], const float (&hs)[2][4], int ai_, int m_, int bj_) const {
;     ...
;     } else if (MODE == E_UKV) {
; #pragma unroll
;       for (int j = 0; j < 8; ++j) v[j] *= q.s;
;       store8bf((bf16_t*)e.out + (size_t)row * NKV + col, v);
	v_pk_mul_f32 v[126:127], v[126:127], v[152:153] op_sel:[0,1]
	v_pk_mul_f32 v[128:129], v[128:129], v[152:153] op_sel:[0,1]
	v_pk_mul_f32 v[122:123], v[122:123], v[152:153] op_sel:[0,1]
	v_pk_mul_f32 v[124:125], v[124:125], v[152:153] op_sel:[0,1]
	v_pk_mul_f32 v[118:119], v[118:119], v[154:155] op_sel:[0,1]
	v_pk_mul_f32 v[120:121], v[120:121], v[154:155] op_sel:[0,1]
	v_pk_mul_f32 v[114:115], v[114:115], v[154:155] op_sel:[0,1]
	v_pk_mul_f32 v[116:117], v[116:117], v[154:155] op_sel:[0,1]
	v_pk_mul_f32 v[110:111], v[110:111], v[152:153] op_sel:[0,1]
	v_pk_mul_f32 v[112:113], v[112:113], v[152:153] op_sel:[0,1]
	v_pk_mul_f32 v[170:171], v[102:103], v[152:153] op_sel:[0,1]
	v_pk_mul_f32 v[152:153], v[104:105], v[152:153] op_sel:[0,1]
	v_cvt_pk_bf16_f32 v102, v126, v127
	v_cvt_pk_bf16_f32 v103, v128, v129
	v_cvt_pk_bf16_f32 v104, v122, v123
	v_cvt_pk_bf16_f32 v105, v124, v125
	v_pk_mul_f32 v[92:93], v[92:93], v[154:155] op_sel:[0,1]
	v_pk_mul_f32 v[94:95], v[94:95], v[154:155] op_sel:[0,1]
	v_pk_mul_f32 v[88:89], v[88:89], v[154:155] op_sel:[0,1]
	v_pk_mul_f32 v[90:91], v[90:91], v[154:155] op_sel:[0,1]
	v_pk_mul_f32 v[126:127], v[80:81], v[158:159] op_sel:[0,1]
	v_pk_mul_f32 v[128:129], v[82:83], v[158:159] op_sel:[0,1]
	v_cvt_pk_bf16_f32 v80, v118, v119
	v_cvt_pk_bf16_f32 v81, v120, v121
	v_cvt_pk_bf16_f32 v82, v114, v115
	v_cvt_pk_bf16_f32 v83, v116, v117
	v_cvt_pk_bf16_f32 v110, v110, v111
	v_cvt_pk_bf16_f32 v111, v112, v113
	v_cvt_pk_bf16_f32 v112, v170, v171
	v_cvt_pk_bf16_f32 v113, v152, v153
	v_pk_mul_f32 v[122:123], v[84:85], v[158:159] op_sel:[0,1]
	v_pk_mul_f32 v[124:125], v[86:87], v[158:159] op_sel:[0,1]
	global_store_dwordx4 v[146:147], v[102:105], off
	global_store_dwordx4 v[146:147], v[110:113], off offset:256
	v_cvt_pk_bf16_f32 v84, v92, v93
	v_cvt_pk_bf16_f32 v85, v94, v95
	v_cvt_pk_bf16_f32 v86, v88, v89
	v_cvt_pk_bf16_f32 v87, v90, v91
	global_store_dwordx4 v[164:165], v[80:83], off
	global_store_dwordx4 v[164:165], v[84:87], off offset:256
	v_pk_mul_f32 v[106:107], v[106:107], v[158:159] op_sel:[0,1]
	v_pk_mul_f32 v[80:81], v[72:73], v[162:163] op_sel:[0,1]
	v_lshlrev_b64 v[72:73], 13, v[160:161]
	v_pk_mul_f32 v[108:109], v[108:109], v[158:159] op_sel:[0,1]
	v_pk_mul_f32 v[98:99], v[98:99], v[158:159] op_sel:[0,1]
	v_pk_mul_f32 v[100:101], v[100:101], v[158:159] op_sel:[0,1]
	v_pk_mul_f32 v[76:77], v[76:77], v[162:163] op_sel:[0,1]
	v_pk_mul_f32 v[78:79], v[78:79], v[162:163] op_sel:[0,1]
	v_pk_mul_f32 v[82:83], v[74:75], v[162:163] op_sel:[0,1]
	v_lshl_add_u64 v[72:73], s[6:7], 0, v[72:73]
	v_cvt_pk_bf16_f32 v88, v106, v107
	v_cvt_pk_bf16_f32 v89, v108, v109
	v_cvt_pk_bf16_f32 v90, v98, v99
	v_cvt_pk_bf16_f32 v91, v100, v101
	v_lshl_add_u64 v[84:85], v[72:73], 0, v[166:167]
	v_cvt_pk_bf16_f32 v72, v76, v77
	v_cvt_pk_bf16_f32 v73, v78, v79
	v_cvt_pk_bf16_f32 v74, v80, v81
	v_cvt_pk_bf16_f32 v75, v82, v83
	v_cvt_pk_bf16_f32 v92, v122, v123
	v_cvt_pk_bf16_f32 v93, v124, v125
	v_cvt_pk_bf16_f32 v94, v126, v127
	v_cvt_pk_bf16_f32 v95, v128, v129
	global_store_dwordx4 v[156:157], v[88:91], off
	global_store_dwordx4 v[156:157], v[92:95], off offset:256
	global_store_dwordx4 v[84:85], v[72:75], off
	v_pk_mul_f32 v[68:69], v[68:69], v[162:163] op_sel:[0,1]
	v_pk_mul_f32 v[70:71], v[70:71], v[162:163] op_sel:[0,1]
	v_pk_mul_f32 v[72:73], v[64:65], v[162:163] op_sel:[0,1]
	v_pk_mul_f32 v[74:75], v[66:67], v[162:163] op_sel:[0,1]
	v_cvt_pk_bf16_f32 v64, v68, v69
	v_cvt_pk_bf16_f32 v65, v70, v71
	v_cvt_pk_bf16_f32 v66, v72, v73
	v_cvt_pk_bf16_f32 v67, v74, v75
	v_pk_mul_f32 v[60:61], v[60:61], v[168:169] op_sel:[0,1]
	global_store_dwordx4 v[84:85], v[64:67], off offset:256
	v_pk_mul_f32 v[62:63], v[62:63], v[168:169] op_sel:[0,1]
	v_pk_mul_f32 v[48:49], v[48:49], v[168:169] op_sel:[0,1]
	v_pk_mul_f32 v[64:65], v[56:57], v[168:169] op_sel:[0,1]
; #define PG8_WAIT_V(n) asm volatile("s_waitcnt vmcnt(" #n ")" ::: "memory")
; #define PG8_BAR __builtin_amdgcn_s_barrier()
; template <class Epi>
; __device__ __forceinline__ void gemm_phase(LAS unsigned char* lds, const Gemm g, const StaticOrder& S, const Epi& E, int wv0) {
;     ...
;     if (!has_next) break;
; #pragma unroll
;     for (int a = 0; a < 2; ++a)
; #pragma unroll
;       for (int b = 0; b < 2; ++b)
; #pragma unroll
;         for (int m = 0; m < 4; ++m)
; #pragma unroll
;           for (int n = 0; n < 2; ++n) acc[a][b][m][n] = (f32x4){0.f, 0.f, 0.f, 0.f};
;     cur = nxt; cA = nA; cB = nB; ++ui;
;   }
;   PG8_WAIT_V(0);
;   if (wr == 0) PG8_BAR;
;   PG8_BAR;
;   __device__ __forceinline__ void emit(const EpiPre& q0, int row, int col, f32x4 a, f32x4 b, const f32x4 (&hb)[2][2], const float (&hs)[2][4], int ai_, int m_, int bj_) const {
;     ...
;     } else if (MODE == E_UKV) {
; #pragma unroll
;       for (int j = 0; j < 8; ++j) v[j] *= q.s;
;       store8bf((bf16_t*)e.out + (size_t)row * NKV + col, v);
	v_pk_mul_f32 v[66:67], v[58:59], v[168:169] op_sel:[0,1]
	v_cvt_pk_bf16_f32 v56, v60, v61
	v_add_co_u32_e32 v60, vcc, s94, v146
	v_cvt_pk_bf16_f32 v57, v62, v63
	v_cvt_pk_bf16_f32 v58, v64, v65
	v_cvt_pk_bf16_f32 v59, v66, v67
	v_addc_co_u32_e32 v61, vcc, 0, v147, vcc
	global_store_dwordx4 v[60:61], v[56:59], off
	v_pk_mul_f32 v[50:51], v[50:51], v[168:169] op_sel:[0,1]
	v_lshl_add_u64 v[68:69], v[146:147], 0, s[4:5]
	v_pk_mul_f32 v[56:57], v[40:41], v[168:169] op_sel:[0,1]
	v_pk_mul_f32 v[58:59], v[42:43], v[168:169] op_sel:[0,1]
	v_cvt_pk_bf16_f32 v40, v48, v49
	v_cvt_pk_bf16_f32 v41, v50, v51
	v_cvt_pk_bf16_f32 v42, v56, v57
	v_cvt_pk_bf16_f32 v43, v58, v59
	global_store_dwordx4 v[68:69], v[40:43], off offset:256
	v_pk_mul_f32 v[44:45], v[44:45], v[144:145] op_sel:[0,1]
	v_pk_mul_f32 v[46:47], v[46:47], v[144:145] op_sel:[0,1]
	v_pk_mul_f32 v[40:41], v[52:53], v[144:145] op_sel:[0,1]
	v_pk_mul_f32 v[42:43], v[54:55], v[144:145] op_sel:[0,1]
	v_cvt_pk_bf16_f32 v40, v40, v41
	v_cvt_pk_bf16_f32 v41, v42, v43
	v_cvt_pk_bf16_f32 v42, v44, v45
	v_add_co_u32_e32 v44, vcc, s95, v146
	v_cvt_pk_bf16_f32 v43, v46, v47
	s_nop 0
	v_addc_co_u32_e32 v45, vcc, 0, v147, vcc
	s_mov_b64 s[4:5], 0x120000
	global_store_dwordx4 v[44:45], v[40:43], off
	v_pk_mul_f32 v[32:33], v[32:33], v[144:145] op_sel:[0,1]
	v_pk_mul_f32 v[34:35], v[34:35], v[144:145] op_sel:[0,1]
	v_pk_mul_f32 v[40:41], v[24:25], v[144:145] op_sel:[0,1]
	v_pk_mul_f32 v[42:43], v[26:27], v[144:145] op_sel:[0,1]
	v_lshl_add_u64 v[48:49], v[146:147], 0, s[4:5]
	v_cvt_pk_bf16_f32 v24, v32, v33
	v_cvt_pk_bf16_f32 v25, v34, v35
	v_cvt_pk_bf16_f32 v26, v40, v41
	v_cvt_pk_bf16_f32 v27, v42, v43
	global_store_dwordx4 v[48:49], v[24:27], off offset:256
	v_pk_mul_f32 v[28:29], v[28:29], v[140:141] op_sel:[0,1]
	v_pk_mul_f32 v[30:31], v[30:31], v[140:141] op_sel:[0,1]
	v_pk_mul_f32 v[24:25], v[36:37], v[140:141] op_sel:[0,1]
	v_pk_mul_f32 v[26:27], v[38:39], v[140:141] op_sel:[0,1]
	v_cvt_pk_bf16_f32 v24, v24, v25
	v_cvt_pk_bf16_f32 v25, v26, v27
	v_cvt_pk_bf16_f32 v26, v28, v29
	v_add_co_u32_e32 v28, vcc, s0, v146
	v_cvt_pk_bf16_f32 v27, v30, v31
	s_nop 0
	v_addc_co_u32_e32 v29, vcc, 0, v147, vcc
	s_mov_b64 s[4:5], 0x140000
	global_store_dwordx4 v[28:29], v[24:27], off
	v_pk_mul_f32 v[16:17], v[16:17], v[140:141] op_sel:[0,1]
	v_pk_mul_f32 v[18:19], v[18:19], v[140:141] op_sel:[0,1]
	v_pk_mul_f32 v[24:25], v[8:9], v[140:141] op_sel:[0,1]
	v_pk_mul_f32 v[26:27], v[10:11], v[140:141] op_sel:[0,1]
	v_lshl_add_u64 v[32:33], v[146:147], 0, s[4:5]
	v_cvt_pk_bf16_f32 v8, v16, v17
	v_cvt_pk_bf16_f32 v9, v18, v19
	v_cvt_pk_bf16_f32 v10, v24, v25
	v_cvt_pk_bf16_f32 v11, v26, v27
	global_store_dwordx4 v[32:33], v[8:11], off offset:256
	v_pk_mul_f32 v[12:13], v[12:13], v[142:143] op_sel:[0,1]
	s_mov_b32 s0, 0x160000
	v_pk_mul_f32 v[8:9], v[20:21], v[142:143] op_sel:[0,1]
	v_pk_mul_f32 v[10:11], v[22:23], v[142:143] op_sel:[0,1]
	v_pk_mul_f32 v[14:15], v[14:15], v[142:143] op_sel:[0,1]
	v_cvt_pk_bf16_f32 v8, v8, v9
	v_cvt_pk_bf16_f32 v9, v10, v11
	v_cvt_pk_bf16_f32 v10, v12, v13
	v_add_co_u32_e32 v12, vcc, s0, v146
	v_cvt_pk_bf16_f32 v11, v14, v15
	s_nop 0
	v_addc_co_u32_e32 v13, vcc, 0, v147, vcc
	s_mov_b64 s[4:5], 0x160000
	global_store_dwordx4 v[12:13], v[8:11], off
	v_pk_mul_f32 v[4:5], v[4:5], v[142:143] op_sel:[0,1]
	v_pk_mul_f32 v[6:7], v[6:7], v[142:143] op_sel:[0,1]
	v_pk_mul_f32 v[8:9], v[0:1], v[142:143] op_sel:[0,1]
	v_pk_mul_f32 v[10:11], v[2:3], v[142:143] op_sel:[0,1]
	v_lshl_add_u64 v[16:17], v[146:147], 0, s[4:5]
	v_cvt_pk_bf16_f32 v0, v4, v5
	v_cvt_pk_bf16_f32 v1, v6, v7
	v_cvt_pk_bf16_f32 v2, v8, v9
	v_cvt_pk_bf16_f32 v3, v10, v11
	global_store_dwordx4 v[16:17], v[0:3], off offset:256
	s_and_b64 vcc, exec, s[2:3]
	s_cbranch_vccz .LBB0_747
	s_waitcnt vmcnt(0)
	s_cmpk_gt_u32 s22, 0xff
	s_cbranch_scc1 .LBB0_760
	s_barrier

; #define PG8_STAGE(bufoff, gbase, voff) do { _Pragma("unroll") for (int _i = 0; _i < 2; ++_i) \
;     __builtin_amdgcn_global_load_lds((const unsigned*)((const char*)(gbase) + (voff)[_i]), (LAS unsigned*)(lds + (bufoff) + ldsw + _i * 8192), 16, 0, 0); } while (0)
; #define PG8_LDA(dst, b, h) do { _Pragma("unroll") for (int m = 0; m < 4; ++m) _Pragma("unroll") for (int k = 0; k < 2; ++k) dst[m][k] = *(const LAS bf16x8*)(lds + PG8_SA(b, h) + aoff + m * 2048 + k * 1024); } while (0)
; #define PG8_LDB(dst, b, h) do { _Pragma("unroll") for (int n = 0; n < 2; ++n) _Pragma("unroll") for (int k = 0; k < 2; ++k) dst[n][k] = *(const LAS bf16x8*)(lds + PG8_SB(b, h) + boff + n * 2048 + k * 1024); } while (0)
; #define PG8_MMA(ai, bj, At, Bt) do { __builtin_amdgcn_s_setprio(1); _Pragma("unroll") for (int m = 0; m < 4; ++m) _Pragma("unroll") for (int n = 0; n < 2; ++n) _Pragma("unroll") for (int k = 0; k < 2; ++k) \
;     acc[ai][bj][m][n] = __builtin_amdgcn_mfma_f32_16x16x32_bf16(Bt[n][k], At[m][k], acc[ai][bj][m][n], 0, 0, 0); __builtin_amdgcn_s_setprio(0); } while (0)
; #define PG8_WAIT_L(n) asm volatile("s_waitcnt lgkmcnt(" #n ")" ::: "memory")
; #define PG8_BAR __builtin_amdgcn_s_barrier()
; #define PG8_SCHED __builtin_amdgcn_sched_barrier(0)
; template <class Epi>
; __device__ __forceinline__ void gemm_phase(LAS unsigned char* lds, const Gemm g, const StaticOrder& S, const Epi& E, int wv0) {
;     ...
;     for (int t = 0; t < nt; t += 2) {
;       const bool last = (t == nt - 2);
;       const char* a1 = cA + (size_t)(t + 1) * kstep;
;       const char* a2 = last ? nA : cA + (size_t)(t + 2) * kstep; const char* b2 = last ? nB : cB + (size_t)(t + 2) * kstep;
;       const char* a3 = a2 + kstep; const char* b3 = b2 + kstep;
;       PG8_LDB(B0, 0, 0); PG8_SCHED; PG8_LDA(At, 0, 0); PG8_STAGE(PG8_SA(1, 1), a1 + hstepA, voffA);
;       PG8_WAIT_L(8); PG8_BAR; PG8_WAIT_L(0); PG8_MMA(0, 0, At, B0); PG8_BAR; PG8_SCHED;
;       PG8_LDB(B1, 0, 1); PG8_STAGE(PG8_SB(0, 0), b2, voffB);
;       PG8_BAR; PG8_WAIT_L(0); PG8_MMA(0, 1, At, B1); PG8_BAR;
;       PG8_LDA(At, 0, 1); PG8_STAGE(PG8_SA(0, 0), a2, voffA);
;       PG8_BAR; PG8_WAIT_L(0); PG8_MMA(1, 0, At, B0); PG8_BAR; PG8_SCHED;
.LBB0_906:
	s_add_u32 s0, s20, 0xfff80080
	s_addc_u32 s22, s21, -1
	s_add_i32 s50, 0, 0x10000
	v_add_u32_e32 v152, s50, v157
	ds_read_b128 v[140:143], v152
	ds_read_b128 v[144:147], v152 offset:1024
	ds_read_b128 v[148:151], v152 offset:2048
	ds_read_b128 v[152:155], v152 offset:3072
	s_cmp_eq_u32 s49, 28
	s_cselect_b32 s25, s13, s22
	s_cselect_b32 s24, s45, s0
	s_cselect_b32 s23, s11, s48
	s_cselect_b32 s22, s46, s47
	v_lshl_add_u64 v[192:193], s[20:21], 0, v[136:137]
	s_add_i32 m0, s19, 0xc000
	ds_read_b128 v[160:163], v159
	ds_read_b128 v[164:167], v159 offset:1024
	ds_read_b128 v[168:171], v159 offset:2048
	ds_read_b128 v[172:175], v159 offset:3072
	ds_read_b128 v[176:179], v159 offset:4096
	ds_read_b128 v[180:183], v159 offset:5120
	ds_read_b128 v[184:187], v159 offset:6144
	ds_read_b128 v[188:191], v159 offset:7168
	global_load_lds_dwordx4 v[192:193], off
	v_lshl_add_u64 v[192:193], s[20:21], 0, v[138:139]
	s_add_i32 m0, s19, 0xe000
	s_nop 0
	global_load_lds_dwordx4 v[192:193], off
	s_waitcnt lgkmcnt(8)
	s_barrier
	s_waitcnt lgkmcnt(0)
	s_waitcnt lgkmcnt(0)
	v_mfma_f32_16x16x32_bf16 v[126:129], v[140:143], v[160:163], v[126:129]
	v_mfma_f32_16x16x32_bf16 v[122:125], v[148:151], v[160:163], v[122:125]
	v_mfma_f32_16x16x32_bf16 v[110:113], v[140:143], v[168:171], v[110:113]
	v_mfma_f32_16x16x32_bf16 v[106:109], v[148:151], v[168:171], v[106:109]
	v_mfma_f32_16x16x32_bf16 v[92:95], v[140:143], v[176:179], v[92:95]
	v_mfma_f32_16x16x32_bf16 v[88:91], v[148:151], v[176:179], v[88:91]
	v_mfma_f32_16x16x32_bf16 v[76:79], v[140:143], v[184:187], v[76:79]
	v_mfma_f32_16x16x32_bf16 v[72:75], v[148:151], v[184:187], v[72:75]
	v_mfma_f32_16x16x32_bf16 v[126:129], v[144:147], v[164:167], v[126:129]
	v_mfma_f32_16x16x32_bf16 v[122:125], v[152:155], v[164:167], v[122:125]
	v_mfma_f32_16x16x32_bf16 v[110:113], v[144:147], v[172:175], v[110:113]
	v_mfma_f32_16x16x32_bf16 v[106:109], v[152:155], v[172:175], v[106:109]
	v_mfma_f32_16x16x32_bf16 v[92:95], v[144:147], v[180:183], v[92:95]
	v_mfma_f32_16x16x32_bf16 v[88:91], v[152:155], v[180:183], v[88:91]
	v_mfma_f32_16x16x32_bf16 v[76:79], v[144:147], v[188:191], v[76:79]
	v_mfma_f32_16x16x32_bf16 v[72:75], v[152:155], v[188:191], v[72:75]
	s_barrier
	s_add_i32 s0, 0, 0x14000
	s_add_i32 s50, s50, s36
	v_add_u32_e32 v204, s0, v157
	v_lshl_add_u64 v[208:209], s[22:23], 0, v[96:97]
	s_mov_b32 m0, s50
	ds_read_b128 v[192:195], v204
	ds_read_b128 v[196:199], v204 offset:1024
	ds_read_b128 v[200:203], v204 offset:2048
	ds_read_b128 v[204:207], v204 offset:3072
	global_load_lds_dwordx4 v[208:209], off
	v_lshl_add_u64 v[210:211], s[22:23], 0, v[130:131]
	s_add_i32 m0, s50, 0x2000
	s_nop 0
	global_load_lds_dwordx4 v[210:211], off
	s_barrier
	s_waitcnt lgkmcnt(0)
	s_waitcnt lgkmcnt(0)
	v_mfma_f32_16x16x32_bf16 v[118:121], v[192:195], v[160:163], v[118:121]
	v_mfma_f32_16x16x32_bf16 v[114:117], v[200:203], v[160:163], v[114:117]
	v_mfma_f32_16x16x32_bf16 v[102:105], v[192:195], v[168:171], v[102:105]
	v_mfma_f32_16x16x32_bf16 v[98:101], v[200:203], v[168:171], v[98:101]
	v_mfma_f32_16x16x32_bf16 v[84:87], v[192:195], v[176:179], v[84:87]
	v_mfma_f32_16x16x32_bf16 v[80:83], v[200:203], v[176:179], v[80:83]
	v_mfma_f32_16x16x32_bf16 v[68:71], v[192:195], v[184:187], v[68:71]
	v_mfma_f32_16x16x32_bf16 v[64:67], v[200:203], v[184:187], v[64:67]
	v_mfma_f32_16x16x32_bf16 v[118:121], v[196:199], v[164:167], v[118:121]
	v_mfma_f32_16x16x32_bf16 v[114:117], v[204:207], v[164:167], v[114:117]
	v_mfma_f32_16x16x32_bf16 v[102:105], v[196:199], v[172:175], v[102:105]
	v_mfma_f32_16x16x32_bf16 v[98:101], v[204:207], v[172:175], v[98:101]
	v_mfma_f32_16x16x32_bf16 v[84:87], v[196:199], v[180:183], v[84:87]
	v_mfma_f32_16x16x32_bf16 v[80:83], v[204:207], v[180:183], v[80:83]
	v_mfma_f32_16x16x32_bf16 v[68:71], v[196:199], v[188:191], v[68:71]
	v_mfma_f32_16x16x32_bf16 v[64:67], v[204:207], v[188:191], v[64:67]
	s_mov_b32 m0, s19
	v_lshl_add_u64 v[212:213], s[24:25], 0, v[134:135]
	s_barrier
	ds_read_b128 v[160:163], v159 offset:16384
	ds_read_b128 v[164:167], v159 offset:17408
	ds_read_b128 v[168:171], v159 offset:18432
	ds_read_b128 v[172:175], v159 offset:19456
	ds_read_b128 v[176:179], v159 offset:20480
	ds_read_b128 v[180:183], v159 offset:21504
	ds_read_b128 v[184:187], v159 offset:22528
	ds_read_b128 v[188:191], v159 offset:23552
	global_load_lds_dwordx4 v[212:213], off
	v_lshl_add_u64 v[214:215], s[24:25], 0, v[132:133]
	s_mov_b32 m0, s38
	s_nop 0
	global_load_lds_dwordx4 v[214:215], off
	s_barrier
	s_waitcnt lgkmcnt(0)
	s_waitcnt lgkmcnt(0)
	v_mfma_f32_16x16x32_bf16 v[60:63], v[140:143], v[160:163], v[60:63]
	v_mfma_f32_16x16x32_bf16 v[56:59], v[148:151], v[160:163], v[56:59]
	v_mfma_f32_16x16x32_bf16 v[44:47], v[140:143], v[168:171], v[44:47]
	v_mfma_f32_16x16x32_bf16 v[40:43], v[148:151], v[168:171], v[40:43]
	v_mfma_f32_16x16x32_bf16 v[28:31], v[140:143], v[176:179], v[28:31]
	v_mfma_f32_16x16x32_bf16 v[24:27], v[148:151], v[176:179], v[24:27]
	v_mfma_f32_16x16x32_bf16 v[12:15], v[140:143], v[184:187], v[12:15]
	v_mfma_f32_16x16x32_bf16 v[8:11], v[148:151], v[184:187], v[8:11]
	v_mfma_f32_16x16x32_bf16 v[60:63], v[144:147], v[164:167], v[60:63]
	v_mfma_f32_16x16x32_bf16 v[56:59], v[152:155], v[164:167], v[56:59]
	v_mfma_f32_16x16x32_bf16 v[44:47], v[144:147], v[172:175], v[44:47]
	v_mfma_f32_16x16x32_bf16 v[40:43], v[152:155], v[172:175], v[40:43]
	v_mfma_f32_16x16x32_bf16 v[28:31], v[144:147], v[180:183], v[28:31]
	v_mfma_f32_16x16x32_bf16 v[24:27], v[152:155], v[180:183], v[24:27]
	v_mfma_f32_16x16x32_bf16 v[12:15], v[144:147], v[188:191], v[12:15]
	v_mfma_f32_16x16x32_bf16 v[8:11], v[152:155], v[188:191], v[8:11]
	s_barrier
; #define PG8_STAGE(bufoff, gbase, voff) do { _Pragma("unroll") for (int _i = 0; _i < 2; ++_i) \
;     __builtin_amdgcn_global_load_lds((const unsigned*)((const char*)(gbase) + (voff)[_i]), (LAS unsigned*)(lds + (bufoff) + ldsw + _i * 8192), 16, 0, 0); } while (0)
; #define PG8_LDA(dst, b, h) do { _Pragma("unroll") for (int m = 0; m < 4; ++m) _Pragma("unroll") for (int k = 0; k < 2; ++k) dst[m][k] = *(const LAS bf16x8*)(lds + PG8_SA(b, h) + aoff + m * 2048 + k * 1024); } while (0)
; #define PG8_LDB(dst, b, h) do { _Pragma("unroll") for (int n = 0; n < 2; ++n) _Pragma("unroll") for (int k = 0; k < 2; ++k) dst[n][k] = *(const LAS bf16x8*)(lds + PG8_SB(b, h) + boff + n * 2048 + k * 1024); } while (0)
; #define PG8_MMA(ai, bj, At, Bt) do { __builtin_amdgcn_s_setprio(1); _Pragma("unroll") for (int m = 0; m < 4; ++m) _Pragma("unroll") for (int n = 0; n < 2; ++n) _Pragma("unroll") for (int k = 0; k < 2; ++k) \
;     acc[ai][bj][m][n] = __builtin_amdgcn_mfma_f32_16x16x32_bf16(Bt[n][k], At[m][k], acc[ai][bj][m][n], 0, 0, 0); __builtin_amdgcn_s_setprio(0); } while (0)
; #define PG8_WAIT_V(n) asm volatile("s_waitcnt vmcnt(" #n ")" ::: "memory")
; #define PG8_WAIT_L(n) asm volatile("s_waitcnt lgkmcnt(" #n ")" ::: "memory")
; #define PG8_BAR __builtin_amdgcn_s_barrier()
; #define PG8_SCHED __builtin_amdgcn_sched_barrier(0)
; template <class Epi>
; __device__ __forceinline__ void gemm_phase(LAS unsigned char* lds, const Gemm g, const StaticOrder& S, const Epi& E, int wv0) {
;     ...
;       PG8_STAGE(PG8_SB(0, 1), b2 + hstepB, voffB);
;       PG8_WAIT_V(6); PG8_BAR; PG8_MMA(1, 1, At, B1); PG8_BAR;
;       PG8_LDB(B0, 1, 0); PG8_SCHED; PG8_LDA(At, 1, 0); PG8_STAGE(PG8_SA(0, 1), a2 + hstepA, voffA);
;       PG8_WAIT_L(8); PG8_BAR; PG8_WAIT_L(0); PG8_MMA(0, 0, At, B0); PG8_BAR; PG8_SCHED;
;       PG8_LDB(B1, 1, 1); PG8_STAGE(PG8_SB(1, 0), b3, voffB);
;       PG8_BAR; PG8_WAIT_L(0); PG8_MMA(0, 1, At, B1); PG8_BAR;
;       PG8_LDA(At, 1, 1); PG8_STAGE(PG8_SA(1, 0), a3, voffA);
;       PG8_BAR; PG8_WAIT_L(0); PG8_MMA(1, 0, At, B0); PG8_BAR; PG8_SCHED;
	s_add_u32 s50, s22, 0x80000
	s_addc_u32 s51, s23, 0
	s_add_i32 s0, s0, s36
	v_lshl_add_u64 v[140:141], s[50:51], 0, v[96:97]
	s_mov_b32 m0, s0
	s_nop 0
	global_load_lds_dwordx4 v[140:141], off
	v_lshl_add_u64 v[140:141], s[50:51], 0, v[130:131]
	s_add_i32 m0, s0, 0x2000
	s_nop 0
	global_load_lds_dwordx4 v[140:141], off
	s_waitcnt vmcnt(6)
	s_barrier
	v_mfma_f32_16x16x32_bf16 v[52:55], v[192:195], v[160:163], v[52:55]
	v_mfma_f32_16x16x32_bf16 v[48:51], v[200:203], v[160:163], v[48:51]
	v_mfma_f32_16x16x32_bf16 v[36:39], v[192:195], v[168:171], v[36:39]
	v_mfma_f32_16x16x32_bf16 v[32:35], v[200:203], v[168:171], v[32:35]
	v_mfma_f32_16x16x32_bf16 v[20:23], v[192:195], v[176:179], v[20:23]
	v_mfma_f32_16x16x32_bf16 v[16:19], v[200:203], v[176:179], v[16:19]
	v_mfma_f32_16x16x32_bf16 v[4:7], v[192:195], v[184:187], v[4:7]
	v_mfma_f32_16x16x32_bf16 v[0:3], v[200:203], v[184:187], v[0:3]
	v_mfma_f32_16x16x32_bf16 v[52:55], v[196:199], v[164:167], v[52:55]
	v_mfma_f32_16x16x32_bf16 v[48:51], v[204:207], v[164:167], v[48:51]
	v_mfma_f32_16x16x32_bf16 v[36:39], v[196:199], v[172:175], v[36:39]
	v_mfma_f32_16x16x32_bf16 v[32:35], v[204:207], v[172:175], v[32:35]
	v_mfma_f32_16x16x32_bf16 v[20:23], v[196:199], v[180:183], v[20:23]
	v_mfma_f32_16x16x32_bf16 v[16:19], v[204:207], v[180:183], v[16:19]
	v_mfma_f32_16x16x32_bf16 v[4:7], v[196:199], v[188:191], v[4:7]
	v_mfma_f32_16x16x32_bf16 v[0:3], v[204:207], v[188:191], v[0:3]
	s_add_i32 s0, 0, 0x18000
	v_add_u32_e32 v152, s0, v157
	s_barrier
	ds_read_b128 v[140:143], v152
	ds_read_b128 v[144:147], v152 offset:1024
	ds_read_b128 v[148:151], v152 offset:2048
	ds_read_b128 v[152:155], v152 offset:3072
	s_add_u32 s24, s24, 0x80000
	s_addc_u32 s25, s25, 0
	s_mov_b32 m0, s39
	v_lshl_add_u64 v[192:193], s[24:25], 0, v[134:135]
	ds_read_b128 v[160:163], v159 offset:32768
	ds_read_b128 v[164:167], v159 offset:33792
	ds_read_b128 v[168:171], v159 offset:34816
	ds_read_b128 v[172:175], v159 offset:35840
	ds_read_b128 v[176:179], v159 offset:36864
	ds_read_b128 v[180:183], v159 offset:37888
	ds_read_b128 v[184:187], v159 offset:38912
	ds_read_b128 v[188:191], v159 offset:39936
	global_load_lds_dwordx4 v[192:193], off
	v_lshl_add_u64 v[192:193], s[24:25], 0, v[132:133]
	s_mov_b32 m0, s40
	s_nop 0
	global_load_lds_dwordx4 v[192:193], off
	s_waitcnt lgkmcnt(8)
	s_barrier
	s_waitcnt lgkmcnt(0)
	s_waitcnt lgkmcnt(0)
	v_mfma_f32_16x16x32_bf16 v[126:129], v[140:143], v[160:163], v[126:129]
	v_mfma_f32_16x16x32_bf16 v[122:125], v[148:151], v[160:163], v[122:125]
	v_mfma_f32_16x16x32_bf16 v[110:113], v[140:143], v[168:171], v[110:113]
	v_mfma_f32_16x16x32_bf16 v[106:109], v[148:151], v[168:171], v[106:109]
	v_mfma_f32_16x16x32_bf16 v[92:95], v[140:143], v[176:179], v[92:95]
	v_mfma_f32_16x16x32_bf16 v[88:91], v[148:151], v[176:179], v[88:91]
	v_mfma_f32_16x16x32_bf16 v[76:79], v[140:143], v[184:187], v[76:79]
	v_mfma_f32_16x16x32_bf16 v[72:75], v[148:151], v[184:187], v[72:75]
	v_mfma_f32_16x16x32_bf16 v[126:129], v[144:147], v[164:167], v[126:129]
	v_mfma_f32_16x16x32_bf16 v[122:125], v[152:155], v[164:167], v[122:125]
	v_mfma_f32_16x16x32_bf16 v[110:113], v[144:147], v[172:175], v[110:113]
	v_mfma_f32_16x16x32_bf16 v[106:109], v[152:155], v[172:175], v[106:109]
	v_mfma_f32_16x16x32_bf16 v[92:95], v[144:147], v[180:183], v[92:95]
	v_mfma_f32_16x16x32_bf16 v[88:91], v[152:155], v[180:183], v[88:91]
	v_mfma_f32_16x16x32_bf16 v[76:79], v[144:147], v[188:191], v[76:79]
	v_mfma_f32_16x16x32_bf16 v[72:75], v[152:155], v[188:191], v[72:75]
	s_barrier
	s_add_i32 s24, 0, 0x1c000
	s_add_i32 s0, s0, s36
	v_add_u32_e32 v204, s24, v157
	v_lshl_add_u64 v[208:209], v[208:209], 0, s[72:73]
	s_mov_b32 m0, s0
	ds_read_b128 v[192:195], v204
	ds_read_b128 v[196:199], v204 offset:1024
	ds_read_b128 v[200:203], v204 offset:2048
	ds_read_b128 v[204:207], v204 offset:3072
	global_load_lds_dwordx4 v[208:209], off
	v_lshl_add_u64 v[208:209], v[210:211], 0, s[72:73]
	s_add_i32 m0, s0, 0x2000
	s_nop 0
	global_load_lds_dwordx4 v[208:209], off
	s_barrier
	s_waitcnt lgkmcnt(0)
	s_waitcnt lgkmcnt(0)
	v_mfma_f32_16x16x32_bf16 v[118:121], v[192:195], v[160:163], v[118:121]
	v_mfma_f32_16x16x32_bf16 v[114:117], v[200:203], v[160:163], v[114:117]
	v_mfma_f32_16x16x32_bf16 v[102:105], v[192:195], v[168:171], v[102:105]
	v_mfma_f32_16x16x32_bf16 v[98:101], v[200:203], v[168:171], v[98:101]
	v_mfma_f32_16x16x32_bf16 v[84:87], v[192:195], v[176:179], v[84:87]
	v_mfma_f32_16x16x32_bf16 v[80:83], v[200:203], v[176:179], v[80:83]
	v_mfma_f32_16x16x32_bf16 v[68:71], v[192:195], v[184:187], v[68:71]
	v_mfma_f32_16x16x32_bf16 v[64:67], v[200:203], v[184:187], v[64:67]
	v_mfma_f32_16x16x32_bf16 v[118:121], v[196:199], v[164:167], v[118:121]
	v_mfma_f32_16x16x32_bf16 v[114:117], v[204:207], v[164:167], v[114:117]
	v_mfma_f32_16x16x32_bf16 v[102:105], v[196:199], v[172:175], v[102:105]
	v_mfma_f32_16x16x32_bf16 v[98:101], v[204:207], v[172:175], v[98:101]
	v_mfma_f32_16x16x32_bf16 v[84:87], v[196:199], v[180:183], v[84:87]
	v_mfma_f32_16x16x32_bf16 v[80:83], v[204:207], v[180:183], v[80:83]
	v_mfma_f32_16x16x32_bf16 v[68:71], v[196:199], v[188:191], v[68:71]
	v_mfma_f32_16x16x32_bf16 v[64:67], v[204:207], v[188:191], v[64:67]
	s_mov_b32 m0, s41
	v_lshl_add_u64 v[208:209], v[212:213], 0, s[72:73]
	s_barrier
	ds_read_b128 v[160:163], v159 offset:49152
	ds_read_b128 v[164:167], v159 offset:50176
	ds_read_b128 v[168:171], v159 offset:51200
	ds_read_b128 v[172:175], v159 offset:52224
	ds_read_b128 v[176:179], v159 offset:53248
	ds_read_b128 v[180:183], v159 offset:54272
	ds_read_b128 v[184:187], v159 offset:55296
	ds_read_b128 v[188:191], v159 offset:56320
	global_load_lds_dwordx4 v[208:209], off
	v_lshl_add_u64 v[208:209], v[214:215], 0, s[72:73]
	s_mov_b32 m0, s42
	s_nop 0
	global_load_lds_dwordx4 v[208:209], off
	s_barrier
; __device__ __forceinline__ float fexp2(float x) { return __builtin_amdgcn_exp2f(x); }
; __device__ __forceinline__ float frcp(float x) { return __builtin_amdgcn_rcpf(x); }
; #define PG8_STAGE(bufoff, gbase, voff) do { _Pragma("unroll") for (int _i = 0; _i < 2; ++_i) \
;     __builtin_amdgcn_global_load_lds((const unsigned*)((const char*)(gbase) + (voff)[_i]), (LAS unsigned*)(lds + (bufoff) + ldsw + _i * 8192), 16, 0, 0); } while (0)
; #define PG8_LDA(dst, b, h) do { _Pragma("unroll") for (int m = 0; m < 4; ++m) _Pragma("unroll") for (int k = 0; k < 2; ++k) dst[m][k] = *(const LAS bf16x8*)(lds + PG8_SA(b, h) + aoff + m * 2048 + k * 1024); } while (0)
; #define PG8_MMA(ai, bj, At, Bt) do { __builtin_amdgcn_s_setprio(1); _Pragma("unroll") for (int m = 0; m < 4; ++m) _Pragma("unroll") for (int n = 0; n < 2; ++n) _Pragma("unroll") for (int k = 0; k < 2; ++k) \
;     acc[ai][bj][m][n] = __builtin_amdgcn_mfma_f32_16x16x32_bf16(Bt[n][k], At[m][k], acc[ai][bj][m][n], 0, 0, 0); __builtin_amdgcn_s_setprio(0); } while (0)
; #define PG8_WAIT_V(n) asm volatile("s_waitcnt vmcnt(" #n ")" ::: "memory")
; #define PG8_WAIT_L(n) asm volatile("s_waitcnt lgkmcnt(" #n ")" ::: "memory")
; #define PG8_BAR __builtin_amdgcn_s_barrier()
; #define PG8_SCHED __builtin_amdgcn_sched_barrier(0)
; template <class Epi>
; __device__ __forceinline__ void gemm_phase(LAS unsigned char* lds, const Gemm g, const StaticOrder& S, const Epi& E, int wv0) {
;     ...
;       PG8_BAR; PG8_WAIT_L(0); PG8_MMA(0, 1, At, B1); PG8_BAR;
;       PG8_LDA(At, 1, 1); PG8_STAGE(PG8_SA(1, 0), a3, voffA);
;       PG8_BAR; PG8_WAIT_L(0); PG8_MMA(1, 0, At, B0); PG8_BAR; PG8_SCHED;
;       PG8_STAGE(PG8_SB(1, 1), b3 + hstepB, voffB);
;       PG8_WAIT_V(6); PG8_BAR; PG8_MMA(1, 1, At, B1); PG8_BAR;
;     }
;     E(acc, cur, wr, wc, fr, fq);
;     if (!has_next) break;
;   __device__ __forceinline__ void emit(const EpiPre& q0, int row, int col, f32x4 a, f32x4 b, const f32x4 (&hb)[2][2], const float (&hs)[2][4], int ai_, int m_, int bj_) const {
;     ...
;       const float bb[8] = {q.a0[0], q.a0[1], q.a0[2], q.a0[3], q.a1[0], q.a1[1], q.a1[2], q.a1[3]};
; #pragma unroll
;       for (int j = 0; j < 8; ++j) v[j] = frcp(1.0f + fexp2(__builtin_fmaf(v[j], -LOG2E, bb[j])));
;       store8bf((bf16_t*)e.out + (size_t)row * NG + col, v);
	s_waitcnt lgkmcnt(0)
	s_waitcnt lgkmcnt(0)
	v_mfma_f32_16x16x32_bf16 v[60:63], v[140:143], v[160:163], v[60:63]
	v_mfma_f32_16x16x32_bf16 v[56:59], v[148:151], v[160:163], v[56:59]
	v_mfma_f32_16x16x32_bf16 v[44:47], v[140:143], v[168:171], v[44:47]
	v_mfma_f32_16x16x32_bf16 v[40:43], v[148:151], v[168:171], v[40:43]
	v_mfma_f32_16x16x32_bf16 v[28:31], v[140:143], v[176:179], v[28:31]
	v_mfma_f32_16x16x32_bf16 v[24:27], v[148:151], v[176:179], v[24:27]
	v_mfma_f32_16x16x32_bf16 v[12:15], v[140:143], v[184:187], v[12:15]
	v_mfma_f32_16x16x32_bf16 v[8:11], v[148:151], v[184:187], v[8:11]
	v_mfma_f32_16x16x32_bf16 v[60:63], v[144:147], v[164:167], v[60:63]
	v_mfma_f32_16x16x32_bf16 v[56:59], v[152:155], v[164:167], v[56:59]
	v_mfma_f32_16x16x32_bf16 v[44:47], v[144:147], v[172:175], v[44:47]
	v_mfma_f32_16x16x32_bf16 v[40:43], v[152:155], v[172:175], v[40:43]
	v_mfma_f32_16x16x32_bf16 v[28:31], v[144:147], v[180:183], v[28:31]
	v_mfma_f32_16x16x32_bf16 v[24:27], v[152:155], v[180:183], v[24:27]
	v_mfma_f32_16x16x32_bf16 v[12:15], v[144:147], v[188:191], v[12:15]
	v_mfma_f32_16x16x32_bf16 v[8:11], v[152:155], v[188:191], v[8:11]
	s_barrier
	s_add_u32 s22, s22, 0x80080
	s_addc_u32 s23, s23, 0
	s_add_i32 s0, s24, s36
	v_lshl_add_u64 v[140:141], s[22:23], 0, v[96:97]
	s_mov_b32 m0, s0
	s_nop 0
	global_load_lds_dwordx4 v[140:141], off
	v_lshl_add_u64 v[140:141], s[22:23], 0, v[130:131]
	s_add_i32 m0, s0, 0x2000
	s_nop 0
	global_load_lds_dwordx4 v[140:141], off
	s_waitcnt vmcnt(6)
	s_barrier
	v_mfma_f32_16x16x32_bf16 v[52:55], v[192:195], v[160:163], v[52:55]
	v_mfma_f32_16x16x32_bf16 v[48:51], v[200:203], v[160:163], v[48:51]
	v_mfma_f32_16x16x32_bf16 v[36:39], v[192:195], v[168:171], v[36:39]
	v_mfma_f32_16x16x32_bf16 v[32:35], v[200:203], v[168:171], v[32:35]
	v_mfma_f32_16x16x32_bf16 v[20:23], v[192:195], v[176:179], v[20:23]
	v_mfma_f32_16x16x32_bf16 v[16:19], v[200:203], v[176:179], v[16:19]
	v_mfma_f32_16x16x32_bf16 v[4:7], v[192:195], v[184:187], v[4:7]
	v_mfma_f32_16x16x32_bf16 v[0:3], v[200:203], v[184:187], v[0:3]
	v_mfma_f32_16x16x32_bf16 v[52:55], v[196:199], v[164:167], v[52:55]
	v_mfma_f32_16x16x32_bf16 v[48:51], v[204:207], v[164:167], v[48:51]
	v_mfma_f32_16x16x32_bf16 v[36:39], v[196:199], v[172:175], v[36:39]
	v_mfma_f32_16x16x32_bf16 v[32:35], v[204:207], v[172:175], v[32:35]
	v_mfma_f32_16x16x32_bf16 v[20:23], v[196:199], v[180:183], v[20:23]
	v_mfma_f32_16x16x32_bf16 v[16:19], v[204:207], v[180:183], v[16:19]
	v_mfma_f32_16x16x32_bf16 v[4:7], v[196:199], v[188:191], v[4:7]
	v_mfma_f32_16x16x32_bf16 v[0:3], v[204:207], v[188:191], v[0:3]
	s_add_i32 s49, s49, 2
	s_add_u32 s20, s20, 0x100
	s_addc_u32 s21, s21, 0
	s_add_u32 s47, s47, 0x100
	s_addc_u32 s48, s48, 0
	s_cmp_gt_u32 s49, 29
	s_barrier
	s_cbranch_scc0 .LBB0_906
	s_setprio 0
	v_lshl_or_b32 v164, s1, 8, v158
	v_ashrrev_i32_e32 v165, 31, v164
	v_lshl_add_u64 v[166:167], v[164:165], 2, s[8:9]
	global_load_dwordx4 v[140:143], v[166:167], off offset:16
	global_load_dwordx4 v[144:147], v[166:167], off
	s_mov_b32 s0, 0xbfb8aa3b
	s_and_b64 vcc, exec, s[2:3]
	s_mov_b64 s[22:23], s[16:17]
	s_mov_b64 s[20:21], s[14:15]
	s_waitcnt vmcnt(0)
	v_pk_mul_f32 v[148:149], v[142:143], s[0:1] op_sel_hi:[1,0]
	v_pk_mul_f32 v[150:151], v[140:141], s[0:1] op_sel_hi:[1,0]
	global_load_dwordx4 v[160:163], v[166:167], off offset:528
	global_load_dwordx4 v[140:143], v[166:167], off offset:512
	v_pk_mul_f32 v[154:155], v[144:145], s[0:1] op_sel_hi:[1,0]
	v_pk_mul_f32 v[152:153], v[146:147], s[0:1] op_sel_hi:[1,0]
	v_fmamk_f32 v126, v126, 0xbfb8aa3b, v154
	v_exp_f32_e32 v126, v126
	v_fmamk_f32 v122, v122, 0xbfb8aa3b, v150
	v_exp_f32_e32 v122, v122
	v_fmamk_f32 v110, v110, 0xbfb8aa3b, v154
	v_add_f32_e32 v126, 1.0, v126
	v_fmamk_f32 v106, v106, 0xbfb8aa3b, v150
	v_add_f32_e32 v122, 1.0, v122
	v_rcp_f32_e32 v166, v122
	v_fmamk_f32 v122, v123, 0xbfb8aa3b, v151
	v_exp_f32_e32 v122, v122
	v_exp_f32_e32 v110, v110
	v_exp_f32_e32 v106, v106
	v_add_f32_e32 v122, 1.0, v122
	v_rcp_f32_e32 v167, v122
	v_fmamk_f32 v122, v124, 0xbfb8aa3b, v148
	v_exp_f32_e32 v122, v122
	v_add_f32_e32 v110, 1.0, v110
	v_add_f32_e32 v106, 1.0, v106
	v_fmamk_f32 v92, v92, 0xbfb8aa3b, v154
	v_add_f32_e32 v122, 1.0, v122
	v_rcp_f32_e32 v168, v122
	v_fmamk_f32 v122, v125, 0xbfb8aa3b, v149
	v_exp_f32_e32 v122, v122
	v_lshlrev_b64 v[124:125], 1, v[164:165]
	v_fmamk_f32 v88, v88, 0xbfb8aa3b, v150
	v_exp_f32_e32 v92, v92
	v_add_f32_e32 v122, 1.0, v122
	v_rcp_f32_e32 v169, v122
	v_mov_b64_e32 v[122:123], s[6:7]
	v_exp_f32_e32 v88, v88
	v_add_f32_e32 v92, 1.0, v92
	v_cvt_pk_bf16_f32 v164, v166, v167
	v_cvt_pk_bf16_f32 v165, v168, v169
	v_add_f32_e32 v88, 1.0, v88
	v_fmamk_f32 v76, v76, 0xbfb8aa3b, v154
	v_fmamk_f32 v72, v72, 0xbfb8aa3b, v150
	v_exp_f32_e32 v76, v76
	v_exp_f32_e32 v72, v72
	v_fmamk_f32 v60, v60, 0xbfb8aa3b, v154
	v_fmamk_f32 v56, v56, 0xbfb8aa3b, v150
	v_add_f32_e32 v76, 1.0, v76
	v_add_f32_e32 v72, 1.0, v72
	v_exp_f32_e32 v60, v60
	v_exp_f32_e32 v56, v56
	v_fmamk_f32 v44, v44, 0xbfb8aa3b, v154
	v_fmamk_f32 v40, v40, 0xbfb8aa3b, v150
	v_add_f32_e32 v60, 1.0, v60
	v_add_f32_e32 v56, 1.0, v56
	v_exp_f32_e32 v44, v44
	v_exp_f32_e32 v40, v40
	v_fmamk_f32 v28, v28, 0xbfb8aa3b, v154
	v_fmamk_f32 v24, v24, 0xbfb8aa3b, v150
	v_add_f32_e32 v44, 1.0, v44
	v_add_f32_e32 v40, 1.0, v40
	v_exp_f32_e32 v28, v28
	v_exp_f32_e32 v24, v24
	v_fmamk_f32 v12, v12, 0xbfb8aa3b, v154
	v_fmamk_f32 v8, v8, 0xbfb8aa3b, v150
	v_add_f32_e32 v28, 1.0, v28
	v_add_f32_e32 v24, 1.0, v24
	v_exp_f32_e32 v12, v12
	v_exp_f32_e32 v8, v8
	v_add_f32_e32 v12, 1.0, v12
	v_add_f32_e32 v8, 1.0, v8
	s_waitcnt vmcnt(0)
; __device__ __forceinline__ float fexp2(float x) { return __builtin_amdgcn_exp2f(x); }
; __device__ __forceinline__ float frcp(float x) { return __builtin_amdgcn_rcpf(x); }
;   __device__ __forceinline__ void emit(const EpiPre& q0, int row, int col, f32x4 a, f32x4 b, const f32x4 (&hb)[2][2], const float (&hs)[2][4], int ai_, int m_, int bj_) const {
;     ...
;     } else if (MODE == E_GATE) {
;       const float bb[8] = {q.a0[0], q.a0[1], q.a0[2], q.a0[3], q.a1[0], q.a1[1], q.a1[2], q.a1[3]};
; #pragma unroll
;       for (int j = 0; j < 8; ++j) v[j] = frcp(1.0f + fexp2(__builtin_fmaf(v[j], -LOG2E, bb[j])));
;       store8bf((bf16_t*)e.out + (size_t)row * NG + col, v);
	v_pk_mul_f32 v[144:145], v[142:143], s[0:1] op_sel_hi:[1,0]
	v_pk_mul_f32 v[142:143], v[160:161], s[0:1] op_sel_hi:[1,0]
	v_rcp_f32_e32 v161, v126
	v_fmamk_f32 v126, v127, 0xbfb8aa3b, v155
	v_exp_f32_e32 v126, v126
	v_pk_mul_f32 v[146:147], v[140:141], s[0:1] op_sel_hi:[1,0]
	v_pk_mul_f32 v[140:141], v[162:163], s[0:1] op_sel_hi:[1,0]
	v_fmamk_f32 v114, v114, 0xbfb8aa3b, v142
	v_add_f32_e32 v126, 1.0, v126
	v_rcp_f32_e32 v162, v126
	v_fmamk_f32 v126, v128, 0xbfb8aa3b, v152
	v_exp_f32_e32 v126, v126
	v_exp_f32_e32 v114, v114
	v_cvt_pk_bf16_f32 v162, v161, v162
	v_fmamk_f32 v118, v118, 0xbfb8aa3b, v146
	v_add_f32_e32 v126, 1.0, v126
	v_rcp_f32_e32 v128, v126
	v_fmamk_f32 v126, v129, 0xbfb8aa3b, v153
	v_exp_f32_e32 v126, v126
	v_add_f32_e32 v114, 1.0, v114
	v_fmamk_f32 v119, v119, 0xbfb8aa3b, v147
	v_fmamk_f32 v120, v120, 0xbfb8aa3b, v144
	v_add_f32_e32 v126, 1.0, v126
	v_rcp_f32_e32 v129, v126
	v_fmamk_f32 v121, v121, 0xbfb8aa3b, v145
	v_exp_f32_e32 v118, v118
	v_exp_f32_e32 v119, v119
	v_cvt_pk_bf16_f32 v163, v128, v129
	v_rcp_f32_e32 v128, v114
	v_fmamk_f32 v114, v115, 0xbfb8aa3b, v143
	v_exp_f32_e32 v114, v114
	v_exp_f32_e32 v120, v120
	v_exp_f32_e32 v121, v121
	v_add_f32_e32 v118, 1.0, v118
	v_add_f32_e32 v114, 1.0, v114
	v_rcp_f32_e32 v129, v114
	v_fmamk_f32 v114, v116, 0xbfb8aa3b, v140
	v_exp_f32_e32 v114, v114
	v_add_f32_e32 v119, 1.0, v119
	v_add_f32_e32 v120, 1.0, v120
	v_add_f32_e32 v121, 1.0, v121
	v_add_f32_e32 v114, 1.0, v114
	v_rcp_f32_e32 v161, v114
	v_fmamk_f32 v114, v117, 0xbfb8aa3b, v141
	v_exp_f32_e32 v114, v114
	v_rcp_f32_e32 v118, v118
	v_rcp_f32_e32 v119, v119
	v_rcp_f32_e32 v120, v120
	v_add_f32_e32 v114, 1.0, v114
	v_rcp_f32_e32 v121, v121
	v_rcp_f32_e32 v117, v114
	v_lshl_add_u32 v160, s18, 8, v156
	v_mad_i64_i32 v[126:127], s[0:1], v160, s33, v[122:123]
	v_lshl_add_u64 v[126:127], v[126:127], 0, v[124:125]
	v_cvt_pk_bf16_f32 v114, v118, v119
	v_cvt_pk_bf16_f32 v115, v120, v121
	v_cvt_pk_bf16_f32 v116, v128, v129
	v_cvt_pk_bf16_f32 v117, v161, v117
	global_store_dwordx4 v[126:127], v[114:117], off offset:256
	v_fmamk_f32 v98, v98, 0xbfb8aa3b, v142
	v_exp_f32_e32 v98, v98
	v_rcp_f32_e32 v115, v110
	v_fmamk_f32 v110, v111, 0xbfb8aa3b, v155
	v_rcp_f32_e32 v117, v106
	v_fmamk_f32 v106, v107, 0xbfb8aa3b, v151
	v_exp_f32_e32 v110, v110
	v_exp_f32_e32 v106, v106
	v_or_b32_e32 v114, 16, v160
	v_add_f32_e32 v98, 1.0, v98
	v_add_f32_e32 v110, 1.0, v110
	v_add_f32_e32 v106, 1.0, v106
	v_rcp_f32_e32 v116, v110
	v_fmamk_f32 v110, v112, 0xbfb8aa3b, v152
	v_rcp_f32_e32 v118, v106
	v_fmamk_f32 v106, v108, 0xbfb8aa3b, v148
	v_exp_f32_e32 v110, v110
	v_exp_f32_e32 v106, v106
	v_cvt_pk_bf16_f32 v108, v117, v118
	v_fmamk_f32 v102, v102, 0xbfb8aa3b, v146
	v_add_f32_e32 v110, 1.0, v110
	v_add_f32_e32 v106, 1.0, v106
	v_rcp_f32_e32 v112, v110
	v_fmamk_f32 v110, v113, 0xbfb8aa3b, v153
	v_rcp_f32_e32 v119, v106
	v_fmamk_f32 v106, v109, 0xbfb8aa3b, v149
	v_exp_f32_e32 v110, v110
	v_exp_f32_e32 v106, v106
	v_fmamk_f32 v103, v103, 0xbfb8aa3b, v147
	v_fmamk_f32 v104, v104, 0xbfb8aa3b, v144
	v_add_f32_e32 v110, 1.0, v110
	v_add_f32_e32 v106, 1.0, v106
	v_rcp_f32_e32 v113, v110
	v_rcp_f32_e32 v109, v106
	v_mad_i64_i32 v[106:107], s[0:1], v114, s33, v[122:123]
	v_lshl_add_u64 v[110:111], v[106:107], 0, v[124:125]
	v_cvt_pk_bf16_f32 v106, v115, v116
	v_cvt_pk_bf16_f32 v107, v112, v113
	v_cvt_pk_bf16_f32 v109, v119, v109
	global_store_dwordx4 v[110:111], v[106:109], off
	v_fmamk_f32 v105, v105, 0xbfb8aa3b, v145
	v_exp_f32_e32 v102, v102
	v_rcp_f32_e32 v106, v98
	v_fmamk_f32 v98, v99, 0xbfb8aa3b, v143
	v_exp_f32_e32 v98, v98
	v_exp_f32_e32 v103, v103
	v_exp_f32_e32 v104, v104
	v_exp_f32_e32 v105, v105
	v_add_f32_e32 v98, 1.0, v98
	v_rcp_f32_e32 v107, v98
	v_fmamk_f32 v98, v100, 0xbfb8aa3b, v140
	v_exp_f32_e32 v98, v98
	v_add_f32_e32 v102, 1.0, v102
	v_add_f32_e32 v103, 1.0, v103
	v_add_f32_e32 v104, 1.0, v104
	v_add_f32_e32 v98, 1.0, v98
	v_rcp_f32_e32 v108, v98
	v_fmamk_f32 v98, v101, 0xbfb8aa3b, v141
	v_exp_f32_e32 v98, v98
	v_add_f32_e32 v105, 1.0, v105
	v_rcp_f32_e32 v102, v102
	v_rcp_f32_e32 v103, v103
	v_add_f32_e32 v98, 1.0, v98
	v_rcp_f32_e32 v104, v104
	v_rcp_f32_e32 v105, v105
	v_rcp_f32_e32 v101, v98
	v_cvt_pk_bf16_f32 v98, v102, v103
	v_cvt_pk_bf16_f32 v100, v106, v107
	v_cvt_pk_bf16_f32 v99, v104, v105
	v_cvt_pk_bf16_f32 v101, v108, v101
	global_store_dwordx4 v[110:111], v[98:101], off offset:256
	v_fmamk_f32 v80, v80, 0xbfb8aa3b, v142
	v_exp_f32_e32 v80, v80
	v_rcp_f32_e32 v99, v92
	v_fmamk_f32 v92, v93, 0xbfb8aa3b, v155
	v_rcp_f32_e32 v101, v88
	v_fmamk_f32 v88, v89, 0xbfb8aa3b, v151
	v_exp_f32_e32 v92, v92
	v_exp_f32_e32 v88, v88
	v_or_b32_e32 v98, 32, v160
	global_store_dwordx4 v[126:127], v[162:165], off
	v_add_f32_e32 v92, 1.0, v92
	v_add_f32_e32 v88, 1.0, v88
	v_rcp_f32_e32 v100, v92
	v_fmamk_f32 v92, v94, 0xbfb8aa3b, v152
	v_rcp_f32_e32 v102, v88
	v_fmamk_f32 v88, v90, 0xbfb8aa3b, v148
	v_exp_f32_e32 v92, v92
	v_exp_f32_e32 v88, v88
	v_cvt_pk_bf16_f32 v90, v101, v102
	v_add_f32_e32 v92, 1.0, v92
	v_add_f32_e32 v88, 1.0, v88
	v_rcp_f32_e32 v94, v92
	v_fmamk_f32 v92, v95, 0xbfb8aa3b, v153
	v_rcp_f32_e32 v103, v88
	v_fmamk_f32 v88, v91, 0xbfb8aa3b, v149
	v_exp_f32_e32 v92, v92
	v_exp_f32_e32 v88, v88
	v_add_f32_e32 v80, 1.0, v80
	v_add_f32_e32 v92, 1.0, v92
	v_add_f32_e32 v88, 1.0, v88
	v_rcp_f32_e32 v95, v92
	v_rcp_f32_e32 v91, v88
	v_mad_i64_i32 v[88:89], s[0:1], v98, s33, v[122:123]
	v_lshl_add_u64 v[92:93], v[88:89], 0, v[124:125]
	v_cvt_pk_bf16_f32 v88, v99, v100
	v_cvt_pk_bf16_f32 v89, v94, v95
	v_cvt_pk_bf16_f32 v91, v103, v91
	global_store_dwordx4 v[92:93], v[88:91], off
	v_fmamk_f32 v84, v84, 0xbfb8aa3b, v146
; __device__ __forceinline__ float fexp2(float x) { return __builtin_amdgcn_exp2f(x); }
; __device__ __forceinline__ float frcp(float x) { return __builtin_amdgcn_rcpf(x); }
;   __device__ __forceinline__ void emit(const EpiPre& q0, int row, int col, f32x4 a, f32x4 b, const f32x4 (&hb)[2][2], const float (&hs)[2][4], int ai_, int m_, int bj_) const {
;     ...
;     } else if (MODE == E_GATE) {
;       const float bb[8] = {q.a0[0], q.a0[1], q.a0[2], q.a0[3], q.a1[0], q.a1[1], q.a1[2], q.a1[3]};
; #pragma unroll
;       for (int j = 0; j < 8; ++j) v[j] = frcp(1.0f + fexp2(__builtin_fmaf(v[j], -LOG2E, bb[j])));
;       store8bf((bf16_t*)e.out + (size_t)row * NG + col, v);
	v_fmamk_f32 v85, v85, 0xbfb8aa3b, v147
	v_rcp_f32_e32 v88, v80
	v_fmamk_f32 v80, v81, 0xbfb8aa3b, v143
	v_exp_f32_e32 v80, v80
	v_fmamk_f32 v86, v86, 0xbfb8aa3b, v144
	v_fmamk_f32 v87, v87, 0xbfb8aa3b, v145
	v_exp_f32_e32 v84, v84
	v_add_f32_e32 v80, 1.0, v80
	v_rcp_f32_e32 v89, v80
	v_fmamk_f32 v80, v82, 0xbfb8aa3b, v140
	v_exp_f32_e32 v80, v80
	v_exp_f32_e32 v85, v85
	v_exp_f32_e32 v86, v86
	v_exp_f32_e32 v87, v87
	v_add_f32_e32 v80, 1.0, v80
	v_rcp_f32_e32 v90, v80
	v_fmamk_f32 v80, v83, 0xbfb8aa3b, v141
	v_exp_f32_e32 v80, v80
	v_add_f32_e32 v84, 1.0, v84
	v_add_f32_e32 v85, 1.0, v85
	v_add_f32_e32 v86, 1.0, v86
	v_add_f32_e32 v87, 1.0, v87
	v_add_f32_e32 v80, 1.0, v80
	v_rcp_f32_e32 v84, v84
	v_rcp_f32_e32 v85, v85
	v_rcp_f32_e32 v86, v86
	v_rcp_f32_e32 v87, v87
	v_rcp_f32_e32 v83, v80
	v_cvt_pk_bf16_f32 v80, v84, v85
	v_cvt_pk_bf16_f32 v82, v88, v89
	v_cvt_pk_bf16_f32 v81, v86, v87
	v_cvt_pk_bf16_f32 v83, v90, v83
	global_store_dwordx4 v[92:93], v[80:83], off offset:256
	v_fmamk_f32 v64, v64, 0xbfb8aa3b, v142
	v_exp_f32_e32 v64, v64
	v_rcp_f32_e32 v81, v76
	v_fmamk_f32 v76, v77, 0xbfb8aa3b, v155
	v_rcp_f32_e32 v83, v72
	v_fmamk_f32 v72, v73, 0xbfb8aa3b, v151
	v_exp_f32_e32 v76, v76
	v_exp_f32_e32 v72, v72
	v_or_b32_e32 v80, 48, v160
	v_add_f32_e32 v64, 1.0, v64
	v_add_f32_e32 v76, 1.0, v76
	v_add_f32_e32 v72, 1.0, v72
	v_rcp_f32_e32 v82, v76
	v_fmamk_f32 v76, v78, 0xbfb8aa3b, v152
	v_rcp_f32_e32 v84, v72
	v_fmamk_f32 v72, v74, 0xbfb8aa3b, v148
	v_exp_f32_e32 v76, v76
	v_exp_f32_e32 v72, v72
	v_cvt_pk_bf16_f32 v74, v83, v84
	v_fmamk_f32 v68, v68, 0xbfb8aa3b, v146
	v_add_f32_e32 v76, 1.0, v76
	v_add_f32_e32 v72, 1.0, v72
	v_rcp_f32_e32 v78, v76
	v_fmamk_f32 v76, v79, 0xbfb8aa3b, v153
	v_rcp_f32_e32 v85, v72
	v_fmamk_f32 v72, v75, 0xbfb8aa3b, v149
	v_exp_f32_e32 v76, v76
	v_exp_f32_e32 v72, v72
	v_fmamk_f32 v69, v69, 0xbfb8aa3b, v147
	v_fmamk_f32 v70, v70, 0xbfb8aa3b, v144
	v_add_f32_e32 v76, 1.0, v76
	v_add_f32_e32 v72, 1.0, v72
	v_rcp_f32_e32 v79, v76
	v_rcp_f32_e32 v75, v72
	v_mad_i64_i32 v[72:73], s[0:1], v80, s33, v[122:123]
	v_lshl_add_u64 v[76:77], v[72:73], 0, v[124:125]
	v_cvt_pk_bf16_f32 v72, v81, v82
	v_cvt_pk_bf16_f32 v73, v78, v79
	v_cvt_pk_bf16_f32 v75, v85, v75
	global_store_dwordx4 v[76:77], v[72:75], off
	v_fmamk_f32 v71, v71, 0xbfb8aa3b, v145
	v_exp_f32_e32 v68, v68
	v_rcp_f32_e32 v72, v64
	v_fmamk_f32 v64, v65, 0xbfb8aa3b, v143
	v_exp_f32_e32 v64, v64
	v_exp_f32_e32 v69, v69
	v_exp_f32_e32 v70, v70
	v_exp_f32_e32 v71, v71
	v_add_f32_e32 v64, 1.0, v64
	v_rcp_f32_e32 v73, v64
	v_fmamk_f32 v64, v66, 0xbfb8aa3b, v140
	v_exp_f32_e32 v64, v64
	v_add_f32_e32 v68, 1.0, v68
	v_add_f32_e32 v69, 1.0, v69
	v_add_f32_e32 v70, 1.0, v70
	v_add_f32_e32 v64, 1.0, v64
	v_rcp_f32_e32 v74, v64
	v_fmamk_f32 v64, v67, 0xbfb8aa3b, v141
	v_exp_f32_e32 v64, v64
	v_add_f32_e32 v71, 1.0, v71
	v_rcp_f32_e32 v68, v68
	v_rcp_f32_e32 v69, v69
	v_add_f32_e32 v64, 1.0, v64
	v_rcp_f32_e32 v70, v70
	v_rcp_f32_e32 v71, v71
	v_rcp_f32_e32 v67, v64
	v_cvt_pk_bf16_f32 v64, v68, v69
	v_cvt_pk_bf16_f32 v66, v72, v73
	v_cvt_pk_bf16_f32 v65, v70, v71
	v_cvt_pk_bf16_f32 v67, v74, v67
	global_store_dwordx4 v[76:77], v[64:67], off offset:256
	v_fmamk_f32 v48, v48, 0xbfb8aa3b, v142
	v_exp_f32_e32 v48, v48
	v_rcp_f32_e32 v65, v60
	v_fmamk_f32 v60, v61, 0xbfb8aa3b, v155
	v_rcp_f32_e32 v67, v56
	v_fmamk_f32 v56, v57, 0xbfb8aa3b, v151
	v_exp_f32_e32 v60, v60
	v_exp_f32_e32 v56, v56
	v_add_u32_e32 v64, 0x80, v160
	v_add_f32_e32 v60, 1.0, v60
	v_add_f32_e32 v56, 1.0, v56
	v_rcp_f32_e32 v66, v60
	v_fmamk_f32 v60, v62, 0xbfb8aa3b, v152
	v_rcp_f32_e32 v68, v56
	v_fmamk_f32 v56, v58, 0xbfb8aa3b, v148
	v_exp_f32_e32 v60, v60
	v_exp_f32_e32 v56, v56
	v_cvt_pk_bf16_f32 v58, v67, v68
	v_add_f32_e32 v48, 1.0, v48
	v_add_f32_e32 v60, 1.0, v60
	v_add_f32_e32 v56, 1.0, v56
	v_rcp_f32_e32 v62, v60
	v_fmamk_f32 v60, v63, 0xbfb8aa3b, v153
	v_rcp_f32_e32 v69, v56
	v_fmamk_f32 v56, v59, 0xbfb8aa3b, v149
	v_exp_f32_e32 v60, v60
	v_exp_f32_e32 v56, v56
	v_fmamk_f32 v52, v52, 0xbfb8aa3b, v146
	v_add_f32_e32 v60, 1.0, v60
	v_add_f32_e32 v56, 1.0, v56
	v_rcp_f32_e32 v63, v60
	v_rcp_f32_e32 v59, v56
	v_mad_i64_i32 v[56:57], s[0:1], v64, s33, v[122:123]
	v_lshl_add_u64 v[60:61], v[56:57], 0, v[124:125]
	v_cvt_pk_bf16_f32 v56, v65, v66
	v_cvt_pk_bf16_f32 v57, v62, v63
	v_cvt_pk_bf16_f32 v59, v69, v59
	global_store_dwordx4 v[60:61], v[56:59], off
	v_fmamk_f32 v53, v53, 0xbfb8aa3b, v147
	v_fmamk_f32 v54, v54, 0xbfb8aa3b, v144
	v_rcp_f32_e32 v56, v48
	v_fmamk_f32 v48, v49, 0xbfb8aa3b, v143
	v_exp_f32_e32 v48, v48
	v_fmamk_f32 v55, v55, 0xbfb8aa3b, v145
	v_exp_f32_e32 v52, v52
	v_exp_f32_e32 v53, v53
	v_add_f32_e32 v48, 1.0, v48
	v_rcp_f32_e32 v57, v48
	v_fmamk_f32 v48, v50, 0xbfb8aa3b, v140
	v_exp_f32_e32 v48, v48
	v_exp_f32_e32 v54, v54
	v_exp_f32_e32 v55, v55
	v_add_f32_e32 v52, 1.0, v52
	v_add_f32_e32 v48, 1.0, v48
	v_rcp_f32_e32 v58, v48
	v_fmamk_f32 v48, v51, 0xbfb8aa3b, v141
	v_exp_f32_e32 v48, v48
	v_add_f32_e32 v53, 1.0, v53
	v_add_f32_e32 v54, 1.0, v54
	v_add_f32_e32 v55, 1.0, v55
	v_add_f32_e32 v48, 1.0, v48
	v_rcp_f32_e32 v52, v52
	v_rcp_f32_e32 v53, v53
	v_rcp_f32_e32 v54, v54
	v_rcp_f32_e32 v55, v55
	v_rcp_f32_e32 v51, v48
	v_cvt_pk_bf16_f32 v48, v52, v53
	v_cvt_pk_bf16_f32 v50, v56, v57
	v_cvt_pk_bf16_f32 v49, v54, v55
	v_cvt_pk_bf16_f32 v51, v58, v51
	global_store_dwordx4 v[60:61], v[48:51], off offset:256
	v_fmamk_f32 v32, v32, 0xbfb8aa3b, v142
	v_exp_f32_e32 v32, v32
	v_rcp_f32_e32 v49, v44
	v_fmamk_f32 v44, v45, 0xbfb8aa3b, v155
	v_rcp_f32_e32 v51, v40
	v_fmamk_f32 v40, v41, 0xbfb8aa3b, v151
	v_exp_f32_e32 v44, v44
	v_exp_f32_e32 v40, v40
	v_add_u32_e32 v48, 0x90, v160
; __device__ __forceinline__ float fexp2(float x) { return __builtin_amdgcn_exp2f(x); }
; __device__ __forceinline__ float frcp(float x) { return __builtin_amdgcn_rcpf(x); }
; #define PG8_WAIT_V(n) asm volatile("s_waitcnt vmcnt(" #n ")" ::: "memory")
; #define PG8_BAR __builtin_amdgcn_s_barrier()
; template <class Epi>
; __device__ __forceinline__ void gemm_phase(LAS unsigned char* lds, const Gemm g, const StaticOrder& S, const Epi& E, int wv0) {
;     ...
;     if (!has_next) break;
; #pragma unroll
;     for (int a = 0; a < 2; ++a)
; #pragma unroll
;       for (int b = 0; b < 2; ++b)
; #pragma unroll
;         for (int m = 0; m < 4; ++m)
; #pragma unroll
;           for (int n = 0; n < 2; ++n) acc[a][b][m][n] = (f32x4){0.f, 0.f, 0.f, 0.f};
;     cur = nxt; cA = nA; cB = nB; ++ui;
;   }
;   PG8_WAIT_V(0);
;   if (wr == 0) PG8_BAR;
;   PG8_BAR;
;   __device__ __forceinline__ void emit(const EpiPre& q0, int row, int col, f32x4 a, f32x4 b, const f32x4 (&hb)[2][2], const float (&hs)[2][4], int ai_, int m_, int bj_) const {
;     ...
;     } else if (MODE == E_GATE) {
;       const float bb[8] = {q.a0[0], q.a0[1], q.a0[2], q.a0[3], q.a1[0], q.a1[1], q.a1[2], q.a1[3]};
; #pragma unroll
;       for (int j = 0; j < 8; ++j) v[j] = frcp(1.0f + fexp2(__builtin_fmaf(v[j], -LOG2E, bb[j])));
;       store8bf((bf16_t*)e.out + (size_t)row * NG + col, v);
	v_add_f32_e32 v32, 1.0, v32
	v_add_f32_e32 v44, 1.0, v44
	v_add_f32_e32 v40, 1.0, v40
	v_rcp_f32_e32 v50, v44
	v_fmamk_f32 v44, v46, 0xbfb8aa3b, v152
	v_rcp_f32_e32 v52, v40
	v_fmamk_f32 v40, v42, 0xbfb8aa3b, v148
	v_exp_f32_e32 v44, v44
	v_exp_f32_e32 v40, v40
	v_cvt_pk_bf16_f32 v42, v51, v52
	v_fmamk_f32 v36, v36, 0xbfb8aa3b, v146
	v_add_f32_e32 v44, 1.0, v44
	v_add_f32_e32 v40, 1.0, v40
	v_rcp_f32_e32 v46, v44
	v_fmamk_f32 v44, v47, 0xbfb8aa3b, v153
	v_rcp_f32_e32 v53, v40
	v_fmamk_f32 v40, v43, 0xbfb8aa3b, v149
	v_exp_f32_e32 v44, v44
	v_exp_f32_e32 v40, v40
	v_fmamk_f32 v37, v37, 0xbfb8aa3b, v147
	v_fmamk_f32 v38, v38, 0xbfb8aa3b, v144
	v_add_f32_e32 v44, 1.0, v44
	v_add_f32_e32 v40, 1.0, v40
	v_rcp_f32_e32 v47, v44
	v_rcp_f32_e32 v43, v40
	v_mad_i64_i32 v[40:41], s[0:1], v48, s33, v[122:123]
	v_lshl_add_u64 v[44:45], v[40:41], 0, v[124:125]
	v_cvt_pk_bf16_f32 v40, v49, v50
	v_cvt_pk_bf16_f32 v41, v46, v47
	v_cvt_pk_bf16_f32 v43, v53, v43
	global_store_dwordx4 v[44:45], v[40:43], off
	v_fmamk_f32 v39, v39, 0xbfb8aa3b, v145
	v_exp_f32_e32 v36, v36
	v_rcp_f32_e32 v40, v32
	v_fmamk_f32 v32, v33, 0xbfb8aa3b, v143
	v_exp_f32_e32 v32, v32
	v_exp_f32_e32 v37, v37
	v_exp_f32_e32 v38, v38
	v_exp_f32_e32 v39, v39
	v_add_f32_e32 v32, 1.0, v32
	v_rcp_f32_e32 v41, v32
	v_fmamk_f32 v32, v34, 0xbfb8aa3b, v140
	v_exp_f32_e32 v32, v32
	v_add_f32_e32 v36, 1.0, v36
	v_add_f32_e32 v37, 1.0, v37
	v_add_f32_e32 v38, 1.0, v38
	v_add_f32_e32 v32, 1.0, v32
	v_rcp_f32_e32 v42, v32
	v_fmamk_f32 v32, v35, 0xbfb8aa3b, v141
	v_exp_f32_e32 v32, v32
	v_add_f32_e32 v39, 1.0, v39
	v_rcp_f32_e32 v36, v36
	v_rcp_f32_e32 v37, v37
	v_add_f32_e32 v32, 1.0, v32
	v_rcp_f32_e32 v38, v38
	v_rcp_f32_e32 v39, v39
	v_rcp_f32_e32 v35, v32
	v_cvt_pk_bf16_f32 v32, v36, v37
	v_cvt_pk_bf16_f32 v34, v40, v41
	v_cvt_pk_bf16_f32 v33, v38, v39
	v_cvt_pk_bf16_f32 v35, v42, v35
	global_store_dwordx4 v[44:45], v[32:35], off offset:256
	v_fmamk_f32 v16, v16, 0xbfb8aa3b, v142
	v_exp_f32_e32 v16, v16
	v_rcp_f32_e32 v33, v28
	v_fmamk_f32 v28, v29, 0xbfb8aa3b, v155
	v_rcp_f32_e32 v35, v24
	v_fmamk_f32 v24, v25, 0xbfb8aa3b, v151
	v_exp_f32_e32 v28, v28
	v_exp_f32_e32 v24, v24
	v_add_u32_e32 v32, 0xa0, v160
	v_add_f32_e32 v28, 1.0, v28
	v_add_f32_e32 v24, 1.0, v24
	v_rcp_f32_e32 v34, v28
	v_fmamk_f32 v28, v30, 0xbfb8aa3b, v152
	v_rcp_f32_e32 v36, v24
	v_fmamk_f32 v24, v26, 0xbfb8aa3b, v148
	v_exp_f32_e32 v28, v28
	v_exp_f32_e32 v24, v24
	v_cvt_pk_bf16_f32 v26, v35, v36
	v_add_f32_e32 v16, 1.0, v16
	v_add_f32_e32 v28, 1.0, v28
	v_add_f32_e32 v24, 1.0, v24
	v_rcp_f32_e32 v30, v28
	v_fmamk_f32 v28, v31, 0xbfb8aa3b, v153
	v_rcp_f32_e32 v37, v24
	v_fmamk_f32 v24, v27, 0xbfb8aa3b, v149
	v_exp_f32_e32 v28, v28
	v_exp_f32_e32 v24, v24
	v_fmamk_f32 v20, v20, 0xbfb8aa3b, v146
	v_add_f32_e32 v28, 1.0, v28
	v_add_f32_e32 v24, 1.0, v24
	v_rcp_f32_e32 v31, v28
	v_rcp_f32_e32 v27, v24
	v_mad_i64_i32 v[24:25], s[0:1], v32, s33, v[122:123]
	v_lshl_add_u64 v[28:29], v[24:25], 0, v[124:125]
	v_cvt_pk_bf16_f32 v24, v33, v34
	v_cvt_pk_bf16_f32 v25, v30, v31
	v_cvt_pk_bf16_f32 v27, v37, v27
	global_store_dwordx4 v[28:29], v[24:27], off
	v_fmamk_f32 v21, v21, 0xbfb8aa3b, v147
	v_fmamk_f32 v22, v22, 0xbfb8aa3b, v144
	v_rcp_f32_e32 v24, v16
	v_fmamk_f32 v16, v17, 0xbfb8aa3b, v143
	v_exp_f32_e32 v16, v16
	v_fmamk_f32 v23, v23, 0xbfb8aa3b, v145
	v_exp_f32_e32 v20, v20
	v_exp_f32_e32 v21, v21
	v_add_f32_e32 v16, 1.0, v16
	v_rcp_f32_e32 v25, v16
	v_fmamk_f32 v16, v18, 0xbfb8aa3b, v140
	v_exp_f32_e32 v16, v16
	v_exp_f32_e32 v22, v22
	v_exp_f32_e32 v23, v23
	v_add_f32_e32 v20, 1.0, v20
	v_add_f32_e32 v16, 1.0, v16
	v_rcp_f32_e32 v26, v16
	v_fmamk_f32 v16, v19, 0xbfb8aa3b, v141
	v_exp_f32_e32 v16, v16
	v_add_f32_e32 v21, 1.0, v21
	v_add_f32_e32 v22, 1.0, v22
	v_add_f32_e32 v23, 1.0, v23
	v_add_f32_e32 v16, 1.0, v16
	v_rcp_f32_e32 v20, v20
	v_rcp_f32_e32 v21, v21
	v_rcp_f32_e32 v22, v22
	v_rcp_f32_e32 v23, v23
	v_rcp_f32_e32 v19, v16
	v_cvt_pk_bf16_f32 v16, v20, v21
	v_cvt_pk_bf16_f32 v18, v24, v25
	v_cvt_pk_bf16_f32 v17, v22, v23
	v_cvt_pk_bf16_f32 v19, v26, v19
	v_fmac_f32_e32 v155, 0xbfb8aa3b, v13
	v_fmac_f32_e32 v151, 0xbfb8aa3b, v9
	global_store_dwordx4 v[28:29], v[16:19], off offset:256
	v_fmac_f32_e32 v153, 0xbfb8aa3b, v15
	v_fmac_f32_e32 v149, 0xbfb8aa3b, v11
	v_rcp_f32_e32 v17, v12
	v_exp_f32_e32 v12, v155
	v_rcp_f32_e32 v19, v8
	v_exp_f32_e32 v8, v151
	v_fmamk_f32 v0, v0, 0xbfb8aa3b, v142
	v_add_f32_e32 v12, 1.0, v12
	v_rcp_f32_e32 v18, v12
	v_add_f32_e32 v8, 1.0, v8
	v_fmamk_f32 v12, v14, 0xbfb8aa3b, v152
	v_rcp_f32_e32 v20, v8
	v_fmamk_f32 v8, v10, 0xbfb8aa3b, v148
	v_exp_f32_e32 v12, v12
	v_exp_f32_e32 v8, v8
	v_exp_f32_e32 v0, v0
	v_add_u32_e32 v16, 0xb0, v160
	v_add_f32_e32 v12, 1.0, v12
	v_add_f32_e32 v8, 1.0, v8
	v_rcp_f32_e32 v14, v12
	v_exp_f32_e32 v12, v153
	v_rcp_f32_e32 v21, v8
	v_exp_f32_e32 v8, v149
	v_cvt_pk_bf16_f32 v10, v19, v20
	v_add_f32_e32 v12, 1.0, v12
	v_rcp_f32_e32 v15, v12
	v_add_f32_e32 v8, 1.0, v8
	v_rcp_f32_e32 v11, v8
	v_mad_i64_i32 v[8:9], s[0:1], v16, s33, v[122:123]
	v_lshl_add_u64 v[12:13], v[8:9], 0, v[124:125]
	v_cvt_pk_bf16_f32 v8, v17, v18
	v_cvt_pk_bf16_f32 v9, v14, v15
	v_cvt_pk_bf16_f32 v11, v21, v11
	v_add_f32_e32 v0, 1.0, v0
	v_fmac_f32_e32 v143, 0xbfb8aa3b, v1
	global_store_dwordx4 v[12:13], v[8:11], off
	v_fmamk_f32 v4, v4, 0xbfb8aa3b, v146
	v_fmac_f32_e32 v147, 0xbfb8aa3b, v5
	v_rcp_f32_e32 v8, v0
	v_exp_f32_e32 v0, v143
	v_fmamk_f32 v6, v6, 0xbfb8aa3b, v144
	v_fmac_f32_e32 v145, 0xbfb8aa3b, v7
	v_fmac_f32_e32 v141, 0xbfb8aa3b, v3
	v_add_f32_e32 v0, 1.0, v0
	v_rcp_f32_e32 v9, v0
	v_fmamk_f32 v0, v2, 0xbfb8aa3b, v140
	v_exp_f32_e32 v0, v0
	v_exp_f32_e32 v4, v4
	v_exp_f32_e32 v5, v147
	v_exp_f32_e32 v6, v6
	v_add_f32_e32 v0, 1.0, v0
	v_exp_f32_e32 v7, v145
	v_rcp_f32_e32 v10, v0
	v_exp_f32_e32 v0, v141
	v_add_f32_e32 v4, 1.0, v4
	v_add_f32_e32 v5, 1.0, v5
	v_add_f32_e32 v6, 1.0, v6
	v_add_f32_e32 v7, 1.0, v7
	v_add_f32_e32 v0, 1.0, v0
	v_rcp_f32_e32 v4, v4
	v_rcp_f32_e32 v5, v5
	v_rcp_f32_e32 v6, v6
	v_rcp_f32_e32 v7, v7
	v_rcp_f32_e32 v3, v0
	v_cvt_pk_bf16_f32 v0, v4, v5
	v_cvt_pk_bf16_f32 v2, v8, v9
	v_cvt_pk_bf16_f32 v1, v6, v7
	v_cvt_pk_bf16_f32 v3, v10, v3
	global_store_dwordx4 v[12:13], v[0:3], off offset:256
	s_mov_b32 s1, s10
	s_mov_b32 s18, s12
	s_cbranch_vccz .LBB0_903
	s_waitcnt vmcnt(0)
	s_cmpk_gt_u32 s29, 0xff
	s_cbranch_scc1 .LBB0_910
	s_barrier

; #define PG8_STAGE(bufoff, gbase, voff) do { _Pragma("unroll") for (int _i = 0; _i < 2; ++_i) \
;     __builtin_amdgcn_global_load_lds((const unsigned*)((const char*)(gbase) + (voff)[_i]), (LAS unsigned*)(lds + (bufoff) + ldsw + _i * 8192), 16, 0, 0); } while (0)
; #define PG8_LDA(dst, b, h) do { _Pragma("unroll") for (int m = 0; m < 4; ++m) _Pragma("unroll") for (int k = 0; k < 2; ++k) dst[m][k] = *(const LAS bf16x8*)(lds + PG8_SA(b, h) + aoff + m * 2048 + k * 1024); } while (0)
; #define PG8_LDB(dst, b, h) do { _Pragma("unroll") for (int n = 0; n < 2; ++n) _Pragma("unroll") for (int k = 0; k < 2; ++k) dst[n][k] = *(const LAS bf16x8*)(lds + PG8_SB(b, h) + boff + n * 2048 + k * 1024); } while (0)
; #define PG8_MMA(ai, bj, At, Bt) do { __builtin_amdgcn_s_setprio(1); _Pragma("unroll") for (int m = 0; m < 4; ++m) _Pragma("unroll") for (int n = 0; n < 2; ++n) _Pragma("unroll") for (int k = 0; k < 2; ++k) \
;     acc[ai][bj][m][n] = __builtin_amdgcn_mfma_f32_16x16x32_bf16(Bt[n][k], At[m][k], acc[ai][bj][m][n], 0, 0, 0); __builtin_amdgcn_s_setprio(0); } while (0)
; #define PG8_WAIT_L(n) asm volatile("s_waitcnt lgkmcnt(" #n ")" ::: "memory")
; #define PG8_BAR __builtin_amdgcn_s_barrier()
; #define PG8_SCHED __builtin_amdgcn_sched_barrier(0)
; template <class Epi>
; __device__ __forceinline__ void gemm_phase(LAS unsigned char* lds, const Gemm g, const StaticOrder& S, const Epi& E, int wv0) {
;     ...
;     for (int t = 0; t < nt; t += 2) {
;       const bool last = (t == nt - 2);
;       const char* a1 = cA + (size_t)(t + 1) * kstep;
;       const char* a2 = last ? nA : cA + (size_t)(t + 2) * kstep; const char* b2 = last ? nB : cB + (size_t)(t + 2) * kstep;
;       const char* a3 = a2 + kstep; const char* b3 = b2 + kstep;
;       PG8_LDB(B0, 0, 0); PG8_SCHED; PG8_LDA(At, 0, 0); PG8_STAGE(PG8_SA(1, 1), a1 + hstepA, voffA);
;       PG8_WAIT_L(8); PG8_BAR; PG8_WAIT_L(0); PG8_MMA(0, 0, At, B0); PG8_BAR; PG8_SCHED;
;       PG8_LDB(B1, 0, 1); PG8_STAGE(PG8_SB(0, 0), b2, voffB);
;       PG8_BAR; PG8_WAIT_L(0); PG8_MMA(0, 1, At, B1); PG8_BAR;
;       PG8_LDA(At, 0, 1); PG8_STAGE(PG8_SA(0, 0), a2, voffA);
;       PG8_BAR; PG8_WAIT_L(0); PG8_MMA(1, 0, At, B0); PG8_BAR; PG8_SCHED;
.LBB0_981:
	s_add_u32 s4, s18, 0x100
	s_addc_u32 s5, s19, 0
	s_add_i32 s0, 0, 0x10000
	v_add_u32_e32 v142, s0, v173
	ds_read_b128 v[130:133], v142
	ds_read_b128 v[134:137], v142 offset:1024
	ds_read_b128 v[138:141], v142 offset:2048
	ds_read_b128 v[142:145], v142 offset:3072
	s_cmp_eq_u32 s49, 12
	s_cselect_b32 s23, s15, s5
	s_cselect_b32 s22, s14, s4
	s_cselect_b32 s21, s13, s48
	s_cselect_b32 s20, s46, s47
	v_lshl_add_u64 v[192:193], s[18:19], 0, v[156:157]
	s_add_i32 m0, s36, 0xc000
	ds_read_b128 v[146:149], v175
	ds_read_b128 v[160:163], v175 offset:1024
	ds_read_b128 v[164:167], v175 offset:2048
	ds_read_b128 v[168:171], v175 offset:3072
	ds_read_b128 v[176:179], v175 offset:4096
	ds_read_b128 v[180:183], v175 offset:5120
	ds_read_b128 v[184:187], v175 offset:6144
	ds_read_b128 v[188:191], v175 offset:7168
	global_load_lds_dwordx4 v[192:193], off
	v_lshl_add_u64 v[192:193], s[18:19], 0, v[158:159]
	s_add_i32 m0, s36, 0xe000
	s_nop 0
	global_load_lds_dwordx4 v[192:193], off
	s_waitcnt lgkmcnt(8)
	s_barrier
	s_waitcnt lgkmcnt(0)
	s_waitcnt lgkmcnt(0)
	v_mfma_f32_16x16x32_bf16 v[126:129], v[130:133], v[146:149], v[126:129]
	v_mfma_f32_16x16x32_bf16 v[122:125], v[138:141], v[146:149], v[122:125]
	v_mfma_f32_16x16x32_bf16 v[118:121], v[130:133], v[164:167], v[118:121]
	v_mfma_f32_16x16x32_bf16 v[110:113], v[138:141], v[164:167], v[110:113]
	v_mfma_f32_16x16x32_bf16 v[92:95], v[130:133], v[176:179], v[92:95]
	v_mfma_f32_16x16x32_bf16 v[88:91], v[138:141], v[176:179], v[88:91]
	v_mfma_f32_16x16x32_bf16 v[80:83], v[130:133], v[184:187], v[80:83]
	v_mfma_f32_16x16x32_bf16 v[72:75], v[138:141], v[184:187], v[72:75]
	v_mfma_f32_16x16x32_bf16 v[126:129], v[134:137], v[160:163], v[126:129]
	v_mfma_f32_16x16x32_bf16 v[122:125], v[142:145], v[160:163], v[122:125]
	v_mfma_f32_16x16x32_bf16 v[118:121], v[134:137], v[168:171], v[118:121]
	v_mfma_f32_16x16x32_bf16 v[110:113], v[142:145], v[168:171], v[110:113]
	v_mfma_f32_16x16x32_bf16 v[92:95], v[134:137], v[180:183], v[92:95]
	v_mfma_f32_16x16x32_bf16 v[88:91], v[142:145], v[180:183], v[88:91]
	v_mfma_f32_16x16x32_bf16 v[80:83], v[134:137], v[188:191], v[80:83]
	v_mfma_f32_16x16x32_bf16 v[72:75], v[142:145], v[188:191], v[72:75]
	s_barrier
	s_add_i32 s50, 0, 0x14000
	s_add_i32 s0, s0, s35
	v_add_u32_e32 v204, s50, v173
	v_lshl_add_u64 v[208:209], s[20:21], 0, v[96:97]
	s_mov_b32 m0, s0
	ds_read_b128 v[192:195], v204
	ds_read_b128 v[196:199], v204 offset:1024
	ds_read_b128 v[200:203], v204 offset:2048
	ds_read_b128 v[204:207], v204 offset:3072
	global_load_lds_dwordx4 v[208:209], off
	v_lshl_add_u64 v[210:211], s[20:21], 0, v[154:155]
	s_add_i32 m0, s0, 0x2000
	s_nop 0
	global_load_lds_dwordx4 v[210:211], off
	s_barrier
	s_waitcnt lgkmcnt(0)
	s_waitcnt lgkmcnt(0)
	v_mfma_f32_16x16x32_bf16 v[114:117], v[192:195], v[146:149], v[114:117]
	v_mfma_f32_16x16x32_bf16 v[106:109], v[200:203], v[146:149], v[106:109]
	v_mfma_f32_16x16x32_bf16 v[102:105], v[192:195], v[164:167], v[102:105]
	v_mfma_f32_16x16x32_bf16 v[98:101], v[200:203], v[164:167], v[98:101]
	v_mfma_f32_16x16x32_bf16 v[84:87], v[192:195], v[176:179], v[84:87]
	v_mfma_f32_16x16x32_bf16 v[76:79], v[200:203], v[176:179], v[76:79]
	v_mfma_f32_16x16x32_bf16 v[68:71], v[192:195], v[184:187], v[68:71]
	v_mfma_f32_16x16x32_bf16 v[64:67], v[200:203], v[184:187], v[64:67]
	v_mfma_f32_16x16x32_bf16 v[114:117], v[196:199], v[160:163], v[114:117]
	v_mfma_f32_16x16x32_bf16 v[106:109], v[204:207], v[160:163], v[106:109]
	v_mfma_f32_16x16x32_bf16 v[102:105], v[196:199], v[168:171], v[102:105]
	v_mfma_f32_16x16x32_bf16 v[98:101], v[204:207], v[168:171], v[98:101]
	v_mfma_f32_16x16x32_bf16 v[84:87], v[196:199], v[180:183], v[84:87]
	v_mfma_f32_16x16x32_bf16 v[76:79], v[204:207], v[180:183], v[76:79]
	v_mfma_f32_16x16x32_bf16 v[68:71], v[196:199], v[188:191], v[68:71]
	v_mfma_f32_16x16x32_bf16 v[64:67], v[204:207], v[188:191], v[64:67]
	s_mov_b32 m0, s36
	v_lshl_add_u64 v[212:213], s[22:23], 0, v[150:151]
	s_barrier
	ds_read_b128 v[146:149], v175 offset:16384
	ds_read_b128 v[160:163], v175 offset:17408
	ds_read_b128 v[164:167], v175 offset:18432
	ds_read_b128 v[168:171], v175 offset:19456
	ds_read_b128 v[176:179], v175 offset:20480
	ds_read_b128 v[180:183], v175 offset:21504
	ds_read_b128 v[184:187], v175 offset:22528
	ds_read_b128 v[188:191], v175 offset:23552
	global_load_lds_dwordx4 v[212:213], off
	v_lshl_add_u64 v[214:215], s[22:23], 0, v[152:153]
	s_mov_b32 m0, s37
	s_nop 0
	global_load_lds_dwordx4 v[214:215], off
	s_barrier
	s_waitcnt lgkmcnt(0)
	s_waitcnt lgkmcnt(0)
	v_mfma_f32_16x16x32_bf16 v[60:63], v[130:133], v[146:149], v[60:63]
	v_mfma_f32_16x16x32_bf16 v[56:59], v[138:141], v[146:149], v[56:59]
	v_mfma_f32_16x16x32_bf16 v[48:51], v[130:133], v[164:167], v[48:51]
	v_mfma_f32_16x16x32_bf16 v[40:43], v[138:141], v[164:167], v[40:43]
	v_mfma_f32_16x16x32_bf16 v[32:35], v[130:133], v[176:179], v[32:35]
	v_mfma_f32_16x16x32_bf16 v[24:27], v[138:141], v[176:179], v[24:27]
	v_mfma_f32_16x16x32_bf16 v[16:19], v[130:133], v[184:187], v[16:19]
	v_mfma_f32_16x16x32_bf16 v[8:11], v[138:141], v[184:187], v[8:11]
	v_mfma_f32_16x16x32_bf16 v[60:63], v[134:137], v[160:163], v[60:63]
	v_mfma_f32_16x16x32_bf16 v[56:59], v[142:145], v[160:163], v[56:59]
	v_mfma_f32_16x16x32_bf16 v[48:51], v[134:137], v[168:171], v[48:51]
	v_mfma_f32_16x16x32_bf16 v[40:43], v[142:145], v[168:171], v[40:43]
	v_mfma_f32_16x16x32_bf16 v[32:35], v[134:137], v[180:183], v[32:35]
	v_mfma_f32_16x16x32_bf16 v[24:27], v[142:145], v[180:183], v[24:27]
	v_mfma_f32_16x16x32_bf16 v[16:19], v[134:137], v[188:191], v[16:19]
	v_mfma_f32_16x16x32_bf16 v[8:11], v[142:145], v[188:191], v[8:11]
	s_barrier
; #define PG8_STAGE(bufoff, gbase, voff) do { _Pragma("unroll") for (int _i = 0; _i < 2; ++_i) \
;     __builtin_amdgcn_global_load_lds((const unsigned*)((const char*)(gbase) + (voff)[_i]), (LAS unsigned*)(lds + (bufoff) + ldsw + _i * 8192), 16, 0, 0); } while (0)
; #define PG8_LDA(dst, b, h) do { _Pragma("unroll") for (int m = 0; m < 4; ++m) _Pragma("unroll") for (int k = 0; k < 2; ++k) dst[m][k] = *(const LAS bf16x8*)(lds + PG8_SA(b, h) + aoff + m * 2048 + k * 1024); } while (0)
; #define PG8_LDB(dst, b, h) do { _Pragma("unroll") for (int n = 0; n < 2; ++n) _Pragma("unroll") for (int k = 0; k < 2; ++k) dst[n][k] = *(const LAS bf16x8*)(lds + PG8_SB(b, h) + boff + n * 2048 + k * 1024); } while (0)
; #define PG8_MMA(ai, bj, At, Bt) do { __builtin_amdgcn_s_setprio(1); _Pragma("unroll") for (int m = 0; m < 4; ++m) _Pragma("unroll") for (int n = 0; n < 2; ++n) _Pragma("unroll") for (int k = 0; k < 2; ++k) \
;     acc[ai][bj][m][n] = __builtin_amdgcn_mfma_f32_16x16x32_bf16(Bt[n][k], At[m][k], acc[ai][bj][m][n], 0, 0, 0); __builtin_amdgcn_s_setprio(0); } while (0)
; #define PG8_WAIT_V(n) asm volatile("s_waitcnt vmcnt(" #n ")" ::: "memory")
; #define PG8_WAIT_L(n) asm volatile("s_waitcnt lgkmcnt(" #n ")" ::: "memory")
; #define PG8_BAR __builtin_amdgcn_s_barrier()
; #define PG8_SCHED __builtin_amdgcn_sched_barrier(0)
; template <class Epi>
; __device__ __forceinline__ void gemm_phase(LAS unsigned char* lds, const Gemm g, const StaticOrder& S, const Epi& E, int wv0) {
;     ...
;       PG8_STAGE(PG8_SB(0, 1), b2 + hstepB, voffB);
;       PG8_WAIT_V(6); PG8_BAR; PG8_MMA(1, 1, At, B1); PG8_BAR;
;       PG8_LDB(B0, 1, 0); PG8_SCHED; PG8_LDA(At, 1, 0); PG8_STAGE(PG8_SA(0, 1), a2 + hstepA, voffA);
;       PG8_WAIT_L(8); PG8_BAR; PG8_WAIT_L(0); PG8_MMA(0, 0, At, B0); PG8_BAR; PG8_SCHED;
;       PG8_LDB(B1, 1, 1); PG8_STAGE(PG8_SB(1, 0), b3, voffB);
;       PG8_BAR; PG8_WAIT_L(0); PG8_MMA(0, 1, At, B1); PG8_BAR;
;       PG8_LDA(At, 1, 1); PG8_STAGE(PG8_SA(1, 0), a3, voffA);
;       PG8_BAR; PG8_WAIT_L(0); PG8_MMA(1, 0, At, B0); PG8_BAR; PG8_SCHED;
	s_add_u32 s18, s20, 0x40000
	s_addc_u32 s19, s21, 0
	s_add_i32 s0, s50, s35
	v_lshl_add_u64 v[130:131], s[18:19], 0, v[96:97]
	s_mov_b32 m0, s0
	s_nop 0
	global_load_lds_dwordx4 v[130:131], off
	v_lshl_add_u64 v[130:131], s[18:19], 0, v[154:155]
	s_add_i32 m0, s0, 0x2000
	s_nop 0
	global_load_lds_dwordx4 v[130:131], off
	s_waitcnt vmcnt(6)
	s_barrier
	v_mfma_f32_16x16x32_bf16 v[52:55], v[192:195], v[146:149], v[52:55]
	v_mfma_f32_16x16x32_bf16 v[44:47], v[200:203], v[146:149], v[44:47]
	v_mfma_f32_16x16x32_bf16 v[36:39], v[192:195], v[164:167], v[36:39]
	v_mfma_f32_16x16x32_bf16 v[28:31], v[200:203], v[164:167], v[28:31]
	v_mfma_f32_16x16x32_bf16 v[20:23], v[192:195], v[176:179], v[20:23]
	v_mfma_f32_16x16x32_bf16 v[12:15], v[200:203], v[176:179], v[12:15]
	v_mfma_f32_16x16x32_bf16 v[4:7], v[192:195], v[184:187], v[4:7]
	v_mfma_f32_16x16x32_bf16 v[0:3], v[200:203], v[184:187], v[0:3]
	v_mfma_f32_16x16x32_bf16 v[52:55], v[196:199], v[160:163], v[52:55]
	v_mfma_f32_16x16x32_bf16 v[44:47], v[204:207], v[160:163], v[44:47]
	v_mfma_f32_16x16x32_bf16 v[36:39], v[196:199], v[168:171], v[36:39]
	v_mfma_f32_16x16x32_bf16 v[28:31], v[204:207], v[168:171], v[28:31]
	v_mfma_f32_16x16x32_bf16 v[20:23], v[196:199], v[180:183], v[20:23]
	v_mfma_f32_16x16x32_bf16 v[12:15], v[204:207], v[180:183], v[12:15]
	v_mfma_f32_16x16x32_bf16 v[4:7], v[196:199], v[188:191], v[4:7]
	v_mfma_f32_16x16x32_bf16 v[0:3], v[204:207], v[188:191], v[0:3]
	s_add_i32 s0, 0, 0x18000
	v_add_u32_e32 v142, s0, v173
	s_barrier
	ds_read_b128 v[130:133], v142
	ds_read_b128 v[134:137], v142 offset:1024
	ds_read_b128 v[138:141], v142 offset:2048
	ds_read_b128 v[142:145], v142 offset:3072
	s_add_u32 s18, s22, 0x114000
	s_addc_u32 s19, s23, 0
	s_mov_b32 m0, s38
	v_lshl_add_u64 v[192:193], s[18:19], 0, v[150:151]
	ds_read_b128 v[146:149], v175 offset:32768
	ds_read_b128 v[160:163], v175 offset:33792
	ds_read_b128 v[164:167], v175 offset:34816
	ds_read_b128 v[168:171], v175 offset:35840
	ds_read_b128 v[176:179], v175 offset:36864
	ds_read_b128 v[180:183], v175 offset:37888
	ds_read_b128 v[184:187], v175 offset:38912
	ds_read_b128 v[188:191], v175 offset:39936
	global_load_lds_dwordx4 v[192:193], off
	v_lshl_add_u64 v[192:193], s[18:19], 0, v[152:153]
	s_mov_b32 m0, s39
	s_nop 0
	global_load_lds_dwordx4 v[192:193], off
	s_waitcnt lgkmcnt(8)
	s_barrier
	s_waitcnt lgkmcnt(0)
	s_waitcnt lgkmcnt(0)
	v_mfma_f32_16x16x32_bf16 v[126:129], v[130:133], v[146:149], v[126:129]
	v_mfma_f32_16x16x32_bf16 v[122:125], v[138:141], v[146:149], v[122:125]
	v_mfma_f32_16x16x32_bf16 v[118:121], v[130:133], v[164:167], v[118:121]
	v_mfma_f32_16x16x32_bf16 v[110:113], v[138:141], v[164:167], v[110:113]
	v_mfma_f32_16x16x32_bf16 v[92:95], v[130:133], v[176:179], v[92:95]
	v_mfma_f32_16x16x32_bf16 v[88:91], v[138:141], v[176:179], v[88:91]
	v_mfma_f32_16x16x32_bf16 v[80:83], v[130:133], v[184:187], v[80:83]
	v_mfma_f32_16x16x32_bf16 v[72:75], v[138:141], v[184:187], v[72:75]
	v_mfma_f32_16x16x32_bf16 v[126:129], v[134:137], v[160:163], v[126:129]
	v_mfma_f32_16x16x32_bf16 v[122:125], v[142:145], v[160:163], v[122:125]
	v_mfma_f32_16x16x32_bf16 v[118:121], v[134:137], v[168:171], v[118:121]
	v_mfma_f32_16x16x32_bf16 v[110:113], v[142:145], v[168:171], v[110:113]
	v_mfma_f32_16x16x32_bf16 v[92:95], v[134:137], v[180:183], v[92:95]
	v_mfma_f32_16x16x32_bf16 v[88:91], v[142:145], v[180:183], v[88:91]
	v_mfma_f32_16x16x32_bf16 v[80:83], v[134:137], v[188:191], v[80:83]
	v_mfma_f32_16x16x32_bf16 v[72:75], v[142:145], v[188:191], v[72:75]
	s_barrier
	s_add_i32 s22, 0, 0x1c000
	s_add_i32 s0, s0, s35
	v_add_u32_e32 v204, s22, v173
	v_lshl_add_u64 v[208:209], v[208:209], 0, s[72:73]
	s_mov_b32 m0, s0
	ds_read_b128 v[192:195], v204
	ds_read_b128 v[196:199], v204 offset:1024
	ds_read_b128 v[200:203], v204 offset:2048
	ds_read_b128 v[204:207], v204 offset:3072
	global_load_lds_dwordx4 v[208:209], off
	v_lshl_add_u64 v[208:209], v[210:211], 0, s[72:73]
	s_add_i32 m0, s0, 0x2000
	s_nop 0
	global_load_lds_dwordx4 v[208:209], off
	s_barrier
	s_waitcnt lgkmcnt(0)
	s_waitcnt lgkmcnt(0)
	v_mfma_f32_16x16x32_bf16 v[114:117], v[192:195], v[146:149], v[114:117]
	v_mfma_f32_16x16x32_bf16 v[106:109], v[200:203], v[146:149], v[106:109]
	v_mfma_f32_16x16x32_bf16 v[102:105], v[192:195], v[164:167], v[102:105]
	v_mfma_f32_16x16x32_bf16 v[98:101], v[200:203], v[164:167], v[98:101]
	v_mfma_f32_16x16x32_bf16 v[84:87], v[192:195], v[176:179], v[84:87]
	v_mfma_f32_16x16x32_bf16 v[76:79], v[200:203], v[176:179], v[76:79]
	v_mfma_f32_16x16x32_bf16 v[68:71], v[192:195], v[184:187], v[68:71]
	v_mfma_f32_16x16x32_bf16 v[64:67], v[200:203], v[184:187], v[64:67]
	v_mfma_f32_16x16x32_bf16 v[114:117], v[196:199], v[160:163], v[114:117]
	v_mfma_f32_16x16x32_bf16 v[106:109], v[204:207], v[160:163], v[106:109]
	v_mfma_f32_16x16x32_bf16 v[102:105], v[196:199], v[168:171], v[102:105]
	v_mfma_f32_16x16x32_bf16 v[98:101], v[204:207], v[168:171], v[98:101]
	v_mfma_f32_16x16x32_bf16 v[84:87], v[196:199], v[180:183], v[84:87]
	v_mfma_f32_16x16x32_bf16 v[76:79], v[204:207], v[180:183], v[76:79]
	v_mfma_f32_16x16x32_bf16 v[68:71], v[196:199], v[188:191], v[68:71]
	v_mfma_f32_16x16x32_bf16 v[64:67], v[204:207], v[188:191], v[64:67]
	s_mov_b32 m0, s40
	v_lshl_add_u64 v[208:209], v[212:213], 0, s[72:73]
	s_barrier
	ds_read_b128 v[146:149], v175 offset:49152
	ds_read_b128 v[160:163], v175 offset:50176
	ds_read_b128 v[164:167], v175 offset:51200
	ds_read_b128 v[168:171], v175 offset:52224
	ds_read_b128 v[176:179], v175 offset:53248
	ds_read_b128 v[180:183], v175 offset:54272
	ds_read_b128 v[184:187], v175 offset:55296
	ds_read_b128 v[188:191], v175 offset:56320
	global_load_lds_dwordx4 v[208:209], off
	v_lshl_add_u64 v[208:209], v[214:215], 0, s[72:73]
	s_mov_b32 m0, s41
	s_nop 0
	global_load_lds_dwordx4 v[208:209], off
	s_barrier
; __device__ __forceinline__ float bf_lo(unsigned u) { return __uint_as_float(u << 16); }
; __device__ __forceinline__ float bf_hi(unsigned u) { return __uint_as_float(u & 0xffff0000u); }
; #define PG8_STAGE(bufoff, gbase, voff) do { _Pragma("unroll") for (int _i = 0; _i < 2; ++_i) \
;     __builtin_amdgcn_global_load_lds((const unsigned*)((const char*)(gbase) + (voff)[_i]), (LAS unsigned*)(lds + (bufoff) + ldsw + _i * 8192), 16, 0, 0); } while (0)
; #define PG8_MMA(ai, bj, At, Bt) do { __builtin_amdgcn_s_setprio(1); _Pragma("unroll") for (int m = 0; m < 4; ++m) _Pragma("unroll") for (int n = 0; n < 2; ++n) _Pragma("unroll") for (int k = 0; k < 2; ++k) \
;     acc[ai][bj][m][n] = __builtin_amdgcn_mfma_f32_16x16x32_bf16(Bt[n][k], At[m][k], acc[ai][bj][m][n], 0, 0, 0); __builtin_amdgcn_s_setprio(0); } while (0)
; #define PG8_WAIT_V(n) asm volatile("s_waitcnt vmcnt(" #n ")" ::: "memory")
; #define PG8_WAIT_L(n) asm volatile("s_waitcnt lgkmcnt(" #n ")" ::: "memory")
; #define PG8_BAR __builtin_amdgcn_s_barrier()
; #define PG8_SCHED __builtin_amdgcn_sched_barrier(0)
; template <class Epi>
; __device__ __forceinline__ void gemm_phase(LAS unsigned char* lds, const Gemm g, const StaticOrder& S, const Epi& E, int wv0) {
;     ...
;       PG8_BAR; PG8_WAIT_L(0); PG8_MMA(1, 0, At, B0); PG8_BAR; PG8_SCHED;
;       PG8_STAGE(PG8_SB(1, 1), b3 + hstepB, voffB);
;       PG8_WAIT_V(6); PG8_BAR; PG8_MMA(1, 1, At, B1); PG8_BAR;
;     }
;   __device__ __forceinline__ void emit(const EpiPre& q0, int row, int col, f32x4 a, f32x4 b, const f32x4 (&hb)[2][2], const float (&hs)[2][4], int ai_, int m_, int bj_) const {
;     ...
;     } else if (MODE == E_PROJ) {
;       const int br = e.aux; const u32x4 gw = q.u0;
;       v[0] *= bf_lo(gw.x); v[1] *= bf_hi(gw.x); v[2] *= bf_lo(gw.y); v[3] *= bf_hi(gw.y);
;       v[4] *= bf_lo(gw.z); v[5] *= bf_hi(gw.z); v[6] *= bf_lo(gw.w); v[7] *= bf_hi(gw.w);
;       bf16_t* fa = (bf16_t*)e.facc + (size_t)row * DM + col;
;       if (br > 0) { const u32x4 pw = q.u1;
;         v[0] += bf_lo(pw.x); v[1] += bf_hi(pw.x); v[2] += bf_lo(pw.y); v[3] += bf_hi(pw.y); v[4] += bf_lo(pw.z); v[5] += bf_hi(pw.z); v[6] += bf_lo(pw.w); v[7] += bf_hi(pw.w); }
;       if (br == 2) store8bf((bf16_t*)e.out + (size_t)row * DM + col, v);
;       else store8bf(fa, v);
	s_waitcnt lgkmcnt(0)
	s_waitcnt lgkmcnt(0)
	v_mfma_f32_16x16x32_bf16 v[60:63], v[130:133], v[146:149], v[60:63]
	v_mfma_f32_16x16x32_bf16 v[56:59], v[138:141], v[146:149], v[56:59]
	v_mfma_f32_16x16x32_bf16 v[48:51], v[130:133], v[164:167], v[48:51]
	v_mfma_f32_16x16x32_bf16 v[40:43], v[138:141], v[164:167], v[40:43]
	v_mfma_f32_16x16x32_bf16 v[32:35], v[130:133], v[176:179], v[32:35]
	v_mfma_f32_16x16x32_bf16 v[24:27], v[138:141], v[176:179], v[24:27]
	v_mfma_f32_16x16x32_bf16 v[16:19], v[130:133], v[184:187], v[16:19]
	v_mfma_f32_16x16x32_bf16 v[8:11], v[138:141], v[184:187], v[8:11]
	v_mfma_f32_16x16x32_bf16 v[60:63], v[134:137], v[160:163], v[60:63]
	v_mfma_f32_16x16x32_bf16 v[56:59], v[142:145], v[160:163], v[56:59]
	v_mfma_f32_16x16x32_bf16 v[48:51], v[134:137], v[168:171], v[48:51]
	v_mfma_f32_16x16x32_bf16 v[40:43], v[142:145], v[168:171], v[40:43]
	v_mfma_f32_16x16x32_bf16 v[32:35], v[134:137], v[180:183], v[32:35]
	v_mfma_f32_16x16x32_bf16 v[24:27], v[142:145], v[180:183], v[24:27]
	v_mfma_f32_16x16x32_bf16 v[16:19], v[134:137], v[188:191], v[16:19]
	v_mfma_f32_16x16x32_bf16 v[8:11], v[142:145], v[188:191], v[8:11]
	s_barrier
	s_add_u32 s18, s20, 0x40080
	s_addc_u32 s19, s21, 0
	s_add_i32 s0, s22, s35
	v_lshl_add_u64 v[130:131], s[18:19], 0, v[96:97]
	s_mov_b32 m0, s0
	s_nop 0
	global_load_lds_dwordx4 v[130:131], off
	v_lshl_add_u64 v[130:131], s[18:19], 0, v[154:155]
	s_add_i32 m0, s0, 0x2000
	s_nop 0
	global_load_lds_dwordx4 v[130:131], off
	s_waitcnt vmcnt(6)
	s_barrier
	v_mfma_f32_16x16x32_bf16 v[52:55], v[192:195], v[146:149], v[52:55]
	v_mfma_f32_16x16x32_bf16 v[44:47], v[200:203], v[146:149], v[44:47]
	v_mfma_f32_16x16x32_bf16 v[36:39], v[192:195], v[164:167], v[36:39]
	v_mfma_f32_16x16x32_bf16 v[28:31], v[200:203], v[164:167], v[28:31]
	v_mfma_f32_16x16x32_bf16 v[20:23], v[192:195], v[176:179], v[20:23]
	v_mfma_f32_16x16x32_bf16 v[12:15], v[200:203], v[176:179], v[12:15]
	v_mfma_f32_16x16x32_bf16 v[4:7], v[192:195], v[184:187], v[4:7]
	v_mfma_f32_16x16x32_bf16 v[0:3], v[200:203], v[184:187], v[0:3]
	v_mfma_f32_16x16x32_bf16 v[52:55], v[196:199], v[160:163], v[52:55]
	v_mfma_f32_16x16x32_bf16 v[44:47], v[204:207], v[160:163], v[44:47]
	v_mfma_f32_16x16x32_bf16 v[36:39], v[196:199], v[168:171], v[36:39]
	v_mfma_f32_16x16x32_bf16 v[28:31], v[204:207], v[168:171], v[28:31]
	v_mfma_f32_16x16x32_bf16 v[20:23], v[196:199], v[180:183], v[20:23]
	v_mfma_f32_16x16x32_bf16 v[12:15], v[204:207], v[180:183], v[12:15]
	v_mfma_f32_16x16x32_bf16 v[4:7], v[196:199], v[188:191], v[4:7]
	v_mfma_f32_16x16x32_bf16 v[0:3], v[204:207], v[188:191], v[0:3]
	s_add_i32 s49, s49, 2
	s_add_u32 s47, s47, 0x100
	s_addc_u32 s48, s48, 0
	s_cmp_gt_u32 s49, 13
	s_mov_b64 s[18:19], s[4:5]
	s_barrier
	s_cbranch_scc0 .LBB0_981
	s_setprio 0
	v_lshl_add_u32 v213, s1, 8, v172
	v_lshl_or_b32 v214, s45, 8, v174
	v_mul_u32_u24_e32 v212, 0x3000, v213
	v_lshlrev_b32_e32 v213, 12, v213
	v_lshl_add_u32 v212, v214, 1, v212
	v_lshl_add_u32 v213, v214, 1, v213
	v_add_u32_e32 v214, 0x0, v212
	global_load_dwordx4 v[130:133], v214, s[6:7]
	global_load_dwordx4 v[134:137], v214, s[6:7] offset:256
	v_add_u32_e32 v214, 0x30000, v212
	global_load_dwordx4 v[138:141], v214, s[6:7]
	global_load_dwordx4 v[142:145], v214, s[6:7] offset:256
	v_add_u32_e32 v214, 0x60000, v212
	global_load_dwordx4 v[146:149], v214, s[6:7]
	global_load_dwordx4 v[160:163], v214, s[6:7] offset:256
	v_add_u32_e32 v214, 0x90000, v212
	global_load_dwordx4 v[164:167], v214, s[6:7]
	global_load_dwordx4 v[168:171], v214, s[6:7] offset:256
	v_add_u32_e32 v214, 0x180000, v212
	global_load_dwordx4 v[176:179], v214, s[6:7]
	global_load_dwordx4 v[180:183], v214, s[6:7] offset:256
	v_add_u32_e32 v214, 0x1b0000, v212
	global_load_dwordx4 v[184:187], v214, s[6:7]
	global_load_dwordx4 v[188:191], v214, s[6:7] offset:256
	v_add_u32_e32 v214, 0x1e0000, v212
	global_load_dwordx4 v[192:195], v214, s[6:7]
	global_load_dwordx4 v[196:199], v214, s[6:7] offset:256
	v_add_u32_e32 v214, 0x210000, v212
	global_load_dwordx4 v[200:203], v214, s[6:7]
	global_load_dwordx4 v[204:207], v214, s[6:7] offset:256
	s_waitcnt vmcnt(15)
	v_lshlrev_b32_e32 v208, 16, v130
	v_and_b32_e32 v209, 0xffff0000, v130
	v_pk_mul_f32 v[126:127], v[126:127], v[208:209]
	v_lshlrev_b32_e32 v208, 16, v131
	v_and_b32_e32 v209, 0xffff0000, v131
	v_pk_mul_f32 v[128:129], v[128:129], v[208:209]
	v_lshlrev_b32_e32 v208, 16, v132
	v_and_b32_e32 v209, 0xffff0000, v132
	v_pk_mul_f32 v[122:123], v[122:123], v[208:209]
	v_lshlrev_b32_e32 v208, 16, v133
	v_and_b32_e32 v209, 0xffff0000, v133
	v_pk_mul_f32 v[124:125], v[124:125], v[208:209]
	v_cvt_pk_bf16_f32 v126, v126, v127
	v_cvt_pk_bf16_f32 v127, v128, v129
	v_cvt_pk_bf16_f32 v128, v122, v123
	v_cvt_pk_bf16_f32 v129, v124, v125
	v_add_u32_e32 v215, 0x0, v213
	global_store_dwordx4 v215, v[126:129], s[8:9]
	s_waitcnt vmcnt(15)
	v_lshlrev_b32_e32 v208, 16, v134
	v_and_b32_e32 v209, 0xffff0000, v134
	v_pk_mul_f32 v[114:115], v[114:115], v[208:209]
	v_lshlrev_b32_e32 v208, 16, v135
	v_and_b32_e32 v209, 0xffff0000, v135
	v_pk_mul_f32 v[116:117], v[116:117], v[208:209]
	v_lshlrev_b32_e32 v208, 16, v136
	v_and_b32_e32 v209, 0xffff0000, v136
	v_pk_mul_f32 v[106:107], v[106:107], v[208:209]
	v_lshlrev_b32_e32 v208, 16, v137
	v_and_b32_e32 v209, 0xffff0000, v137
	v_pk_mul_f32 v[108:109], v[108:109], v[208:209]
	v_cvt_pk_bf16_f32 v114, v114, v115
	v_cvt_pk_bf16_f32 v115, v116, v117
	v_cvt_pk_bf16_f32 v116, v106, v107
	v_cvt_pk_bf16_f32 v117, v108, v109
	global_store_dwordx4 v215, v[114:117], s[8:9] offset:256
	s_waitcnt vmcnt(15)
; __device__ __forceinline__ float bf_lo(unsigned u) { return __uint_as_float(u << 16); }
; __device__ __forceinline__ float bf_hi(unsigned u) { return __uint_as_float(u & 0xffff0000u); }
;   __device__ __forceinline__ void emit(const EpiPre& q0, int row, int col, f32x4 a, f32x4 b, const f32x4 (&hb)[2][2], const float (&hs)[2][4], int ai_, int m_, int bj_) const {
;     ...
;     } else if (MODE == E_PROJ) {
;       const int br = e.aux; const u32x4 gw = q.u0;
;       v[0] *= bf_lo(gw.x); v[1] *= bf_hi(gw.x); v[2] *= bf_lo(gw.y); v[3] *= bf_hi(gw.y);
;       v[4] *= bf_lo(gw.z); v[5] *= bf_hi(gw.z); v[6] *= bf_lo(gw.w); v[7] *= bf_hi(gw.w);
;       bf16_t* fa = (bf16_t*)e.facc + (size_t)row * DM + col;
;       if (br > 0) { const u32x4 pw = q.u1;
;         v[0] += bf_lo(pw.x); v[1] += bf_hi(pw.x); v[2] += bf_lo(pw.y); v[3] += bf_hi(pw.y); v[4] += bf_lo(pw.z); v[5] += bf_hi(pw.z); v[6] += bf_lo(pw.w); v[7] += bf_hi(pw.w); }
;       if (br == 2) store8bf((bf16_t*)e.out + (size_t)row * DM + col, v);
;       else store8bf(fa, v);
	v_lshlrev_b32_e32 v208, 16, v138
	v_and_b32_e32 v209, 0xffff0000, v138
	v_pk_mul_f32 v[118:119], v[118:119], v[208:209]
	v_lshlrev_b32_e32 v208, 16, v139
	v_and_b32_e32 v209, 0xffff0000, v139
	v_pk_mul_f32 v[120:121], v[120:121], v[208:209]
	v_lshlrev_b32_e32 v208, 16, v140
	v_and_b32_e32 v209, 0xffff0000, v140
	v_pk_mul_f32 v[110:111], v[110:111], v[208:209]
	v_lshlrev_b32_e32 v208, 16, v141
	v_and_b32_e32 v209, 0xffff0000, v141
	v_pk_mul_f32 v[112:113], v[112:113], v[208:209]
	v_cvt_pk_bf16_f32 v118, v118, v119
	v_cvt_pk_bf16_f32 v119, v120, v121
	v_cvt_pk_bf16_f32 v120, v110, v111
	v_cvt_pk_bf16_f32 v121, v112, v113
	v_add_u32_e32 v215, 0x10000, v213
	global_store_dwordx4 v215, v[118:121], s[8:9]
	s_waitcnt vmcnt(15)
	v_lshlrev_b32_e32 v208, 16, v142
	v_and_b32_e32 v209, 0xffff0000, v142
	v_pk_mul_f32 v[102:103], v[102:103], v[208:209]
	v_lshlrev_b32_e32 v208, 16, v143
	v_and_b32_e32 v209, 0xffff0000, v143
	v_pk_mul_f32 v[104:105], v[104:105], v[208:209]
	v_lshlrev_b32_e32 v208, 16, v144
	v_and_b32_e32 v209, 0xffff0000, v144
	v_pk_mul_f32 v[98:99], v[98:99], v[208:209]
	v_lshlrev_b32_e32 v208, 16, v145
	v_and_b32_e32 v209, 0xffff0000, v145
	v_pk_mul_f32 v[100:101], v[100:101], v[208:209]
	v_cvt_pk_bf16_f32 v102, v102, v103
	v_cvt_pk_bf16_f32 v103, v104, v105
	v_cvt_pk_bf16_f32 v104, v98, v99
	v_cvt_pk_bf16_f32 v105, v100, v101
	global_store_dwordx4 v215, v[102:105], s[8:9] offset:256
	s_waitcnt vmcnt(15)
	v_lshlrev_b32_e32 v208, 16, v146
	v_and_b32_e32 v209, 0xffff0000, v146
	v_pk_mul_f32 v[92:93], v[92:93], v[208:209]
	v_lshlrev_b32_e32 v208, 16, v147
	v_and_b32_e32 v209, 0xffff0000, v147
	v_pk_mul_f32 v[94:95], v[94:95], v[208:209]
	v_lshlrev_b32_e32 v208, 16, v148
	v_and_b32_e32 v209, 0xffff0000, v148
	v_pk_mul_f32 v[88:89], v[88:89], v[208:209]
	v_lshlrev_b32_e32 v208, 16, v149
	v_and_b32_e32 v209, 0xffff0000, v149
	v_pk_mul_f32 v[90:91], v[90:91], v[208:209]
	v_cvt_pk_bf16_f32 v92, v92, v93
	v_cvt_pk_bf16_f32 v93, v94, v95
	v_cvt_pk_bf16_f32 v94, v88, v89
	v_cvt_pk_bf16_f32 v95, v90, v91
	v_add_u32_e32 v215, 0x20000, v213
	global_store_dwordx4 v215, v[92:95], s[8:9]
	s_waitcnt vmcnt(15)
	v_lshlrev_b32_e32 v208, 16, v160
	v_and_b32_e32 v209, 0xffff0000, v160
	v_pk_mul_f32 v[84:85], v[84:85], v[208:209]
	v_lshlrev_b32_e32 v208, 16, v161
	v_and_b32_e32 v209, 0xffff0000, v161
	v_pk_mul_f32 v[86:87], v[86:87], v[208:209]
	v_lshlrev_b32_e32 v208, 16, v162
	v_and_b32_e32 v209, 0xffff0000, v162
	v_pk_mul_f32 v[76:77], v[76:77], v[208:209]
	v_lshlrev_b32_e32 v208, 16, v163
	v_and_b32_e32 v209, 0xffff0000, v163
	v_pk_mul_f32 v[78:79], v[78:79], v[208:209]
	v_cvt_pk_bf16_f32 v84, v84, v85
	v_cvt_pk_bf16_f32 v85, v86, v87
	v_cvt_pk_bf16_f32 v86, v76, v77
	v_cvt_pk_bf16_f32 v87, v78, v79
	global_store_dwordx4 v215, v[84:87], s[8:9] offset:256
	s_waitcnt vmcnt(15)
	v_lshlrev_b32_e32 v208, 16, v164
	v_and_b32_e32 v209, 0xffff0000, v164
	v_pk_mul_f32 v[80:81], v[80:81], v[208:209]
	v_lshlrev_b32_e32 v208, 16, v165
	v_and_b32_e32 v209, 0xffff0000, v165
	v_pk_mul_f32 v[82:83], v[82:83], v[208:209]
	v_lshlrev_b32_e32 v208, 16, v166
	v_and_b32_e32 v209, 0xffff0000, v166
	v_pk_mul_f32 v[72:73], v[72:73], v[208:209]
	v_lshlrev_b32_e32 v208, 16, v167
	v_and_b32_e32 v209, 0xffff0000, v167
	v_pk_mul_f32 v[74:75], v[74:75], v[208:209]
	v_cvt_pk_bf16_f32 v80, v80, v81
	v_cvt_pk_bf16_f32 v81, v82, v83
	v_cvt_pk_bf16_f32 v82, v72, v73
	v_cvt_pk_bf16_f32 v83, v74, v75
	v_add_u32_e32 v215, 0x30000, v213
	global_store_dwordx4 v215, v[80:83], s[8:9]
	s_waitcnt vmcnt(15)
	v_lshlrev_b32_e32 v208, 16, v168
	v_and_b32_e32 v209, 0xffff0000, v168
	v_pk_mul_f32 v[68:69], v[68:69], v[208:209]
	v_lshlrev_b32_e32 v208, 16, v169
	v_and_b32_e32 v209, 0xffff0000, v169
	v_pk_mul_f32 v[70:71], v[70:71], v[208:209]
	v_lshlrev_b32_e32 v208, 16, v170
	v_and_b32_e32 v209, 0xffff0000, v170
	v_pk_mul_f32 v[64:65], v[64:65], v[208:209]
	v_lshlrev_b32_e32 v208, 16, v171
	v_and_b32_e32 v209, 0xffff0000, v171
	v_pk_mul_f32 v[66:67], v[66:67], v[208:209]
	v_cvt_pk_bf16_f32 v68, v68, v69
	v_cvt_pk_bf16_f32 v69, v70, v71
	v_cvt_pk_bf16_f32 v70, v64, v65
	v_cvt_pk_bf16_f32 v71, v66, v67
	global_store_dwordx4 v215, v[68:71], s[8:9] offset:256
	s_waitcnt vmcnt(15)
	v_lshlrev_b32_e32 v208, 16, v176
	v_and_b32_e32 v209, 0xffff0000, v176
	v_pk_mul_f32 v[60:61], v[60:61], v[208:209]
	v_lshlrev_b32_e32 v208, 16, v177
	v_and_b32_e32 v209, 0xffff0000, v177
	v_pk_mul_f32 v[62:63], v[62:63], v[208:209]
	v_lshlrev_b32_e32 v208, 16, v178
	v_and_b32_e32 v209, 0xffff0000, v178
	v_pk_mul_f32 v[56:57], v[56:57], v[208:209]
	v_lshlrev_b32_e32 v208, 16, v179
	v_and_b32_e32 v209, 0xffff0000, v179
	v_pk_mul_f32 v[58:59], v[58:59], v[208:209]
	v_cvt_pk_bf16_f32 v60, v60, v61
	v_cvt_pk_bf16_f32 v61, v62, v63
	v_cvt_pk_bf16_f32 v62, v56, v57
	v_cvt_pk_bf16_f32 v63, v58, v59
	v_add_u32_e32 v215, 0x80000, v213
	global_store_dwordx4 v215, v[60:63], s[8:9]
	s_waitcnt vmcnt(15)
; __device__ __forceinline__ float bf_lo(unsigned u) { return __uint_as_float(u << 16); }
; __device__ __forceinline__ float bf_hi(unsigned u) { return __uint_as_float(u & 0xffff0000u); }
; #define PG8_WAIT_V(n) asm volatile("s_waitcnt vmcnt(" #n ")" ::: "memory")
; #define PG8_BAR __builtin_amdgcn_s_barrier()
; template <class Epi>
; __device__ __forceinline__ void gemm_phase(LAS unsigned char* lds, const Gemm g, const StaticOrder& S, const Epi& E, int wv0) {
;     ...
;     if (!has_next) break;
; #pragma unroll
;     for (int a = 0; a < 2; ++a)
; #pragma unroll
;       for (int b = 0; b < 2; ++b)
; #pragma unroll
;         for (int m = 0; m < 4; ++m)
; #pragma unroll
;           for (int n = 0; n < 2; ++n) acc[a][b][m][n] = (f32x4){0.f, 0.f, 0.f, 0.f};
;     cur = nxt; cA = nA; cB = nB; ++ui;
;   }
;   PG8_WAIT_V(0);
;   if (wr == 0) PG8_BAR;
;   PG8_BAR;
;   __device__ __forceinline__ void emit(const EpiPre& q0, int row, int col, f32x4 a, f32x4 b, const f32x4 (&hb)[2][2], const float (&hs)[2][4], int ai_, int m_, int bj_) const {
;     ...
;     } else if (MODE == E_PROJ) {
;       const int br = e.aux; const u32x4 gw = q.u0;
;       v[0] *= bf_lo(gw.x); v[1] *= bf_hi(gw.x); v[2] *= bf_lo(gw.y); v[3] *= bf_hi(gw.y);
;       v[4] *= bf_lo(gw.z); v[5] *= bf_hi(gw.z); v[6] *= bf_lo(gw.w); v[7] *= bf_hi(gw.w);
;       bf16_t* fa = (bf16_t*)e.facc + (size_t)row * DM + col;
;       if (br > 0) { const u32x4 pw = q.u1;
;         v[0] += bf_lo(pw.x); v[1] += bf_hi(pw.x); v[2] += bf_lo(pw.y); v[3] += bf_hi(pw.y); v[4] += bf_lo(pw.z); v[5] += bf_hi(pw.z); v[6] += bf_lo(pw.w); v[7] += bf_hi(pw.w); }
;       if (br == 2) store8bf((bf16_t*)e.out + (size_t)row * DM + col, v);
;       else store8bf(fa, v);
	v_lshlrev_b32_e32 v208, 16, v180
	v_and_b32_e32 v209, 0xffff0000, v180
	v_pk_mul_f32 v[52:53], v[52:53], v[208:209]
	v_lshlrev_b32_e32 v208, 16, v181
	v_and_b32_e32 v209, 0xffff0000, v181
	v_pk_mul_f32 v[54:55], v[54:55], v[208:209]
	v_lshlrev_b32_e32 v208, 16, v182
	v_and_b32_e32 v209, 0xffff0000, v182
	v_pk_mul_f32 v[44:45], v[44:45], v[208:209]
	v_lshlrev_b32_e32 v208, 16, v183
	v_and_b32_e32 v209, 0xffff0000, v183
	v_pk_mul_f32 v[46:47], v[46:47], v[208:209]
	v_cvt_pk_bf16_f32 v52, v52, v53
	v_cvt_pk_bf16_f32 v53, v54, v55
	v_cvt_pk_bf16_f32 v54, v44, v45
	v_cvt_pk_bf16_f32 v55, v46, v47
	global_store_dwordx4 v215, v[52:55], s[8:9] offset:256
	s_waitcnt vmcnt(15)
	v_lshlrev_b32_e32 v208, 16, v184
	v_and_b32_e32 v209, 0xffff0000, v184
	v_pk_mul_f32 v[48:49], v[48:49], v[208:209]
	v_lshlrev_b32_e32 v208, 16, v185
	v_and_b32_e32 v209, 0xffff0000, v185
	v_pk_mul_f32 v[50:51], v[50:51], v[208:209]
	v_lshlrev_b32_e32 v208, 16, v186
	v_and_b32_e32 v209, 0xffff0000, v186
	v_pk_mul_f32 v[40:41], v[40:41], v[208:209]
	v_lshlrev_b32_e32 v208, 16, v187
	v_and_b32_e32 v209, 0xffff0000, v187
	v_pk_mul_f32 v[42:43], v[42:43], v[208:209]
	v_cvt_pk_bf16_f32 v48, v48, v49
	v_cvt_pk_bf16_f32 v49, v50, v51
	v_cvt_pk_bf16_f32 v50, v40, v41
	v_cvt_pk_bf16_f32 v51, v42, v43
	v_add_u32_e32 v215, 0x90000, v213
	global_store_dwordx4 v215, v[48:51], s[8:9]
	s_waitcnt vmcnt(15)
	v_lshlrev_b32_e32 v208, 16, v188
	v_and_b32_e32 v209, 0xffff0000, v188
	v_pk_mul_f32 v[36:37], v[36:37], v[208:209]
	v_lshlrev_b32_e32 v208, 16, v189
	v_and_b32_e32 v209, 0xffff0000, v189
	v_pk_mul_f32 v[38:39], v[38:39], v[208:209]
	v_lshlrev_b32_e32 v208, 16, v190
	v_and_b32_e32 v209, 0xffff0000, v190
	v_pk_mul_f32 v[28:29], v[28:29], v[208:209]
	v_lshlrev_b32_e32 v208, 16, v191
	v_and_b32_e32 v209, 0xffff0000, v191
	v_pk_mul_f32 v[30:31], v[30:31], v[208:209]
	v_cvt_pk_bf16_f32 v36, v36, v37
	v_cvt_pk_bf16_f32 v37, v38, v39
	v_cvt_pk_bf16_f32 v38, v28, v29
	v_cvt_pk_bf16_f32 v39, v30, v31
	global_store_dwordx4 v215, v[36:39], s[8:9] offset:256
	s_waitcnt vmcnt(15)
	v_lshlrev_b32_e32 v208, 16, v192
	v_and_b32_e32 v209, 0xffff0000, v192
	v_pk_mul_f32 v[32:33], v[32:33], v[208:209]
	v_lshlrev_b32_e32 v208, 16, v193
	v_and_b32_e32 v209, 0xffff0000, v193
	v_pk_mul_f32 v[34:35], v[34:35], v[208:209]
	v_lshlrev_b32_e32 v208, 16, v194
	v_and_b32_e32 v209, 0xffff0000, v194
	v_pk_mul_f32 v[24:25], v[24:25], v[208:209]
	v_lshlrev_b32_e32 v208, 16, v195
	v_and_b32_e32 v209, 0xffff0000, v195
	v_pk_mul_f32 v[26:27], v[26:27], v[208:209]
	v_cvt_pk_bf16_f32 v32, v32, v33
	v_cvt_pk_bf16_f32 v33, v34, v35
	v_cvt_pk_bf16_f32 v34, v24, v25
	v_cvt_pk_bf16_f32 v35, v26, v27
	v_add_u32_e32 v215, 0xa0000, v213
	global_store_dwordx4 v215, v[32:35], s[8:9]
	s_waitcnt vmcnt(15)
	v_lshlrev_b32_e32 v208, 16, v196
	v_and_b32_e32 v209, 0xffff0000, v196
	v_pk_mul_f32 v[20:21], v[20:21], v[208:209]
	v_lshlrev_b32_e32 v208, 16, v197
	v_and_b32_e32 v209, 0xffff0000, v197
	v_pk_mul_f32 v[22:23], v[22:23], v[208:209]
	v_lshlrev_b32_e32 v208, 16, v198
	v_and_b32_e32 v209, 0xffff0000, v198
	v_pk_mul_f32 v[12:13], v[12:13], v[208:209]
	v_lshlrev_b32_e32 v208, 16, v199
	v_and_b32_e32 v209, 0xffff0000, v199
	v_pk_mul_f32 v[14:15], v[14:15], v[208:209]
	v_cvt_pk_bf16_f32 v20, v20, v21
	v_cvt_pk_bf16_f32 v21, v22, v23
	v_cvt_pk_bf16_f32 v22, v12, v13
	v_cvt_pk_bf16_f32 v23, v14, v15
	global_store_dwordx4 v215, v[20:23], s[8:9] offset:256
	s_waitcnt vmcnt(15)
	v_lshlrev_b32_e32 v208, 16, v200
	v_and_b32_e32 v209, 0xffff0000, v200
	v_pk_mul_f32 v[16:17], v[16:17], v[208:209]
	v_lshlrev_b32_e32 v208, 16, v201
	v_and_b32_e32 v209, 0xffff0000, v201
	v_pk_mul_f32 v[18:19], v[18:19], v[208:209]
	v_lshlrev_b32_e32 v208, 16, v202
	v_and_b32_e32 v209, 0xffff0000, v202
	v_pk_mul_f32 v[8:9], v[8:9], v[208:209]
	v_lshlrev_b32_e32 v208, 16, v203
	v_and_b32_e32 v209, 0xffff0000, v203
	v_pk_mul_f32 v[10:11], v[10:11], v[208:209]
	v_cvt_pk_bf16_f32 v16, v16, v17
	v_cvt_pk_bf16_f32 v17, v18, v19
	v_cvt_pk_bf16_f32 v18, v8, v9
	v_cvt_pk_bf16_f32 v19, v10, v11
	v_add_u32_e32 v215, 0xb0000, v213
	global_store_dwordx4 v215, v[16:19], s[8:9]
	s_waitcnt vmcnt(15)
	v_lshlrev_b32_e32 v208, 16, v204
	v_and_b32_e32 v209, 0xffff0000, v204
	v_pk_mul_f32 v[4:5], v[4:5], v[208:209]
	v_lshlrev_b32_e32 v208, 16, v205
	v_and_b32_e32 v209, 0xffff0000, v205
	v_pk_mul_f32 v[6:7], v[6:7], v[208:209]
	v_lshlrev_b32_e32 v208, 16, v206
	v_and_b32_e32 v209, 0xffff0000, v206
	v_pk_mul_f32 v[0:1], v[0:1], v[208:209]
	v_lshlrev_b32_e32 v208, 16, v207
	v_and_b32_e32 v209, 0xffff0000, v207
	v_pk_mul_f32 v[2:3], v[2:3], v[208:209]
	v_cvt_pk_bf16_f32 v4, v4, v5
	v_cvt_pk_bf16_f32 v5, v6, v7
	v_cvt_pk_bf16_f32 v6, v0, v1
	v_cvt_pk_bf16_f32 v7, v2, v3
	global_store_dwordx4 v215, v[4:7], s[8:9] offset:256
	s_mov_b32 s45, s12
	s_mov_b64 s[20:21], s[16:17]
	s_mov_b64 s[18:19], s[14:15]
	s_and_b64 vcc, exec, s[2:3]
	s_mov_b32 s1, s44
	s_cbranch_vccz .LBB0_972
	s_waitcnt vmcnt(0)
	s_cmpk_gt_u32 s27, 0xff
	s_cbranch_scc1 .LBB0_985
	s_barrier

; #define PG8_STAGE(bufoff, gbase, voff) do { _Pragma("unroll") for (int _i = 0; _i < 2; ++_i) \
;     __builtin_amdgcn_global_load_lds((const unsigned*)((const char*)(gbase) + (voff)[_i]), (LAS unsigned*)(lds + (bufoff) + ldsw + _i * 8192), 16, 0, 0); } while (0)
; #define PG8_LDA(dst, b, h) do { _Pragma("unroll") for (int m = 0; m < 4; ++m) _Pragma("unroll") for (int k = 0; k < 2; ++k) dst[m][k] = *(const LAS bf16x8*)(lds + PG8_SA(b, h) + aoff + m * 2048 + k * 1024); } while (0)
; #define PG8_LDB(dst, b, h) do { _Pragma("unroll") for (int n = 0; n < 2; ++n) _Pragma("unroll") for (int k = 0; k < 2; ++k) dst[n][k] = *(const LAS bf16x8*)(lds + PG8_SB(b, h) + boff + n * 2048 + k * 1024); } while (0)
; #define PG8_MMA(ai, bj, At, Bt) do { __builtin_amdgcn_s_setprio(1); _Pragma("unroll") for (int m = 0; m < 4; ++m) _Pragma("unroll") for (int n = 0; n < 2; ++n) _Pragma("unroll") for (int k = 0; k < 2; ++k) \
;     acc[ai][bj][m][n] = __builtin_amdgcn_mfma_f32_16x16x32_bf16(Bt[n][k], At[m][k], acc[ai][bj][m][n], 0, 0, 0); __builtin_amdgcn_s_setprio(0); } while (0)
; #define PG8_WAIT_L(n) asm volatile("s_waitcnt lgkmcnt(" #n ")" ::: "memory")
; #define PG8_BAR __builtin_amdgcn_s_barrier()
; #define PG8_SCHED __builtin_amdgcn_sched_barrier(0)
; template <class Epi>
; __device__ __forceinline__ void gemm_phase(LAS unsigned char* lds, const Gemm g, const StaticOrder& S, const Epi& E, int wv0) {
;     ...
;     for (int t = 0; t < nt; t += 2) {
;       const bool last = (t == nt - 2);
;       const char* a1 = cA + (size_t)(t + 1) * kstep;
;       const char* a2 = last ? nA : cA + (size_t)(t + 2) * kstep; const char* b2 = last ? nB : cB + (size_t)(t + 2) * kstep;
;       const char* a3 = a2 + kstep; const char* b3 = b2 + kstep;
;       PG8_LDB(B0, 0, 0); PG8_SCHED; PG8_LDA(At, 0, 0); PG8_STAGE(PG8_SA(1, 1), a1 + hstepA, voffA);
;       PG8_WAIT_L(8); PG8_BAR; PG8_WAIT_L(0); PG8_MMA(0, 0, At, B0); PG8_BAR; PG8_SCHED;
;       PG8_LDB(B1, 0, 1); PG8_STAGE(PG8_SB(0, 0), b2, voffB);
;       PG8_BAR; PG8_WAIT_L(0); PG8_MMA(0, 1, At, B1); PG8_BAR;
;       PG8_LDA(At, 0, 1); PG8_STAGE(PG8_SA(0, 0), a2, voffA);
;       PG8_BAR; PG8_WAIT_L(0); PG8_MMA(1, 0, At, B0); PG8_BAR; PG8_SCHED;
.LBB0_1003:
	s_add_u32 s4, s18, 0x100
	s_addc_u32 s5, s19, 0
	s_add_i32 s0, 0, 0x10000
	v_add_u32_e32 v142, s0, v219
	ds_read_b128 v[130:133], v142
	ds_read_b128 v[134:137], v142 offset:1024
	ds_read_b128 v[138:141], v142 offset:2048
	ds_read_b128 v[142:145], v142 offset:3072
	s_cmp_eq_u32 s49, 28
	s_cselect_b32 s23, s15, s5
	s_cselect_b32 s22, s14, s4
	s_cselect_b32 s21, s13, s48
	s_cselect_b32 s20, s46, s47
	v_lshl_add_u64 v[178:179], s[18:19], 0, v[200:201]
	s_add_i32 m0, s36, 0xc000
	ds_read_b128 v[146:149], v225
	ds_read_b128 v[150:153], v225 offset:1024
	ds_read_b128 v[154:157], v225 offset:2048
	ds_read_b128 v[158:161], v225 offset:3072
	ds_read_b128 v[162:165], v225 offset:4096
	ds_read_b128 v[166:169], v225 offset:5120
	ds_read_b128 v[170:173], v225 offset:6144
	ds_read_b128 v[174:177], v225 offset:7168
	global_load_lds_dwordx4 v[178:179], off
	v_lshl_add_u64 v[178:179], s[18:19], 0, v[202:203]
	s_add_i32 m0, s36, 0xe000
	s_nop 0
	global_load_lds_dwordx4 v[178:179], off
	s_waitcnt lgkmcnt(8)
	s_barrier
	s_waitcnt lgkmcnt(0)
	s_waitcnt lgkmcnt(0)
	v_mfma_f32_16x16x32_bf16 v[126:129], v[130:133], v[146:149], v[126:129]
	v_mfma_f32_16x16x32_bf16 v[122:125], v[138:141], v[146:149], v[122:125]
	v_mfma_f32_16x16x32_bf16 v[110:113], v[130:133], v[154:157], v[110:113]
	v_mfma_f32_16x16x32_bf16 v[106:109], v[138:141], v[154:157], v[106:109]
	v_mfma_f32_16x16x32_bf16 v[92:95], v[130:133], v[162:165], v[92:95]
	v_mfma_f32_16x16x32_bf16 v[88:91], v[138:141], v[162:165], v[88:91]
	v_mfma_f32_16x16x32_bf16 v[76:79], v[130:133], v[170:173], v[76:79]
	v_mfma_f32_16x16x32_bf16 v[72:75], v[138:141], v[170:173], v[72:75]
	v_mfma_f32_16x16x32_bf16 v[126:129], v[134:137], v[150:153], v[126:129]
	v_mfma_f32_16x16x32_bf16 v[122:125], v[142:145], v[150:153], v[122:125]
	v_mfma_f32_16x16x32_bf16 v[110:113], v[134:137], v[158:161], v[110:113]
	v_mfma_f32_16x16x32_bf16 v[106:109], v[142:145], v[158:161], v[106:109]
	v_mfma_f32_16x16x32_bf16 v[92:95], v[134:137], v[166:169], v[92:95]
	v_mfma_f32_16x16x32_bf16 v[88:91], v[142:145], v[166:169], v[88:91]
	v_mfma_f32_16x16x32_bf16 v[76:79], v[134:137], v[174:177], v[76:79]
	v_mfma_f32_16x16x32_bf16 v[72:75], v[142:145], v[174:177], v[72:75]
	s_barrier
	s_add_i32 s50, 0, 0x14000
	s_add_i32 s0, s0, s35
	v_add_u32_e32 v190, s50, v219
	v_lshl_add_u64 v[204:205], s[20:21], 0, v[96:97]
	s_mov_b32 m0, s0
	ds_read_b128 v[178:181], v190
	ds_read_b128 v[182:185], v190 offset:1024
	ds_read_b128 v[186:189], v190 offset:2048
	ds_read_b128 v[190:193], v190 offset:3072
	global_load_lds_dwordx4 v[204:205], off
	v_lshl_add_u64 v[206:207], s[20:21], 0, v[198:199]
	s_add_i32 m0, s0, 0x2000
	s_nop 0
	global_load_lds_dwordx4 v[206:207], off
	s_barrier
	s_waitcnt lgkmcnt(0)
	s_waitcnt lgkmcnt(0)
	v_mfma_f32_16x16x32_bf16 v[118:121], v[178:181], v[146:149], v[118:121]
	v_mfma_f32_16x16x32_bf16 v[114:117], v[186:189], v[146:149], v[114:117]
	v_mfma_f32_16x16x32_bf16 v[102:105], v[178:181], v[154:157], v[102:105]
	v_mfma_f32_16x16x32_bf16 v[98:101], v[186:189], v[154:157], v[98:101]
	v_mfma_f32_16x16x32_bf16 v[84:87], v[178:181], v[162:165], v[84:87]
	v_mfma_f32_16x16x32_bf16 v[80:83], v[186:189], v[162:165], v[80:83]
	v_mfma_f32_16x16x32_bf16 v[68:71], v[178:181], v[170:173], v[68:71]
	v_mfma_f32_16x16x32_bf16 v[64:67], v[186:189], v[170:173], v[64:67]
	v_mfma_f32_16x16x32_bf16 v[118:121], v[182:185], v[150:153], v[118:121]
	v_mfma_f32_16x16x32_bf16 v[114:117], v[190:193], v[150:153], v[114:117]
	v_mfma_f32_16x16x32_bf16 v[102:105], v[182:185], v[158:161], v[102:105]
	v_mfma_f32_16x16x32_bf16 v[98:101], v[190:193], v[158:161], v[98:101]
	v_mfma_f32_16x16x32_bf16 v[84:87], v[182:185], v[166:169], v[84:87]
	v_mfma_f32_16x16x32_bf16 v[80:83], v[190:193], v[166:169], v[80:83]
	v_mfma_f32_16x16x32_bf16 v[68:71], v[182:185], v[174:177], v[68:71]
	v_mfma_f32_16x16x32_bf16 v[64:67], v[190:193], v[174:177], v[64:67]
	s_mov_b32 m0, s36
	v_lshl_add_u64 v[208:209], s[22:23], 0, v[194:195]
	s_barrier
	ds_read_b128 v[146:149], v225 offset:16384
	ds_read_b128 v[150:153], v225 offset:17408
	ds_read_b128 v[154:157], v225 offset:18432
	ds_read_b128 v[158:161], v225 offset:19456
	ds_read_b128 v[162:165], v225 offset:20480
	ds_read_b128 v[166:169], v225 offset:21504
	ds_read_b128 v[170:173], v225 offset:22528
	ds_read_b128 v[174:177], v225 offset:23552
	global_load_lds_dwordx4 v[208:209], off
	v_lshl_add_u64 v[210:211], s[22:23], 0, v[196:197]
	s_mov_b32 m0, s37
	s_nop 0
	global_load_lds_dwordx4 v[210:211], off
	s_barrier
	s_waitcnt lgkmcnt(0)
	s_waitcnt lgkmcnt(0)
	v_mfma_f32_16x16x32_bf16 v[60:63], v[130:133], v[146:149], v[60:63]
	v_mfma_f32_16x16x32_bf16 v[56:59], v[138:141], v[146:149], v[56:59]
	v_mfma_f32_16x16x32_bf16 v[44:47], v[130:133], v[154:157], v[44:47]
	v_mfma_f32_16x16x32_bf16 v[40:43], v[138:141], v[154:157], v[40:43]
	v_mfma_f32_16x16x32_bf16 v[28:31], v[130:133], v[162:165], v[28:31]
	v_mfma_f32_16x16x32_bf16 v[24:27], v[138:141], v[162:165], v[24:27]
	v_mfma_f32_16x16x32_bf16 v[12:15], v[130:133], v[170:173], v[12:15]
	v_mfma_f32_16x16x32_bf16 v[8:11], v[138:141], v[170:173], v[8:11]
	v_mfma_f32_16x16x32_bf16 v[60:63], v[134:137], v[150:153], v[60:63]
	v_mfma_f32_16x16x32_bf16 v[56:59], v[142:145], v[150:153], v[56:59]
	v_mfma_f32_16x16x32_bf16 v[44:47], v[134:137], v[158:161], v[44:47]
	v_mfma_f32_16x16x32_bf16 v[40:43], v[142:145], v[158:161], v[40:43]
	v_mfma_f32_16x16x32_bf16 v[28:31], v[134:137], v[166:169], v[28:31]
	v_mfma_f32_16x16x32_bf16 v[24:27], v[142:145], v[166:169], v[24:27]
	v_mfma_f32_16x16x32_bf16 v[12:15], v[134:137], v[174:177], v[12:15]
	v_mfma_f32_16x16x32_bf16 v[8:11], v[142:145], v[174:177], v[8:11]
	s_barrier
; #define PG8_STAGE(bufoff, gbase, voff) do { _Pragma("unroll") for (int _i = 0; _i < 2; ++_i) \
;     __builtin_amdgcn_global_load_lds((const unsigned*)((const char*)(gbase) + (voff)[_i]), (LAS unsigned*)(lds + (bufoff) + ldsw + _i * 8192), 16, 0, 0); } while (0)
; #define PG8_LDA(dst, b, h) do { _Pragma("unroll") for (int m = 0; m < 4; ++m) _Pragma("unroll") for (int k = 0; k < 2; ++k) dst[m][k] = *(const LAS bf16x8*)(lds + PG8_SA(b, h) + aoff + m * 2048 + k * 1024); } while (0)
; #define PG8_LDB(dst, b, h) do { _Pragma("unroll") for (int n = 0; n < 2; ++n) _Pragma("unroll") for (int k = 0; k < 2; ++k) dst[n][k] = *(const LAS bf16x8*)(lds + PG8_SB(b, h) + boff + n * 2048 + k * 1024); } while (0)
; #define PG8_MMA(ai, bj, At, Bt) do { __builtin_amdgcn_s_setprio(1); _Pragma("unroll") for (int m = 0; m < 4; ++m) _Pragma("unroll") for (int n = 0; n < 2; ++n) _Pragma("unroll") for (int k = 0; k < 2; ++k) \
;     acc[ai][bj][m][n] = __builtin_amdgcn_mfma_f32_16x16x32_bf16(Bt[n][k], At[m][k], acc[ai][bj][m][n], 0, 0, 0); __builtin_amdgcn_s_setprio(0); } while (0)
; #define PG8_WAIT_V(n) asm volatile("s_waitcnt vmcnt(" #n ")" ::: "memory")
; #define PG8_WAIT_L(n) asm volatile("s_waitcnt lgkmcnt(" #n ")" ::: "memory")
; #define PG8_BAR __builtin_amdgcn_s_barrier()
; #define PG8_SCHED __builtin_amdgcn_sched_barrier(0)
; template <class Epi>
; __device__ __forceinline__ void gemm_phase(LAS unsigned char* lds, const Gemm g, const StaticOrder& S, const Epi& E, int wv0) {
;     ...
;       PG8_STAGE(PG8_SB(0, 1), b2 + hstepB, voffB);
;       PG8_WAIT_V(6); PG8_BAR; PG8_MMA(1, 1, At, B1); PG8_BAR;
;       PG8_LDB(B0, 1, 0); PG8_SCHED; PG8_LDA(At, 1, 0); PG8_STAGE(PG8_SA(0, 1), a2 + hstepA, voffA);
;       PG8_WAIT_L(8); PG8_BAR; PG8_WAIT_L(0); PG8_MMA(0, 0, At, B0); PG8_BAR; PG8_SCHED;
;       PG8_LDB(B1, 1, 1); PG8_STAGE(PG8_SB(1, 0), b3, voffB);
;       PG8_BAR; PG8_WAIT_L(0); PG8_MMA(0, 1, At, B1); PG8_BAR;
;       PG8_LDA(At, 1, 1); PG8_STAGE(PG8_SA(1, 0), a3, voffA);
;       PG8_BAR; PG8_WAIT_L(0); PG8_MMA(1, 0, At, B0); PG8_BAR; PG8_SCHED;
	s_add_u32 s18, s20, 0x80000
	s_addc_u32 s19, s21, 0
	s_add_i32 s0, s50, s35
	v_lshl_add_u64 v[130:131], s[18:19], 0, v[96:97]
	s_mov_b32 m0, s0
	s_nop 0
	global_load_lds_dwordx4 v[130:131], off
	v_lshl_add_u64 v[130:131], s[18:19], 0, v[198:199]
	s_add_i32 m0, s0, 0x2000
	s_nop 0
	global_load_lds_dwordx4 v[130:131], off
	s_waitcnt vmcnt(6)
	s_barrier
	v_mfma_f32_16x16x32_bf16 v[52:55], v[178:181], v[146:149], v[52:55]
	v_mfma_f32_16x16x32_bf16 v[48:51], v[186:189], v[146:149], v[48:51]
	v_mfma_f32_16x16x32_bf16 v[36:39], v[178:181], v[154:157], v[36:39]
	v_mfma_f32_16x16x32_bf16 v[32:35], v[186:189], v[154:157], v[32:35]
	v_mfma_f32_16x16x32_bf16 v[20:23], v[178:181], v[162:165], v[20:23]
	v_mfma_f32_16x16x32_bf16 v[16:19], v[186:189], v[162:165], v[16:19]
	v_mfma_f32_16x16x32_bf16 v[4:7], v[178:181], v[170:173], v[4:7]
	v_mfma_f32_16x16x32_bf16 v[0:3], v[186:189], v[170:173], v[0:3]
	v_mfma_f32_16x16x32_bf16 v[52:55], v[182:185], v[150:153], v[52:55]
	v_mfma_f32_16x16x32_bf16 v[48:51], v[190:193], v[150:153], v[48:51]
	v_mfma_f32_16x16x32_bf16 v[36:39], v[182:185], v[158:161], v[36:39]
	v_mfma_f32_16x16x32_bf16 v[32:35], v[190:193], v[158:161], v[32:35]
	v_mfma_f32_16x16x32_bf16 v[20:23], v[182:185], v[166:169], v[20:23]
	v_mfma_f32_16x16x32_bf16 v[16:19], v[190:193], v[166:169], v[16:19]
	v_mfma_f32_16x16x32_bf16 v[4:7], v[182:185], v[174:177], v[4:7]
	v_mfma_f32_16x16x32_bf16 v[0:3], v[190:193], v[174:177], v[0:3]
	s_add_i32 s0, 0, 0x18000
	v_add_u32_e32 v142, s0, v219
	s_barrier
	ds_read_b128 v[130:133], v142
	ds_read_b128 v[134:137], v142 offset:1024
	ds_read_b128 v[138:141], v142 offset:2048
	ds_read_b128 v[142:145], v142 offset:3072
	s_add_u32 s18, s22, 0x114000
	s_addc_u32 s19, s23, 0
	s_mov_b32 m0, s38
	v_lshl_add_u64 v[178:179], s[18:19], 0, v[194:195]
	ds_read_b128 v[146:149], v225 offset:32768
	ds_read_b128 v[150:153], v225 offset:33792
	ds_read_b128 v[154:157], v225 offset:34816
	ds_read_b128 v[158:161], v225 offset:35840
	ds_read_b128 v[162:165], v225 offset:36864
	ds_read_b128 v[166:169], v225 offset:37888
	ds_read_b128 v[170:173], v225 offset:38912
	ds_read_b128 v[174:177], v225 offset:39936
	global_load_lds_dwordx4 v[178:179], off
	v_lshl_add_u64 v[178:179], s[18:19], 0, v[196:197]
	s_mov_b32 m0, s39
	s_nop 0
	global_load_lds_dwordx4 v[178:179], off
	s_waitcnt lgkmcnt(8)
	s_barrier
	s_waitcnt lgkmcnt(0)
	s_waitcnt lgkmcnt(0)
	v_mfma_f32_16x16x32_bf16 v[126:129], v[130:133], v[146:149], v[126:129]
	v_mfma_f32_16x16x32_bf16 v[122:125], v[138:141], v[146:149], v[122:125]
	v_mfma_f32_16x16x32_bf16 v[110:113], v[130:133], v[154:157], v[110:113]
	v_mfma_f32_16x16x32_bf16 v[106:109], v[138:141], v[154:157], v[106:109]
	v_mfma_f32_16x16x32_bf16 v[92:95], v[130:133], v[162:165], v[92:95]
	v_mfma_f32_16x16x32_bf16 v[88:91], v[138:141], v[162:165], v[88:91]
	v_mfma_f32_16x16x32_bf16 v[76:79], v[130:133], v[170:173], v[76:79]
	v_mfma_f32_16x16x32_bf16 v[72:75], v[138:141], v[170:173], v[72:75]
	v_mfma_f32_16x16x32_bf16 v[126:129], v[134:137], v[150:153], v[126:129]
	v_mfma_f32_16x16x32_bf16 v[122:125], v[142:145], v[150:153], v[122:125]
	v_mfma_f32_16x16x32_bf16 v[110:113], v[134:137], v[158:161], v[110:113]
	v_mfma_f32_16x16x32_bf16 v[106:109], v[142:145], v[158:161], v[106:109]
	v_mfma_f32_16x16x32_bf16 v[92:95], v[134:137], v[166:169], v[92:95]
	v_mfma_f32_16x16x32_bf16 v[88:91], v[142:145], v[166:169], v[88:91]
	v_mfma_f32_16x16x32_bf16 v[76:79], v[134:137], v[174:177], v[76:79]
	v_mfma_f32_16x16x32_bf16 v[72:75], v[142:145], v[174:177], v[72:75]
	s_barrier
	s_add_i32 s22, 0, 0x1c000
	s_add_i32 s0, s0, s35
	v_add_u32_e32 v190, s22, v219
	v_lshl_add_u64 v[204:205], v[204:205], 0, s[72:73]
	s_mov_b32 m0, s0
	ds_read_b128 v[178:181], v190
	ds_read_b128 v[182:185], v190 offset:1024
	ds_read_b128 v[186:189], v190 offset:2048
	ds_read_b128 v[190:193], v190 offset:3072
	global_load_lds_dwordx4 v[204:205], off
	v_lshl_add_u64 v[204:205], v[206:207], 0, s[72:73]
	s_add_i32 m0, s0, 0x2000
	s_nop 0
	global_load_lds_dwordx4 v[204:205], off
	s_barrier
	s_waitcnt lgkmcnt(0)
	s_waitcnt lgkmcnt(0)
	v_mfma_f32_16x16x32_bf16 v[118:121], v[178:181], v[146:149], v[118:121]
	v_mfma_f32_16x16x32_bf16 v[114:117], v[186:189], v[146:149], v[114:117]
	v_mfma_f32_16x16x32_bf16 v[102:105], v[178:181], v[154:157], v[102:105]
	v_mfma_f32_16x16x32_bf16 v[98:101], v[186:189], v[154:157], v[98:101]
	v_mfma_f32_16x16x32_bf16 v[84:87], v[178:181], v[162:165], v[84:87]
	v_mfma_f32_16x16x32_bf16 v[80:83], v[186:189], v[162:165], v[80:83]
	v_mfma_f32_16x16x32_bf16 v[68:71], v[178:181], v[170:173], v[68:71]
	v_mfma_f32_16x16x32_bf16 v[64:67], v[186:189], v[170:173], v[64:67]
	v_mfma_f32_16x16x32_bf16 v[118:121], v[182:185], v[150:153], v[118:121]
	v_mfma_f32_16x16x32_bf16 v[114:117], v[190:193], v[150:153], v[114:117]
	v_mfma_f32_16x16x32_bf16 v[102:105], v[182:185], v[158:161], v[102:105]
	v_mfma_f32_16x16x32_bf16 v[98:101], v[190:193], v[158:161], v[98:101]
	v_mfma_f32_16x16x32_bf16 v[84:87], v[182:185], v[166:169], v[84:87]
	v_mfma_f32_16x16x32_bf16 v[80:83], v[190:193], v[166:169], v[80:83]
	v_mfma_f32_16x16x32_bf16 v[68:71], v[182:185], v[174:177], v[68:71]
	v_mfma_f32_16x16x32_bf16 v[64:67], v[190:193], v[174:177], v[64:67]
	s_mov_b32 m0, s40
	v_lshl_add_u64 v[204:205], v[208:209], 0, s[72:73]
	s_barrier
	ds_read_b128 v[146:149], v225 offset:49152
	ds_read_b128 v[150:153], v225 offset:50176
	ds_read_b128 v[154:157], v225 offset:51200
	ds_read_b128 v[158:161], v225 offset:52224
	ds_read_b128 v[162:165], v225 offset:53248
	ds_read_b128 v[166:169], v225 offset:54272
	ds_read_b128 v[170:173], v225 offset:55296
	ds_read_b128 v[174:177], v225 offset:56320
	global_load_lds_dwordx4 v[204:205], off
	v_lshl_add_u64 v[204:205], v[210:211], 0, s[72:73]
	s_mov_b32 m0, s41
	s_nop 0
	global_load_lds_dwordx4 v[204:205], off
	s_barrier
; __device__ __forceinline__ float bf_lo(unsigned u) { return __uint_as_float(u << 16); }
; __device__ __forceinline__ float bf_hi(unsigned u) { return __uint_as_float(u & 0xffff0000u); }
; #define PG8_STAGE(bufoff, gbase, voff) do { _Pragma("unroll") for (int _i = 0; _i < 2; ++_i) \
;     __builtin_amdgcn_global_load_lds((const unsigned*)((const char*)(gbase) + (voff)[_i]), (LAS unsigned*)(lds + (bufoff) + ldsw + _i * 8192), 16, 0, 0); } while (0)
; #define PG8_MMA(ai, bj, At, Bt) do { __builtin_amdgcn_s_setprio(1); _Pragma("unroll") for (int m = 0; m < 4; ++m) _Pragma("unroll") for (int n = 0; n < 2; ++n) _Pragma("unroll") for (int k = 0; k < 2; ++k) \
;     acc[ai][bj][m][n] = __builtin_amdgcn_mfma_f32_16x16x32_bf16(Bt[n][k], At[m][k], acc[ai][bj][m][n], 0, 0, 0); __builtin_amdgcn_s_setprio(0); } while (0)
; #define PG8_WAIT_V(n) asm volatile("s_waitcnt vmcnt(" #n ")" ::: "memory")
; #define PG8_WAIT_L(n) asm volatile("s_waitcnt lgkmcnt(" #n ")" ::: "memory")
; #define PG8_BAR __builtin_amdgcn_s_barrier()
; #define PG8_SCHED __builtin_amdgcn_sched_barrier(0)
; template <class Epi>
; __device__ __forceinline__ void gemm_phase(LAS unsigned char* lds, const Gemm g, const StaticOrder& S, const Epi& E, int wv0) {
;     ...
;       PG8_BAR; PG8_WAIT_L(0); PG8_MMA(1, 0, At, B0); PG8_BAR; PG8_SCHED;
;       PG8_STAGE(PG8_SB(1, 1), b3 + hstepB, voffB);
;       PG8_WAIT_V(6); PG8_BAR; PG8_MMA(1, 1, At, B1); PG8_BAR;
;     }
;   __device__ __forceinline__ void emit(const EpiPre& q0, int row, int col, f32x4 a, f32x4 b, const f32x4 (&hb)[2][2], const float (&hs)[2][4], int ai_, int m_, int bj_) const {
;     ...
;     } else if (MODE == E_PROJ) {
;       const int br = e.aux; const u32x4 gw = q.u0;
;       v[0] *= bf_lo(gw.x); v[1] *= bf_hi(gw.x); v[2] *= bf_lo(gw.y); v[3] *= bf_hi(gw.y);
;       v[4] *= bf_lo(gw.z); v[5] *= bf_hi(gw.z); v[6] *= bf_lo(gw.w); v[7] *= bf_hi(gw.w);
;       bf16_t* fa = (bf16_t*)e.facc + (size_t)row * DM + col;
;       if (br > 0) { const u32x4 pw = q.u1;
;         v[0] += bf_lo(pw.x); v[1] += bf_hi(pw.x); v[2] += bf_lo(pw.y); v[3] += bf_hi(pw.y); v[4] += bf_lo(pw.z); v[5] += bf_hi(pw.z); v[6] += bf_lo(pw.w); v[7] += bf_hi(pw.w); }
	s_waitcnt lgkmcnt(0)
	s_waitcnt lgkmcnt(0)
	v_mfma_f32_16x16x32_bf16 v[60:63], v[130:133], v[146:149], v[60:63]
	v_mfma_f32_16x16x32_bf16 v[56:59], v[138:141], v[146:149], v[56:59]
	v_mfma_f32_16x16x32_bf16 v[44:47], v[130:133], v[154:157], v[44:47]
	v_mfma_f32_16x16x32_bf16 v[40:43], v[138:141], v[154:157], v[40:43]
	v_mfma_f32_16x16x32_bf16 v[28:31], v[130:133], v[162:165], v[28:31]
	v_mfma_f32_16x16x32_bf16 v[24:27], v[138:141], v[162:165], v[24:27]
	v_mfma_f32_16x16x32_bf16 v[12:15], v[130:133], v[170:173], v[12:15]
	v_mfma_f32_16x16x32_bf16 v[8:11], v[138:141], v[170:173], v[8:11]
	v_mfma_f32_16x16x32_bf16 v[60:63], v[134:137], v[150:153], v[60:63]
	v_mfma_f32_16x16x32_bf16 v[56:59], v[142:145], v[150:153], v[56:59]
	v_mfma_f32_16x16x32_bf16 v[44:47], v[134:137], v[158:161], v[44:47]
	v_mfma_f32_16x16x32_bf16 v[40:43], v[142:145], v[158:161], v[40:43]
	v_mfma_f32_16x16x32_bf16 v[28:31], v[134:137], v[166:169], v[28:31]
	v_mfma_f32_16x16x32_bf16 v[24:27], v[142:145], v[166:169], v[24:27]
	v_mfma_f32_16x16x32_bf16 v[12:15], v[134:137], v[174:177], v[12:15]
	v_mfma_f32_16x16x32_bf16 v[8:11], v[142:145], v[174:177], v[8:11]
	s_barrier
	s_add_u32 s18, s20, 0x80080
	s_addc_u32 s19, s21, 0
	s_add_i32 s0, s22, s35
	v_lshl_add_u64 v[130:131], s[18:19], 0, v[96:97]
	s_mov_b32 m0, s0
	s_nop 0
	global_load_lds_dwordx4 v[130:131], off
	v_lshl_add_u64 v[130:131], s[18:19], 0, v[198:199]
	s_add_i32 m0, s0, 0x2000
	s_nop 0
	global_load_lds_dwordx4 v[130:131], off
	s_waitcnt vmcnt(6)
	s_barrier
	v_mfma_f32_16x16x32_bf16 v[52:55], v[178:181], v[146:149], v[52:55]
	v_mfma_f32_16x16x32_bf16 v[48:51], v[186:189], v[146:149], v[48:51]
	v_mfma_f32_16x16x32_bf16 v[36:39], v[178:181], v[154:157], v[36:39]
	v_mfma_f32_16x16x32_bf16 v[32:35], v[186:189], v[154:157], v[32:35]
	v_mfma_f32_16x16x32_bf16 v[20:23], v[178:181], v[162:165], v[20:23]
	v_mfma_f32_16x16x32_bf16 v[16:19], v[186:189], v[162:165], v[16:19]
	v_mfma_f32_16x16x32_bf16 v[4:7], v[178:181], v[170:173], v[4:7]
	v_mfma_f32_16x16x32_bf16 v[0:3], v[186:189], v[170:173], v[0:3]
	v_mfma_f32_16x16x32_bf16 v[52:55], v[182:185], v[150:153], v[52:55]
	v_mfma_f32_16x16x32_bf16 v[48:51], v[190:193], v[150:153], v[48:51]
	v_mfma_f32_16x16x32_bf16 v[36:39], v[182:185], v[158:161], v[36:39]
	v_mfma_f32_16x16x32_bf16 v[32:35], v[190:193], v[158:161], v[32:35]
	v_mfma_f32_16x16x32_bf16 v[20:23], v[182:185], v[166:169], v[20:23]
	v_mfma_f32_16x16x32_bf16 v[16:19], v[190:193], v[166:169], v[16:19]
	v_mfma_f32_16x16x32_bf16 v[4:7], v[182:185], v[174:177], v[4:7]
	v_mfma_f32_16x16x32_bf16 v[0:3], v[190:193], v[174:177], v[0:3]
	s_add_i32 s49, s49, 2
	s_add_u32 s47, s47, 0x100
	s_addc_u32 s48, s48, 0
	s_cmp_gt_u32 s49, 29
	s_mov_b64 s[18:19], s[4:5]
	s_barrier
	s_cbranch_scc0 .LBB0_1003
	s_setprio 0
	v_lshl_add_u32 v209, s1, 8, v218
	v_lshl_or_b32 v211, s45, 8, v224
	v_mul_u32_u24_e32 v208, 0x3000, v209
	v_lshlrev_b32_e32 v209, 12, v209
	v_lshl_add_u32 v208, v211, 1, v208
	v_lshl_add_u32 v209, v211, 1, v209
	v_add_u32_e32 v211, 0x0, v208
	global_load_dwordx4 v[130:133], v211, s[8:9]
	v_add_u32_e32 v212, 0x0, v209
	global_load_dwordx4 v[134:137], v212, s[6:7]
	global_load_dwordx4 v[138:141], v211, s[8:9] offset:256
	global_load_dwordx4 v[142:145], v212, s[6:7] offset:256
	v_add_u32_e32 v211, 0x30000, v208
	global_load_dwordx4 v[146:149], v211, s[8:9]
	v_add_u32_e32 v212, 0x10000, v209
	global_load_dwordx4 v[150:153], v212, s[6:7]
	global_load_dwordx4 v[154:157], v211, s[8:9] offset:256
	global_load_dwordx4 v[158:161], v212, s[6:7] offset:256
	v_add_u32_e32 v211, 0x60000, v208
	global_load_dwordx4 v[162:165], v211, s[8:9]
	v_add_u32_e32 v212, 0x20000, v209
	global_load_dwordx4 v[166:169], v212, s[6:7]
	global_load_dwordx4 v[170:173], v211, s[8:9] offset:256
	global_load_dwordx4 v[174:177], v212, s[6:7] offset:256
	v_add_u32_e32 v211, 0x90000, v208
	global_load_dwordx4 v[178:181], v211, s[8:9]
	v_add_u32_e32 v212, 0x30000, v209
	global_load_dwordx4 v[182:185], v212, s[6:7]
	global_load_dwordx4 v[186:189], v211, s[8:9] offset:256
	global_load_dwordx4 v[190:193], v212, s[6:7] offset:256
	s_waitcnt vmcnt(14)
	v_lshlrev_b32_e32 v204, 16, v130
	v_and_b32_e32 v205, 0xffff0000, v130
	v_lshlrev_b32_e32 v206, 16, v134
	v_and_b32_e32 v207, 0xffff0000, v134
	v_pk_fma_f32 v[126:127], v[126:127], v[204:205], v[206:207]
	v_lshlrev_b32_e32 v204, 16, v131
	v_and_b32_e32 v205, 0xffff0000, v131
	v_lshlrev_b32_e32 v206, 16, v135
	v_and_b32_e32 v207, 0xffff0000, v135
	v_pk_fma_f32 v[128:129], v[128:129], v[204:205], v[206:207]
	v_lshlrev_b32_e32 v204, 16, v132
	v_and_b32_e32 v205, 0xffff0000, v132
	v_lshlrev_b32_e32 v206, 16, v136
	v_and_b32_e32 v207, 0xffff0000, v136
	v_pk_fma_f32 v[122:123], v[122:123], v[204:205], v[206:207]
	v_lshlrev_b32_e32 v204, 16, v133
	v_and_b32_e32 v205, 0xffff0000, v133
	v_lshlrev_b32_e32 v206, 16, v137
	v_and_b32_e32 v207, 0xffff0000, v137
	v_pk_fma_f32 v[124:125], v[124:125], v[204:205], v[206:207]
	v_cvt_pk_bf16_f32 v126, v126, v127
	v_cvt_pk_bf16_f32 v127, v128, v129
	v_cvt_pk_bf16_f32 v128, v122, v123
	v_cvt_pk_bf16_f32 v129, v124, v125
	v_add_u32_e32 v211, 0x180000, v208
	global_load_dwordx4 v[130:133], v211, s[8:9]
	v_add_u32_e32 v212, 0x80000, v209
	global_load_dwordx4 v[134:137], v212, s[6:7]
	s_waitcnt vmcnt(14)
; __device__ __forceinline__ float bf_lo(unsigned u) { return __uint_as_float(u << 16); }
; __device__ __forceinline__ float bf_hi(unsigned u) { return __uint_as_float(u & 0xffff0000u); }
;   __device__ __forceinline__ void emit(const EpiPre& q0, int row, int col, f32x4 a, f32x4 b, const f32x4 (&hb)[2][2], const float (&hs)[2][4], int ai_, int m_, int bj_) const {
;     ...
;     } else if (MODE == E_PROJ) {
;       const int br = e.aux; const u32x4 gw = q.u0;
;       v[0] *= bf_lo(gw.x); v[1] *= bf_hi(gw.x); v[2] *= bf_lo(gw.y); v[3] *= bf_hi(gw.y);
;       v[4] *= bf_lo(gw.z); v[5] *= bf_hi(gw.z); v[6] *= bf_lo(gw.w); v[7] *= bf_hi(gw.w);
;       bf16_t* fa = (bf16_t*)e.facc + (size_t)row * DM + col;
;       if (br > 0) { const u32x4 pw = q.u1;
;         v[0] += bf_lo(pw.x); v[1] += bf_hi(pw.x); v[2] += bf_lo(pw.y); v[3] += bf_hi(pw.y); v[4] += bf_lo(pw.z); v[5] += bf_hi(pw.z); v[6] += bf_lo(pw.w); v[7] += bf_hi(pw.w); }
;       if (br == 2) store8bf((bf16_t*)e.out + (size_t)row * DM + col, v);
;       else store8bf(fa, v);
	v_lshlrev_b32_e32 v204, 16, v138
	v_and_b32_e32 v205, 0xffff0000, v138
	v_lshlrev_b32_e32 v206, 16, v142
	v_and_b32_e32 v207, 0xffff0000, v142
	v_pk_fma_f32 v[118:119], v[118:119], v[204:205], v[206:207]
	v_lshlrev_b32_e32 v204, 16, v139
	v_and_b32_e32 v205, 0xffff0000, v139
	v_lshlrev_b32_e32 v206, 16, v143
	v_and_b32_e32 v207, 0xffff0000, v143
	v_pk_fma_f32 v[120:121], v[120:121], v[204:205], v[206:207]
	v_lshlrev_b32_e32 v204, 16, v140
	v_and_b32_e32 v205, 0xffff0000, v140
	v_lshlrev_b32_e32 v206, 16, v144
	v_and_b32_e32 v207, 0xffff0000, v144
	v_pk_fma_f32 v[114:115], v[114:115], v[204:205], v[206:207]
	v_lshlrev_b32_e32 v204, 16, v141
	v_and_b32_e32 v205, 0xffff0000, v141
	v_lshlrev_b32_e32 v206, 16, v145
	v_and_b32_e32 v207, 0xffff0000, v145
	v_pk_fma_f32 v[116:117], v[116:117], v[204:205], v[206:207]
	v_cvt_pk_bf16_f32 v118, v118, v119
	v_cvt_pk_bf16_f32 v119, v120, v121
	v_cvt_pk_bf16_f32 v120, v114, v115
	v_cvt_pk_bf16_f32 v121, v116, v117
	global_load_dwordx4 v[138:141], v211, s[8:9] offset:256
	global_load_dwordx4 v[142:145], v212, s[6:7] offset:256
	s_waitcnt vmcnt(14)
	v_lshlrev_b32_e32 v204, 16, v146
	v_and_b32_e32 v205, 0xffff0000, v146
	v_lshlrev_b32_e32 v206, 16, v150
	v_and_b32_e32 v207, 0xffff0000, v150
	v_pk_fma_f32 v[110:111], v[110:111], v[204:205], v[206:207]
	v_lshlrev_b32_e32 v204, 16, v147
	v_and_b32_e32 v205, 0xffff0000, v147
	v_lshlrev_b32_e32 v206, 16, v151
	v_and_b32_e32 v207, 0xffff0000, v151
	v_pk_fma_f32 v[112:113], v[112:113], v[204:205], v[206:207]
	v_lshlrev_b32_e32 v204, 16, v148
	v_and_b32_e32 v205, 0xffff0000, v148
	v_lshlrev_b32_e32 v206, 16, v152
	v_and_b32_e32 v207, 0xffff0000, v152
	v_pk_fma_f32 v[106:107], v[106:107], v[204:205], v[206:207]
	v_lshlrev_b32_e32 v204, 16, v149
	v_and_b32_e32 v205, 0xffff0000, v149
	v_lshlrev_b32_e32 v206, 16, v153
	v_and_b32_e32 v207, 0xffff0000, v153
	v_pk_fma_f32 v[108:109], v[108:109], v[204:205], v[206:207]
	v_cvt_pk_bf16_f32 v110, v110, v111
	v_cvt_pk_bf16_f32 v111, v112, v113
	v_cvt_pk_bf16_f32 v112, v106, v107
	v_cvt_pk_bf16_f32 v113, v108, v109
	v_add_u32_e32 v211, 0x1b0000, v208
	global_load_dwordx4 v[146:149], v211, s[8:9]
	v_add_u32_e32 v212, 0x90000, v209
	global_load_dwordx4 v[150:153], v212, s[6:7]
	s_waitcnt vmcnt(14)
	v_lshlrev_b32_e32 v204, 16, v154
	v_and_b32_e32 v205, 0xffff0000, v154
	v_lshlrev_b32_e32 v206, 16, v158
	v_and_b32_e32 v207, 0xffff0000, v158
	v_pk_fma_f32 v[102:103], v[102:103], v[204:205], v[206:207]
	v_lshlrev_b32_e32 v204, 16, v155
	v_and_b32_e32 v205, 0xffff0000, v155
	v_lshlrev_b32_e32 v206, 16, v159
	v_and_b32_e32 v207, 0xffff0000, v159
	v_pk_fma_f32 v[104:105], v[104:105], v[204:205], v[206:207]
	v_lshlrev_b32_e32 v204, 16, v156
	v_and_b32_e32 v205, 0xffff0000, v156
	v_lshlrev_b32_e32 v206, 16, v160
	v_and_b32_e32 v207, 0xffff0000, v160
	v_pk_fma_f32 v[98:99], v[98:99], v[204:205], v[206:207]
	v_lshlrev_b32_e32 v204, 16, v157
	v_and_b32_e32 v205, 0xffff0000, v157
	v_lshlrev_b32_e32 v206, 16, v161
	v_and_b32_e32 v207, 0xffff0000, v161
	v_pk_fma_f32 v[100:101], v[100:101], v[204:205], v[206:207]
	v_cvt_pk_bf16_f32 v102, v102, v103
	v_cvt_pk_bf16_f32 v103, v104, v105
	v_cvt_pk_bf16_f32 v104, v98, v99
	v_cvt_pk_bf16_f32 v105, v100, v101
	global_load_dwordx4 v[154:157], v211, s[8:9] offset:256
	global_load_dwordx4 v[158:161], v212, s[6:7] offset:256
	s_waitcnt vmcnt(14)
	v_lshlrev_b32_e32 v204, 16, v162
	v_and_b32_e32 v205, 0xffff0000, v162
	v_lshlrev_b32_e32 v206, 16, v166
	v_and_b32_e32 v207, 0xffff0000, v166
	v_pk_fma_f32 v[92:93], v[92:93], v[204:205], v[206:207]
	v_lshlrev_b32_e32 v204, 16, v163
	v_and_b32_e32 v205, 0xffff0000, v163
	v_lshlrev_b32_e32 v206, 16, v167
	v_and_b32_e32 v207, 0xffff0000, v167
	v_pk_fma_f32 v[94:95], v[94:95], v[204:205], v[206:207]
	v_lshlrev_b32_e32 v204, 16, v164
	v_and_b32_e32 v205, 0xffff0000, v164
	v_lshlrev_b32_e32 v206, 16, v168
	v_and_b32_e32 v207, 0xffff0000, v168
	v_pk_fma_f32 v[88:89], v[88:89], v[204:205], v[206:207]
	v_lshlrev_b32_e32 v204, 16, v165
	v_and_b32_e32 v205, 0xffff0000, v165
	v_lshlrev_b32_e32 v206, 16, v169
	v_and_b32_e32 v207, 0xffff0000, v169
	v_pk_fma_f32 v[90:91], v[90:91], v[204:205], v[206:207]
	v_cvt_pk_bf16_f32 v92, v92, v93
	v_cvt_pk_bf16_f32 v93, v94, v95
	v_cvt_pk_bf16_f32 v94, v88, v89
	v_cvt_pk_bf16_f32 v95, v90, v91
	v_add_u32_e32 v211, 0x1e0000, v208
	global_load_dwordx4 v[162:165], v211, s[8:9]
	v_add_u32_e32 v212, 0xa0000, v209
	global_load_dwordx4 v[166:169], v212, s[6:7]
	s_waitcnt vmcnt(14)
	v_lshlrev_b32_e32 v204, 16, v170
	v_and_b32_e32 v205, 0xffff0000, v170
	v_lshlrev_b32_e32 v206, 16, v174
	v_and_b32_e32 v207, 0xffff0000, v174
	v_pk_fma_f32 v[84:85], v[84:85], v[204:205], v[206:207]
	v_lshlrev_b32_e32 v204, 16, v171
	v_and_b32_e32 v205, 0xffff0000, v171
	v_lshlrev_b32_e32 v206, 16, v175
	v_and_b32_e32 v207, 0xffff0000, v175
	v_pk_fma_f32 v[86:87], v[86:87], v[204:205], v[206:207]
	v_lshlrev_b32_e32 v204, 16, v172
	v_and_b32_e32 v205, 0xffff0000, v172
	v_lshlrev_b32_e32 v206, 16, v176
	v_and_b32_e32 v207, 0xffff0000, v176
	v_pk_fma_f32 v[80:81], v[80:81], v[204:205], v[206:207]
	v_lshlrev_b32_e32 v204, 16, v173
	v_and_b32_e32 v205, 0xffff0000, v173
	v_lshlrev_b32_e32 v206, 16, v177
	v_and_b32_e32 v207, 0xffff0000, v177
	v_pk_fma_f32 v[82:83], v[82:83], v[204:205], v[206:207]
	v_cvt_pk_bf16_f32 v84, v84, v85
	v_cvt_pk_bf16_f32 v85, v86, v87
	v_cvt_pk_bf16_f32 v86, v80, v81
	v_cvt_pk_bf16_f32 v87, v82, v83
	global_load_dwordx4 v[170:173], v211, s[8:9] offset:256
	global_load_dwordx4 v[174:177], v212, s[6:7] offset:256
	s_waitcnt vmcnt(14)
; __device__ __forceinline__ float bf_lo(unsigned u) { return __uint_as_float(u << 16); }
; __device__ __forceinline__ float bf_hi(unsigned u) { return __uint_as_float(u & 0xffff0000u); }
;   __device__ __forceinline__ void emit(const EpiPre& q0, int row, int col, f32x4 a, f32x4 b, const f32x4 (&hb)[2][2], const float (&hs)[2][4], int ai_, int m_, int bj_) const {
;     ...
;     } else if (MODE == E_PROJ) {
;       const int br = e.aux; const u32x4 gw = q.u0;
;       v[0] *= bf_lo(gw.x); v[1] *= bf_hi(gw.x); v[2] *= bf_lo(gw.y); v[3] *= bf_hi(gw.y);
;       v[4] *= bf_lo(gw.z); v[5] *= bf_hi(gw.z); v[6] *= bf_lo(gw.w); v[7] *= bf_hi(gw.w);
;       bf16_t* fa = (bf16_t*)e.facc + (size_t)row * DM + col;
;       if (br > 0) { const u32x4 pw = q.u1;
;         v[0] += bf_lo(pw.x); v[1] += bf_hi(pw.x); v[2] += bf_lo(pw.y); v[3] += bf_hi(pw.y); v[4] += bf_lo(pw.z); v[5] += bf_hi(pw.z); v[6] += bf_lo(pw.w); v[7] += bf_hi(pw.w); }
;       if (br == 2) store8bf((bf16_t*)e.out + (size_t)row * DM + col, v);
;       else store8bf(fa, v);
	v_lshlrev_b32_e32 v204, 16, v178
	v_and_b32_e32 v205, 0xffff0000, v178
	v_lshlrev_b32_e32 v206, 16, v182
	v_and_b32_e32 v207, 0xffff0000, v182
	v_pk_fma_f32 v[76:77], v[76:77], v[204:205], v[206:207]
	v_lshlrev_b32_e32 v204, 16, v179
	v_and_b32_e32 v205, 0xffff0000, v179
	v_lshlrev_b32_e32 v206, 16, v183
	v_and_b32_e32 v207, 0xffff0000, v183
	v_pk_fma_f32 v[78:79], v[78:79], v[204:205], v[206:207]
	v_lshlrev_b32_e32 v204, 16, v180
	v_and_b32_e32 v205, 0xffff0000, v180
	v_lshlrev_b32_e32 v206, 16, v184
	v_and_b32_e32 v207, 0xffff0000, v184
	v_pk_fma_f32 v[72:73], v[72:73], v[204:205], v[206:207]
	v_lshlrev_b32_e32 v204, 16, v181
	v_and_b32_e32 v205, 0xffff0000, v181
	v_lshlrev_b32_e32 v206, 16, v185
	v_and_b32_e32 v207, 0xffff0000, v185
	v_pk_fma_f32 v[74:75], v[74:75], v[204:205], v[206:207]
	v_cvt_pk_bf16_f32 v76, v76, v77
	v_cvt_pk_bf16_f32 v77, v78, v79
	v_cvt_pk_bf16_f32 v78, v72, v73
	v_cvt_pk_bf16_f32 v79, v74, v75
	v_add_u32_e32 v211, 0x210000, v208
	global_load_dwordx4 v[178:181], v211, s[8:9]
	v_add_u32_e32 v212, 0xb0000, v209
	global_load_dwordx4 v[182:185], v212, s[6:7]
	s_waitcnt vmcnt(14)
	v_lshlrev_b32_e32 v204, 16, v186
	v_and_b32_e32 v205, 0xffff0000, v186
	v_lshlrev_b32_e32 v206, 16, v190
	v_and_b32_e32 v207, 0xffff0000, v190
	v_pk_fma_f32 v[68:69], v[68:69], v[204:205], v[206:207]
	v_lshlrev_b32_e32 v204, 16, v187
	v_and_b32_e32 v205, 0xffff0000, v187
	v_lshlrev_b32_e32 v206, 16, v191
	v_and_b32_e32 v207, 0xffff0000, v191
	v_pk_fma_f32 v[70:71], v[70:71], v[204:205], v[206:207]
	v_lshlrev_b32_e32 v204, 16, v188
	v_and_b32_e32 v205, 0xffff0000, v188
	v_lshlrev_b32_e32 v206, 16, v192
	v_and_b32_e32 v207, 0xffff0000, v192
	v_pk_fma_f32 v[64:65], v[64:65], v[204:205], v[206:207]
	v_lshlrev_b32_e32 v204, 16, v189
	v_and_b32_e32 v205, 0xffff0000, v189
	v_lshlrev_b32_e32 v206, 16, v193
	v_and_b32_e32 v207, 0xffff0000, v193
	v_pk_fma_f32 v[66:67], v[66:67], v[204:205], v[206:207]
	v_cvt_pk_bf16_f32 v68, v68, v69
	v_cvt_pk_bf16_f32 v69, v70, v71
	v_cvt_pk_bf16_f32 v70, v64, v65
	v_cvt_pk_bf16_f32 v71, v66, v67
	global_load_dwordx4 v[186:189], v211, s[8:9] offset:256
	global_load_dwordx4 v[190:193], v212, s[6:7] offset:256
	v_add_u32_e32 v212, 0x0, v209
	global_store_dwordx4 v212, v[126:129], s[6:7]
	global_store_dwordx4 v212, v[118:121], s[6:7] offset:256
	v_add_u32_e32 v212, 0x10000, v209
	global_store_dwordx4 v212, v[110:113], s[6:7]
	global_store_dwordx4 v212, v[102:105], s[6:7] offset:256
	v_add_u32_e32 v212, 0x20000, v209
	global_store_dwordx4 v212, v[92:95], s[6:7]
	global_store_dwordx4 v212, v[84:87], s[6:7] offset:256
	v_add_u32_e32 v212, 0x30000, v209
	global_store_dwordx4 v212, v[76:79], s[6:7]
	global_store_dwordx4 v212, v[68:71], s[6:7] offset:256
	s_waitcnt vmcnt(22)
	v_lshlrev_b32_e32 v204, 16, v130
	v_and_b32_e32 v205, 0xffff0000, v130
	v_lshlrev_b32_e32 v206, 16, v134
	v_and_b32_e32 v207, 0xffff0000, v134
	v_pk_fma_f32 v[60:61], v[60:61], v[204:205], v[206:207]
	v_lshlrev_b32_e32 v204, 16, v131
	v_and_b32_e32 v205, 0xffff0000, v131
	v_lshlrev_b32_e32 v206, 16, v135
	v_and_b32_e32 v207, 0xffff0000, v135
	v_pk_fma_f32 v[62:63], v[62:63], v[204:205], v[206:207]
	v_lshlrev_b32_e32 v204, 16, v132
	v_and_b32_e32 v205, 0xffff0000, v132
	v_lshlrev_b32_e32 v206, 16, v136
	v_and_b32_e32 v207, 0xffff0000, v136
	v_pk_fma_f32 v[56:57], v[56:57], v[204:205], v[206:207]
	v_lshlrev_b32_e32 v204, 16, v133
	v_and_b32_e32 v205, 0xffff0000, v133
	v_lshlrev_b32_e32 v206, 16, v137
	v_and_b32_e32 v207, 0xffff0000, v137
	v_pk_fma_f32 v[58:59], v[58:59], v[204:205], v[206:207]
	v_cvt_pk_bf16_f32 v60, v60, v61
	v_cvt_pk_bf16_f32 v61, v62, v63
	v_cvt_pk_bf16_f32 v62, v56, v57
	v_cvt_pk_bf16_f32 v63, v58, v59
	v_add_u32_e32 v212, 0x80000, v209
	global_store_dwordx4 v212, v[60:63], s[6:7]
	s_waitcnt vmcnt(21)
	v_lshlrev_b32_e32 v204, 16, v138
	v_and_b32_e32 v205, 0xffff0000, v138
	v_lshlrev_b32_e32 v206, 16, v142
	v_and_b32_e32 v207, 0xffff0000, v142
	v_pk_fma_f32 v[52:53], v[52:53], v[204:205], v[206:207]
	v_lshlrev_b32_e32 v204, 16, v139
	v_and_b32_e32 v205, 0xffff0000, v139
	v_lshlrev_b32_e32 v206, 16, v143
	v_and_b32_e32 v207, 0xffff0000, v143
	v_pk_fma_f32 v[54:55], v[54:55], v[204:205], v[206:207]
	v_lshlrev_b32_e32 v204, 16, v140
	v_and_b32_e32 v205, 0xffff0000, v140
	v_lshlrev_b32_e32 v206, 16, v144
	v_and_b32_e32 v207, 0xffff0000, v144
	v_pk_fma_f32 v[48:49], v[48:49], v[204:205], v[206:207]
	v_lshlrev_b32_e32 v204, 16, v141
	v_and_b32_e32 v205, 0xffff0000, v141
	v_lshlrev_b32_e32 v206, 16, v145
	v_and_b32_e32 v207, 0xffff0000, v145
	v_pk_fma_f32 v[50:51], v[50:51], v[204:205], v[206:207]
	v_cvt_pk_bf16_f32 v52, v52, v53
	v_cvt_pk_bf16_f32 v53, v54, v55
	v_cvt_pk_bf16_f32 v54, v48, v49
	v_cvt_pk_bf16_f32 v55, v50, v51
	global_store_dwordx4 v212, v[52:55], s[6:7] offset:256
	s_waitcnt vmcnt(20)
	v_lshlrev_b32_e32 v204, 16, v146
	v_and_b32_e32 v205, 0xffff0000, v146
	v_lshlrev_b32_e32 v206, 16, v150
	v_and_b32_e32 v207, 0xffff0000, v150
	v_pk_fma_f32 v[44:45], v[44:45], v[204:205], v[206:207]
	v_lshlrev_b32_e32 v204, 16, v147
	v_and_b32_e32 v205, 0xffff0000, v147
	v_lshlrev_b32_e32 v206, 16, v151
	v_and_b32_e32 v207, 0xffff0000, v151
	v_pk_fma_f32 v[46:47], v[46:47], v[204:205], v[206:207]
	v_lshlrev_b32_e32 v204, 16, v148
	v_and_b32_e32 v205, 0xffff0000, v148
	v_lshlrev_b32_e32 v206, 16, v152
	v_and_b32_e32 v207, 0xffff0000, v152
	v_pk_fma_f32 v[40:41], v[40:41], v[204:205], v[206:207]
	v_lshlrev_b32_e32 v204, 16, v149
	v_and_b32_e32 v205, 0xffff0000, v149
	v_lshlrev_b32_e32 v206, 16, v153
	v_and_b32_e32 v207, 0xffff0000, v153
	v_pk_fma_f32 v[42:43], v[42:43], v[204:205], v[206:207]
	v_cvt_pk_bf16_f32 v44, v44, v45
	v_cvt_pk_bf16_f32 v45, v46, v47
	v_cvt_pk_bf16_f32 v46, v40, v41
	v_cvt_pk_bf16_f32 v47, v42, v43
	v_add_u32_e32 v212, 0x90000, v209
	global_store_dwordx4 v212, v[44:47], s[6:7]
	s_waitcnt vmcnt(19)
; __device__ __forceinline__ float bf_lo(unsigned u) { return __uint_as_float(u << 16); }
; __device__ __forceinline__ float bf_hi(unsigned u) { return __uint_as_float(u & 0xffff0000u); }
; #define PG8_WAIT_V(n) asm volatile("s_waitcnt vmcnt(" #n ")" ::: "memory")
; #define PG8_BAR __builtin_amdgcn_s_barrier()
; template <class Epi>
; __device__ __forceinline__ void gemm_phase(LAS unsigned char* lds, const Gemm g, const StaticOrder& S, const Epi& E, int wv0) {
;     ...
;     if (!has_next) break;
; #pragma unroll
;     for (int a = 0; a < 2; ++a)
; #pragma unroll
;       for (int b = 0; b < 2; ++b)
; #pragma unroll
;         for (int m = 0; m < 4; ++m)
; #pragma unroll
;           for (int n = 0; n < 2; ++n) acc[a][b][m][n] = (f32x4){0.f, 0.f, 0.f, 0.f};
;     cur = nxt; cA = nA; cB = nB; ++ui;
;   }
;   PG8_WAIT_V(0);
;   if (wr == 0) PG8_BAR;
;   PG8_BAR;
;   __device__ __forceinline__ void emit(const EpiPre& q0, int row, int col, f32x4 a, f32x4 b, const f32x4 (&hb)[2][2], const float (&hs)[2][4], int ai_, int m_, int bj_) const {
;     ...
;     } else if (MODE == E_PROJ) {
;       const int br = e.aux; const u32x4 gw = q.u0;
;       v[0] *= bf_lo(gw.x); v[1] *= bf_hi(gw.x); v[2] *= bf_lo(gw.y); v[3] *= bf_hi(gw.y);
;       v[4] *= bf_lo(gw.z); v[5] *= bf_hi(gw.z); v[6] *= bf_lo(gw.w); v[7] *= bf_hi(gw.w);
;       bf16_t* fa = (bf16_t*)e.facc + (size_t)row * DM + col;
;       if (br > 0) { const u32x4 pw = q.u1;
;         v[0] += bf_lo(pw.x); v[1] += bf_hi(pw.x); v[2] += bf_lo(pw.y); v[3] += bf_hi(pw.y); v[4] += bf_lo(pw.z); v[5] += bf_hi(pw.z); v[6] += bf_lo(pw.w); v[7] += bf_hi(pw.w); }
;       if (br == 2) store8bf((bf16_t*)e.out + (size_t)row * DM + col, v);
;       else store8bf(fa, v);
	v_lshlrev_b32_e32 v204, 16, v154
	v_and_b32_e32 v205, 0xffff0000, v154
	v_lshlrev_b32_e32 v206, 16, v158
	v_and_b32_e32 v207, 0xffff0000, v158
	v_pk_fma_f32 v[36:37], v[36:37], v[204:205], v[206:207]
	v_lshlrev_b32_e32 v204, 16, v155
	v_and_b32_e32 v205, 0xffff0000, v155
	v_lshlrev_b32_e32 v206, 16, v159
	v_and_b32_e32 v207, 0xffff0000, v159
	v_pk_fma_f32 v[38:39], v[38:39], v[204:205], v[206:207]
	v_lshlrev_b32_e32 v204, 16, v156
	v_and_b32_e32 v205, 0xffff0000, v156
	v_lshlrev_b32_e32 v206, 16, v160
	v_and_b32_e32 v207, 0xffff0000, v160
	v_pk_fma_f32 v[32:33], v[32:33], v[204:205], v[206:207]
	v_lshlrev_b32_e32 v204, 16, v157
	v_and_b32_e32 v205, 0xffff0000, v157
	v_lshlrev_b32_e32 v206, 16, v161
	v_and_b32_e32 v207, 0xffff0000, v161
	v_pk_fma_f32 v[34:35], v[34:35], v[204:205], v[206:207]
	v_cvt_pk_bf16_f32 v36, v36, v37
	v_cvt_pk_bf16_f32 v37, v38, v39
	v_cvt_pk_bf16_f32 v38, v32, v33
	v_cvt_pk_bf16_f32 v39, v34, v35
	global_store_dwordx4 v212, v[36:39], s[6:7] offset:256
	s_waitcnt vmcnt(18)
	v_lshlrev_b32_e32 v204, 16, v162
	v_and_b32_e32 v205, 0xffff0000, v162
	v_lshlrev_b32_e32 v206, 16, v166
	v_and_b32_e32 v207, 0xffff0000, v166
	v_pk_fma_f32 v[28:29], v[28:29], v[204:205], v[206:207]
	v_lshlrev_b32_e32 v204, 16, v163
	v_and_b32_e32 v205, 0xffff0000, v163
	v_lshlrev_b32_e32 v206, 16, v167
	v_and_b32_e32 v207, 0xffff0000, v167
	v_pk_fma_f32 v[30:31], v[30:31], v[204:205], v[206:207]
	v_lshlrev_b32_e32 v204, 16, v164
	v_and_b32_e32 v205, 0xffff0000, v164
	v_lshlrev_b32_e32 v206, 16, v168
	v_and_b32_e32 v207, 0xffff0000, v168
	v_pk_fma_f32 v[24:25], v[24:25], v[204:205], v[206:207]
	v_lshlrev_b32_e32 v204, 16, v165
	v_and_b32_e32 v205, 0xffff0000, v165
	v_lshlrev_b32_e32 v206, 16, v169
	v_and_b32_e32 v207, 0xffff0000, v169
	v_pk_fma_f32 v[26:27], v[26:27], v[204:205], v[206:207]
	v_cvt_pk_bf16_f32 v28, v28, v29
	v_cvt_pk_bf16_f32 v29, v30, v31
	v_cvt_pk_bf16_f32 v30, v24, v25
	v_cvt_pk_bf16_f32 v31, v26, v27
	v_add_u32_e32 v212, 0xa0000, v209
	global_store_dwordx4 v212, v[28:31], s[6:7]
	s_waitcnt vmcnt(17)
	v_lshlrev_b32_e32 v204, 16, v170
	v_and_b32_e32 v205, 0xffff0000, v170
	v_lshlrev_b32_e32 v206, 16, v174
	v_and_b32_e32 v207, 0xffff0000, v174
	v_pk_fma_f32 v[20:21], v[20:21], v[204:205], v[206:207]
	v_lshlrev_b32_e32 v204, 16, v171
	v_and_b32_e32 v205, 0xffff0000, v171
	v_lshlrev_b32_e32 v206, 16, v175
	v_and_b32_e32 v207, 0xffff0000, v175
	v_pk_fma_f32 v[22:23], v[22:23], v[204:205], v[206:207]
	v_lshlrev_b32_e32 v204, 16, v172
	v_and_b32_e32 v205, 0xffff0000, v172
	v_lshlrev_b32_e32 v206, 16, v176
	v_and_b32_e32 v207, 0xffff0000, v176
	v_pk_fma_f32 v[16:17], v[16:17], v[204:205], v[206:207]
	v_lshlrev_b32_e32 v204, 16, v173
	v_and_b32_e32 v205, 0xffff0000, v173
	v_lshlrev_b32_e32 v206, 16, v177
	v_and_b32_e32 v207, 0xffff0000, v177
	v_pk_fma_f32 v[18:19], v[18:19], v[204:205], v[206:207]
	v_cvt_pk_bf16_f32 v20, v20, v21
	v_cvt_pk_bf16_f32 v21, v22, v23
	v_cvt_pk_bf16_f32 v22, v16, v17
	v_cvt_pk_bf16_f32 v23, v18, v19
	global_store_dwordx4 v212, v[20:23], s[6:7] offset:256
	s_waitcnt vmcnt(16)
	v_lshlrev_b32_e32 v204, 16, v178
	v_and_b32_e32 v205, 0xffff0000, v178
	v_lshlrev_b32_e32 v206, 16, v182
	v_and_b32_e32 v207, 0xffff0000, v182
	v_pk_fma_f32 v[12:13], v[12:13], v[204:205], v[206:207]
	v_lshlrev_b32_e32 v204, 16, v179
	v_and_b32_e32 v205, 0xffff0000, v179
	v_lshlrev_b32_e32 v206, 16, v183
	v_and_b32_e32 v207, 0xffff0000, v183
	v_pk_fma_f32 v[14:15], v[14:15], v[204:205], v[206:207]
	v_lshlrev_b32_e32 v204, 16, v180
	v_and_b32_e32 v205, 0xffff0000, v180
	v_lshlrev_b32_e32 v206, 16, v184
	v_and_b32_e32 v207, 0xffff0000, v184
	v_pk_fma_f32 v[8:9], v[8:9], v[204:205], v[206:207]
	v_lshlrev_b32_e32 v204, 16, v181
	v_and_b32_e32 v205, 0xffff0000, v181
	v_lshlrev_b32_e32 v206, 16, v185
	v_and_b32_e32 v207, 0xffff0000, v185
	v_pk_fma_f32 v[10:11], v[10:11], v[204:205], v[206:207]
	v_cvt_pk_bf16_f32 v12, v12, v13
	v_cvt_pk_bf16_f32 v13, v14, v15
	v_cvt_pk_bf16_f32 v14, v8, v9
	v_cvt_pk_bf16_f32 v15, v10, v11
	v_add_u32_e32 v212, 0xb0000, v209
	global_store_dwordx4 v212, v[12:15], s[6:7]
	s_waitcnt vmcnt(15)
	v_lshlrev_b32_e32 v204, 16, v186
	v_and_b32_e32 v205, 0xffff0000, v186
	v_lshlrev_b32_e32 v206, 16, v190
	v_and_b32_e32 v207, 0xffff0000, v190
	v_pk_fma_f32 v[4:5], v[4:5], v[204:205], v[206:207]
	v_lshlrev_b32_e32 v204, 16, v187
	v_and_b32_e32 v205, 0xffff0000, v187
	v_lshlrev_b32_e32 v206, 16, v191
	v_and_b32_e32 v207, 0xffff0000, v191
	v_pk_fma_f32 v[6:7], v[6:7], v[204:205], v[206:207]
	v_lshlrev_b32_e32 v204, 16, v188
	v_and_b32_e32 v205, 0xffff0000, v188
	v_lshlrev_b32_e32 v206, 16, v192
	v_and_b32_e32 v207, 0xffff0000, v192
	v_pk_fma_f32 v[0:1], v[0:1], v[204:205], v[206:207]
	v_lshlrev_b32_e32 v204, 16, v189
	v_and_b32_e32 v205, 0xffff0000, v189
	v_lshlrev_b32_e32 v206, 16, v193
	v_and_b32_e32 v207, 0xffff0000, v193
	v_pk_fma_f32 v[2:3], v[2:3], v[204:205], v[206:207]
	v_cvt_pk_bf16_f32 v4, v4, v5
	v_cvt_pk_bf16_f32 v5, v6, v7
	v_cvt_pk_bf16_f32 v6, v0, v1
	v_cvt_pk_bf16_f32 v7, v2, v3
	global_store_dwordx4 v212, v[4:7], s[6:7] offset:256
	s_and_b64 vcc, exec, s[2:3]
	s_mov_b32 s45, s12
	s_mov_b64 s[20:21], s[16:17]
	s_mov_b64 s[18:19], s[14:15]
	s_mov_b32 s1, s44
	s_cbranch_vccz .LBB0_994
	s_waitcnt vmcnt(0)
	s_cmpk_gt_u32 s27, 0xff
	s_cbranch_scc1 .LBB0_1007
	s_barrier

; #define PG8_STAGE(bufoff, gbase, voff) do { _Pragma("unroll") for (int _i = 0; _i < 2; ++_i) \
;     __builtin_amdgcn_global_load_lds((const unsigned*)((const char*)(gbase) + (voff)[_i]), (LAS unsigned*)(lds + (bufoff) + ldsw + _i * 8192), 16, 0, 0); } while (0)
; #define PG8_LDA(dst, b, h) do { _Pragma("unroll") for (int m = 0; m < 4; ++m) _Pragma("unroll") for (int k = 0; k < 2; ++k) dst[m][k] = *(const LAS bf16x8*)(lds + PG8_SA(b, h) + aoff + m * 2048 + k * 1024); } while (0)
; #define PG8_LDB(dst, b, h) do { _Pragma("unroll") for (int n = 0; n < 2; ++n) _Pragma("unroll") for (int k = 0; k < 2; ++k) dst[n][k] = *(const LAS bf16x8*)(lds + PG8_SB(b, h) + boff + n * 2048 + k * 1024); } while (0)
; #define PG8_MMA(ai, bj, At, Bt) do { __builtin_amdgcn_s_setprio(1); _Pragma("unroll") for (int m = 0; m < 4; ++m) _Pragma("unroll") for (int n = 0; n < 2; ++n) _Pragma("unroll") for (int k = 0; k < 2; ++k) \
;     acc[ai][bj][m][n] = __builtin_amdgcn_mfma_f32_16x16x32_bf16(Bt[n][k], At[m][k], acc[ai][bj][m][n], 0, 0, 0); __builtin_amdgcn_s_setprio(0); } while (0)
; #define PG8_WAIT_L(n) asm volatile("s_waitcnt lgkmcnt(" #n ")" ::: "memory")
; #define PG8_BAR __builtin_amdgcn_s_barrier()
; #define PG8_SCHED __builtin_amdgcn_sched_barrier(0)
; template <class Epi>
; __device__ __forceinline__ void gemm_phase(LAS unsigned char* lds, const Gemm g, const StaticOrder& S, const Epi& E, int wv0) {
;     ...
;     for (int t = 0; t < nt; t += 2) {
;       const bool last = (t == nt - 2);
;       const char* a1 = cA + (size_t)(t + 1) * kstep;
;       const char* a2 = last ? nA : cA + (size_t)(t + 2) * kstep; const char* b2 = last ? nB : cB + (size_t)(t + 2) * kstep;
;       const char* a3 = a2 + kstep; const char* b3 = b2 + kstep;
;       PG8_LDB(B0, 0, 0); PG8_SCHED; PG8_LDA(At, 0, 0); PG8_STAGE(PG8_SA(1, 1), a1 + hstepA, voffA);
;       PG8_WAIT_L(8); PG8_BAR; PG8_WAIT_L(0); PG8_MMA(0, 0, At, B0); PG8_BAR; PG8_SCHED;
;       PG8_LDB(B1, 0, 1); PG8_STAGE(PG8_SB(0, 0), b2, voffB);
;       PG8_BAR; PG8_WAIT_L(0); PG8_MMA(0, 1, At, B1); PG8_BAR;
;       PG8_LDA(At, 0, 1); PG8_STAGE(PG8_SA(0, 0), a2, voffA);
;       PG8_BAR; PG8_WAIT_L(0); PG8_MMA(1, 0, At, B0); PG8_BAR; PG8_SCHED;
.LBB0_1025:
	s_add_u32 s4, s20, 0x100
	s_addc_u32 s5, s21, 0
	s_add_i32 s0, 0, 0x10000
	v_add_u32_e32 v142, s0, v211
	ds_read_b128 v[130:133], v142
	ds_read_b128 v[134:137], v142 offset:1024
	ds_read_b128 v[138:141], v142 offset:2048
	ds_read_b128 v[142:145], v142 offset:3072
	s_cmp_eq_u32 s51, 12
	s_cselect_b32 s25, s17, s5
	s_cselect_b32 s24, s16, s4
	s_cselect_b32 s23, s15, s50
	s_cselect_b32 s22, s48, s49
	v_lshl_add_u64 v[178:179], s[20:21], 0, v[192:193]
	s_add_i32 m0, s38, 0xc000
	ds_read_b128 v[146:149], v213
	ds_read_b128 v[150:153], v213 offset:1024
	ds_read_b128 v[154:157], v213 offset:2048
	ds_read_b128 v[158:161], v213 offset:3072
	ds_read_b128 v[162:165], v213 offset:4096
	ds_read_b128 v[166:169], v213 offset:5120
	ds_read_b128 v[170:173], v213 offset:6144
	ds_read_b128 v[174:177], v213 offset:7168
	global_load_lds_dwordx4 v[178:179], off
	v_lshl_add_u64 v[178:179], s[20:21], 0, v[194:195]
	s_add_i32 m0, s38, 0xe000
	s_nop 0
	global_load_lds_dwordx4 v[178:179], off
	s_waitcnt lgkmcnt(8)
	s_barrier
	s_waitcnt lgkmcnt(0)
	s_waitcnt lgkmcnt(0)
	v_mfma_f32_16x16x32_bf16 v[126:129], v[130:133], v[146:149], v[126:129]
	v_mfma_f32_16x16x32_bf16 v[122:125], v[138:141], v[146:149], v[122:125]
	v_mfma_f32_16x16x32_bf16 v[110:113], v[130:133], v[154:157], v[110:113]
	v_mfma_f32_16x16x32_bf16 v[106:109], v[138:141], v[154:157], v[106:109]
	v_mfma_f32_16x16x32_bf16 v[92:95], v[130:133], v[162:165], v[92:95]
	v_mfma_f32_16x16x32_bf16 v[88:91], v[138:141], v[162:165], v[88:91]
	v_mfma_f32_16x16x32_bf16 v[76:79], v[130:133], v[170:173], v[76:79]
	v_mfma_f32_16x16x32_bf16 v[72:75], v[138:141], v[170:173], v[72:75]
	v_mfma_f32_16x16x32_bf16 v[126:129], v[134:137], v[150:153], v[126:129]
	v_mfma_f32_16x16x32_bf16 v[122:125], v[142:145], v[150:153], v[122:125]
	v_mfma_f32_16x16x32_bf16 v[110:113], v[134:137], v[158:161], v[110:113]
	v_mfma_f32_16x16x32_bf16 v[106:109], v[142:145], v[158:161], v[106:109]
	v_mfma_f32_16x16x32_bf16 v[92:95], v[134:137], v[166:169], v[92:95]
	v_mfma_f32_16x16x32_bf16 v[88:91], v[142:145], v[166:169], v[88:91]
	v_mfma_f32_16x16x32_bf16 v[76:79], v[134:137], v[174:177], v[76:79]
	v_mfma_f32_16x16x32_bf16 v[72:75], v[142:145], v[174:177], v[72:75]
	s_barrier
	s_add_i32 s52, 0, 0x14000
	s_add_i32 s0, s0, s37
	v_add_u32_e32 v200, s52, v211
	v_lshl_add_u64 v[204:205], s[22:23], 0, v[96:97]
	s_mov_b32 m0, s0
	ds_read_b128 v[178:181], v200
	ds_read_b128 v[182:185], v200 offset:1024
	ds_read_b128 v[196:199], v200 offset:2048
	ds_read_b128 v[200:203], v200 offset:3072
	global_load_lds_dwordx4 v[204:205], off
	v_lshl_add_u64 v[206:207], s[22:23], 0, v[190:191]
	s_add_i32 m0, s0, 0x2000
	s_nop 0
	global_load_lds_dwordx4 v[206:207], off
	s_barrier
	s_waitcnt lgkmcnt(0)
	s_waitcnt lgkmcnt(0)
	v_mfma_f32_16x16x32_bf16 v[118:121], v[178:181], v[146:149], v[118:121]
	v_mfma_f32_16x16x32_bf16 v[114:117], v[196:199], v[146:149], v[114:117]
	v_mfma_f32_16x16x32_bf16 v[102:105], v[178:181], v[154:157], v[102:105]
	v_mfma_f32_16x16x32_bf16 v[98:101], v[196:199], v[154:157], v[98:101]
	v_mfma_f32_16x16x32_bf16 v[84:87], v[178:181], v[162:165], v[84:87]
	v_mfma_f32_16x16x32_bf16 v[80:83], v[196:199], v[162:165], v[80:83]
	v_mfma_f32_16x16x32_bf16 v[68:71], v[178:181], v[170:173], v[68:71]
	v_mfma_f32_16x16x32_bf16 v[64:67], v[196:199], v[170:173], v[64:67]
	v_mfma_f32_16x16x32_bf16 v[118:121], v[182:185], v[150:153], v[118:121]
	v_mfma_f32_16x16x32_bf16 v[114:117], v[200:203], v[150:153], v[114:117]
	v_mfma_f32_16x16x32_bf16 v[102:105], v[182:185], v[158:161], v[102:105]
	v_mfma_f32_16x16x32_bf16 v[98:101], v[200:203], v[158:161], v[98:101]
	v_mfma_f32_16x16x32_bf16 v[84:87], v[182:185], v[166:169], v[84:87]
	v_mfma_f32_16x16x32_bf16 v[80:83], v[200:203], v[166:169], v[80:83]
	v_mfma_f32_16x16x32_bf16 v[68:71], v[182:185], v[174:177], v[68:71]
	v_mfma_f32_16x16x32_bf16 v[64:67], v[200:203], v[174:177], v[64:67]
	s_mov_b32 m0, s38
	v_lshl_add_u64 v[208:209], s[24:25], 0, v[186:187]
	s_barrier
	ds_read_b128 v[146:149], v213 offset:16384
	ds_read_b128 v[150:153], v213 offset:17408
	ds_read_b128 v[154:157], v213 offset:18432
	ds_read_b128 v[158:161], v213 offset:19456
	ds_read_b128 v[162:165], v213 offset:20480
	ds_read_b128 v[166:169], v213 offset:21504
	ds_read_b128 v[170:173], v213 offset:22528
	ds_read_b128 v[174:177], v213 offset:23552
	global_load_lds_dwordx4 v[208:209], off
	v_lshl_add_u64 v[214:215], s[24:25], 0, v[188:189]
	s_mov_b32 m0, s39
	s_nop 0
	global_load_lds_dwordx4 v[214:215], off
	s_barrier
	s_waitcnt lgkmcnt(0)
	s_waitcnt lgkmcnt(0)
	v_mfma_f32_16x16x32_bf16 v[60:63], v[130:133], v[146:149], v[60:63]
	v_mfma_f32_16x16x32_bf16 v[56:59], v[138:141], v[146:149], v[56:59]
	v_mfma_f32_16x16x32_bf16 v[44:47], v[130:133], v[154:157], v[44:47]
	v_mfma_f32_16x16x32_bf16 v[40:43], v[138:141], v[154:157], v[40:43]
	v_mfma_f32_16x16x32_bf16 v[28:31], v[130:133], v[162:165], v[28:31]
	v_mfma_f32_16x16x32_bf16 v[24:27], v[138:141], v[162:165], v[24:27]
	v_mfma_f32_16x16x32_bf16 v[12:15], v[130:133], v[170:173], v[12:15]
	v_mfma_f32_16x16x32_bf16 v[8:11], v[138:141], v[170:173], v[8:11]
	v_mfma_f32_16x16x32_bf16 v[60:63], v[134:137], v[150:153], v[60:63]
	v_mfma_f32_16x16x32_bf16 v[56:59], v[142:145], v[150:153], v[56:59]
	v_mfma_f32_16x16x32_bf16 v[44:47], v[134:137], v[158:161], v[44:47]
	v_mfma_f32_16x16x32_bf16 v[40:43], v[142:145], v[158:161], v[40:43]
	v_mfma_f32_16x16x32_bf16 v[28:31], v[134:137], v[166:169], v[28:31]
	v_mfma_f32_16x16x32_bf16 v[24:27], v[142:145], v[166:169], v[24:27]
	v_mfma_f32_16x16x32_bf16 v[12:15], v[134:137], v[174:177], v[12:15]
	v_mfma_f32_16x16x32_bf16 v[8:11], v[142:145], v[174:177], v[8:11]
	s_barrier
; #define PG8_STAGE(bufoff, gbase, voff) do { _Pragma("unroll") for (int _i = 0; _i < 2; ++_i) \
;     __builtin_amdgcn_global_load_lds((const unsigned*)((const char*)(gbase) + (voff)[_i]), (LAS unsigned*)(lds + (bufoff) + ldsw + _i * 8192), 16, 0, 0); } while (0)
; #define PG8_LDA(dst, b, h) do { _Pragma("unroll") for (int m = 0; m < 4; ++m) _Pragma("unroll") for (int k = 0; k < 2; ++k) dst[m][k] = *(const LAS bf16x8*)(lds + PG8_SA(b, h) + aoff + m * 2048 + k * 1024); } while (0)
; #define PG8_LDB(dst, b, h) do { _Pragma("unroll") for (int n = 0; n < 2; ++n) _Pragma("unroll") for (int k = 0; k < 2; ++k) dst[n][k] = *(const LAS bf16x8*)(lds + PG8_SB(b, h) + boff + n * 2048 + k * 1024); } while (0)
; #define PG8_MMA(ai, bj, At, Bt) do { __builtin_amdgcn_s_setprio(1); _Pragma("unroll") for (int m = 0; m < 4; ++m) _Pragma("unroll") for (int n = 0; n < 2; ++n) _Pragma("unroll") for (int k = 0; k < 2; ++k) \
;     acc[ai][bj][m][n] = __builtin_amdgcn_mfma_f32_16x16x32_bf16(Bt[n][k], At[m][k], acc[ai][bj][m][n], 0, 0, 0); __builtin_amdgcn_s_setprio(0); } while (0)
; #define PG8_WAIT_V(n) asm volatile("s_waitcnt vmcnt(" #n ")" ::: "memory")
; #define PG8_WAIT_L(n) asm volatile("s_waitcnt lgkmcnt(" #n ")" ::: "memory")
; #define PG8_BAR __builtin_amdgcn_s_barrier()
; #define PG8_SCHED __builtin_amdgcn_sched_barrier(0)
; template <class Epi>
; __device__ __forceinline__ void gemm_phase(LAS unsigned char* lds, const Gemm g, const StaticOrder& S, const Epi& E, int wv0) {
;     ...
;       PG8_STAGE(PG8_SB(0, 1), b2 + hstepB, voffB);
;       PG8_WAIT_V(6); PG8_BAR; PG8_MMA(1, 1, At, B1); PG8_BAR;
;       PG8_LDB(B0, 1, 0); PG8_SCHED; PG8_LDA(At, 1, 0); PG8_STAGE(PG8_SA(0, 1), a2 + hstepA, voffA);
;       PG8_WAIT_L(8); PG8_BAR; PG8_WAIT_L(0); PG8_MMA(0, 0, At, B0); PG8_BAR; PG8_SCHED;
;       PG8_LDB(B1, 1, 1); PG8_STAGE(PG8_SB(1, 0), b3, voffB);
;       PG8_BAR; PG8_WAIT_L(0); PG8_MMA(0, 1, At, B1); PG8_BAR;
;       PG8_LDA(At, 1, 1); PG8_STAGE(PG8_SA(1, 0), a3, voffA);
;       PG8_BAR; PG8_WAIT_L(0); PG8_MMA(1, 0, At, B0); PG8_BAR; PG8_SCHED;
	s_add_u32 s20, s22, 0x40000
	s_addc_u32 s21, s23, 0
	s_add_i32 s0, s52, s37
	v_lshl_add_u64 v[130:131], s[20:21], 0, v[96:97]
	s_mov_b32 m0, s0
	s_nop 0
	global_load_lds_dwordx4 v[130:131], off
	v_lshl_add_u64 v[130:131], s[20:21], 0, v[190:191]
	s_add_i32 m0, s0, 0x2000
	s_nop 0
	global_load_lds_dwordx4 v[130:131], off
	s_waitcnt vmcnt(6)
	s_barrier
	v_mfma_f32_16x16x32_bf16 v[52:55], v[178:181], v[146:149], v[52:55]
	v_mfma_f32_16x16x32_bf16 v[48:51], v[196:199], v[146:149], v[48:51]
	v_mfma_f32_16x16x32_bf16 v[36:39], v[178:181], v[154:157], v[36:39]
	v_mfma_f32_16x16x32_bf16 v[32:35], v[196:199], v[154:157], v[32:35]
	v_mfma_f32_16x16x32_bf16 v[20:23], v[178:181], v[162:165], v[20:23]
	v_mfma_f32_16x16x32_bf16 v[16:19], v[196:199], v[162:165], v[16:19]
	v_mfma_f32_16x16x32_bf16 v[4:7], v[178:181], v[170:173], v[4:7]
	v_mfma_f32_16x16x32_bf16 v[0:3], v[196:199], v[170:173], v[0:3]
	v_mfma_f32_16x16x32_bf16 v[52:55], v[182:185], v[150:153], v[52:55]
	v_mfma_f32_16x16x32_bf16 v[48:51], v[200:203], v[150:153], v[48:51]
	v_mfma_f32_16x16x32_bf16 v[36:39], v[182:185], v[158:161], v[36:39]
	v_mfma_f32_16x16x32_bf16 v[32:35], v[200:203], v[158:161], v[32:35]
	v_mfma_f32_16x16x32_bf16 v[20:23], v[182:185], v[166:169], v[20:23]
	v_mfma_f32_16x16x32_bf16 v[16:19], v[200:203], v[166:169], v[16:19]
	v_mfma_f32_16x16x32_bf16 v[4:7], v[182:185], v[174:177], v[4:7]
	v_mfma_f32_16x16x32_bf16 v[0:3], v[200:203], v[174:177], v[0:3]
	s_add_i32 s0, 0, 0x18000
	v_add_u32_e32 v142, s0, v211
	s_barrier
	ds_read_b128 v[130:133], v142
	ds_read_b128 v[134:137], v142 offset:1024
	ds_read_b128 v[138:141], v142 offset:2048
	ds_read_b128 v[142:145], v142 offset:3072
	s_add_u32 s20, s24, 0x114000
	s_addc_u32 s21, s25, 0
	s_mov_b32 m0, s40
	v_lshl_add_u64 v[178:179], s[20:21], 0, v[186:187]
	ds_read_b128 v[146:149], v213 offset:32768
	ds_read_b128 v[150:153], v213 offset:33792
	ds_read_b128 v[154:157], v213 offset:34816
	ds_read_b128 v[158:161], v213 offset:35840
	ds_read_b128 v[162:165], v213 offset:36864
	ds_read_b128 v[166:169], v213 offset:37888
	ds_read_b128 v[170:173], v213 offset:38912
	ds_read_b128 v[174:177], v213 offset:39936
	global_load_lds_dwordx4 v[178:179], off
	v_lshl_add_u64 v[178:179], s[20:21], 0, v[188:189]
	s_mov_b32 m0, s41
	s_nop 0
	global_load_lds_dwordx4 v[178:179], off
	s_waitcnt lgkmcnt(8)
	s_barrier
	s_waitcnt lgkmcnt(0)
	s_waitcnt lgkmcnt(0)
	v_mfma_f32_16x16x32_bf16 v[126:129], v[130:133], v[146:149], v[126:129]
	v_mfma_f32_16x16x32_bf16 v[122:125], v[138:141], v[146:149], v[122:125]
	v_mfma_f32_16x16x32_bf16 v[110:113], v[130:133], v[154:157], v[110:113]
	v_mfma_f32_16x16x32_bf16 v[106:109], v[138:141], v[154:157], v[106:109]
	v_mfma_f32_16x16x32_bf16 v[92:95], v[130:133], v[162:165], v[92:95]
	v_mfma_f32_16x16x32_bf16 v[88:91], v[138:141], v[162:165], v[88:91]
	v_mfma_f32_16x16x32_bf16 v[76:79], v[130:133], v[170:173], v[76:79]
	v_mfma_f32_16x16x32_bf16 v[72:75], v[138:141], v[170:173], v[72:75]
	v_mfma_f32_16x16x32_bf16 v[126:129], v[134:137], v[150:153], v[126:129]
	v_mfma_f32_16x16x32_bf16 v[122:125], v[142:145], v[150:153], v[122:125]
	v_mfma_f32_16x16x32_bf16 v[110:113], v[134:137], v[158:161], v[110:113]
	v_mfma_f32_16x16x32_bf16 v[106:109], v[142:145], v[158:161], v[106:109]
	v_mfma_f32_16x16x32_bf16 v[92:95], v[134:137], v[166:169], v[92:95]
	v_mfma_f32_16x16x32_bf16 v[88:91], v[142:145], v[166:169], v[88:91]
	v_mfma_f32_16x16x32_bf16 v[76:79], v[134:137], v[174:177], v[76:79]
	v_mfma_f32_16x16x32_bf16 v[72:75], v[142:145], v[174:177], v[72:75]
	s_barrier
	s_add_i32 s24, 0, 0x1c000
	s_add_i32 s0, s0, s37
	v_add_u32_e32 v200, s24, v211
	v_lshl_add_u64 v[204:205], v[204:205], 0, s[72:73]
	s_mov_b32 m0, s0
	ds_read_b128 v[178:181], v200
	ds_read_b128 v[182:185], v200 offset:1024
	ds_read_b128 v[196:199], v200 offset:2048
	ds_read_b128 v[200:203], v200 offset:3072
	global_load_lds_dwordx4 v[204:205], off
	v_lshl_add_u64 v[204:205], v[206:207], 0, s[72:73]
	s_add_i32 m0, s0, 0x2000
	s_nop 0
	global_load_lds_dwordx4 v[204:205], off
	s_barrier
	s_waitcnt lgkmcnt(0)
	s_waitcnt lgkmcnt(0)
	v_mfma_f32_16x16x32_bf16 v[118:121], v[178:181], v[146:149], v[118:121]
	v_mfma_f32_16x16x32_bf16 v[114:117], v[196:199], v[146:149], v[114:117]
	v_mfma_f32_16x16x32_bf16 v[102:105], v[178:181], v[154:157], v[102:105]
	v_mfma_f32_16x16x32_bf16 v[98:101], v[196:199], v[154:157], v[98:101]
	v_mfma_f32_16x16x32_bf16 v[84:87], v[178:181], v[162:165], v[84:87]
	v_mfma_f32_16x16x32_bf16 v[80:83], v[196:199], v[162:165], v[80:83]
	v_mfma_f32_16x16x32_bf16 v[68:71], v[178:181], v[170:173], v[68:71]
	v_mfma_f32_16x16x32_bf16 v[64:67], v[196:199], v[170:173], v[64:67]
	v_mfma_f32_16x16x32_bf16 v[118:121], v[182:185], v[150:153], v[118:121]
	v_mfma_f32_16x16x32_bf16 v[114:117], v[200:203], v[150:153], v[114:117]
	v_mfma_f32_16x16x32_bf16 v[102:105], v[182:185], v[158:161], v[102:105]
	v_mfma_f32_16x16x32_bf16 v[98:101], v[200:203], v[158:161], v[98:101]
	v_mfma_f32_16x16x32_bf16 v[84:87], v[182:185], v[166:169], v[84:87]
	v_mfma_f32_16x16x32_bf16 v[80:83], v[200:203], v[166:169], v[80:83]
	v_mfma_f32_16x16x32_bf16 v[68:71], v[182:185], v[174:177], v[68:71]
	v_mfma_f32_16x16x32_bf16 v[64:67], v[200:203], v[174:177], v[64:67]
	s_mov_b32 m0, s42
	v_lshl_add_u64 v[204:205], v[208:209], 0, s[72:73]
	s_barrier
	ds_read_b128 v[146:149], v213 offset:49152
	ds_read_b128 v[150:153], v213 offset:50176
	ds_read_b128 v[154:157], v213 offset:51200
	ds_read_b128 v[158:161], v213 offset:52224
	ds_read_b128 v[162:165], v213 offset:53248
	ds_read_b128 v[166:169], v213 offset:54272
	ds_read_b128 v[170:173], v213 offset:55296
	ds_read_b128 v[174:177], v213 offset:56320
	global_load_lds_dwordx4 v[204:205], off
	v_lshl_add_u64 v[204:205], v[214:215], 0, s[72:73]
	s_mov_b32 m0, s43
	s_nop 0
	global_load_lds_dwordx4 v[204:205], off
	s_barrier
; __device__ __forceinline__ float bf_lo(unsigned u) { return __uint_as_float(u << 16); }
; __device__ __forceinline__ float bf_hi(unsigned u) { return __uint_as_float(u & 0xffff0000u); }
; #define PG8_STAGE(bufoff, gbase, voff) do { _Pragma("unroll") for (int _i = 0; _i < 2; ++_i) \
;     __builtin_amdgcn_global_load_lds((const unsigned*)((const char*)(gbase) + (voff)[_i]), (LAS unsigned*)(lds + (bufoff) + ldsw + _i * 8192), 16, 0, 0); } while (0)
; #define PG8_MMA(ai, bj, At, Bt) do { __builtin_amdgcn_s_setprio(1); _Pragma("unroll") for (int m = 0; m < 4; ++m) _Pragma("unroll") for (int n = 0; n < 2; ++n) _Pragma("unroll") for (int k = 0; k < 2; ++k) \
;     acc[ai][bj][m][n] = __builtin_amdgcn_mfma_f32_16x16x32_bf16(Bt[n][k], At[m][k], acc[ai][bj][m][n], 0, 0, 0); __builtin_amdgcn_s_setprio(0); } while (0)
; #define PG8_WAIT_V(n) asm volatile("s_waitcnt vmcnt(" #n ")" ::: "memory")
; #define PG8_WAIT_L(n) asm volatile("s_waitcnt lgkmcnt(" #n ")" ::: "memory")
; #define PG8_BAR __builtin_amdgcn_s_barrier()
; #define PG8_SCHED __builtin_amdgcn_sched_barrier(0)
; template <class Epi>
; __device__ __forceinline__ void gemm_phase(LAS unsigned char* lds, const Gemm g, const StaticOrder& S, const Epi& E, int wv0) {
;     ...
;       PG8_BAR; PG8_WAIT_L(0); PG8_MMA(1, 0, At, B0); PG8_BAR; PG8_SCHED;
;       PG8_STAGE(PG8_SB(1, 1), b3 + hstepB, voffB);
;       PG8_WAIT_V(6); PG8_BAR; PG8_MMA(1, 1, At, B1); PG8_BAR;
;     }
;   __device__ __forceinline__ void emit(const EpiPre& q0, int row, int col, f32x4 a, f32x4 b, const f32x4 (&hb)[2][2], const float (&hs)[2][4], int ai_, int m_, int bj_) const {
;     ...
;     } else if (MODE == E_PROJ) {
;       const int br = e.aux; const u32x4 gw = q.u0;
;       v[0] *= bf_lo(gw.x); v[1] *= bf_hi(gw.x); v[2] *= bf_lo(gw.y); v[3] *= bf_hi(gw.y);
;       v[4] *= bf_lo(gw.z); v[5] *= bf_hi(gw.z); v[6] *= bf_lo(gw.w); v[7] *= bf_hi(gw.w);
;       bf16_t* fa = (bf16_t*)e.facc + (size_t)row * DM + col;
;       if (br > 0) { const u32x4 pw = q.u1;
;         v[0] += bf_lo(pw.x); v[1] += bf_hi(pw.x); v[2] += bf_lo(pw.y); v[3] += bf_hi(pw.y); v[4] += bf_lo(pw.z); v[5] += bf_hi(pw.z); v[6] += bf_lo(pw.w); v[7] += bf_hi(pw.w); }
;       if (br == 2) store8bf((bf16_t*)e.out + (size_t)row * DM + col, v);
;       else store8bf(fa, v);
	s_waitcnt lgkmcnt(0)
	s_waitcnt lgkmcnt(0)
	v_mfma_f32_16x16x32_bf16 v[60:63], v[130:133], v[146:149], v[60:63]
	v_mfma_f32_16x16x32_bf16 v[56:59], v[138:141], v[146:149], v[56:59]
	v_mfma_f32_16x16x32_bf16 v[44:47], v[130:133], v[154:157], v[44:47]
	v_mfma_f32_16x16x32_bf16 v[40:43], v[138:141], v[154:157], v[40:43]
	v_mfma_f32_16x16x32_bf16 v[28:31], v[130:133], v[162:165], v[28:31]
	v_mfma_f32_16x16x32_bf16 v[24:27], v[138:141], v[162:165], v[24:27]
	v_mfma_f32_16x16x32_bf16 v[12:15], v[130:133], v[170:173], v[12:15]
	v_mfma_f32_16x16x32_bf16 v[8:11], v[138:141], v[170:173], v[8:11]
	v_mfma_f32_16x16x32_bf16 v[60:63], v[134:137], v[150:153], v[60:63]
	v_mfma_f32_16x16x32_bf16 v[56:59], v[142:145], v[150:153], v[56:59]
	v_mfma_f32_16x16x32_bf16 v[44:47], v[134:137], v[158:161], v[44:47]
	v_mfma_f32_16x16x32_bf16 v[40:43], v[142:145], v[158:161], v[40:43]
	v_mfma_f32_16x16x32_bf16 v[28:31], v[134:137], v[166:169], v[28:31]
	v_mfma_f32_16x16x32_bf16 v[24:27], v[142:145], v[166:169], v[24:27]
	v_mfma_f32_16x16x32_bf16 v[12:15], v[134:137], v[174:177], v[12:15]
	v_mfma_f32_16x16x32_bf16 v[8:11], v[142:145], v[174:177], v[8:11]
	s_barrier
	s_add_u32 s20, s22, 0x40080
	s_addc_u32 s21, s23, 0
	s_add_i32 s0, s24, s37
	v_lshl_add_u64 v[130:131], s[20:21], 0, v[96:97]
	s_mov_b32 m0, s0
	s_nop 0
	global_load_lds_dwordx4 v[130:131], off
	v_lshl_add_u64 v[130:131], s[20:21], 0, v[190:191]
	s_add_i32 m0, s0, 0x2000
	s_nop 0
	global_load_lds_dwordx4 v[130:131], off
	s_waitcnt vmcnt(6)
	s_barrier
	v_mfma_f32_16x16x32_bf16 v[52:55], v[178:181], v[146:149], v[52:55]
	v_mfma_f32_16x16x32_bf16 v[48:51], v[196:199], v[146:149], v[48:51]
	v_mfma_f32_16x16x32_bf16 v[36:39], v[178:181], v[154:157], v[36:39]
	v_mfma_f32_16x16x32_bf16 v[32:35], v[196:199], v[154:157], v[32:35]
	v_mfma_f32_16x16x32_bf16 v[20:23], v[178:181], v[162:165], v[20:23]
	v_mfma_f32_16x16x32_bf16 v[16:19], v[196:199], v[162:165], v[16:19]
	v_mfma_f32_16x16x32_bf16 v[4:7], v[178:181], v[170:173], v[4:7]
	v_mfma_f32_16x16x32_bf16 v[0:3], v[196:199], v[170:173], v[0:3]
	v_mfma_f32_16x16x32_bf16 v[52:55], v[182:185], v[150:153], v[52:55]
	v_mfma_f32_16x16x32_bf16 v[48:51], v[200:203], v[150:153], v[48:51]
	v_mfma_f32_16x16x32_bf16 v[36:39], v[182:185], v[158:161], v[36:39]
	v_mfma_f32_16x16x32_bf16 v[32:35], v[200:203], v[158:161], v[32:35]
	v_mfma_f32_16x16x32_bf16 v[20:23], v[182:185], v[166:169], v[20:23]
	v_mfma_f32_16x16x32_bf16 v[16:19], v[200:203], v[166:169], v[16:19]
	v_mfma_f32_16x16x32_bf16 v[4:7], v[182:185], v[174:177], v[4:7]
	v_mfma_f32_16x16x32_bf16 v[0:3], v[200:203], v[174:177], v[0:3]
	s_add_i32 s51, s51, 2
	s_add_u32 s49, s49, 0x100
	s_addc_u32 s50, s50, 0
	s_cmp_gt_u32 s51, 13
	s_mov_b64 s[20:21], s[4:5]
	s_barrier
	s_cbranch_scc0 .LBB0_1025
	s_setprio 0
	v_lshl_add_u32 v209, s1, 8, v210
	v_lshl_or_b32 v214, s47, 8, v212
	v_mul_u32_u24_e32 v208, 0x3000, v209
	v_lshlrev_b32_e32 v209, 12, v209
	v_lshl_add_u32 v208, v214, 1, v208
	v_lshl_add_u32 v209, v214, 1, v209
	v_add_u32_e32 v214, 0x0, v208
	global_load_dwordx4 v[130:133], v214, s[8:9]
	v_add_u32_e32 v215, 0x0, v209
	global_load_dwordx4 v[134:137], v215, s[6:7]
	global_load_dwordx4 v[138:141], v214, s[8:9] offset:256
	global_load_dwordx4 v[142:145], v215, s[6:7] offset:256
	v_add_u32_e32 v214, 0x30000, v208
	global_load_dwordx4 v[146:149], v214, s[8:9]
	v_add_u32_e32 v215, 0x10000, v209
	global_load_dwordx4 v[150:153], v215, s[6:7]
	global_load_dwordx4 v[154:157], v214, s[8:9] offset:256
	global_load_dwordx4 v[158:161], v215, s[6:7] offset:256
	v_add_u32_e32 v214, 0x60000, v208
	global_load_dwordx4 v[162:165], v214, s[8:9]
	v_add_u32_e32 v215, 0x20000, v209
	global_load_dwordx4 v[166:169], v215, s[6:7]
	global_load_dwordx4 v[170:173], v214, s[8:9] offset:256
	global_load_dwordx4 v[174:177], v215, s[6:7] offset:256
	v_add_u32_e32 v214, 0x90000, v208
	global_load_dwordx4 v[178:181], v214, s[8:9]
	v_add_u32_e32 v215, 0x30000, v209
	global_load_dwordx4 v[182:185], v215, s[6:7]
	global_load_dwordx4 v[196:199], v214, s[8:9] offset:256
	global_load_dwordx4 v[200:203], v215, s[6:7] offset:256
	s_waitcnt vmcnt(14)
	v_lshlrev_b32_e32 v204, 16, v130
	v_and_b32_e32 v205, 0xffff0000, v130
	v_lshlrev_b32_e32 v206, 16, v134
	v_and_b32_e32 v207, 0xffff0000, v134
	v_pk_fma_f32 v[126:127], v[126:127], v[204:205], v[206:207]
	v_lshlrev_b32_e32 v204, 16, v131
	v_and_b32_e32 v205, 0xffff0000, v131
	v_lshlrev_b32_e32 v206, 16, v135
	v_and_b32_e32 v207, 0xffff0000, v135
	v_pk_fma_f32 v[128:129], v[128:129], v[204:205], v[206:207]
	v_lshlrev_b32_e32 v204, 16, v132
	v_and_b32_e32 v205, 0xffff0000, v132
	v_lshlrev_b32_e32 v206, 16, v136
	v_and_b32_e32 v207, 0xffff0000, v136
	v_pk_fma_f32 v[122:123], v[122:123], v[204:205], v[206:207]
	v_lshlrev_b32_e32 v204, 16, v133
	v_and_b32_e32 v205, 0xffff0000, v133
	v_lshlrev_b32_e32 v206, 16, v137
	v_and_b32_e32 v207, 0xffff0000, v137
	v_pk_fma_f32 v[124:125], v[124:125], v[204:205], v[206:207]
	v_cvt_pk_bf16_f32 v126, v126, v127
	v_cvt_pk_bf16_f32 v127, v128, v129
	v_cvt_pk_bf16_f32 v128, v122, v123
	v_cvt_pk_bf16_f32 v129, v124, v125
	v_add_u32_e32 v214, 0x180000, v208
	global_load_dwordx4 v[130:133], v214, s[8:9]
	v_add_u32_e32 v215, 0x80000, v209
	global_load_dwordx4 v[134:137], v215, s[6:7]
	s_waitcnt vmcnt(14)
; __device__ __forceinline__ float bf_lo(unsigned u) { return __uint_as_float(u << 16); }
; __device__ __forceinline__ float bf_hi(unsigned u) { return __uint_as_float(u & 0xffff0000u); }
;   __device__ __forceinline__ void emit(const EpiPre& q0, int row, int col, f32x4 a, f32x4 b, const f32x4 (&hb)[2][2], const float (&hs)[2][4], int ai_, int m_, int bj_) const {
;     ...
;     } else if (MODE == E_PROJ) {
;       const int br = e.aux; const u32x4 gw = q.u0;
;       v[0] *= bf_lo(gw.x); v[1] *= bf_hi(gw.x); v[2] *= bf_lo(gw.y); v[3] *= bf_hi(gw.y);
;       v[4] *= bf_lo(gw.z); v[5] *= bf_hi(gw.z); v[6] *= bf_lo(gw.w); v[7] *= bf_hi(gw.w);
;       bf16_t* fa = (bf16_t*)e.facc + (size_t)row * DM + col;
;       if (br > 0) { const u32x4 pw = q.u1;
;         v[0] += bf_lo(pw.x); v[1] += bf_hi(pw.x); v[2] += bf_lo(pw.y); v[3] += bf_hi(pw.y); v[4] += bf_lo(pw.z); v[5] += bf_hi(pw.z); v[6] += bf_lo(pw.w); v[7] += bf_hi(pw.w); }
;       if (br == 2) store8bf((bf16_t*)e.out + (size_t)row * DM + col, v);
;       else store8bf(fa, v);
;   __device__ __forceinline__ void operator()(const f32x4 (&acc)[2][2][4][2], const pg8::Unit& u, int wr, int wc, int fr, int fq) const {
;     ...
;     for (int gi = 0; gi < 4; ++gi) {
;       const int ai = gi >> 1, mp = gi & 1;
;       if (gi + 1 < 4) { const int ai2 = (gi + 1) >> 1, mp2 = (gi + 1) & 1;
; #pragma unroll
;         for (int i = 0; i < 4; ++i) preload(q[(gi + 1) & 1][i], row0 + ai2 * 128 + (2 * mp2 + (i >> 1)) * 16, col0 + (i & 1) * 128); }
;       asm volatile("" ::: "memory");
; #pragma unroll
;       for (int i = 0; i < 4; ++i) { const int m = 2 * mp + (i >> 1), bj = i & 1; emit(q[gi & 1][i], row0 + ai * 128 + m * 16, col0 + bj * 128, acc[ai][bj][m][0], acc[ai][bj][m][1], hb, hs, ai, m, bj); }
;       asm volatile("" ::: "memory");
;     }
	v_lshlrev_b32_e32 v204, 16, v138
	v_and_b32_e32 v205, 0xffff0000, v138
	v_lshlrev_b32_e32 v206, 16, v142
	v_and_b32_e32 v207, 0xffff0000, v142
	v_pk_fma_f32 v[118:119], v[118:119], v[204:205], v[206:207]
	v_lshlrev_b32_e32 v204, 16, v139
	v_and_b32_e32 v205, 0xffff0000, v139
	v_lshlrev_b32_e32 v206, 16, v143
	v_and_b32_e32 v207, 0xffff0000, v143
	v_pk_fma_f32 v[120:121], v[120:121], v[204:205], v[206:207]
	v_lshlrev_b32_e32 v204, 16, v140
	v_and_b32_e32 v205, 0xffff0000, v140
	v_lshlrev_b32_e32 v206, 16, v144
	v_and_b32_e32 v207, 0xffff0000, v144
	v_pk_fma_f32 v[114:115], v[114:115], v[204:205], v[206:207]
	v_lshlrev_b32_e32 v204, 16, v141
	v_and_b32_e32 v205, 0xffff0000, v141
	v_lshlrev_b32_e32 v206, 16, v145
	v_and_b32_e32 v207, 0xffff0000, v145
	v_pk_fma_f32 v[116:117], v[116:117], v[204:205], v[206:207]
	v_cvt_pk_bf16_f32 v118, v118, v119
	v_cvt_pk_bf16_f32 v119, v120, v121
	v_cvt_pk_bf16_f32 v120, v114, v115
	v_cvt_pk_bf16_f32 v121, v116, v117
	global_load_dwordx4 v[138:141], v214, s[8:9] offset:256
	global_load_dwordx4 v[142:145], v215, s[6:7] offset:256
	s_waitcnt vmcnt(14)
	v_lshlrev_b32_e32 v204, 16, v146
	v_and_b32_e32 v205, 0xffff0000, v146
	v_lshlrev_b32_e32 v206, 16, v150
	v_and_b32_e32 v207, 0xffff0000, v150
	v_pk_fma_f32 v[110:111], v[110:111], v[204:205], v[206:207]
	v_lshlrev_b32_e32 v204, 16, v147
	v_and_b32_e32 v205, 0xffff0000, v147
	v_lshlrev_b32_e32 v206, 16, v151
	v_and_b32_e32 v207, 0xffff0000, v151
	v_pk_fma_f32 v[112:113], v[112:113], v[204:205], v[206:207]
	v_lshlrev_b32_e32 v204, 16, v148
	v_and_b32_e32 v205, 0xffff0000, v148
	v_lshlrev_b32_e32 v206, 16, v152
	v_and_b32_e32 v207, 0xffff0000, v152
	v_pk_fma_f32 v[106:107], v[106:107], v[204:205], v[206:207]
	v_lshlrev_b32_e32 v204, 16, v149
	v_and_b32_e32 v205, 0xffff0000, v149
	v_lshlrev_b32_e32 v206, 16, v153
	v_and_b32_e32 v207, 0xffff0000, v153
	v_pk_fma_f32 v[108:109], v[108:109], v[204:205], v[206:207]
	v_cvt_pk_bf16_f32 v110, v110, v111
	v_cvt_pk_bf16_f32 v111, v112, v113
	v_cvt_pk_bf16_f32 v112, v106, v107
	v_cvt_pk_bf16_f32 v113, v108, v109
	v_add_u32_e32 v214, 0x1b0000, v208
	global_load_dwordx4 v[146:149], v214, s[8:9]
	v_add_u32_e32 v215, 0x90000, v209
	global_load_dwordx4 v[150:153], v215, s[6:7]
	s_waitcnt vmcnt(14)
	v_lshlrev_b32_e32 v204, 16, v154
	v_and_b32_e32 v205, 0xffff0000, v154
	v_lshlrev_b32_e32 v206, 16, v158
	v_and_b32_e32 v207, 0xffff0000, v158
	v_pk_fma_f32 v[102:103], v[102:103], v[204:205], v[206:207]
	v_lshlrev_b32_e32 v204, 16, v155
	v_and_b32_e32 v205, 0xffff0000, v155
	v_lshlrev_b32_e32 v206, 16, v159
	v_and_b32_e32 v207, 0xffff0000, v159
	v_pk_fma_f32 v[104:105], v[104:105], v[204:205], v[206:207]
	v_lshlrev_b32_e32 v204, 16, v156
	v_and_b32_e32 v205, 0xffff0000, v156
	v_lshlrev_b32_e32 v206, 16, v160
	v_and_b32_e32 v207, 0xffff0000, v160
	v_pk_fma_f32 v[98:99], v[98:99], v[204:205], v[206:207]
	v_lshlrev_b32_e32 v204, 16, v157
	v_and_b32_e32 v205, 0xffff0000, v157
	v_lshlrev_b32_e32 v206, 16, v161
	v_and_b32_e32 v207, 0xffff0000, v161
	v_pk_fma_f32 v[100:101], v[100:101], v[204:205], v[206:207]
	v_cvt_pk_bf16_f32 v102, v102, v103
	v_cvt_pk_bf16_f32 v103, v104, v105
	v_cvt_pk_bf16_f32 v104, v98, v99
	v_cvt_pk_bf16_f32 v105, v100, v101
	global_load_dwordx4 v[154:157], v214, s[8:9] offset:256
	global_load_dwordx4 v[158:161], v215, s[6:7] offset:256
	s_waitcnt vmcnt(14)
	v_lshlrev_b32_e32 v204, 16, v162
	v_and_b32_e32 v205, 0xffff0000, v162
	v_lshlrev_b32_e32 v206, 16, v166
	v_and_b32_e32 v207, 0xffff0000, v166
	v_pk_fma_f32 v[92:93], v[92:93], v[204:205], v[206:207]
	v_lshlrev_b32_e32 v204, 16, v163
	v_and_b32_e32 v205, 0xffff0000, v163
	v_lshlrev_b32_e32 v206, 16, v167
	v_and_b32_e32 v207, 0xffff0000, v167
	v_pk_fma_f32 v[94:95], v[94:95], v[204:205], v[206:207]
	v_lshlrev_b32_e32 v204, 16, v164
	v_and_b32_e32 v205, 0xffff0000, v164
	v_lshlrev_b32_e32 v206, 16, v168
	v_and_b32_e32 v207, 0xffff0000, v168
	v_pk_fma_f32 v[88:89], v[88:89], v[204:205], v[206:207]
	v_lshlrev_b32_e32 v204, 16, v165
	v_and_b32_e32 v205, 0xffff0000, v165
	v_lshlrev_b32_e32 v206, 16, v169
	v_and_b32_e32 v207, 0xffff0000, v169
	v_pk_fma_f32 v[90:91], v[90:91], v[204:205], v[206:207]
	v_cvt_pk_bf16_f32 v92, v92, v93
	v_cvt_pk_bf16_f32 v93, v94, v95
	v_cvt_pk_bf16_f32 v94, v88, v89
	v_cvt_pk_bf16_f32 v95, v90, v91
	v_add_u32_e32 v214, 0x1e0000, v208
	global_load_dwordx4 v[162:165], v214, s[8:9]
	v_add_u32_e32 v215, 0xa0000, v209
	global_load_dwordx4 v[166:169], v215, s[6:7]
	s_waitcnt vmcnt(14)
	v_lshlrev_b32_e32 v204, 16, v170
	v_and_b32_e32 v205, 0xffff0000, v170
	v_lshlrev_b32_e32 v206, 16, v174
	v_and_b32_e32 v207, 0xffff0000, v174
	v_pk_fma_f32 v[84:85], v[84:85], v[204:205], v[206:207]
	v_lshlrev_b32_e32 v204, 16, v171
	v_and_b32_e32 v205, 0xffff0000, v171
	v_lshlrev_b32_e32 v206, 16, v175
	v_and_b32_e32 v207, 0xffff0000, v175
	v_pk_fma_f32 v[86:87], v[86:87], v[204:205], v[206:207]
	v_lshlrev_b32_e32 v204, 16, v172
	v_and_b32_e32 v205, 0xffff0000, v172
	v_lshlrev_b32_e32 v206, 16, v176
	v_and_b32_e32 v207, 0xffff0000, v176
	v_pk_fma_f32 v[80:81], v[80:81], v[204:205], v[206:207]
	v_lshlrev_b32_e32 v204, 16, v173
	v_and_b32_e32 v205, 0xffff0000, v173
	v_lshlrev_b32_e32 v206, 16, v177
	v_and_b32_e32 v207, 0xffff0000, v177
	v_pk_fma_f32 v[82:83], v[82:83], v[204:205], v[206:207]
	v_cvt_pk_bf16_f32 v84, v84, v85
	v_cvt_pk_bf16_f32 v85, v86, v87
	v_cvt_pk_bf16_f32 v86, v80, v81
	v_cvt_pk_bf16_f32 v87, v82, v83
	global_load_dwordx4 v[170:173], v214, s[8:9] offset:256
	global_load_dwordx4 v[174:177], v215, s[6:7] offset:256
	s_waitcnt vmcnt(14)
; __device__ __forceinline__ float bf_lo(unsigned u) { return __uint_as_float(u << 16); }
; __device__ __forceinline__ float bf_hi(unsigned u) { return __uint_as_float(u & 0xffff0000u); }
;   __device__ __forceinline__ void emit(const EpiPre& q0, int row, int col, f32x4 a, f32x4 b, const f32x4 (&hb)[2][2], const float (&hs)[2][4], int ai_, int m_, int bj_) const {
;     ...
;     } else if (MODE == E_PROJ) {
;       const int br = e.aux; const u32x4 gw = q.u0;
;       v[0] *= bf_lo(gw.x); v[1] *= bf_hi(gw.x); v[2] *= bf_lo(gw.y); v[3] *= bf_hi(gw.y);
;       v[4] *= bf_lo(gw.z); v[5] *= bf_hi(gw.z); v[6] *= bf_lo(gw.w); v[7] *= bf_hi(gw.w);
;       bf16_t* fa = (bf16_t*)e.facc + (size_t)row * DM + col;
;       if (br > 0) { const u32x4 pw = q.u1;
;         v[0] += bf_lo(pw.x); v[1] += bf_hi(pw.x); v[2] += bf_lo(pw.y); v[3] += bf_hi(pw.y); v[4] += bf_lo(pw.z); v[5] += bf_hi(pw.z); v[6] += bf_lo(pw.w); v[7] += bf_hi(pw.w); }
;       if (br == 2) store8bf((bf16_t*)e.out + (size_t)row * DM + col, v);
;       else store8bf(fa, v);
;   __device__ __forceinline__ void operator()(const f32x4 (&acc)[2][2][4][2], const pg8::Unit& u, int wr, int wc, int fr, int fq) const {
;     ...
;     for (int gi = 0; gi < 4; ++gi) {
;       const int ai = gi >> 1, mp = gi & 1;
;       if (gi + 1 < 4) { const int ai2 = (gi + 1) >> 1, mp2 = (gi + 1) & 1;
; #pragma unroll
;         for (int i = 0; i < 4; ++i) preload(q[(gi + 1) & 1][i], row0 + ai2 * 128 + (2 * mp2 + (i >> 1)) * 16, col0 + (i & 1) * 128); }
;       asm volatile("" ::: "memory");
; #pragma unroll
;       for (int i = 0; i < 4; ++i) { const int m = 2 * mp + (i >> 1), bj = i & 1; emit(q[gi & 1][i], row0 + ai * 128 + m * 16, col0 + bj * 128, acc[ai][bj][m][0], acc[ai][bj][m][1], hb, hs, ai, m, bj); }
;       asm volatile("" ::: "memory");
;     }
	v_lshlrev_b32_e32 v204, 16, v178
	v_and_b32_e32 v205, 0xffff0000, v178
	v_lshlrev_b32_e32 v206, 16, v182
	v_and_b32_e32 v207, 0xffff0000, v182
	v_pk_fma_f32 v[76:77], v[76:77], v[204:205], v[206:207]
	v_lshlrev_b32_e32 v204, 16, v179
	v_and_b32_e32 v205, 0xffff0000, v179
	v_lshlrev_b32_e32 v206, 16, v183
	v_and_b32_e32 v207, 0xffff0000, v183
	v_pk_fma_f32 v[78:79], v[78:79], v[204:205], v[206:207]
	v_lshlrev_b32_e32 v204, 16, v180
	v_and_b32_e32 v205, 0xffff0000, v180
	v_lshlrev_b32_e32 v206, 16, v184
	v_and_b32_e32 v207, 0xffff0000, v184
	v_pk_fma_f32 v[72:73], v[72:73], v[204:205], v[206:207]
	v_lshlrev_b32_e32 v204, 16, v181
	v_and_b32_e32 v205, 0xffff0000, v181
	v_lshlrev_b32_e32 v206, 16, v185
	v_and_b32_e32 v207, 0xffff0000, v185
	v_pk_fma_f32 v[74:75], v[74:75], v[204:205], v[206:207]
	v_cvt_pk_bf16_f32 v76, v76, v77
	v_cvt_pk_bf16_f32 v77, v78, v79
	v_cvt_pk_bf16_f32 v78, v72, v73
	v_cvt_pk_bf16_f32 v79, v74, v75
	v_add_u32_e32 v214, 0x210000, v208
	global_load_dwordx4 v[178:181], v214, s[8:9]
	v_add_u32_e32 v215, 0xb0000, v209
	global_load_dwordx4 v[182:185], v215, s[6:7]
	s_waitcnt vmcnt(14)
	v_lshlrev_b32_e32 v204, 16, v196
	v_and_b32_e32 v205, 0xffff0000, v196
	v_lshlrev_b32_e32 v206, 16, v200
	v_and_b32_e32 v207, 0xffff0000, v200
	v_pk_fma_f32 v[68:69], v[68:69], v[204:205], v[206:207]
	v_lshlrev_b32_e32 v204, 16, v197
	v_and_b32_e32 v205, 0xffff0000, v197
	v_lshlrev_b32_e32 v206, 16, v201
	v_and_b32_e32 v207, 0xffff0000, v201
	v_pk_fma_f32 v[70:71], v[70:71], v[204:205], v[206:207]
	v_lshlrev_b32_e32 v204, 16, v198
	v_and_b32_e32 v205, 0xffff0000, v198
	v_lshlrev_b32_e32 v206, 16, v202
	v_and_b32_e32 v207, 0xffff0000, v202
	v_pk_fma_f32 v[64:65], v[64:65], v[204:205], v[206:207]
	v_lshlrev_b32_e32 v204, 16, v199
	v_and_b32_e32 v205, 0xffff0000, v199
	v_lshlrev_b32_e32 v206, 16, v203
	v_and_b32_e32 v207, 0xffff0000, v203
	v_pk_fma_f32 v[66:67], v[66:67], v[204:205], v[206:207]
	v_cvt_pk_bf16_f32 v68, v68, v69
	v_cvt_pk_bf16_f32 v69, v70, v71
	v_cvt_pk_bf16_f32 v70, v64, v65
	v_cvt_pk_bf16_f32 v71, v66, v67
	global_load_dwordx4 v[196:199], v214, s[8:9] offset:256
	global_load_dwordx4 v[200:203], v215, s[6:7] offset:256
	v_add_u32_e32 v215, 0x0, v209
	global_store_dwordx4 v215, v[126:129], s[12:13]
	global_store_dwordx4 v215, v[118:121], s[12:13] offset:256
	v_add_u32_e32 v215, 0x10000, v209
	global_store_dwordx4 v215, v[110:113], s[12:13]
	global_store_dwordx4 v215, v[102:105], s[12:13] offset:256
	v_add_u32_e32 v215, 0x20000, v209
	global_store_dwordx4 v215, v[92:95], s[12:13]
	global_store_dwordx4 v215, v[84:87], s[12:13] offset:256
	v_add_u32_e32 v215, 0x30000, v209
	global_store_dwordx4 v215, v[76:79], s[12:13]
	global_store_dwordx4 v215, v[68:71], s[12:13] offset:256
	s_waitcnt vmcnt(22)
	v_lshlrev_b32_e32 v204, 16, v130
	v_and_b32_e32 v205, 0xffff0000, v130
	v_lshlrev_b32_e32 v206, 16, v134
	v_and_b32_e32 v207, 0xffff0000, v134
	v_pk_fma_f32 v[60:61], v[60:61], v[204:205], v[206:207]
	v_lshlrev_b32_e32 v204, 16, v131
	v_and_b32_e32 v205, 0xffff0000, v131
	v_lshlrev_b32_e32 v206, 16, v135
	v_and_b32_e32 v207, 0xffff0000, v135
	v_pk_fma_f32 v[62:63], v[62:63], v[204:205], v[206:207]
	v_lshlrev_b32_e32 v204, 16, v132
	v_and_b32_e32 v205, 0xffff0000, v132
	v_lshlrev_b32_e32 v206, 16, v136
	v_and_b32_e32 v207, 0xffff0000, v136
	v_pk_fma_f32 v[56:57], v[56:57], v[204:205], v[206:207]
	v_lshlrev_b32_e32 v204, 16, v133
	v_and_b32_e32 v205, 0xffff0000, v133
	v_lshlrev_b32_e32 v206, 16, v137
	v_and_b32_e32 v207, 0xffff0000, v137
	v_pk_fma_f32 v[58:59], v[58:59], v[204:205], v[206:207]
	v_cvt_pk_bf16_f32 v60, v60, v61
	v_cvt_pk_bf16_f32 v61, v62, v63
	v_cvt_pk_bf16_f32 v62, v56, v57
	v_cvt_pk_bf16_f32 v63, v58, v59
	v_add_u32_e32 v215, 0x80000, v209
	global_store_dwordx4 v215, v[60:63], s[12:13]
	s_waitcnt vmcnt(21)
	v_lshlrev_b32_e32 v204, 16, v138
	v_and_b32_e32 v205, 0xffff0000, v138
	v_lshlrev_b32_e32 v206, 16, v142
	v_and_b32_e32 v207, 0xffff0000, v142
	v_pk_fma_f32 v[52:53], v[52:53], v[204:205], v[206:207]
	v_lshlrev_b32_e32 v204, 16, v139
	v_and_b32_e32 v205, 0xffff0000, v139
	v_lshlrev_b32_e32 v206, 16, v143
	v_and_b32_e32 v207, 0xffff0000, v143
	v_pk_fma_f32 v[54:55], v[54:55], v[204:205], v[206:207]
	v_lshlrev_b32_e32 v204, 16, v140
	v_and_b32_e32 v205, 0xffff0000, v140
	v_lshlrev_b32_e32 v206, 16, v144
	v_and_b32_e32 v207, 0xffff0000, v144
	v_pk_fma_f32 v[48:49], v[48:49], v[204:205], v[206:207]
	v_lshlrev_b32_e32 v204, 16, v141
	v_and_b32_e32 v205, 0xffff0000, v141
	v_lshlrev_b32_e32 v206, 16, v145
	v_and_b32_e32 v207, 0xffff0000, v145
	v_pk_fma_f32 v[50:51], v[50:51], v[204:205], v[206:207]
	v_cvt_pk_bf16_f32 v52, v52, v53
	v_cvt_pk_bf16_f32 v53, v54, v55
	v_cvt_pk_bf16_f32 v54, v48, v49
	v_cvt_pk_bf16_f32 v55, v50, v51
	global_store_dwordx4 v215, v[52:55], s[12:13] offset:256
	s_waitcnt vmcnt(20)
	v_lshlrev_b32_e32 v204, 16, v146
	v_and_b32_e32 v205, 0xffff0000, v146
	v_lshlrev_b32_e32 v206, 16, v150
	v_and_b32_e32 v207, 0xffff0000, v150
	v_pk_fma_f32 v[44:45], v[44:45], v[204:205], v[206:207]
	v_lshlrev_b32_e32 v204, 16, v147
	v_and_b32_e32 v205, 0xffff0000, v147
	v_lshlrev_b32_e32 v206, 16, v151
	v_and_b32_e32 v207, 0xffff0000, v151
	v_pk_fma_f32 v[46:47], v[46:47], v[204:205], v[206:207]
	v_lshlrev_b32_e32 v204, 16, v148
	v_and_b32_e32 v205, 0xffff0000, v148
	v_lshlrev_b32_e32 v206, 16, v152
	v_and_b32_e32 v207, 0xffff0000, v152
	v_pk_fma_f32 v[40:41], v[40:41], v[204:205], v[206:207]
	v_lshlrev_b32_e32 v204, 16, v149
	v_and_b32_e32 v205, 0xffff0000, v149
	v_lshlrev_b32_e32 v206, 16, v153
	v_and_b32_e32 v207, 0xffff0000, v153
	v_pk_fma_f32 v[42:43], v[42:43], v[204:205], v[206:207]
	v_cvt_pk_bf16_f32 v44, v44, v45
	v_cvt_pk_bf16_f32 v45, v46, v47
	v_cvt_pk_bf16_f32 v46, v40, v41
	v_cvt_pk_bf16_f32 v47, v42, v43
	v_add_u32_e32 v215, 0x90000, v209
	global_store_dwordx4 v215, v[44:47], s[12:13]
	s_waitcnt vmcnt(19)
; __device__ __forceinline__ float bf_lo(unsigned u) { return __uint_as_float(u << 16); }
; __device__ __forceinline__ float bf_hi(unsigned u) { return __uint_as_float(u & 0xffff0000u); }
; #define PG8_WAIT_V(n) asm volatile("s_waitcnt vmcnt(" #n ")" ::: "memory")
; #define PG8_BAR __builtin_amdgcn_s_barrier()
; template <class Epi>
; __device__ __forceinline__ void gemm_phase(LAS unsigned char* lds, const Gemm g, const StaticOrder& S, const Epi& E, int wv0) {
;     ...
;     E(acc, cur, wr, wc, fr, fq);
;     if (!has_next) break;
; #pragma unroll
;     for (int a = 0; a < 2; ++a)
; #pragma unroll
;       for (int b = 0; b < 2; ++b)
; #pragma unroll
;         for (int m = 0; m < 4; ++m)
; #pragma unroll
;           for (int n = 0; n < 2; ++n) acc[a][b][m][n] = (f32x4){0.f, 0.f, 0.f, 0.f};
;     cur = nxt; cA = nA; cB = nB; ++ui;
;   }
;   PG8_WAIT_V(0);
;   if (wr == 0) PG8_BAR;
;   PG8_BAR;
;   __device__ __forceinline__ void emit(const EpiPre& q0, int row, int col, f32x4 a, f32x4 b, const f32x4 (&hb)[2][2], const float (&hs)[2][4], int ai_, int m_, int bj_) const {
;     ...
;     } else if (MODE == E_PROJ) {
;       const int br = e.aux; const u32x4 gw = q.u0;
;       v[0] *= bf_lo(gw.x); v[1] *= bf_hi(gw.x); v[2] *= bf_lo(gw.y); v[3] *= bf_hi(gw.y);
;       v[4] *= bf_lo(gw.z); v[5] *= bf_hi(gw.z); v[6] *= bf_lo(gw.w); v[7] *= bf_hi(gw.w);
;       bf16_t* fa = (bf16_t*)e.facc + (size_t)row * DM + col;
;       if (br > 0) { const u32x4 pw = q.u1;
;         v[0] += bf_lo(pw.x); v[1] += bf_hi(pw.x); v[2] += bf_lo(pw.y); v[3] += bf_hi(pw.y); v[4] += bf_lo(pw.z); v[5] += bf_hi(pw.z); v[6] += bf_lo(pw.w); v[7] += bf_hi(pw.w); }
;       if (br == 2) store8bf((bf16_t*)e.out + (size_t)row * DM + col, v);
;       else store8bf(fa, v);
	v_lshlrev_b32_e32 v204, 16, v154
	v_and_b32_e32 v205, 0xffff0000, v154
	v_lshlrev_b32_e32 v206, 16, v158
	v_and_b32_e32 v207, 0xffff0000, v158
	v_pk_fma_f32 v[36:37], v[36:37], v[204:205], v[206:207]
	v_lshlrev_b32_e32 v204, 16, v155
	v_and_b32_e32 v205, 0xffff0000, v155
	v_lshlrev_b32_e32 v206, 16, v159
	v_and_b32_e32 v207, 0xffff0000, v159
	v_pk_fma_f32 v[38:39], v[38:39], v[204:205], v[206:207]
	v_lshlrev_b32_e32 v204, 16, v156
	v_and_b32_e32 v205, 0xffff0000, v156
	v_lshlrev_b32_e32 v206, 16, v160
	v_and_b32_e32 v207, 0xffff0000, v160
	v_pk_fma_f32 v[32:33], v[32:33], v[204:205], v[206:207]
	v_lshlrev_b32_e32 v204, 16, v157
	v_and_b32_e32 v205, 0xffff0000, v157
	v_lshlrev_b32_e32 v206, 16, v161
	v_and_b32_e32 v207, 0xffff0000, v161
	v_pk_fma_f32 v[34:35], v[34:35], v[204:205], v[206:207]
	v_cvt_pk_bf16_f32 v36, v36, v37
	v_cvt_pk_bf16_f32 v37, v38, v39
	v_cvt_pk_bf16_f32 v38, v32, v33
	v_cvt_pk_bf16_f32 v39, v34, v35
	global_store_dwordx4 v215, v[36:39], s[12:13] offset:256
	s_waitcnt vmcnt(18)
	v_lshlrev_b32_e32 v204, 16, v162
	v_and_b32_e32 v205, 0xffff0000, v162
	v_lshlrev_b32_e32 v206, 16, v166
	v_and_b32_e32 v207, 0xffff0000, v166
	v_pk_fma_f32 v[28:29], v[28:29], v[204:205], v[206:207]
	v_lshlrev_b32_e32 v204, 16, v163
	v_and_b32_e32 v205, 0xffff0000, v163
	v_lshlrev_b32_e32 v206, 16, v167
	v_and_b32_e32 v207, 0xffff0000, v167
	v_pk_fma_f32 v[30:31], v[30:31], v[204:205], v[206:207]
	v_lshlrev_b32_e32 v204, 16, v164
	v_and_b32_e32 v205, 0xffff0000, v164
	v_lshlrev_b32_e32 v206, 16, v168
	v_and_b32_e32 v207, 0xffff0000, v168
	v_pk_fma_f32 v[24:25], v[24:25], v[204:205], v[206:207]
	v_lshlrev_b32_e32 v204, 16, v165
	v_and_b32_e32 v205, 0xffff0000, v165
	v_lshlrev_b32_e32 v206, 16, v169
	v_and_b32_e32 v207, 0xffff0000, v169
	v_pk_fma_f32 v[26:27], v[26:27], v[204:205], v[206:207]
	v_cvt_pk_bf16_f32 v28, v28, v29
	v_cvt_pk_bf16_f32 v29, v30, v31
	v_cvt_pk_bf16_f32 v30, v24, v25
	v_cvt_pk_bf16_f32 v31, v26, v27
	v_add_u32_e32 v215, 0xa0000, v209
	global_store_dwordx4 v215, v[28:31], s[12:13]
	s_waitcnt vmcnt(17)
	v_lshlrev_b32_e32 v204, 16, v170
	v_and_b32_e32 v205, 0xffff0000, v170
	v_lshlrev_b32_e32 v206, 16, v174
	v_and_b32_e32 v207, 0xffff0000, v174
	v_pk_fma_f32 v[20:21], v[20:21], v[204:205], v[206:207]
	v_lshlrev_b32_e32 v204, 16, v171
	v_and_b32_e32 v205, 0xffff0000, v171
	v_lshlrev_b32_e32 v206, 16, v175
	v_and_b32_e32 v207, 0xffff0000, v175
	v_pk_fma_f32 v[22:23], v[22:23], v[204:205], v[206:207]
	v_lshlrev_b32_e32 v204, 16, v172
	v_and_b32_e32 v205, 0xffff0000, v172
	v_lshlrev_b32_e32 v206, 16, v176
	v_and_b32_e32 v207, 0xffff0000, v176
	v_pk_fma_f32 v[16:17], v[16:17], v[204:205], v[206:207]
	v_lshlrev_b32_e32 v204, 16, v173
	v_and_b32_e32 v205, 0xffff0000, v173
	v_lshlrev_b32_e32 v206, 16, v177
	v_and_b32_e32 v207, 0xffff0000, v177
	v_pk_fma_f32 v[18:19], v[18:19], v[204:205], v[206:207]
	v_cvt_pk_bf16_f32 v20, v20, v21
	v_cvt_pk_bf16_f32 v21, v22, v23
	v_cvt_pk_bf16_f32 v22, v16, v17
	v_cvt_pk_bf16_f32 v23, v18, v19
	global_store_dwordx4 v215, v[20:23], s[12:13] offset:256
	s_waitcnt vmcnt(16)
	v_lshlrev_b32_e32 v204, 16, v178
	v_and_b32_e32 v205, 0xffff0000, v178
	v_lshlrev_b32_e32 v206, 16, v182
	v_and_b32_e32 v207, 0xffff0000, v182
	v_pk_fma_f32 v[12:13], v[12:13], v[204:205], v[206:207]
	v_lshlrev_b32_e32 v204, 16, v179
	v_and_b32_e32 v205, 0xffff0000, v179
	v_lshlrev_b32_e32 v206, 16, v183
	v_and_b32_e32 v207, 0xffff0000, v183
	v_pk_fma_f32 v[14:15], v[14:15], v[204:205], v[206:207]
	v_lshlrev_b32_e32 v204, 16, v180
	v_and_b32_e32 v205, 0xffff0000, v180
	v_lshlrev_b32_e32 v206, 16, v184
	v_and_b32_e32 v207, 0xffff0000, v184
	v_pk_fma_f32 v[8:9], v[8:9], v[204:205], v[206:207]
	v_lshlrev_b32_e32 v204, 16, v181
	v_and_b32_e32 v205, 0xffff0000, v181
	v_lshlrev_b32_e32 v206, 16, v185
	v_and_b32_e32 v207, 0xffff0000, v185
	v_pk_fma_f32 v[10:11], v[10:11], v[204:205], v[206:207]
	v_cvt_pk_bf16_f32 v12, v12, v13
	v_cvt_pk_bf16_f32 v13, v14, v15
	v_cvt_pk_bf16_f32 v14, v8, v9
	v_cvt_pk_bf16_f32 v15, v10, v11
	v_add_u32_e32 v215, 0xb0000, v209
	global_store_dwordx4 v215, v[12:15], s[12:13]
	s_waitcnt vmcnt(15)
	v_lshlrev_b32_e32 v204, 16, v196
	v_and_b32_e32 v205, 0xffff0000, v196
	v_lshlrev_b32_e32 v206, 16, v200
	v_and_b32_e32 v207, 0xffff0000, v200
	v_pk_fma_f32 v[4:5], v[4:5], v[204:205], v[206:207]
	v_lshlrev_b32_e32 v204, 16, v197
	v_and_b32_e32 v205, 0xffff0000, v197
	v_lshlrev_b32_e32 v206, 16, v201
	v_and_b32_e32 v207, 0xffff0000, v201
	v_pk_fma_f32 v[6:7], v[6:7], v[204:205], v[206:207]
	v_lshlrev_b32_e32 v204, 16, v198
	v_and_b32_e32 v205, 0xffff0000, v198
	v_lshlrev_b32_e32 v206, 16, v202
	v_and_b32_e32 v207, 0xffff0000, v202
	v_pk_fma_f32 v[0:1], v[0:1], v[204:205], v[206:207]
	v_lshlrev_b32_e32 v204, 16, v199
	v_and_b32_e32 v205, 0xffff0000, v199
	v_lshlrev_b32_e32 v206, 16, v203
	v_and_b32_e32 v207, 0xffff0000, v203
	v_pk_fma_f32 v[2:3], v[2:3], v[204:205], v[206:207]
	v_cvt_pk_bf16_f32 v4, v4, v5
	v_cvt_pk_bf16_f32 v5, v6, v7
	v_cvt_pk_bf16_f32 v6, v0, v1
	v_cvt_pk_bf16_f32 v7, v2, v3
	global_store_dwordx4 v215, v[4:7], s[12:13] offset:256
	s_mov_b32 s47, s14
	s_mov_b64 s[22:23], s[18:19]
	s_mov_b64 s[20:21], s[16:17]
	s_and_b64 vcc, exec, s[2:3]
	s_mov_b32 s1, s46
	s_cbranch_vccz .LBB0_1016
	s_waitcnt vmcnt(0)
	s_cmpk_gt_u32 s29, 0xff
	s_cbranch_scc1 .LBB0_1029
	s_barrier

; #define PG8_STAGE(bufoff, gbase, voff) do { _Pragma("unroll") for (int _i = 0; _i < 2; ++_i) \
;     __builtin_amdgcn_global_load_lds((const unsigned*)((const char*)(gbase) + (voff)[_i]), (LAS unsigned*)(lds + (bufoff) + ldsw + _i * 8192), 16, 0, 0); } while (0)
; #define PG8_LDA(dst, b, h) do { _Pragma("unroll") for (int m = 0; m < 4; ++m) _Pragma("unroll") for (int k = 0; k < 2; ++k) dst[m][k] = *(const LAS bf16x8*)(lds + PG8_SA(b, h) + aoff + m * 2048 + k * 1024); } while (0)
; #define PG8_LDB(dst, b, h) do { _Pragma("unroll") for (int n = 0; n < 2; ++n) _Pragma("unroll") for (int k = 0; k < 2; ++k) dst[n][k] = *(const LAS bf16x8*)(lds + PG8_SB(b, h) + boff + n * 2048 + k * 1024); } while (0)
; #define PG8_MMA(ai, bj, At, Bt) do { __builtin_amdgcn_s_setprio(1); _Pragma("unroll") for (int m = 0; m < 4; ++m) _Pragma("unroll") for (int n = 0; n < 2; ++n) _Pragma("unroll") for (int k = 0; k < 2; ++k) \
;     acc[ai][bj][m][n] = __builtin_amdgcn_mfma_f32_16x16x32_bf16(Bt[n][k], At[m][k], acc[ai][bj][m][n], 0, 0, 0); __builtin_amdgcn_s_setprio(0); } while (0)
; #define PG8_WAIT_V(n) asm volatile("s_waitcnt vmcnt(" #n ")" ::: "memory")
; #define PG8_WAIT_L(n) asm volatile("s_waitcnt lgkmcnt(" #n ")" ::: "memory")
; #define PG8_BAR __builtin_amdgcn_s_barrier()
; #define PG8_SCHED __builtin_amdgcn_sched_barrier(0)
; template <class Epi>
; __device__ __forceinline__ void gemm_phase(LAS unsigned char* lds, const Gemm g, const StaticOrder& S, const Epi& E, int wv0) {
;     ...
;       PG8_LDB(B0, 0, 0); PG8_SCHED; PG8_LDA(At, 0, 0); PG8_STAGE(PG8_SA(1, 1), a1 + hstepA, voffA);
;       PG8_WAIT_L(8); PG8_BAR; PG8_WAIT_L(0); PG8_MMA(0, 0, At, B0); PG8_BAR; PG8_SCHED;
;       PG8_LDB(B1, 0, 1); PG8_STAGE(PG8_SB(0, 0), b2, voffB);
;       PG8_BAR; PG8_WAIT_L(0); PG8_MMA(0, 1, At, B1); PG8_BAR;
;       PG8_LDA(At, 0, 1); PG8_STAGE(PG8_SA(0, 0), a2, voffA);
;       PG8_BAR; PG8_WAIT_L(0); PG8_MMA(1, 0, At, B0); PG8_BAR; PG8_SCHED;
;       PG8_STAGE(PG8_SB(0, 1), b2 + hstepB, voffB);
;       PG8_WAIT_V(6); PG8_BAR; PG8_MMA(1, 1, At, B1); PG8_BAR;
.LBB0_1100:
	s_add_u32 s0, s20, 0xfff80080
	s_addc_u32 s22, s21, -1
	s_add_i32 s50, 0, 0x10000
	v_add_u32_e32 v142, s50, v185
	ds_read_b128 v[130:133], v142
	ds_read_b128 v[134:137], v142 offset:1024
	ds_read_b128 v[138:141], v142 offset:2048
	ds_read_b128 v[142:145], v142 offset:3072
	s_cmp_eq_u32 s49, 28
	s_cselect_b32 s25, s13, s22
	s_cselect_b32 s24, s45, s0
	s_cselect_b32 s23, s11, s48
	s_cselect_b32 s22, s46, s47
	v_lshl_add_u64 v[192:193], s[20:21], 0, v[168:169]
	s_add_i32 m0, s19, 0xc000
	ds_read_b128 v[146:149], v187
	ds_read_b128 v[150:153], v187 offset:1024
	ds_read_b128 v[154:157], v187 offset:2048
	ds_read_b128 v[158:161], v187 offset:3072
	ds_read_b128 v[172:175], v187 offset:4096
	ds_read_b128 v[176:179], v187 offset:5120
	ds_read_b128 v[180:183], v187 offset:6144
	ds_read_b128 v[188:191], v187 offset:7168
	global_load_lds_dwordx4 v[192:193], off
	v_lshl_add_u64 v[192:193], s[20:21], 0, v[170:171]
	s_add_i32 m0, s19, 0xe000
	s_nop 0
	global_load_lds_dwordx4 v[192:193], off
	s_waitcnt lgkmcnt(8)
	s_barrier
	s_waitcnt lgkmcnt(0)
	s_waitcnt lgkmcnt(0)
	v_mfma_f32_16x16x32_bf16 v[126:129], v[130:133], v[146:149], v[126:129]
	v_mfma_f32_16x16x32_bf16 v[122:125], v[138:141], v[146:149], v[122:125]
	v_mfma_f32_16x16x32_bf16 v[118:121], v[130:133], v[154:157], v[118:121]
	v_mfma_f32_16x16x32_bf16 v[114:117], v[138:141], v[154:157], v[114:117]
	v_mfma_f32_16x16x32_bf16 v[92:95], v[130:133], v[172:175], v[92:95]
	v_mfma_f32_16x16x32_bf16 v[88:91], v[138:141], v[172:175], v[88:91]
	v_mfma_f32_16x16x32_bf16 v[84:87], v[130:133], v[180:183], v[84:87]
	v_mfma_f32_16x16x32_bf16 v[76:79], v[138:141], v[180:183], v[76:79]
	v_mfma_f32_16x16x32_bf16 v[126:129], v[134:137], v[150:153], v[126:129]
	v_mfma_f32_16x16x32_bf16 v[122:125], v[142:145], v[150:153], v[122:125]
	v_mfma_f32_16x16x32_bf16 v[118:121], v[134:137], v[158:161], v[118:121]
	v_mfma_f32_16x16x32_bf16 v[114:117], v[142:145], v[158:161], v[114:117]
	v_mfma_f32_16x16x32_bf16 v[92:95], v[134:137], v[176:179], v[92:95]
	v_mfma_f32_16x16x32_bf16 v[88:91], v[142:145], v[176:179], v[88:91]
	v_mfma_f32_16x16x32_bf16 v[84:87], v[134:137], v[188:191], v[84:87]
	v_mfma_f32_16x16x32_bf16 v[76:79], v[142:145], v[188:191], v[76:79]
	s_barrier
	s_add_i32 s0, 0, 0x14000
	s_add_i32 s50, s50, s31
	v_add_u32_e32 v204, s0, v185
	v_lshl_add_u64 v[208:209], s[22:23], 0, v[96:97]
	s_mov_b32 m0, s50
	ds_read_b128 v[192:195], v204
	ds_read_b128 v[196:199], v204 offset:1024
	ds_read_b128 v[200:203], v204 offset:2048
	ds_read_b128 v[204:207], v204 offset:3072
	global_load_lds_dwordx4 v[208:209], off
	v_lshl_add_u64 v[210:211], s[22:23], 0, v[166:167]
	s_add_i32 m0, s50, 0x2000
	s_nop 0
	global_load_lds_dwordx4 v[210:211], off
	s_barrier
	s_waitcnt lgkmcnt(0)
	s_waitcnt lgkmcnt(0)
	v_mfma_f32_16x16x32_bf16 v[110:113], v[192:195], v[146:149], v[110:113]
	v_mfma_f32_16x16x32_bf16 v[106:109], v[200:203], v[146:149], v[106:109]
	v_mfma_f32_16x16x32_bf16 v[102:105], v[192:195], v[154:157], v[102:105]
	v_mfma_f32_16x16x32_bf16 v[98:101], v[200:203], v[154:157], v[98:101]
	v_mfma_f32_16x16x32_bf16 v[80:83], v[192:195], v[172:175], v[80:83]
	v_mfma_f32_16x16x32_bf16 v[72:75], v[200:203], v[172:175], v[72:75]
	v_mfma_f32_16x16x32_bf16 v[68:71], v[192:195], v[180:183], v[68:71]
	v_mfma_f32_16x16x32_bf16 v[64:67], v[200:203], v[180:183], v[64:67]
	v_mfma_f32_16x16x32_bf16 v[110:113], v[196:199], v[150:153], v[110:113]
	v_mfma_f32_16x16x32_bf16 v[106:109], v[204:207], v[150:153], v[106:109]
	v_mfma_f32_16x16x32_bf16 v[102:105], v[196:199], v[158:161], v[102:105]
	v_mfma_f32_16x16x32_bf16 v[98:101], v[204:207], v[158:161], v[98:101]
	v_mfma_f32_16x16x32_bf16 v[80:83], v[196:199], v[176:179], v[80:83]
	v_mfma_f32_16x16x32_bf16 v[72:75], v[204:207], v[176:179], v[72:75]
	v_mfma_f32_16x16x32_bf16 v[68:71], v[196:199], v[188:191], v[68:71]
	v_mfma_f32_16x16x32_bf16 v[64:67], v[204:207], v[188:191], v[64:67]
	s_mov_b32 m0, s19
	v_lshl_add_u64 v[212:213], s[24:25], 0, v[162:163]
	s_barrier
	ds_read_b128 v[146:149], v187 offset:16384
	ds_read_b128 v[150:153], v187 offset:17408
	ds_read_b128 v[154:157], v187 offset:18432
	ds_read_b128 v[158:161], v187 offset:19456
	ds_read_b128 v[172:175], v187 offset:20480
	ds_read_b128 v[176:179], v187 offset:21504
	ds_read_b128 v[180:183], v187 offset:22528
	ds_read_b128 v[188:191], v187 offset:23552
	global_load_lds_dwordx4 v[212:213], off
	v_lshl_add_u64 v[214:215], s[24:25], 0, v[164:165]
	s_mov_b32 m0, s38
	s_nop 0
	global_load_lds_dwordx4 v[214:215], off
	s_barrier
	s_waitcnt lgkmcnt(0)
	s_waitcnt lgkmcnt(0)
	v_mfma_f32_16x16x32_bf16 v[60:63], v[130:133], v[146:149], v[60:63]
	v_mfma_f32_16x16x32_bf16 v[56:59], v[138:141], v[146:149], v[56:59]
	v_mfma_f32_16x16x32_bf16 v[44:47], v[130:133], v[154:157], v[44:47]
	v_mfma_f32_16x16x32_bf16 v[40:43], v[138:141], v[154:157], v[40:43]
	v_mfma_f32_16x16x32_bf16 v[28:31], v[130:133], v[172:175], v[28:31]
	v_mfma_f32_16x16x32_bf16 v[24:27], v[138:141], v[172:175], v[24:27]
	v_mfma_f32_16x16x32_bf16 v[20:23], v[130:133], v[180:183], v[20:23]
	v_mfma_f32_16x16x32_bf16 v[8:11], v[138:141], v[180:183], v[8:11]
	v_mfma_f32_16x16x32_bf16 v[60:63], v[134:137], v[150:153], v[60:63]
	v_mfma_f32_16x16x32_bf16 v[56:59], v[142:145], v[150:153], v[56:59]
	v_mfma_f32_16x16x32_bf16 v[44:47], v[134:137], v[158:161], v[44:47]
	v_mfma_f32_16x16x32_bf16 v[40:43], v[142:145], v[158:161], v[40:43]
	v_mfma_f32_16x16x32_bf16 v[28:31], v[134:137], v[176:179], v[28:31]
	v_mfma_f32_16x16x32_bf16 v[24:27], v[142:145], v[176:179], v[24:27]
	v_mfma_f32_16x16x32_bf16 v[20:23], v[134:137], v[188:191], v[20:23]
	v_mfma_f32_16x16x32_bf16 v[8:11], v[142:145], v[188:191], v[8:11]
	s_barrier
; #define PG8_STAGE(bufoff, gbase, voff) do { _Pragma("unroll") for (int _i = 0; _i < 2; ++_i) \
;     __builtin_amdgcn_global_load_lds((const unsigned*)((const char*)(gbase) + (voff)[_i]), (LAS unsigned*)(lds + (bufoff) + ldsw + _i * 8192), 16, 0, 0); } while (0)
; #define PG8_LDA(dst, b, h) do { _Pragma("unroll") for (int m = 0; m < 4; ++m) _Pragma("unroll") for (int k = 0; k < 2; ++k) dst[m][k] = *(const LAS bf16x8*)(lds + PG8_SA(b, h) + aoff + m * 2048 + k * 1024); } while (0)
; #define PG8_LDB(dst, b, h) do { _Pragma("unroll") for (int n = 0; n < 2; ++n) _Pragma("unroll") for (int k = 0; k < 2; ++k) dst[n][k] = *(const LAS bf16x8*)(lds + PG8_SB(b, h) + boff + n * 2048 + k * 1024); } while (0)
; #define PG8_MMA(ai, bj, At, Bt) do { __builtin_amdgcn_s_setprio(1); _Pragma("unroll") for (int m = 0; m < 4; ++m) _Pragma("unroll") for (int n = 0; n < 2; ++n) _Pragma("unroll") for (int k = 0; k < 2; ++k) \
;     acc[ai][bj][m][n] = __builtin_amdgcn_mfma_f32_16x16x32_bf16(Bt[n][k], At[m][k], acc[ai][bj][m][n], 0, 0, 0); __builtin_amdgcn_s_setprio(0); } while (0)
; #define PG8_WAIT_V(n) asm volatile("s_waitcnt vmcnt(" #n ")" ::: "memory")
; #define PG8_WAIT_L(n) asm volatile("s_waitcnt lgkmcnt(" #n ")" ::: "memory")
; #define PG8_BAR __builtin_amdgcn_s_barrier()
; #define PG8_SCHED __builtin_amdgcn_sched_barrier(0)
; template <class Epi>
; __device__ __forceinline__ void gemm_phase(LAS unsigned char* lds, const Gemm g, const StaticOrder& S, const Epi& E, int wv0) {
;     ...
;       PG8_STAGE(PG8_SB(0, 1), b2 + hstepB, voffB);
;       PG8_WAIT_V(6); PG8_BAR; PG8_MMA(1, 1, At, B1); PG8_BAR;
;       PG8_LDB(B0, 1, 0); PG8_SCHED; PG8_LDA(At, 1, 0); PG8_STAGE(PG8_SA(0, 1), a2 + hstepA, voffA);
;       PG8_WAIT_L(8); PG8_BAR; PG8_WAIT_L(0); PG8_MMA(0, 0, At, B0); PG8_BAR; PG8_SCHED;
;       PG8_LDB(B1, 1, 1); PG8_STAGE(PG8_SB(1, 0), b3, voffB);
;       PG8_BAR; PG8_WAIT_L(0); PG8_MMA(0, 1, At, B1); PG8_BAR;
;       PG8_LDA(At, 1, 1); PG8_STAGE(PG8_SA(1, 0), a3, voffA);
;       PG8_BAR; PG8_WAIT_L(0); PG8_MMA(1, 0, At, B0); PG8_BAR; PG8_SCHED;
	s_add_u32 s50, s22, 0x80000
	s_addc_u32 s51, s23, 0
	s_add_i32 s0, s0, s31
	v_lshl_add_u64 v[130:131], s[50:51], 0, v[96:97]
	s_mov_b32 m0, s0
	s_nop 0
	global_load_lds_dwordx4 v[130:131], off
	v_lshl_add_u64 v[130:131], s[50:51], 0, v[166:167]
	s_add_i32 m0, s0, 0x2000
	s_nop 0
	global_load_lds_dwordx4 v[130:131], off
	s_waitcnt vmcnt(6)
	s_barrier
	v_mfma_f32_16x16x32_bf16 v[52:55], v[192:195], v[146:149], v[52:55]
	v_mfma_f32_16x16x32_bf16 v[48:51], v[200:203], v[146:149], v[48:51]
	v_mfma_f32_16x16x32_bf16 v[36:39], v[192:195], v[154:157], v[36:39]
	v_mfma_f32_16x16x32_bf16 v[32:35], v[200:203], v[154:157], v[32:35]
	v_mfma_f32_16x16x32_bf16 v[16:19], v[192:195], v[172:175], v[16:19]
	v_mfma_f32_16x16x32_bf16 v[12:15], v[200:203], v[172:175], v[12:15]
	v_mfma_f32_16x16x32_bf16 v[4:7], v[192:195], v[180:183], v[4:7]
	v_mfma_f32_16x16x32_bf16 v[0:3], v[200:203], v[180:183], v[0:3]
	v_mfma_f32_16x16x32_bf16 v[52:55], v[196:199], v[150:153], v[52:55]
	v_mfma_f32_16x16x32_bf16 v[48:51], v[204:207], v[150:153], v[48:51]
	v_mfma_f32_16x16x32_bf16 v[36:39], v[196:199], v[158:161], v[36:39]
	v_mfma_f32_16x16x32_bf16 v[32:35], v[204:207], v[158:161], v[32:35]
	v_mfma_f32_16x16x32_bf16 v[16:19], v[196:199], v[176:179], v[16:19]
	v_mfma_f32_16x16x32_bf16 v[12:15], v[204:207], v[176:179], v[12:15]
	v_mfma_f32_16x16x32_bf16 v[4:7], v[196:199], v[188:191], v[4:7]
	v_mfma_f32_16x16x32_bf16 v[0:3], v[204:207], v[188:191], v[0:3]
	s_add_i32 s0, 0, 0x18000
	v_add_u32_e32 v142, s0, v185
	s_barrier
	ds_read_b128 v[130:133], v142
	ds_read_b128 v[134:137], v142 offset:1024
	ds_read_b128 v[138:141], v142 offset:2048
	ds_read_b128 v[142:145], v142 offset:3072
	s_add_u32 s24, s24, 0x80000
	s_addc_u32 s25, s25, 0
	s_mov_b32 m0, s39
	v_lshl_add_u64 v[192:193], s[24:25], 0, v[162:163]
	ds_read_b128 v[146:149], v187 offset:32768
	ds_read_b128 v[150:153], v187 offset:33792
	ds_read_b128 v[154:157], v187 offset:34816
	ds_read_b128 v[158:161], v187 offset:35840
	ds_read_b128 v[172:175], v187 offset:36864
	ds_read_b128 v[176:179], v187 offset:37888
	ds_read_b128 v[180:183], v187 offset:38912
	ds_read_b128 v[188:191], v187 offset:39936
	global_load_lds_dwordx4 v[192:193], off
	v_lshl_add_u64 v[192:193], s[24:25], 0, v[164:165]
	s_mov_b32 m0, s40
	s_nop 0
	global_load_lds_dwordx4 v[192:193], off
	s_waitcnt lgkmcnt(8)
	s_barrier
	s_waitcnt lgkmcnt(0)
	s_waitcnt lgkmcnt(0)
	v_mfma_f32_16x16x32_bf16 v[126:129], v[130:133], v[146:149], v[126:129]
	v_mfma_f32_16x16x32_bf16 v[122:125], v[138:141], v[146:149], v[122:125]
	v_mfma_f32_16x16x32_bf16 v[118:121], v[130:133], v[154:157], v[118:121]
	v_mfma_f32_16x16x32_bf16 v[114:117], v[138:141], v[154:157], v[114:117]
	v_mfma_f32_16x16x32_bf16 v[92:95], v[130:133], v[172:175], v[92:95]
	v_mfma_f32_16x16x32_bf16 v[88:91], v[138:141], v[172:175], v[88:91]
	v_mfma_f32_16x16x32_bf16 v[84:87], v[130:133], v[180:183], v[84:87]
	v_mfma_f32_16x16x32_bf16 v[76:79], v[138:141], v[180:183], v[76:79]
	v_mfma_f32_16x16x32_bf16 v[126:129], v[134:137], v[150:153], v[126:129]
	v_mfma_f32_16x16x32_bf16 v[122:125], v[142:145], v[150:153], v[122:125]
	v_mfma_f32_16x16x32_bf16 v[118:121], v[134:137], v[158:161], v[118:121]
	v_mfma_f32_16x16x32_bf16 v[114:117], v[142:145], v[158:161], v[114:117]
	v_mfma_f32_16x16x32_bf16 v[92:95], v[134:137], v[176:179], v[92:95]
	v_mfma_f32_16x16x32_bf16 v[88:91], v[142:145], v[176:179], v[88:91]
	v_mfma_f32_16x16x32_bf16 v[84:87], v[134:137], v[188:191], v[84:87]
	v_mfma_f32_16x16x32_bf16 v[76:79], v[142:145], v[188:191], v[76:79]
	s_barrier
	s_add_i32 s24, 0, 0x1c000
	s_add_i32 s0, s0, s31
	v_add_u32_e32 v204, s24, v185
	v_lshl_add_u64 v[208:209], v[208:209], 0, s[72:73]
	s_mov_b32 m0, s0
	ds_read_b128 v[192:195], v204
	ds_read_b128 v[196:199], v204 offset:1024
	ds_read_b128 v[200:203], v204 offset:2048
	ds_read_b128 v[204:207], v204 offset:3072
	global_load_lds_dwordx4 v[208:209], off
	v_lshl_add_u64 v[208:209], v[210:211], 0, s[72:73]
	s_add_i32 m0, s0, 0x2000
	s_nop 0
	global_load_lds_dwordx4 v[208:209], off
	s_barrier
	s_waitcnt lgkmcnt(0)
	s_waitcnt lgkmcnt(0)
	v_mfma_f32_16x16x32_bf16 v[110:113], v[192:195], v[146:149], v[110:113]
	v_mfma_f32_16x16x32_bf16 v[106:109], v[200:203], v[146:149], v[106:109]
	v_mfma_f32_16x16x32_bf16 v[102:105], v[192:195], v[154:157], v[102:105]
	v_mfma_f32_16x16x32_bf16 v[98:101], v[200:203], v[154:157], v[98:101]
	v_mfma_f32_16x16x32_bf16 v[80:83], v[192:195], v[172:175], v[80:83]
	v_mfma_f32_16x16x32_bf16 v[72:75], v[200:203], v[172:175], v[72:75]
	v_mfma_f32_16x16x32_bf16 v[68:71], v[192:195], v[180:183], v[68:71]
	v_mfma_f32_16x16x32_bf16 v[64:67], v[200:203], v[180:183], v[64:67]
	v_mfma_f32_16x16x32_bf16 v[110:113], v[196:199], v[150:153], v[110:113]
	v_mfma_f32_16x16x32_bf16 v[106:109], v[204:207], v[150:153], v[106:109]
	v_mfma_f32_16x16x32_bf16 v[102:105], v[196:199], v[158:161], v[102:105]
	v_mfma_f32_16x16x32_bf16 v[98:101], v[204:207], v[158:161], v[98:101]
	v_mfma_f32_16x16x32_bf16 v[80:83], v[196:199], v[176:179], v[80:83]
	v_mfma_f32_16x16x32_bf16 v[72:75], v[204:207], v[176:179], v[72:75]
	v_mfma_f32_16x16x32_bf16 v[68:71], v[196:199], v[188:191], v[68:71]
	v_mfma_f32_16x16x32_bf16 v[64:67], v[204:207], v[188:191], v[64:67]
	s_mov_b32 m0, s41
	v_lshl_add_u64 v[208:209], v[212:213], 0, s[72:73]
	s_barrier
	ds_read_b128 v[146:149], v187 offset:49152
	ds_read_b128 v[150:153], v187 offset:50176
	ds_read_b128 v[154:157], v187 offset:51200
	ds_read_b128 v[158:161], v187 offset:52224
	ds_read_b128 v[172:175], v187 offset:53248
	ds_read_b128 v[176:179], v187 offset:54272
	ds_read_b128 v[180:183], v187 offset:55296
	ds_read_b128 v[188:191], v187 offset:56320
	global_load_lds_dwordx4 v[208:209], off
	v_lshl_add_u64 v[208:209], v[214:215], 0, s[72:73]
	s_mov_b32 m0, s42
	s_nop 0
	global_load_lds_dwordx4 v[208:209], off
	s_barrier
; #define PG8_STAGE(bufoff, gbase, voff) do { _Pragma("unroll") for (int _i = 0; _i < 2; ++_i) \
;     __builtin_amdgcn_global_load_lds((const unsigned*)((const char*)(gbase) + (voff)[_i]), (LAS unsigned*)(lds + (bufoff) + ldsw + _i * 8192), 16, 0, 0); } while (0)
; #define PG8_MMA(ai, bj, At, Bt) do { __builtin_amdgcn_s_setprio(1); _Pragma("unroll") for (int m = 0; m < 4; ++m) _Pragma("unroll") for (int n = 0; n < 2; ++n) _Pragma("unroll") for (int k = 0; k < 2; ++k) \
;     acc[ai][bj][m][n] = __builtin_amdgcn_mfma_f32_16x16x32_bf16(Bt[n][k], At[m][k], acc[ai][bj][m][n], 0, 0, 0); __builtin_amdgcn_s_setprio(0); } while (0)
; #define PG8_WAIT_V(n) asm volatile("s_waitcnt vmcnt(" #n ")" ::: "memory")
; #define PG8_WAIT_L(n) asm volatile("s_waitcnt lgkmcnt(" #n ")" ::: "memory")
; #define PG8_BAR __builtin_amdgcn_s_barrier()
; #define PG8_SCHED __builtin_amdgcn_sched_barrier(0)
; template <class Epi>
; __device__ __forceinline__ void gemm_phase(LAS unsigned char* lds, const Gemm g, const StaticOrder& S, const Epi& E, int wv0) {
;     ...
;       PG8_BAR; PG8_WAIT_L(0); PG8_MMA(1, 0, At, B0); PG8_BAR; PG8_SCHED;
;       PG8_STAGE(PG8_SB(1, 1), b3 + hstepB, voffB);
;       PG8_WAIT_V(6); PG8_BAR; PG8_MMA(1, 1, At, B1); PG8_BAR;
;     }
;     E(acc, cur, wr, wc, fr, fq);
;   __device__ __forceinline__ void emit(const EpiPre& q0, int row, int col, f32x4 a, f32x4 b, const f32x4 (&hb)[2][2], const float (&hs)[2][4], int ai_, int m_, int bj_) const {
;     ...
;     } else if (MODE == E_RES) {
;       const f32x4 r0 = q.a0, r1 = q.a1;
;       float* o = (float*)e.out + (size_t)row * DM + col;
;       *(f32x4*)o = (f32x4){ALPHA * r0[0] + v[0], ALPHA * r0[1] + v[1], ALPHA * r0[2] + v[2], ALPHA * r0[3] + v[3]};
;       *(f32x4*)(o + 4) = (f32x4){ALPHA * r1[0] + v[4], ALPHA * r1[1] + v[5], ALPHA * r1[2] + v[6], ALPHA * r1[3] + v[7]};
	s_waitcnt lgkmcnt(0)
	s_waitcnt lgkmcnt(0)
	v_mfma_f32_16x16x32_bf16 v[60:63], v[130:133], v[146:149], v[60:63]
	v_mfma_f32_16x16x32_bf16 v[56:59], v[138:141], v[146:149], v[56:59]
	v_mfma_f32_16x16x32_bf16 v[44:47], v[130:133], v[154:157], v[44:47]
	v_mfma_f32_16x16x32_bf16 v[40:43], v[138:141], v[154:157], v[40:43]
	v_mfma_f32_16x16x32_bf16 v[28:31], v[130:133], v[172:175], v[28:31]
	v_mfma_f32_16x16x32_bf16 v[24:27], v[138:141], v[172:175], v[24:27]
	v_mfma_f32_16x16x32_bf16 v[20:23], v[130:133], v[180:183], v[20:23]
	v_mfma_f32_16x16x32_bf16 v[8:11], v[138:141], v[180:183], v[8:11]
	v_mfma_f32_16x16x32_bf16 v[60:63], v[134:137], v[150:153], v[60:63]
	v_mfma_f32_16x16x32_bf16 v[56:59], v[142:145], v[150:153], v[56:59]
	v_mfma_f32_16x16x32_bf16 v[44:47], v[134:137], v[158:161], v[44:47]
	v_mfma_f32_16x16x32_bf16 v[40:43], v[142:145], v[158:161], v[40:43]
	v_mfma_f32_16x16x32_bf16 v[28:31], v[134:137], v[176:179], v[28:31]
	v_mfma_f32_16x16x32_bf16 v[24:27], v[142:145], v[176:179], v[24:27]
	v_mfma_f32_16x16x32_bf16 v[20:23], v[134:137], v[188:191], v[20:23]
	v_mfma_f32_16x16x32_bf16 v[8:11], v[142:145], v[188:191], v[8:11]
	s_barrier
	s_add_u32 s22, s22, 0x80080
	s_addc_u32 s23, s23, 0
	s_add_i32 s0, s24, s31
	v_lshl_add_u64 v[130:131], s[22:23], 0, v[96:97]
	s_mov_b32 m0, s0
	s_nop 0
	global_load_lds_dwordx4 v[130:131], off
	v_lshl_add_u64 v[130:131], s[22:23], 0, v[166:167]
	s_add_i32 m0, s0, 0x2000
	s_nop 0
	global_load_lds_dwordx4 v[130:131], off
	s_waitcnt vmcnt(6)
	s_barrier
	v_mfma_f32_16x16x32_bf16 v[52:55], v[192:195], v[146:149], v[52:55]
	v_mfma_f32_16x16x32_bf16 v[48:51], v[200:203], v[146:149], v[48:51]
	v_mfma_f32_16x16x32_bf16 v[36:39], v[192:195], v[154:157], v[36:39]
	v_mfma_f32_16x16x32_bf16 v[32:35], v[200:203], v[154:157], v[32:35]
	v_mfma_f32_16x16x32_bf16 v[16:19], v[192:195], v[172:175], v[16:19]
	v_mfma_f32_16x16x32_bf16 v[12:15], v[200:203], v[172:175], v[12:15]
	v_mfma_f32_16x16x32_bf16 v[4:7], v[192:195], v[180:183], v[4:7]
	v_mfma_f32_16x16x32_bf16 v[0:3], v[200:203], v[180:183], v[0:3]
	v_mfma_f32_16x16x32_bf16 v[52:55], v[196:199], v[150:153], v[52:55]
	v_mfma_f32_16x16x32_bf16 v[48:51], v[204:207], v[150:153], v[48:51]
	v_mfma_f32_16x16x32_bf16 v[36:39], v[196:199], v[158:161], v[36:39]
	v_mfma_f32_16x16x32_bf16 v[32:35], v[204:207], v[158:161], v[32:35]
	v_mfma_f32_16x16x32_bf16 v[16:19], v[196:199], v[176:179], v[16:19]
	v_mfma_f32_16x16x32_bf16 v[12:15], v[204:207], v[176:179], v[12:15]
	v_mfma_f32_16x16x32_bf16 v[4:7], v[196:199], v[188:191], v[4:7]
	v_mfma_f32_16x16x32_bf16 v[0:3], v[204:207], v[188:191], v[0:3]
	s_add_i32 s49, s49, 2
	s_add_u32 s20, s20, 0x100
	s_addc_u32 s21, s21, 0
	s_add_u32 s47, s47, 0x100
	s_addc_u32 s48, s48, 0
	s_cmp_gt_u32 s49, 29
	s_barrier
	s_cbranch_scc0 .LBB0_1100
	s_setprio 0
	s_cmp_eq_u32 s66, 0
	s_cbranch_scc1 .Lwo_plain
	s_load_dwordx4 s[48:51], s[54:55], 0xb8
	s_load_dwordx2 s[96:97], s[54:55], 0xc8
	v_lshl_add_u32 v243, s18, 8, v184
	v_lshl_or_b32 v247, s1, 8, v186
	v_lshlrev_b32_e32 v242, 13, v243
	v_lshlrev_b32_e32 v247, 2, v247
	v_lshlrev_b32_e32 v243, 3, v243
	v_add_u32_e32 v242, v242, v247
	s_waitcnt lgkmcnt(0)
	s_add_u32 s100, s96, 0x4000000
	s_addc_u32 s101, s97, 0
	s_add_u32 s20, s6, 0x0
	s_addc_u32 s21, s7, 0
	global_load_dwordx2 v[220:221], v243, s[100:101] offset:0
	global_load_dwordx4 v[130:133], v242, s[20:21]
	global_load_dwordx4 v[134:137], v242, s[20:21] offset:16
	global_load_dwordx4 v[138:141], v242, s[20:21] offset:512
	global_load_dwordx4 v[142:145], v242, s[20:21] offset:528
	s_add_u32 s22, s6, 0x20000
	s_addc_u32 s23, s7, 0
	global_load_dwordx2 v[238:239], v243, s[100:101] offset:128
	global_load_dwordx4 v[146:149], v242, s[22:23]
	global_load_dwordx4 v[150:153], v242, s[22:23] offset:16
	global_load_dwordx4 v[154:157], v242, s[22:23] offset:512
	global_load_dwordx4 v[158:161], v242, s[22:23] offset:528
	s_add_u32 s24, s6, 0x40000
	s_addc_u32 s25, s7, 0
	global_load_dwordx2 v[240:241], v243, s[100:101] offset:256
	global_load_dwordx4 v[172:175], v242, s[24:25]
	global_load_dwordx4 v[176:179], v242, s[24:25] offset:16
	global_load_dwordx4 v[180:183], v242, s[24:25] offset:512
	global_load_dwordx4 v[234:237], v242, s[24:25] offset:528
	global_load_dwordx4 v[188:191], v247, s[48:49]
	global_load_dwordx4 v[192:195], v247, s[48:49] offset:16
	global_load_dwordx4 v[196:199], v247, s[48:49] offset:512
	global_load_dwordx4 v[200:203], v247, s[48:49] offset:528
	global_load_dwordx4 v[204:207], v247, s[50:51]
	global_load_dwordx4 v[208:211], v247, s[50:51] offset:16
	global_load_dwordx4 v[212:215], v247, s[50:51] offset:512
	global_load_dwordx4 v[216:219], v247, s[50:51] offset:528
	s_waitcnt vmcnt(0)
;   __device__ __forceinline__ void emit(const EpiPre& q0, int row, int col, f32x4 a, f32x4 b, const f32x4 (&hb)[2][2], const float (&hs)[2][4], int ai_, int m_, int bj_) const {
;     ...
;     } else if (MODE == E_RES) {
;       const f32x4 r0 = q.a0, r1 = q.a1;
;       float* o = (float*)e.out + (size_t)row * DM + col;
;       *(f32x4*)o = (f32x4){ALPHA * r0[0] + v[0], ALPHA * r0[1] + v[1], ALPHA * r0[2] + v[2], ALPHA * r0[3] + v[3]};
;       *(f32x4*)(o + 4) = (f32x4){ALPHA * r1[0] + v[4], ALPHA * r1[1] + v[5], ALPHA * r1[2] + v[6], ALPHA * r1[3] + v[7]};
	v_pk_add_f32 v[130:131], v[130:131], v[220:221] op_sel_hi:[1,0]
	v_pk_add_f32 v[132:133], v[132:133], v[220:221] op_sel_hi:[1,0]
	v_pk_add_f32 v[134:135], v[134:135], v[220:221] op_sel_hi:[1,0]
	v_pk_add_f32 v[136:137], v[136:137], v[220:221] op_sel_hi:[1,0]
	v_pk_add_f32 v[138:139], v[138:139], v[220:221] op_sel_hi:[1,0]
	v_pk_add_f32 v[140:141], v[140:141], v[220:221] op_sel_hi:[1,0]
	v_pk_add_f32 v[142:143], v[142:143], v[220:221] op_sel_hi:[1,0]
	v_pk_add_f32 v[144:145], v[144:145], v[220:221] op_sel_hi:[1,0]
	v_pk_mul_f32 v[130:131], v[130:131], v[220:221] op_sel:[0,1] op_sel_hi:[1,1]
	v_pk_mul_f32 v[132:133], v[132:133], v[220:221] op_sel:[0,1] op_sel_hi:[1,1]
	v_pk_mul_f32 v[134:135], v[134:135], v[220:221] op_sel:[0,1] op_sel_hi:[1,1]
	v_pk_mul_f32 v[136:137], v[136:137], v[220:221] op_sel:[0,1] op_sel_hi:[1,1]
	v_pk_mul_f32 v[138:139], v[138:139], v[220:221] op_sel:[0,1] op_sel_hi:[1,1]
	v_pk_mul_f32 v[140:141], v[140:141], v[220:221] op_sel:[0,1] op_sel_hi:[1,1]
	v_pk_mul_f32 v[142:143], v[142:143], v[220:221] op_sel:[0,1] op_sel_hi:[1,1]
	v_pk_mul_f32 v[144:145], v[144:145], v[220:221] op_sel:[0,1] op_sel_hi:[1,1]
	v_pk_fma_f32 v[130:131], v[188:189], v[130:131], v[204:205]
	v_pk_fma_f32 v[132:133], v[190:191], v[132:133], v[206:207]
	v_pk_fma_f32 v[134:135], v[192:193], v[134:135], v[208:209]
	v_pk_fma_f32 v[136:137], v[194:195], v[136:137], v[210:211]
	v_pk_fma_f32 v[138:139], v[196:197], v[138:139], v[212:213]
	v_pk_fma_f32 v[140:141], v[198:199], v[140:141], v[214:215]
	v_pk_fma_f32 v[142:143], v[200:201], v[142:143], v[216:217]
	v_pk_fma_f32 v[144:145], v[202:203], v[144:145], v[218:219]
	v_pk_fma_f32 v[126:127], v[130:131], s[90:91], v[126:127] op_sel_hi:[1,0,1]
	v_pk_fma_f32 v[128:129], v[132:133], s[90:91], v[128:129] op_sel_hi:[1,0,1]
	v_pk_fma_f32 v[122:123], v[134:135], s[90:91], v[122:123] op_sel_hi:[1,0,1]
	v_pk_fma_f32 v[124:125], v[136:137], s[90:91], v[124:125] op_sel_hi:[1,0,1]
	v_pk_fma_f32 v[110:111], v[138:139], s[90:91], v[110:111] op_sel_hi:[1,0,1]
	v_pk_fma_f32 v[112:113], v[140:141], s[90:91], v[112:113] op_sel_hi:[1,0,1]
	v_pk_fma_f32 v[106:107], v[142:143], s[90:91], v[106:107] op_sel_hi:[1,0,1]
	v_pk_fma_f32 v[108:109], v[144:145], s[90:91], v[108:109] op_sel_hi:[1,0,1]
	s_add_u32 s46, s6, 0x60000
	s_addc_u32 s47, s7, 0
	global_load_dwordx2 v[220:221], v243, s[100:101] offset:384
	global_load_dwordx4 v[130:133], v242, s[46:47]
	global_load_dwordx4 v[134:137], v242, s[46:47] offset:16
	global_load_dwordx4 v[138:141], v242, s[46:47] offset:512
	global_load_dwordx4 v[142:145], v242, s[46:47] offset:528
	s_waitcnt vmcnt(18)
	v_pk_add_f32 v[146:147], v[146:147], v[238:239] op_sel_hi:[1,0]
	v_pk_add_f32 v[148:149], v[148:149], v[238:239] op_sel_hi:[1,0]
	v_pk_add_f32 v[150:151], v[150:151], v[238:239] op_sel_hi:[1,0]
	v_pk_add_f32 v[152:153], v[152:153], v[238:239] op_sel_hi:[1,0]
	v_pk_add_f32 v[154:155], v[154:155], v[238:239] op_sel_hi:[1,0]
	v_pk_add_f32 v[156:157], v[156:157], v[238:239] op_sel_hi:[1,0]
	v_pk_add_f32 v[158:159], v[158:159], v[238:239] op_sel_hi:[1,0]
	v_pk_add_f32 v[160:161], v[160:161], v[238:239] op_sel_hi:[1,0]
	v_pk_mul_f32 v[146:147], v[146:147], v[238:239] op_sel:[0,1] op_sel_hi:[1,1]
	v_pk_mul_f32 v[148:149], v[148:149], v[238:239] op_sel:[0,1] op_sel_hi:[1,1]
	v_pk_mul_f32 v[150:151], v[150:151], v[238:239] op_sel:[0,1] op_sel_hi:[1,1]
	v_pk_mul_f32 v[152:153], v[152:153], v[238:239] op_sel:[0,1] op_sel_hi:[1,1]
	v_pk_mul_f32 v[154:155], v[154:155], v[238:239] op_sel:[0,1] op_sel_hi:[1,1]
	v_pk_mul_f32 v[156:157], v[156:157], v[238:239] op_sel:[0,1] op_sel_hi:[1,1]
	v_pk_mul_f32 v[158:159], v[158:159], v[238:239] op_sel:[0,1] op_sel_hi:[1,1]
	v_pk_mul_f32 v[160:161], v[160:161], v[238:239] op_sel:[0,1] op_sel_hi:[1,1]
	v_pk_fma_f32 v[146:147], v[188:189], v[146:147], v[204:205]
	v_pk_fma_f32 v[148:149], v[190:191], v[148:149], v[206:207]
	v_pk_fma_f32 v[150:151], v[192:193], v[150:151], v[208:209]
	v_pk_fma_f32 v[152:153], v[194:195], v[152:153], v[210:211]
	v_pk_fma_f32 v[154:155], v[196:197], v[154:155], v[212:213]
	v_pk_fma_f32 v[156:157], v[198:199], v[156:157], v[214:215]
	v_pk_fma_f32 v[158:159], v[200:201], v[158:159], v[216:217]
	v_pk_fma_f32 v[160:161], v[202:203], v[160:161], v[218:219]
	v_pk_fma_f32 v[118:119], v[146:147], s[90:91], v[118:119] op_sel_hi:[1,0,1]
	v_pk_fma_f32 v[120:121], v[148:149], s[90:91], v[120:121] op_sel_hi:[1,0,1]
	v_pk_fma_f32 v[114:115], v[150:151], s[90:91], v[114:115] op_sel_hi:[1,0,1]
	v_pk_fma_f32 v[116:117], v[152:153], s[90:91], v[116:117] op_sel_hi:[1,0,1]
	v_pk_fma_f32 v[102:103], v[154:155], s[90:91], v[102:103] op_sel_hi:[1,0,1]
	v_pk_fma_f32 v[104:105], v[156:157], s[90:91], v[104:105] op_sel_hi:[1,0,1]
	v_pk_fma_f32 v[98:99], v[158:159], s[90:91], v[98:99] op_sel_hi:[1,0,1]
	v_pk_fma_f32 v[100:101], v[160:161], s[90:91], v[100:101] op_sel_hi:[1,0,1]
	s_add_u32 s48, s6, 0x100000
	s_addc_u32 s49, s7, 0
	global_load_dwordx2 v[238:239], v243, s[100:101] offset:1024
	global_load_dwordx4 v[146:149], v242, s[48:49]
	global_load_dwordx4 v[150:153], v242, s[48:49] offset:16
	global_load_dwordx4 v[154:157], v242, s[48:49] offset:512
	global_load_dwordx4 v[158:161], v242, s[48:49] offset:528
	s_waitcnt vmcnt(18)
;   __device__ __forceinline__ void emit(const EpiPre& q0, int row, int col, f32x4 a, f32x4 b, const f32x4 (&hb)[2][2], const float (&hs)[2][4], int ai_, int m_, int bj_) const {
;     ...
;     } else if (MODE == E_RES) {
;       const f32x4 r0 = q.a0, r1 = q.a1;
;       float* o = (float*)e.out + (size_t)row * DM + col;
;       *(f32x4*)o = (f32x4){ALPHA * r0[0] + v[0], ALPHA * r0[1] + v[1], ALPHA * r0[2] + v[2], ALPHA * r0[3] + v[3]};
;       *(f32x4*)(o + 4) = (f32x4){ALPHA * r1[0] + v[4], ALPHA * r1[1] + v[5], ALPHA * r1[2] + v[6], ALPHA * r1[3] + v[7]};
;   __device__ __forceinline__ void operator()(const f32x4 (&acc)[2][2][4][2], const pg8::Unit& u, int wr, int wc, int fr, int fq) const {
;     ...
;     for (int gi = 0; gi < 4; ++gi) {
;       const int ai = gi >> 1, mp = gi & 1;
;       if (gi + 1 < 4) { const int ai2 = (gi + 1) >> 1, mp2 = (gi + 1) & 1;
; #pragma unroll
;         for (int i = 0; i < 4; ++i) preload(q[(gi + 1) & 1][i], row0 + ai2 * 128 + (2 * mp2 + (i >> 1)) * 16, col0 + (i & 1) * 128); }
;       asm volatile("" ::: "memory");
; #pragma unroll
;       for (int i = 0; i < 4; ++i) { const int m = 2 * mp + (i >> 1), bj = i & 1; emit(q[gi & 1][i], row0 + ai * 128 + m * 16, col0 + bj * 128, acc[ai][bj][m][0], acc[ai][bj][m][1], hb, hs, ai, m, bj); }
;       asm volatile("" ::: "memory");
;     }
	v_pk_add_f32 v[172:173], v[172:173], v[240:241] op_sel_hi:[1,0]
	v_pk_add_f32 v[174:175], v[174:175], v[240:241] op_sel_hi:[1,0]
	v_pk_add_f32 v[176:177], v[176:177], v[240:241] op_sel_hi:[1,0]
	v_pk_add_f32 v[178:179], v[178:179], v[240:241] op_sel_hi:[1,0]
	v_pk_add_f32 v[180:181], v[180:181], v[240:241] op_sel_hi:[1,0]
	v_pk_add_f32 v[182:183], v[182:183], v[240:241] op_sel_hi:[1,0]
	v_pk_add_f32 v[234:235], v[234:235], v[240:241] op_sel_hi:[1,0]
	v_pk_add_f32 v[236:237], v[236:237], v[240:241] op_sel_hi:[1,0]
	v_pk_mul_f32 v[172:173], v[172:173], v[240:241] op_sel:[0,1] op_sel_hi:[1,1]
	v_pk_mul_f32 v[174:175], v[174:175], v[240:241] op_sel:[0,1] op_sel_hi:[1,1]
	v_pk_mul_f32 v[176:177], v[176:177], v[240:241] op_sel:[0,1] op_sel_hi:[1,1]
	v_pk_mul_f32 v[178:179], v[178:179], v[240:241] op_sel:[0,1] op_sel_hi:[1,1]
	v_pk_mul_f32 v[180:181], v[180:181], v[240:241] op_sel:[0,1] op_sel_hi:[1,1]
	v_pk_mul_f32 v[182:183], v[182:183], v[240:241] op_sel:[0,1] op_sel_hi:[1,1]
	v_pk_mul_f32 v[234:235], v[234:235], v[240:241] op_sel:[0,1] op_sel_hi:[1,1]
	v_pk_mul_f32 v[236:237], v[236:237], v[240:241] op_sel:[0,1] op_sel_hi:[1,1]
	v_pk_fma_f32 v[172:173], v[188:189], v[172:173], v[204:205]
	v_pk_fma_f32 v[174:175], v[190:191], v[174:175], v[206:207]
	v_pk_fma_f32 v[176:177], v[192:193], v[176:177], v[208:209]
	v_pk_fma_f32 v[178:179], v[194:195], v[178:179], v[210:211]
	v_pk_fma_f32 v[180:181], v[196:197], v[180:181], v[212:213]
	v_pk_fma_f32 v[182:183], v[198:199], v[182:183], v[214:215]
	v_pk_fma_f32 v[234:235], v[200:201], v[234:235], v[216:217]
	v_pk_fma_f32 v[236:237], v[202:203], v[236:237], v[218:219]
	v_pk_fma_f32 v[92:93], v[172:173], s[90:91], v[92:93] op_sel_hi:[1,0,1]
	v_pk_fma_f32 v[94:95], v[174:175], s[90:91], v[94:95] op_sel_hi:[1,0,1]
	v_pk_fma_f32 v[88:89], v[176:177], s[90:91], v[88:89] op_sel_hi:[1,0,1]
	v_pk_fma_f32 v[90:91], v[178:179], s[90:91], v[90:91] op_sel_hi:[1,0,1]
	v_pk_fma_f32 v[80:81], v[180:181], s[90:91], v[80:81] op_sel_hi:[1,0,1]
	v_pk_fma_f32 v[82:83], v[182:183], s[90:91], v[82:83] op_sel_hi:[1,0,1]
	v_pk_fma_f32 v[72:73], v[234:235], s[90:91], v[72:73] op_sel_hi:[1,0,1]
	v_pk_fma_f32 v[74:75], v[236:237], s[90:91], v[74:75] op_sel_hi:[1,0,1]
	s_add_u32 s50, s6, 0x120000
	s_addc_u32 s51, s7, 0
	global_load_dwordx2 v[240:241], v243, s[100:101] offset:1152
	global_load_dwordx4 v[172:175], v242, s[50:51]
	global_load_dwordx4 v[176:179], v242, s[50:51] offset:16
	global_load_dwordx4 v[180:183], v242, s[50:51] offset:512
	global_load_dwordx4 v[234:237], v242, s[50:51] offset:528
	global_store_dwordx4 v242, v[126:129], s[20:21]
	global_store_dwordx4 v242, v[122:125], s[20:21] offset:16
	global_store_dwordx4 v242, v[110:113], s[20:21] offset:512
	global_store_dwordx4 v242, v[106:109], s[20:21] offset:528
	global_store_dwordx4 v242, v[118:121], s[22:23]
	global_store_dwordx4 v242, v[114:117], s[22:23] offset:16
	global_store_dwordx4 v242, v[102:105], s[22:23] offset:512
	global_store_dwordx4 v242, v[98:101], s[22:23] offset:528
	global_store_dwordx4 v242, v[92:95], s[24:25]
	global_store_dwordx4 v242, v[88:91], s[24:25] offset:16
	global_store_dwordx4 v242, v[80:83], s[24:25] offset:512
	global_store_dwordx4 v242, v[72:75], s[24:25] offset:528
	s_add_u32 s20, s6, 0x140000
	s_addc_u32 s21, s7, 0
	global_load_dwordx2 v[92:93], v243, s[100:101] offset:1280
	global_load_dwordx4 v[126:129], v242, s[20:21]
	global_load_dwordx4 v[122:125], v242, s[20:21] offset:16
	global_load_dwordx4 v[110:113], v242, s[20:21] offset:512
	global_load_dwordx4 v[106:109], v242, s[20:21] offset:528
	s_add_u32 s22, s6, 0x160000
	s_addc_u32 s23, s7, 0
	global_load_dwordx2 v[88:89], v243, s[100:101] offset:1408
	global_load_dwordx4 v[118:121], v242, s[22:23]
	global_load_dwordx4 v[114:117], v242, s[22:23] offset:16
	global_load_dwordx4 v[102:105], v242, s[22:23] offset:512
	global_load_dwordx4 v[98:101], v242, s[22:23] offset:528
	s_waitcnt vmcnt(32)
	v_pk_add_f32 v[130:131], v[130:131], v[220:221] op_sel_hi:[1,0]
	v_pk_add_f32 v[132:133], v[132:133], v[220:221] op_sel_hi:[1,0]
	v_pk_add_f32 v[134:135], v[134:135], v[220:221] op_sel_hi:[1,0]
	v_pk_add_f32 v[136:137], v[136:137], v[220:221] op_sel_hi:[1,0]
	v_pk_add_f32 v[138:139], v[138:139], v[220:221] op_sel_hi:[1,0]
	v_pk_add_f32 v[140:141], v[140:141], v[220:221] op_sel_hi:[1,0]
	v_pk_add_f32 v[142:143], v[142:143], v[220:221] op_sel_hi:[1,0]
	v_pk_add_f32 v[144:145], v[144:145], v[220:221] op_sel_hi:[1,0]
	v_pk_mul_f32 v[130:131], v[130:131], v[220:221] op_sel:[0,1] op_sel_hi:[1,1]
	v_pk_mul_f32 v[132:133], v[132:133], v[220:221] op_sel:[0,1] op_sel_hi:[1,1]
	v_pk_mul_f32 v[134:135], v[134:135], v[220:221] op_sel:[0,1] op_sel_hi:[1,1]
	v_pk_mul_f32 v[136:137], v[136:137], v[220:221] op_sel:[0,1] op_sel_hi:[1,1]
	v_pk_mul_f32 v[138:139], v[138:139], v[220:221] op_sel:[0,1] op_sel_hi:[1,1]
	v_pk_mul_f32 v[140:141], v[140:141], v[220:221] op_sel:[0,1] op_sel_hi:[1,1]
	v_pk_mul_f32 v[142:143], v[142:143], v[220:221] op_sel:[0,1] op_sel_hi:[1,1]
	v_pk_mul_f32 v[144:145], v[144:145], v[220:221] op_sel:[0,1] op_sel_hi:[1,1]
	v_pk_fma_f32 v[130:131], v[188:189], v[130:131], v[204:205]
	v_pk_fma_f32 v[132:133], v[190:191], v[132:133], v[206:207]
	v_pk_fma_f32 v[134:135], v[192:193], v[134:135], v[208:209]
	v_pk_fma_f32 v[136:137], v[194:195], v[136:137], v[210:211]
	v_pk_fma_f32 v[138:139], v[196:197], v[138:139], v[212:213]
	v_pk_fma_f32 v[140:141], v[198:199], v[140:141], v[214:215]
	v_pk_fma_f32 v[142:143], v[200:201], v[142:143], v[216:217]
	v_pk_fma_f32 v[144:145], v[202:203], v[144:145], v[218:219]
	v_pk_fma_f32 v[84:85], v[130:131], s[90:91], v[84:85] op_sel_hi:[1,0,1]
	v_pk_fma_f32 v[86:87], v[132:133], s[90:91], v[86:87] op_sel_hi:[1,0,1]
	v_pk_fma_f32 v[76:77], v[134:135], s[90:91], v[76:77] op_sel_hi:[1,0,1]
	v_pk_fma_f32 v[78:79], v[136:137], s[90:91], v[78:79] op_sel_hi:[1,0,1]
	v_pk_fma_f32 v[68:69], v[138:139], s[90:91], v[68:69] op_sel_hi:[1,0,1]
	v_pk_fma_f32 v[70:71], v[140:141], s[90:91], v[70:71] op_sel_hi:[1,0,1]
	v_pk_fma_f32 v[64:65], v[142:143], s[90:91], v[64:65] op_sel_hi:[1,0,1]
	v_pk_fma_f32 v[66:67], v[144:145], s[90:91], v[66:67] op_sel_hi:[1,0,1]
	global_store_dwordx4 v242, v[84:87], s[46:47]
	global_store_dwordx4 v242, v[76:79], s[46:47] offset:16
	global_store_dwordx4 v242, v[68:71], s[46:47] offset:512
	global_store_dwordx4 v242, v[64:67], s[46:47] offset:528
	s_waitcnt vmcnt(31)
;   __device__ __forceinline__ void emit(const EpiPre& q0, int row, int col, f32x4 a, f32x4 b, const f32x4 (&hb)[2][2], const float (&hs)[2][4], int ai_, int m_, int bj_) const {
;     ...
;     } else if (MODE == E_RES) {
;       const f32x4 r0 = q.a0, r1 = q.a1;
;       float* o = (float*)e.out + (size_t)row * DM + col;
;       *(f32x4*)o = (f32x4){ALPHA * r0[0] + v[0], ALPHA * r0[1] + v[1], ALPHA * r0[2] + v[2], ALPHA * r0[3] + v[3]};
;       *(f32x4*)(o + 4) = (f32x4){ALPHA * r1[0] + v[4], ALPHA * r1[1] + v[5], ALPHA * r1[2] + v[6], ALPHA * r1[3] + v[7]};
;   __device__ __forceinline__ void operator()(const f32x4 (&acc)[2][2][4][2], const pg8::Unit& u, int wr, int wc, int fr, int fq) const {
;     ...
;     for (int gi = 0; gi < 4; ++gi) {
;       const int ai = gi >> 1, mp = gi & 1;
;       if (gi + 1 < 4) { const int ai2 = (gi + 1) >> 1, mp2 = (gi + 1) & 1;
; #pragma unroll
;         for (int i = 0; i < 4; ++i) preload(q[(gi + 1) & 1][i], row0 + ai2 * 128 + (2 * mp2 + (i >> 1)) * 16, col0 + (i & 1) * 128); }
;       asm volatile("" ::: "memory");
; #pragma unroll
;       for (int i = 0; i < 4; ++i) { const int m = 2 * mp + (i >> 1), bj = i & 1; emit(q[gi & 1][i], row0 + ai * 128 + m * 16, col0 + bj * 128, acc[ai][bj][m][0], acc[ai][bj][m][1], hb, hs, ai, m, bj); }
;       asm volatile("" ::: "memory");
;     }
	v_pk_add_f32 v[146:147], v[146:147], v[238:239] op_sel_hi:[1,0]
	v_pk_add_f32 v[148:149], v[148:149], v[238:239] op_sel_hi:[1,0]
	v_pk_add_f32 v[150:151], v[150:151], v[238:239] op_sel_hi:[1,0]
	v_pk_add_f32 v[152:153], v[152:153], v[238:239] op_sel_hi:[1,0]
	v_pk_add_f32 v[154:155], v[154:155], v[238:239] op_sel_hi:[1,0]
	v_pk_add_f32 v[156:157], v[156:157], v[238:239] op_sel_hi:[1,0]
	v_pk_add_f32 v[158:159], v[158:159], v[238:239] op_sel_hi:[1,0]
	v_pk_add_f32 v[160:161], v[160:161], v[238:239] op_sel_hi:[1,0]
	v_pk_mul_f32 v[146:147], v[146:147], v[238:239] op_sel:[0,1] op_sel_hi:[1,1]
	v_pk_mul_f32 v[148:149], v[148:149], v[238:239] op_sel:[0,1] op_sel_hi:[1,1]
	v_pk_mul_f32 v[150:151], v[150:151], v[238:239] op_sel:[0,1] op_sel_hi:[1,1]
	v_pk_mul_f32 v[152:153], v[152:153], v[238:239] op_sel:[0,1] op_sel_hi:[1,1]
	v_pk_mul_f32 v[154:155], v[154:155], v[238:239] op_sel:[0,1] op_sel_hi:[1,1]
	v_pk_mul_f32 v[156:157], v[156:157], v[238:239] op_sel:[0,1] op_sel_hi:[1,1]
	v_pk_mul_f32 v[158:159], v[158:159], v[238:239] op_sel:[0,1] op_sel_hi:[1,1]
	v_pk_mul_f32 v[160:161], v[160:161], v[238:239] op_sel:[0,1] op_sel_hi:[1,1]
	v_pk_fma_f32 v[146:147], v[188:189], v[146:147], v[204:205]
	v_pk_fma_f32 v[148:149], v[190:191], v[148:149], v[206:207]
	v_pk_fma_f32 v[150:151], v[192:193], v[150:151], v[208:209]
	v_pk_fma_f32 v[152:153], v[194:195], v[152:153], v[210:211]
	v_pk_fma_f32 v[154:155], v[196:197], v[154:155], v[212:213]
	v_pk_fma_f32 v[156:157], v[198:199], v[156:157], v[214:215]
	v_pk_fma_f32 v[158:159], v[200:201], v[158:159], v[216:217]
	v_pk_fma_f32 v[160:161], v[202:203], v[160:161], v[218:219]
	v_pk_fma_f32 v[60:61], v[146:147], s[90:91], v[60:61] op_sel_hi:[1,0,1]
	v_pk_fma_f32 v[62:63], v[148:149], s[90:91], v[62:63] op_sel_hi:[1,0,1]
	v_pk_fma_f32 v[56:57], v[150:151], s[90:91], v[56:57] op_sel_hi:[1,0,1]
	v_pk_fma_f32 v[58:59], v[152:153], s[90:91], v[58:59] op_sel_hi:[1,0,1]
	v_pk_fma_f32 v[52:53], v[154:155], s[90:91], v[52:53] op_sel_hi:[1,0,1]
	v_pk_fma_f32 v[54:55], v[156:157], s[90:91], v[54:55] op_sel_hi:[1,0,1]
	v_pk_fma_f32 v[48:49], v[158:159], s[90:91], v[48:49] op_sel_hi:[1,0,1]
	v_pk_fma_f32 v[50:51], v[160:161], s[90:91], v[50:51] op_sel_hi:[1,0,1]
	global_store_dwordx4 v242, v[60:63], s[48:49]
	global_store_dwordx4 v242, v[56:59], s[48:49] offset:16
	global_store_dwordx4 v242, v[52:55], s[48:49] offset:512
	global_store_dwordx4 v242, v[48:51], s[48:49] offset:528
	s_waitcnt vmcnt(30)
	v_pk_add_f32 v[172:173], v[172:173], v[240:241] op_sel_hi:[1,0]
	v_pk_add_f32 v[174:175], v[174:175], v[240:241] op_sel_hi:[1,0]
	v_pk_add_f32 v[176:177], v[176:177], v[240:241] op_sel_hi:[1,0]
	v_pk_add_f32 v[178:179], v[178:179], v[240:241] op_sel_hi:[1,0]
	v_pk_add_f32 v[180:181], v[180:181], v[240:241] op_sel_hi:[1,0]
	v_pk_add_f32 v[182:183], v[182:183], v[240:241] op_sel_hi:[1,0]
	v_pk_add_f32 v[234:235], v[234:235], v[240:241] op_sel_hi:[1,0]
	v_pk_add_f32 v[236:237], v[236:237], v[240:241] op_sel_hi:[1,0]
	v_pk_mul_f32 v[172:173], v[172:173], v[240:241] op_sel:[0,1] op_sel_hi:[1,1]
	v_pk_mul_f32 v[174:175], v[174:175], v[240:241] op_sel:[0,1] op_sel_hi:[1,1]
	v_pk_mul_f32 v[176:177], v[176:177], v[240:241] op_sel:[0,1] op_sel_hi:[1,1]
	v_pk_mul_f32 v[178:179], v[178:179], v[240:241] op_sel:[0,1] op_sel_hi:[1,1]
	v_pk_mul_f32 v[180:181], v[180:181], v[240:241] op_sel:[0,1] op_sel_hi:[1,1]
	v_pk_mul_f32 v[182:183], v[182:183], v[240:241] op_sel:[0,1] op_sel_hi:[1,1]
	v_pk_mul_f32 v[234:235], v[234:235], v[240:241] op_sel:[0,1] op_sel_hi:[1,1]
	v_pk_mul_f32 v[236:237], v[236:237], v[240:241] op_sel:[0,1] op_sel_hi:[1,1]
	v_pk_fma_f32 v[172:173], v[188:189], v[172:173], v[204:205]
	v_pk_fma_f32 v[174:175], v[190:191], v[174:175], v[206:207]
	v_pk_fma_f32 v[176:177], v[192:193], v[176:177], v[208:209]
	v_pk_fma_f32 v[178:179], v[194:195], v[178:179], v[210:211]
	v_pk_fma_f32 v[180:181], v[196:197], v[180:181], v[212:213]
	v_pk_fma_f32 v[182:183], v[198:199], v[182:183], v[214:215]
	v_pk_fma_f32 v[234:235], v[200:201], v[234:235], v[216:217]
	v_pk_fma_f32 v[236:237], v[202:203], v[236:237], v[218:219]
	v_pk_fma_f32 v[44:45], v[172:173], s[90:91], v[44:45] op_sel_hi:[1,0,1]
	v_pk_fma_f32 v[46:47], v[174:175], s[90:91], v[46:47] op_sel_hi:[1,0,1]
	v_pk_fma_f32 v[40:41], v[176:177], s[90:91], v[40:41] op_sel_hi:[1,0,1]
	v_pk_fma_f32 v[42:43], v[178:179], s[90:91], v[42:43] op_sel_hi:[1,0,1]
	v_pk_fma_f32 v[36:37], v[180:181], s[90:91], v[36:37] op_sel_hi:[1,0,1]
	v_pk_fma_f32 v[38:39], v[182:183], s[90:91], v[38:39] op_sel_hi:[1,0,1]
	v_pk_fma_f32 v[32:33], v[234:235], s[90:91], v[32:33] op_sel_hi:[1,0,1]
	v_pk_fma_f32 v[34:35], v[236:237], s[90:91], v[34:35] op_sel_hi:[1,0,1]
	global_store_dwordx4 v242, v[44:47], s[50:51]
	global_store_dwordx4 v242, v[40:43], s[50:51] offset:16
	global_store_dwordx4 v242, v[36:39], s[50:51] offset:512
	global_store_dwordx4 v242, v[32:35], s[50:51] offset:528
	s_waitcnt vmcnt(17)
; template <class Epi>
; __device__ __forceinline__ void gemm_phase(LAS unsigned char* lds, const Gemm g, const StaticOrder& S, const Epi& E, int wv0) {
;     ...
;     E(acc, cur, wr, wc, fr, fq);
;     if (!has_next) break;
; #pragma unroll
;     for (int a = 0; a < 2; ++a)
; #pragma unroll
;       for (int b = 0; b < 2; ++b)
; #pragma unroll
;         for (int m = 0; m < 4; ++m)
; #pragma unroll
;           for (int n = 0; n < 2; ++n) acc[a][b][m][n] = (f32x4){0.f, 0.f, 0.f, 0.f};
;     cur = nxt; cA = nA; cB = nB; ++ui;
;   __device__ __forceinline__ void emit(const EpiPre& q0, int row, int col, f32x4 a, f32x4 b, const f32x4 (&hb)[2][2], const float (&hs)[2][4], int ai_, int m_, int bj_) const {
;     ...
;     } else if (MODE == E_RES) {
;       const f32x4 r0 = q.a0, r1 = q.a1;
;       float* o = (float*)e.out + (size_t)row * DM + col;
;       *(f32x4*)o = (f32x4){ALPHA * r0[0] + v[0], ALPHA * r0[1] + v[1], ALPHA * r0[2] + v[2], ALPHA * r0[3] + v[3]};
;       *(f32x4*)(o + 4) = (f32x4){ALPHA * r1[0] + v[4], ALPHA * r1[1] + v[5], ALPHA * r1[2] + v[6], ALPHA * r1[3] + v[7]};
	v_pk_add_f32 v[126:127], v[126:127], v[92:93] op_sel_hi:[1,0]
	v_pk_add_f32 v[128:129], v[128:129], v[92:93] op_sel_hi:[1,0]
	v_pk_add_f32 v[122:123], v[122:123], v[92:93] op_sel_hi:[1,0]
	v_pk_add_f32 v[124:125], v[124:125], v[92:93] op_sel_hi:[1,0]
	v_pk_add_f32 v[110:111], v[110:111], v[92:93] op_sel_hi:[1,0]
	v_pk_add_f32 v[112:113], v[112:113], v[92:93] op_sel_hi:[1,0]
	v_pk_add_f32 v[106:107], v[106:107], v[92:93] op_sel_hi:[1,0]
	v_pk_add_f32 v[108:109], v[108:109], v[92:93] op_sel_hi:[1,0]
	v_pk_mul_f32 v[126:127], v[126:127], v[92:93] op_sel:[0,1] op_sel_hi:[1,1]
	v_pk_mul_f32 v[128:129], v[128:129], v[92:93] op_sel:[0,1] op_sel_hi:[1,1]
	v_pk_mul_f32 v[122:123], v[122:123], v[92:93] op_sel:[0,1] op_sel_hi:[1,1]
	v_pk_mul_f32 v[124:125], v[124:125], v[92:93] op_sel:[0,1] op_sel_hi:[1,1]
	v_pk_mul_f32 v[110:111], v[110:111], v[92:93] op_sel:[0,1] op_sel_hi:[1,1]
	v_pk_mul_f32 v[112:113], v[112:113], v[92:93] op_sel:[0,1] op_sel_hi:[1,1]
	v_pk_mul_f32 v[106:107], v[106:107], v[92:93] op_sel:[0,1] op_sel_hi:[1,1]
	v_pk_mul_f32 v[108:109], v[108:109], v[92:93] op_sel:[0,1] op_sel_hi:[1,1]
	v_pk_fma_f32 v[126:127], v[188:189], v[126:127], v[204:205]
	v_pk_fma_f32 v[128:129], v[190:191], v[128:129], v[206:207]
	v_pk_fma_f32 v[122:123], v[192:193], v[122:123], v[208:209]
	v_pk_fma_f32 v[124:125], v[194:195], v[124:125], v[210:211]
	v_pk_fma_f32 v[110:111], v[196:197], v[110:111], v[212:213]
	v_pk_fma_f32 v[112:113], v[198:199], v[112:113], v[214:215]
	v_pk_fma_f32 v[106:107], v[200:201], v[106:107], v[216:217]
	v_pk_fma_f32 v[108:109], v[202:203], v[108:109], v[218:219]
	v_pk_fma_f32 v[28:29], v[126:127], s[90:91], v[28:29] op_sel_hi:[1,0,1]
	v_pk_fma_f32 v[30:31], v[128:129], s[90:91], v[30:31] op_sel_hi:[1,0,1]
	v_pk_fma_f32 v[24:25], v[122:123], s[90:91], v[24:25] op_sel_hi:[1,0,1]
	v_pk_fma_f32 v[26:27], v[124:125], s[90:91], v[26:27] op_sel_hi:[1,0,1]
	v_pk_fma_f32 v[16:17], v[110:111], s[90:91], v[16:17] op_sel_hi:[1,0,1]
	v_pk_fma_f32 v[18:19], v[112:113], s[90:91], v[18:19] op_sel_hi:[1,0,1]
	v_pk_fma_f32 v[12:13], v[106:107], s[90:91], v[12:13] op_sel_hi:[1,0,1]
	v_pk_fma_f32 v[14:15], v[108:109], s[90:91], v[14:15] op_sel_hi:[1,0,1]
	global_store_dwordx4 v242, v[28:31], s[20:21]
	global_store_dwordx4 v242, v[24:27], s[20:21] offset:16
	global_store_dwordx4 v242, v[16:19], s[20:21] offset:512
	global_store_dwordx4 v242, v[12:15], s[20:21] offset:528
	s_waitcnt vmcnt(16)
	v_pk_add_f32 v[118:119], v[118:119], v[88:89] op_sel_hi:[1,0]
	v_pk_add_f32 v[120:121], v[120:121], v[88:89] op_sel_hi:[1,0]
	v_pk_add_f32 v[114:115], v[114:115], v[88:89] op_sel_hi:[1,0]
	v_pk_add_f32 v[116:117], v[116:117], v[88:89] op_sel_hi:[1,0]
	v_pk_add_f32 v[102:103], v[102:103], v[88:89] op_sel_hi:[1,0]
	v_pk_add_f32 v[104:105], v[104:105], v[88:89] op_sel_hi:[1,0]
	v_pk_add_f32 v[98:99], v[98:99], v[88:89] op_sel_hi:[1,0]
	v_pk_add_f32 v[100:101], v[100:101], v[88:89] op_sel_hi:[1,0]
	v_pk_mul_f32 v[118:119], v[118:119], v[88:89] op_sel:[0,1] op_sel_hi:[1,1]
	v_pk_mul_f32 v[120:121], v[120:121], v[88:89] op_sel:[0,1] op_sel_hi:[1,1]
	v_pk_mul_f32 v[114:115], v[114:115], v[88:89] op_sel:[0,1] op_sel_hi:[1,1]
	v_pk_mul_f32 v[116:117], v[116:117], v[88:89] op_sel:[0,1] op_sel_hi:[1,1]
	v_pk_mul_f32 v[102:103], v[102:103], v[88:89] op_sel:[0,1] op_sel_hi:[1,1]
	v_pk_mul_f32 v[104:105], v[104:105], v[88:89] op_sel:[0,1] op_sel_hi:[1,1]
	v_pk_mul_f32 v[98:99], v[98:99], v[88:89] op_sel:[0,1] op_sel_hi:[1,1]
	v_pk_mul_f32 v[100:101], v[100:101], v[88:89] op_sel:[0,1] op_sel_hi:[1,1]
	v_pk_fma_f32 v[118:119], v[188:189], v[118:119], v[204:205]
	v_pk_fma_f32 v[120:121], v[190:191], v[120:121], v[206:207]
	v_pk_fma_f32 v[114:115], v[192:193], v[114:115], v[208:209]
	v_pk_fma_f32 v[116:117], v[194:195], v[116:117], v[210:211]
	v_pk_fma_f32 v[102:103], v[196:197], v[102:103], v[212:213]
	v_pk_fma_f32 v[104:105], v[198:199], v[104:105], v[214:215]
	v_pk_fma_f32 v[98:99], v[200:201], v[98:99], v[216:217]
	v_pk_fma_f32 v[100:101], v[202:203], v[100:101], v[218:219]
	v_pk_fma_f32 v[20:21], v[118:119], s[90:91], v[20:21] op_sel_hi:[1,0,1]
	v_pk_fma_f32 v[22:23], v[120:121], s[90:91], v[22:23] op_sel_hi:[1,0,1]
	v_pk_fma_f32 v[8:9], v[114:115], s[90:91], v[8:9] op_sel_hi:[1,0,1]
	v_pk_fma_f32 v[10:11], v[116:117], s[90:91], v[10:11] op_sel_hi:[1,0,1]
	v_pk_fma_f32 v[4:5], v[102:103], s[90:91], v[4:5] op_sel_hi:[1,0,1]
	v_pk_fma_f32 v[6:7], v[104:105], s[90:91], v[6:7] op_sel_hi:[1,0,1]
	v_pk_fma_f32 v[0:1], v[98:99], s[90:91], v[0:1] op_sel_hi:[1,0,1]
	v_pk_fma_f32 v[2:3], v[100:101], s[90:91], v[2:3] op_sel_hi:[1,0,1]
	global_store_dwordx4 v242, v[20:23], s[22:23]
	global_store_dwordx4 v242, v[8:11], s[22:23] offset:16
	global_store_dwordx4 v242, v[4:7], s[22:23] offset:512
	global_store_dwordx4 v242, v[0:3], s[22:23] offset:528
	s_mov_b32 s18, s12
	s_mov_b64 s[22:23], s[16:17]
	s_mov_b64 s[20:21], s[14:15]
	s_and_b64 vcc, exec, s[2:3]
	s_mov_b32 s1, s10
	s_branch .Lwo_join

; #define PG8_STAGE(bufoff, gbase, voff) do { _Pragma("unroll") for (int _i = 0; _i < 2; ++_i) \
;     __builtin_amdgcn_global_load_lds((const unsigned*)((const char*)(gbase) + (voff)[_i]), (LAS unsigned*)(lds + (bufoff) + ldsw + _i * 8192), 16, 0, 0); } while (0)
; #define PG8_LDA(dst, b, h) do { _Pragma("unroll") for (int m = 0; m < 4; ++m) _Pragma("unroll") for (int k = 0; k < 2; ++k) dst[m][k] = *(const LAS bf16x8*)(lds + PG8_SA(b, h) + aoff + m * 2048 + k * 1024); } while (0)
; #define PG8_LDB(dst, b, h) do { _Pragma("unroll") for (int n = 0; n < 2; ++n) _Pragma("unroll") for (int k = 0; k < 2; ++k) dst[n][k] = *(const LAS bf16x8*)(lds + PG8_SB(b, h) + boff + n * 2048 + k * 1024); } while (0)
; #define PG8_MMA(ai, bj, At, Bt) do { __builtin_amdgcn_s_setprio(1); _Pragma("unroll") for (int m = 0; m < 4; ++m) _Pragma("unroll") for (int n = 0; n < 2; ++n) _Pragma("unroll") for (int k = 0; k < 2; ++k) \
;     acc[ai][bj][m][n] = __builtin_amdgcn_mfma_f32_16x16x32_bf16(Bt[n][k], At[m][k], acc[ai][bj][m][n], 0, 0, 0); __builtin_amdgcn_s_setprio(0); } while (0)
; #define PG8_WAIT_V(n) asm volatile("s_waitcnt vmcnt(" #n ")" ::: "memory")
; #define PG8_WAIT_L(n) asm volatile("s_waitcnt lgkmcnt(" #n ")" ::: "memory")
; #define PG8_BAR __builtin_amdgcn_s_barrier()
; #define PG8_SCHED __builtin_amdgcn_sched_barrier(0)
; template <class Epi>
; __device__ __forceinline__ void gemm_phase(LAS unsigned char* lds, const Gemm g, const StaticOrder& S, const Epi& E, int wv0) {
;     ...
;       PG8_LDB(B0, 0, 0); PG8_SCHED; PG8_LDA(At, 0, 0); PG8_STAGE(PG8_SA(1, 1), a1 + hstepA, voffA);
;       PG8_WAIT_L(8); PG8_BAR; PG8_WAIT_L(0); PG8_MMA(0, 0, At, B0); PG8_BAR; PG8_SCHED;
;       PG8_LDB(B1, 0, 1); PG8_STAGE(PG8_SB(0, 0), b2, voffB);
;       PG8_BAR; PG8_WAIT_L(0); PG8_MMA(0, 1, At, B1); PG8_BAR;
;       PG8_LDA(At, 0, 1); PG8_STAGE(PG8_SA(0, 0), a2, voffA);
;       PG8_BAR; PG8_WAIT_L(0); PG8_MMA(1, 0, At, B0); PG8_BAR; PG8_SCHED;
;       PG8_STAGE(PG8_SB(0, 1), b2 + hstepB, voffB);
;       PG8_WAIT_V(6); PG8_BAR; PG8_MMA(1, 1, At, B1); PG8_BAR;
.LBB0_1270:
	s_add_u32 s0, s60, 0xfff80080
	s_addc_u32 s62, s61, -1
	s_add_i32 s80, 0, 0x10000
	v_add_u32_e32 v134, s80, v213
	ds_read_b128 v[122:125], v134
	ds_read_b128 v[126:129], v134 offset:1024
	ds_read_b128 v[130:133], v134 offset:2048
	ds_read_b128 v[134:137], v134 offset:3072
	s_cmp_eq_u32 s78, 28
	s_cselect_b32 s65, s1, s62
	s_cselect_b32 s64, s51, s0
	s_cselect_b32 s63, s49, s75
	s_cselect_b32 s62, s57, s59
	v_lshl_add_u64 v[192:193], s[60:61], 0, v[172:173]
	s_add_i32 m0, s77, 0xc000
	ds_read_b128 v[138:141], v225
	ds_read_b128 v[142:145], v225 offset:1024
	ds_read_b128 v[146:149], v225 offset:2048
	ds_read_b128 v[150:153], v225 offset:3072
	ds_read_b128 v[176:179], v225 offset:4096
	ds_read_b128 v[180:183], v225 offset:5120
	ds_read_b128 v[184:187], v225 offset:6144
	ds_read_b128 v[188:191], v225 offset:7168
	global_load_lds_dwordx4 v[192:193], off
	v_lshl_add_u64 v[192:193], s[60:61], 0, v[174:175]
	s_add_i32 m0, s77, 0xe000
	s_nop 0
	global_load_lds_dwordx4 v[192:193], off
	s_waitcnt lgkmcnt(8)
	s_barrier
	s_waitcnt lgkmcnt(0)
	s_waitcnt lgkmcnt(0)
	v_mfma_f32_16x16x32_bf16 v[158:161], v[122:125], v[138:141], v[158:161]
	v_mfma_f32_16x16x32_bf16 v[60:63], v[130:133], v[138:141], v[60:63]
	v_mfma_f32_16x16x32_bf16 v[118:121], v[122:125], v[146:149], v[118:121]
	v_mfma_f32_16x16x32_bf16 v[52:55], v[130:133], v[146:149], v[52:55]
	v_mfma_f32_16x16x32_bf16 v[110:113], v[122:125], v[176:179], v[110:113]
	v_mfma_f32_16x16x32_bf16 v[44:47], v[130:133], v[176:179], v[44:47]
	v_mfma_f32_16x16x32_bf16 v[106:109], v[122:125], v[184:187], v[106:109]
	v_mfma_f32_16x16x32_bf16 v[40:43], v[130:133], v[184:187], v[40:43]
	v_mfma_f32_16x16x32_bf16 v[158:161], v[126:129], v[142:145], v[158:161]
	v_mfma_f32_16x16x32_bf16 v[60:63], v[134:137], v[142:145], v[60:63]
	v_mfma_f32_16x16x32_bf16 v[118:121], v[126:129], v[150:153], v[118:121]
	v_mfma_f32_16x16x32_bf16 v[52:55], v[134:137], v[150:153], v[52:55]
	v_mfma_f32_16x16x32_bf16 v[110:113], v[126:129], v[180:183], v[110:113]
	v_mfma_f32_16x16x32_bf16 v[44:47], v[134:137], v[180:183], v[44:47]
	v_mfma_f32_16x16x32_bf16 v[106:109], v[126:129], v[188:191], v[106:109]
	v_mfma_f32_16x16x32_bf16 v[40:43], v[134:137], v[188:191], v[40:43]
	s_barrier
	s_add_i32 s0, 0, 0x14000
	s_add_i32 s80, s80, s76
	v_add_u32_e32 v204, s0, v213
	v_lshl_add_u64 v[208:209], s[62:63], 0, v[96:97]
	s_mov_b32 m0, s80
	ds_read_b128 v[192:195], v204
	ds_read_b128 v[196:199], v204 offset:1024
	ds_read_b128 v[200:203], v204 offset:2048
	ds_read_b128 v[204:207], v204 offset:3072
	global_load_lds_dwordx4 v[208:209], off
	v_lshl_add_u64 v[210:211], s[62:63], 0, v[166:167]
	s_add_i32 m0, s80, 0x2000
	s_nop 0
	global_load_lds_dwordx4 v[210:211], off
	s_barrier
	s_waitcnt lgkmcnt(0)
	s_waitcnt lgkmcnt(0)
	v_mfma_f32_16x16x32_bf16 v[154:157], v[192:195], v[138:141], v[154:157]
	v_mfma_f32_16x16x32_bf16 v[56:59], v[200:203], v[138:141], v[56:59]
	v_mfma_f32_16x16x32_bf16 v[114:117], v[192:195], v[146:149], v[114:117]
	v_mfma_f32_16x16x32_bf16 v[48:51], v[200:203], v[146:149], v[48:51]
	v_mfma_f32_16x16x32_bf16 v[102:105], v[192:195], v[176:179], v[102:105]
	v_mfma_f32_16x16x32_bf16 v[36:39], v[200:203], v[176:179], v[36:39]
	v_mfma_f32_16x16x32_bf16 v[98:101], v[192:195], v[184:187], v[98:101]
	v_mfma_f32_16x16x32_bf16 v[32:35], v[200:203], v[184:187], v[32:35]
	v_mfma_f32_16x16x32_bf16 v[154:157], v[196:199], v[142:145], v[154:157]
	v_mfma_f32_16x16x32_bf16 v[56:59], v[204:207], v[142:145], v[56:59]
	v_mfma_f32_16x16x32_bf16 v[114:117], v[196:199], v[150:153], v[114:117]
	v_mfma_f32_16x16x32_bf16 v[48:51], v[204:207], v[150:153], v[48:51]
	v_mfma_f32_16x16x32_bf16 v[102:105], v[196:199], v[180:183], v[102:105]
	v_mfma_f32_16x16x32_bf16 v[36:39], v[204:207], v[180:183], v[36:39]
	v_mfma_f32_16x16x32_bf16 v[98:101], v[196:199], v[188:191], v[98:101]
	v_mfma_f32_16x16x32_bf16 v[32:35], v[204:207], v[188:191], v[32:35]
	s_mov_b32 m0, s77
	v_lshl_add_u64 v[220:221], s[64:65], 0, v[162:163]
	s_barrier
	ds_read_b128 v[138:141], v225 offset:16384
	ds_read_b128 v[142:145], v225 offset:17408
	ds_read_b128 v[146:149], v225 offset:18432
	ds_read_b128 v[150:153], v225 offset:19456
	ds_read_b128 v[176:179], v225 offset:20480
	ds_read_b128 v[180:183], v225 offset:21504
	ds_read_b128 v[184:187], v225 offset:22528
	ds_read_b128 v[188:191], v225 offset:23552
	global_load_lds_dwordx4 v[220:221], off
	v_lshl_add_u64 v[222:223], s[64:65], 0, v[164:165]
	s_mov_b32 m0, s86
	s_nop 0
	global_load_lds_dwordx4 v[222:223], off
	s_barrier
	s_waitcnt lgkmcnt(0)
	s_waitcnt lgkmcnt(0)
	v_mfma_f32_16x16x32_bf16 v[92:95], v[122:125], v[138:141], v[92:95]
	v_mfma_f32_16x16x32_bf16 v[28:31], v[130:133], v[138:141], v[28:31]
	v_mfma_f32_16x16x32_bf16 v[84:87], v[122:125], v[146:149], v[84:87]
	v_mfma_f32_16x16x32_bf16 v[20:23], v[130:133], v[146:149], v[20:23]
	v_mfma_f32_16x16x32_bf16 v[76:79], v[122:125], v[176:179], v[76:79]
	v_mfma_f32_16x16x32_bf16 v[12:15], v[130:133], v[176:179], v[12:15]
	v_mfma_f32_16x16x32_bf16 v[72:75], v[122:125], v[184:187], v[72:75]
	v_mfma_f32_16x16x32_bf16 v[8:11], v[130:133], v[184:187], v[8:11]
	v_mfma_f32_16x16x32_bf16 v[92:95], v[126:129], v[142:145], v[92:95]
	v_mfma_f32_16x16x32_bf16 v[28:31], v[134:137], v[142:145], v[28:31]
	v_mfma_f32_16x16x32_bf16 v[84:87], v[126:129], v[150:153], v[84:87]
	v_mfma_f32_16x16x32_bf16 v[20:23], v[134:137], v[150:153], v[20:23]
	v_mfma_f32_16x16x32_bf16 v[76:79], v[126:129], v[180:183], v[76:79]
	v_mfma_f32_16x16x32_bf16 v[12:15], v[134:137], v[180:183], v[12:15]
	v_mfma_f32_16x16x32_bf16 v[72:75], v[126:129], v[188:191], v[72:75]
	v_mfma_f32_16x16x32_bf16 v[8:11], v[134:137], v[188:191], v[8:11]
	s_barrier
; #define PG8_STAGE(bufoff, gbase, voff) do { _Pragma("unroll") for (int _i = 0; _i < 2; ++_i) \
;     __builtin_amdgcn_global_load_lds((const unsigned*)((const char*)(gbase) + (voff)[_i]), (LAS unsigned*)(lds + (bufoff) + ldsw + _i * 8192), 16, 0, 0); } while (0)
; #define PG8_LDA(dst, b, h) do { _Pragma("unroll") for (int m = 0; m < 4; ++m) _Pragma("unroll") for (int k = 0; k < 2; ++k) dst[m][k] = *(const LAS bf16x8*)(lds + PG8_SA(b, h) + aoff + m * 2048 + k * 1024); } while (0)
; #define PG8_LDB(dst, b, h) do { _Pragma("unroll") for (int n = 0; n < 2; ++n) _Pragma("unroll") for (int k = 0; k < 2; ++k) dst[n][k] = *(const LAS bf16x8*)(lds + PG8_SB(b, h) + boff + n * 2048 + k * 1024); } while (0)
; #define PG8_MMA(ai, bj, At, Bt) do { __builtin_amdgcn_s_setprio(1); _Pragma("unroll") for (int m = 0; m < 4; ++m) _Pragma("unroll") for (int n = 0; n < 2; ++n) _Pragma("unroll") for (int k = 0; k < 2; ++k) \
;     acc[ai][bj][m][n] = __builtin_amdgcn_mfma_f32_16x16x32_bf16(Bt[n][k], At[m][k], acc[ai][bj][m][n], 0, 0, 0); __builtin_amdgcn_s_setprio(0); } while (0)
; #define PG8_WAIT_V(n) asm volatile("s_waitcnt vmcnt(" #n ")" ::: "memory")
; #define PG8_WAIT_L(n) asm volatile("s_waitcnt lgkmcnt(" #n ")" ::: "memory")
; #define PG8_BAR __builtin_amdgcn_s_barrier()
; #define PG8_SCHED __builtin_amdgcn_sched_barrier(0)
; template <class Epi>
; __device__ __forceinline__ void gemm_phase(LAS unsigned char* lds, const Gemm g, const StaticOrder& S, const Epi& E, int wv0) {
;     ...
;       PG8_STAGE(PG8_SB(0, 1), b2 + hstepB, voffB);
;       PG8_WAIT_V(6); PG8_BAR; PG8_MMA(1, 1, At, B1); PG8_BAR;
;       PG8_LDB(B0, 1, 0); PG8_SCHED; PG8_LDA(At, 1, 0); PG8_STAGE(PG8_SA(0, 1), a2 + hstepA, voffA);
;       PG8_WAIT_L(8); PG8_BAR; PG8_WAIT_L(0); PG8_MMA(0, 0, At, B0); PG8_BAR; PG8_SCHED;
;       PG8_LDB(B1, 1, 1); PG8_STAGE(PG8_SB(1, 0), b3, voffB);
;       PG8_BAR; PG8_WAIT_L(0); PG8_MMA(0, 1, At, B1); PG8_BAR;
	s_add_u32 vcc_lo, s62, 0x80000
	s_addc_u32 vcc_hi, s63, 0
	s_add_i32 s0, s0, s76
	v_lshl_add_u64 v[122:123], vcc, 0, v[96:97]
	s_mov_b32 m0, s0
	s_nop 0
	global_load_lds_dwordx4 v[122:123], off
	v_lshl_add_u64 v[122:123], vcc, 0, v[166:167]
	s_add_i32 m0, s0, 0x2000
	s_nop 0
	global_load_lds_dwordx4 v[122:123], off
	s_waitcnt vmcnt(6)
	s_barrier
	v_mfma_f32_16x16x32_bf16 v[88:91], v[192:195], v[138:141], v[88:91]
	v_mfma_f32_16x16x32_bf16 v[24:27], v[200:203], v[138:141], v[24:27]
	v_mfma_f32_16x16x32_bf16 v[80:83], v[192:195], v[146:149], v[80:83]
	v_mfma_f32_16x16x32_bf16 v[16:19], v[200:203], v[146:149], v[16:19]
	v_mfma_f32_16x16x32_bf16 v[68:71], v[192:195], v[176:179], v[68:71]
	v_mfma_f32_16x16x32_bf16 v[4:7], v[200:203], v[176:179], v[4:7]
	v_mfma_f32_16x16x32_bf16 v[64:67], v[192:195], v[184:187], v[64:67]
	v_mfma_f32_16x16x32_bf16 v[0:3], v[200:203], v[184:187], v[0:3]
	v_mfma_f32_16x16x32_bf16 v[88:91], v[196:199], v[142:145], v[88:91]
	v_mfma_f32_16x16x32_bf16 v[24:27], v[204:207], v[142:145], v[24:27]
	v_mfma_f32_16x16x32_bf16 v[80:83], v[196:199], v[150:153], v[80:83]
	v_mfma_f32_16x16x32_bf16 v[16:19], v[204:207], v[150:153], v[16:19]
	v_mfma_f32_16x16x32_bf16 v[68:71], v[196:199], v[180:183], v[68:71]
	v_mfma_f32_16x16x32_bf16 v[4:7], v[204:207], v[180:183], v[4:7]
	v_mfma_f32_16x16x32_bf16 v[64:67], v[196:199], v[188:191], v[64:67]
	v_mfma_f32_16x16x32_bf16 v[0:3], v[204:207], v[188:191], v[0:3]
	s_add_i32 s0, 0, 0x18000
	v_add_u32_e32 v134, s0, v213
	s_barrier
	ds_read_b128 v[122:125], v134
	ds_read_b128 v[126:129], v134 offset:1024
	ds_read_b128 v[130:133], v134 offset:2048
	ds_read_b128 v[134:137], v134 offset:3072
	s_add_u32 s64, s64, 0x80000
	s_addc_u32 s65, s65, 0
	s_mov_b32 m0, s87
	v_lshl_add_u64 v[192:193], s[64:65], 0, v[162:163]
	ds_read_b128 v[138:141], v225 offset:32768
	ds_read_b128 v[142:145], v225 offset:33792
	ds_read_b128 v[146:149], v225 offset:34816
	ds_read_b128 v[150:153], v225 offset:35840
	ds_read_b128 v[176:179], v225 offset:36864
	ds_read_b128 v[180:183], v225 offset:37888
	ds_read_b128 v[184:187], v225 offset:38912
	ds_read_b128 v[188:191], v225 offset:39936
	global_load_lds_dwordx4 v[192:193], off
	v_lshl_add_u64 v[192:193], s[64:65], 0, v[164:165]
	s_mov_b32 m0, s88
	s_nop 0
	global_load_lds_dwordx4 v[192:193], off
	s_waitcnt lgkmcnt(8)
	s_barrier
	s_waitcnt lgkmcnt(0)
	s_waitcnt lgkmcnt(0)
	v_mfma_f32_16x16x32_bf16 v[158:161], v[122:125], v[138:141], v[158:161]
	v_mfma_f32_16x16x32_bf16 v[60:63], v[130:133], v[138:141], v[60:63]
	v_mfma_f32_16x16x32_bf16 v[118:121], v[122:125], v[146:149], v[118:121]
	v_mfma_f32_16x16x32_bf16 v[52:55], v[130:133], v[146:149], v[52:55]
	v_mfma_f32_16x16x32_bf16 v[110:113], v[122:125], v[176:179], v[110:113]
	v_mfma_f32_16x16x32_bf16 v[44:47], v[130:133], v[176:179], v[44:47]
	v_mfma_f32_16x16x32_bf16 v[106:109], v[122:125], v[184:187], v[106:109]
	v_mfma_f32_16x16x32_bf16 v[40:43], v[130:133], v[184:187], v[40:43]
	v_mfma_f32_16x16x32_bf16 v[158:161], v[126:129], v[142:145], v[158:161]
	v_mfma_f32_16x16x32_bf16 v[60:63], v[134:137], v[142:145], v[60:63]
	v_mfma_f32_16x16x32_bf16 v[118:121], v[126:129], v[150:153], v[118:121]
	v_mfma_f32_16x16x32_bf16 v[52:55], v[134:137], v[150:153], v[52:55]
	v_mfma_f32_16x16x32_bf16 v[110:113], v[126:129], v[180:183], v[110:113]
	v_mfma_f32_16x16x32_bf16 v[44:47], v[134:137], v[180:183], v[44:47]
	v_mfma_f32_16x16x32_bf16 v[106:109], v[126:129], v[188:191], v[106:109]
	v_mfma_f32_16x16x32_bf16 v[40:43], v[134:137], v[188:191], v[40:43]
	s_barrier
	s_add_i32 s64, 0, 0x1c000
	s_add_i32 s0, s0, s76
	v_add_u32_e32 v204, s64, v213
	v_lshl_add_u64 v[208:209], v[208:209], 0, s[72:73]
	s_mov_b32 m0, s0
	ds_read_b128 v[192:195], v204
	ds_read_b128 v[196:199], v204 offset:1024
	ds_read_b128 v[200:203], v204 offset:2048
	ds_read_b128 v[204:207], v204 offset:3072
	global_load_lds_dwordx4 v[208:209], off
	v_lshl_add_u64 v[208:209], v[210:211], 0, s[72:73]
	s_add_i32 m0, s0, 0x2000
	s_nop 0
	global_load_lds_dwordx4 v[208:209], off
	s_barrier
	s_waitcnt lgkmcnt(0)
	s_waitcnt lgkmcnt(0)
	v_mfma_f32_16x16x32_bf16 v[154:157], v[192:195], v[138:141], v[154:157]
	v_mfma_f32_16x16x32_bf16 v[56:59], v[200:203], v[138:141], v[56:59]
	v_mfma_f32_16x16x32_bf16 v[114:117], v[192:195], v[146:149], v[114:117]
	v_mfma_f32_16x16x32_bf16 v[48:51], v[200:203], v[146:149], v[48:51]
	v_mfma_f32_16x16x32_bf16 v[102:105], v[192:195], v[176:179], v[102:105]
	v_mfma_f32_16x16x32_bf16 v[36:39], v[200:203], v[176:179], v[36:39]
	v_mfma_f32_16x16x32_bf16 v[98:101], v[192:195], v[184:187], v[98:101]
	v_mfma_f32_16x16x32_bf16 v[32:35], v[200:203], v[184:187], v[32:35]
	v_mfma_f32_16x16x32_bf16 v[154:157], v[196:199], v[142:145], v[154:157]
	v_mfma_f32_16x16x32_bf16 v[56:59], v[204:207], v[142:145], v[56:59]
	v_mfma_f32_16x16x32_bf16 v[114:117], v[196:199], v[150:153], v[114:117]
	v_mfma_f32_16x16x32_bf16 v[48:51], v[204:207], v[150:153], v[48:51]
	v_mfma_f32_16x16x32_bf16 v[102:105], v[196:199], v[180:183], v[102:105]
	v_mfma_f32_16x16x32_bf16 v[36:39], v[204:207], v[180:183], v[36:39]
	v_mfma_f32_16x16x32_bf16 v[98:101], v[196:199], v[188:191], v[98:101]
	v_mfma_f32_16x16x32_bf16 v[32:35], v[204:207], v[188:191], v[32:35]
	s_mov_b32 m0, s89
	v_lshl_add_u64 v[208:209], v[220:221], 0, s[72:73]
	s_barrier
; #define LAS __attribute__((address_space(3)))
; #define PG8_STAGE(bufoff, gbase, voff) do { _Pragma("unroll") for (int _i = 0; _i < 2; ++_i) \
;     __builtin_amdgcn_global_load_lds((const unsigned*)((const char*)(gbase) + (voff)[_i]), (LAS unsigned*)(lds + (bufoff) + ldsw + _i * 8192), 16, 0, 0); } while (0)
; #define PG8_LDA(dst, b, h) do { _Pragma("unroll") for (int m = 0; m < 4; ++m) _Pragma("unroll") for (int k = 0; k < 2; ++k) dst[m][k] = *(const LAS bf16x8*)(lds + PG8_SA(b, h) + aoff + m * 2048 + k * 1024); } while (0)
; #define PG8_MMA(ai, bj, At, Bt) do { __builtin_amdgcn_s_setprio(1); _Pragma("unroll") for (int m = 0; m < 4; ++m) _Pragma("unroll") for (int n = 0; n < 2; ++n) _Pragma("unroll") for (int k = 0; k < 2; ++k) \
;     acc[ai][bj][m][n] = __builtin_amdgcn_mfma_f32_16x16x32_bf16(Bt[n][k], At[m][k], acc[ai][bj][m][n], 0, 0, 0); __builtin_amdgcn_s_setprio(0); } while (0)
; #define PG8_WAIT_V(n) asm volatile("s_waitcnt vmcnt(" #n ")" ::: "memory")
; #define PG8_WAIT_L(n) asm volatile("s_waitcnt lgkmcnt(" #n ")" ::: "memory")
; #define PG8_BAR __builtin_amdgcn_s_barrier()
; template <class Epi>
; __device__ __forceinline__ void gemm_phase(LAS unsigned char* lds, const Gemm g, const StaticOrder& S, const Epi& E, int wv0) {
;     ...
;       PG8_BAR; PG8_WAIT_L(0); PG8_MMA(0, 1, At, B1); PG8_BAR;
;       PG8_LDA(At, 1, 1); PG8_STAGE(PG8_SA(1, 0), a3, voffA);
;       PG8_BAR; PG8_WAIT_L(0); PG8_MMA(1, 0, At, B0); PG8_BAR; PG8_SCHED;
;       PG8_STAGE(PG8_SB(1, 1), b3 + hstepB, voffB);
;       PG8_WAIT_V(6); PG8_BAR; PG8_MMA(1, 1, At, B1); PG8_BAR;
;     }
;     E(acc, cur, wr, wc, fr, fq);
; __device__ __forceinline__ void epi_upc(const EpiP& e, const f32x4 (&acc)[2][2][4][2], const pg8::Unit& u, int wr, int wc, int fr, int fq) {
;     ...
;         u32x4 w; w.x = pk2(acc[ai][bj][m][0][0], acc[ai][bj][m][0][1]); w.y = pk2(acc[ai][bj][m][0][2], acc[ai][bj][m][0][3]);
;         w.z = pk2(acc[ai][bj][m][1][0], acc[ai][bj][m][1][1]); w.w = pk2(acc[ai][bj][m][1][2], acc[ai][bj][m][1][3]);
;         if (m == 3 && fr >= 14) *(LAS u32x4*)(ex + ((g * 2 + (fr - 14)) * 256 + bj * 128 + lc0) * 2) = w;
;         const int ucol = bj * DFF + 128 * u.pn + lc0;
;         if (g == 15 && fr >= 14) *(u32x4*)(side + ((size_t)u.pm * 4 + 2 + (fr - 14)) * NUP + ucol) = w;
;         if (g == 0 && fr < 2) *(u32x4*)(side + ((size_t)u.pm * 4 + fr) * NUP + ucol) = w;
	ds_read_b128 v[138:141], v225 offset:49152
	ds_read_b128 v[142:145], v225 offset:50176
	ds_read_b128 v[146:149], v225 offset:51200
	ds_read_b128 v[150:153], v225 offset:52224
	ds_read_b128 v[176:179], v225 offset:53248
	ds_read_b128 v[180:183], v225 offset:54272
	ds_read_b128 v[184:187], v225 offset:55296
	ds_read_b128 v[188:191], v225 offset:56320
	global_load_lds_dwordx4 v[208:209], off
	v_lshl_add_u64 v[208:209], v[222:223], 0, s[72:73]
	s_mov_b32 m0, s92
	s_nop 0
	global_load_lds_dwordx4 v[208:209], off
	s_barrier
	s_waitcnt lgkmcnt(0)
	s_waitcnt lgkmcnt(0)
	v_mfma_f32_16x16x32_bf16 v[92:95], v[122:125], v[138:141], v[92:95]
	v_mfma_f32_16x16x32_bf16 v[28:31], v[130:133], v[138:141], v[28:31]
	v_mfma_f32_16x16x32_bf16 v[84:87], v[122:125], v[146:149], v[84:87]
	v_mfma_f32_16x16x32_bf16 v[20:23], v[130:133], v[146:149], v[20:23]
	v_mfma_f32_16x16x32_bf16 v[76:79], v[122:125], v[176:179], v[76:79]
	v_mfma_f32_16x16x32_bf16 v[12:15], v[130:133], v[176:179], v[12:15]
	v_mfma_f32_16x16x32_bf16 v[72:75], v[122:125], v[184:187], v[72:75]
	v_mfma_f32_16x16x32_bf16 v[8:11], v[130:133], v[184:187], v[8:11]
	v_mfma_f32_16x16x32_bf16 v[92:95], v[126:129], v[142:145], v[92:95]
	v_mfma_f32_16x16x32_bf16 v[28:31], v[134:137], v[142:145], v[28:31]
	v_mfma_f32_16x16x32_bf16 v[84:87], v[126:129], v[150:153], v[84:87]
	v_mfma_f32_16x16x32_bf16 v[20:23], v[134:137], v[150:153], v[20:23]
	v_mfma_f32_16x16x32_bf16 v[76:79], v[126:129], v[180:183], v[76:79]
	v_mfma_f32_16x16x32_bf16 v[12:15], v[134:137], v[180:183], v[12:15]
	v_mfma_f32_16x16x32_bf16 v[72:75], v[126:129], v[188:191], v[72:75]
	v_mfma_f32_16x16x32_bf16 v[8:11], v[134:137], v[188:191], v[8:11]
	s_barrier
	s_add_u32 s62, s62, 0x80080
	s_addc_u32 s63, s63, 0
	s_add_i32 s0, s64, s76
	v_lshl_add_u64 v[122:123], s[62:63], 0, v[96:97]
	s_mov_b32 m0, s0
	s_nop 0
	global_load_lds_dwordx4 v[122:123], off
	v_lshl_add_u64 v[122:123], s[62:63], 0, v[166:167]
	s_add_i32 m0, s0, 0x2000
	s_nop 0
	global_load_lds_dwordx4 v[122:123], off
	s_waitcnt vmcnt(6)
	s_barrier
	v_mfma_f32_16x16x32_bf16 v[88:91], v[192:195], v[138:141], v[88:91]
	v_mfma_f32_16x16x32_bf16 v[24:27], v[200:203], v[138:141], v[24:27]
	v_mfma_f32_16x16x32_bf16 v[80:83], v[192:195], v[146:149], v[80:83]
	v_mfma_f32_16x16x32_bf16 v[16:19], v[200:203], v[146:149], v[16:19]
	v_mfma_f32_16x16x32_bf16 v[68:71], v[192:195], v[176:179], v[68:71]
	v_mfma_f32_16x16x32_bf16 v[4:7], v[200:203], v[176:179], v[4:7]
	v_mfma_f32_16x16x32_bf16 v[64:67], v[192:195], v[184:187], v[64:67]
	v_mfma_f32_16x16x32_bf16 v[0:3], v[200:203], v[184:187], v[0:3]
	v_mfma_f32_16x16x32_bf16 v[88:91], v[196:199], v[142:145], v[88:91]
	v_mfma_f32_16x16x32_bf16 v[24:27], v[204:207], v[142:145], v[24:27]
	v_mfma_f32_16x16x32_bf16 v[80:83], v[196:199], v[150:153], v[80:83]
	v_mfma_f32_16x16x32_bf16 v[16:19], v[204:207], v[150:153], v[16:19]
	v_mfma_f32_16x16x32_bf16 v[68:71], v[196:199], v[180:183], v[68:71]
	v_mfma_f32_16x16x32_bf16 v[4:7], v[204:207], v[180:183], v[4:7]
	v_mfma_f32_16x16x32_bf16 v[64:67], v[196:199], v[188:191], v[64:67]
	v_mfma_f32_16x16x32_bf16 v[0:3], v[204:207], v[188:191], v[0:3]
	s_add_i32 s78, s78, 2
	s_add_u32 s60, s60, 0x100
	s_addc_u32 s61, s61, 0
	s_add_u32 s59, s59, 0x100
	s_addc_u32 s75, s75, 0
	s_cmp_gt_u32 s78, 29
	s_barrier
	s_cbranch_scc0 .LBB0_1270
	s_setprio 0
	s_and_saveexec_b64 s[60:61], s[36:37]
	s_movk_i32 s78, 0x5800
	s_cbranch_execz .LBB0_1273
	s_ashr_i32 s57, s56, 31
	s_lshl_b64 s[0:1], s[56:57], 2
	s_lshl_b32 s49, s58, 7
	v_or_b32_e32 v127, s0, v168
	v_mov_b64_e32 v[128:129], s[14:15]
	v_or_b32_e32 v126, s49, v214
	v_mad_u64_u32 v[128:129], s[62:63], v127, s78, v[128:129]
	v_mov_b32_e32 v127, 0x5800
	v_mad_i32_i24 v129, s1, v127, v129
	v_ashrrev_i32_e32 v127, 31, v126
	v_cvt_pk_bf16_f32 v122, v158, v159
	v_cvt_pk_bf16_f32 v123, v160, v161
	v_cvt_pk_bf16_f32 v124, v60, v61
	v_cvt_pk_bf16_f32 v125, v62, v63
	v_lshl_add_u64 v[126:127], v[126:127], 1, v[128:129]
	global_store_dwordx4 v[126:127], v[122:125], off
	v_add_u32_e32 v126, s49, v169
	v_ashrrev_i32_e32 v127, 31, v126
	v_cvt_pk_bf16_f32 v122, v154, v155
	v_cvt_pk_bf16_f32 v123, v156, v157
	v_cvt_pk_bf16_f32 v124, v56, v57
	v_cvt_pk_bf16_f32 v125, v58, v59
	v_lshl_add_u64 v[126:127], v[126:127], 1, v[128:129]
	global_store_dwordx4 v[126:127], v[122:125], off

; #define PG8_STAGE(bufoff, gbase, voff) do { _Pragma("unroll") for (int _i = 0; _i < 2; ++_i) \
;     __builtin_amdgcn_global_load_lds((const unsigned*)((const char*)(gbase) + (voff)[_i]), (LAS unsigned*)(lds + (bufoff) + ldsw + _i * 8192), 16, 0, 0); } while (0)
; #define PG8_LDA(dst, b, h) do { _Pragma("unroll") for (int m = 0; m < 4; ++m) _Pragma("unroll") for (int k = 0; k < 2; ++k) dst[m][k] = *(const LAS bf16x8*)(lds + PG8_SA(b, h) + aoff + m * 2048 + k * 1024); } while (0)
; #define PG8_LDB(dst, b, h) do { _Pragma("unroll") for (int n = 0; n < 2; ++n) _Pragma("unroll") for (int k = 0; k < 2; ++k) dst[n][k] = *(const LAS bf16x8*)(lds + PG8_SB(b, h) + boff + n * 2048 + k * 1024); } while (0)
; #define PG8_MMA(ai, bj, At, Bt) do { __builtin_amdgcn_s_setprio(1); _Pragma("unroll") for (int m = 0; m < 4; ++m) _Pragma("unroll") for (int n = 0; n < 2; ++n) _Pragma("unroll") for (int k = 0; k < 2; ++k) \
;     acc[ai][bj][m][n] = __builtin_amdgcn_mfma_f32_16x16x32_bf16(Bt[n][k], At[m][k], acc[ai][bj][m][n], 0, 0, 0); __builtin_amdgcn_s_setprio(0); } while (0)
; #define PG8_WAIT_V(n) asm volatile("s_waitcnt vmcnt(" #n ")" ::: "memory")
; #define PG8_WAIT_L(n) asm volatile("s_waitcnt lgkmcnt(" #n ")" ::: "memory")
; #define PG8_BAR __builtin_amdgcn_s_barrier()
; #define PG8_SCHED __builtin_amdgcn_sched_barrier(0)
; template <class Epi>
; __device__ __forceinline__ void gemm_phase(LAS unsigned char* lds, const Gemm g, const StaticOrder& S, const Epi& E, int wv0) {
;     ...
;       PG8_LDB(B0, 0, 0); PG8_SCHED; PG8_LDA(At, 0, 0); PG8_STAGE(PG8_SA(1, 1), a1 + hstepA, voffA);
;       PG8_WAIT_L(8); PG8_BAR; PG8_WAIT_L(0); PG8_MMA(0, 0, At, B0); PG8_BAR; PG8_SCHED;
;       PG8_LDB(B1, 0, 1); PG8_STAGE(PG8_SB(0, 0), b2, voffB);
;       PG8_BAR; PG8_WAIT_L(0); PG8_MMA(0, 1, At, B1); PG8_BAR;
;       PG8_LDA(At, 0, 1); PG8_STAGE(PG8_SA(0, 0), a2, voffA);
;       PG8_BAR; PG8_WAIT_L(0); PG8_MMA(1, 0, At, B0); PG8_BAR; PG8_SCHED;
;       PG8_STAGE(PG8_SB(0, 1), b2 + hstepB, voffB);
;       PG8_WAIT_V(6); PG8_BAR; PG8_MMA(1, 1, At, B1); PG8_BAR;
.LBB0_1429:
	s_add_u32 s14, s12, 0x100
	s_addc_u32 s15, s13, 0
	s_add_i32 s0, 0, 0x10000
	v_add_u32_e32 v142, s0, v187
	ds_read_b128 v[130:133], v142
	ds_read_b128 v[134:137], v142 offset:1024
	ds_read_b128 v[138:141], v142 offset:2048
	ds_read_b128 v[142:145], v142 offset:3072
	s_cmpk_eq_i32 s45, 0x54
	s_cselect_b32 s19, s5, s15
	s_cselect_b32 s18, s4, s14
	s_cselect_b32 s17, s7, s44
	s_cselect_b32 s16, s6, s43
	v_lshl_add_u64 v[184:185], s[12:13], 0, v[168:169]
	s_add_i32 m0, s30, 0xc000
	ds_read_b128 v[146:149], v189
	ds_read_b128 v[150:153], v189 offset:1024
	ds_read_b128 v[154:157], v189 offset:2048
	ds_read_b128 v[158:161], v189 offset:3072
	ds_read_b128 v[172:175], v189 offset:4096
	ds_read_b128 v[176:179], v189 offset:5120
	ds_read_b128 v[180:183], v189 offset:6144
	ds_read_b128 v[190:193], v189 offset:7168
	global_load_lds_dwordx4 v[184:185], off
	v_lshl_add_u64 v[184:185], s[12:13], 0, v[170:171]
	s_add_i32 m0, s30, 0xe000
	s_nop 0
	global_load_lds_dwordx4 v[184:185], off
	s_waitcnt lgkmcnt(8)
	s_barrier
	s_waitcnt lgkmcnt(0)
	s_waitcnt lgkmcnt(0)
	v_mfma_f32_16x16x32_bf16 v[126:129], v[130:133], v[146:149], v[126:129]
	v_mfma_f32_16x16x32_bf16 v[122:125], v[138:141], v[146:149], v[122:125]
	v_mfma_f32_16x16x32_bf16 v[118:121], v[130:133], v[154:157], v[118:121]
	v_mfma_f32_16x16x32_bf16 v[114:117], v[138:141], v[154:157], v[114:117]
	v_mfma_f32_16x16x32_bf16 v[92:95], v[130:133], v[172:175], v[92:95]
	v_mfma_f32_16x16x32_bf16 v[88:91], v[138:141], v[172:175], v[88:91]
	v_mfma_f32_16x16x32_bf16 v[84:87], v[130:133], v[180:183], v[84:87]
	v_mfma_f32_16x16x32_bf16 v[76:79], v[138:141], v[180:183], v[76:79]
	v_mfma_f32_16x16x32_bf16 v[126:129], v[134:137], v[150:153], v[126:129]
	v_mfma_f32_16x16x32_bf16 v[122:125], v[142:145], v[150:153], v[122:125]
	v_mfma_f32_16x16x32_bf16 v[118:121], v[134:137], v[158:161], v[118:121]
	v_mfma_f32_16x16x32_bf16 v[114:117], v[142:145], v[158:161], v[114:117]
	v_mfma_f32_16x16x32_bf16 v[92:95], v[134:137], v[176:179], v[92:95]
	v_mfma_f32_16x16x32_bf16 v[88:91], v[142:145], v[176:179], v[88:91]
	v_mfma_f32_16x16x32_bf16 v[84:87], v[134:137], v[190:193], v[84:87]
	v_mfma_f32_16x16x32_bf16 v[76:79], v[142:145], v[190:193], v[76:79]
	s_barrier
	s_add_i32 s46, 0, 0x14000
	v_add_u32_e32 v184, s46, v187
	s_add_i32 s0, s0, s29
	ds_read_b128 v[194:197], v184
	ds_read_b128 v[198:201], v184 offset:1024
	ds_read_b128 v[202:205], v184 offset:2048
	ds_read_b128 v[206:209], v184 offset:3072
	v_lshl_add_u64 v[184:185], s[16:17], 0, v[96:97]
	s_mov_b32 m0, s0
	v_lshl_add_u64 v[210:211], s[16:17], 0, v[166:167]
	global_load_lds_dwordx4 v[184:185], off
	s_add_i32 m0, s0, 0x2000
	s_nop 0
	global_load_lds_dwordx4 v[210:211], off
	s_barrier
	s_waitcnt lgkmcnt(0)
	s_waitcnt lgkmcnt(0)
	v_mfma_f32_16x16x32_bf16 v[110:113], v[194:197], v[146:149], v[110:113]
	v_mfma_f32_16x16x32_bf16 v[106:109], v[202:205], v[146:149], v[106:109]
	v_mfma_f32_16x16x32_bf16 v[102:105], v[194:197], v[154:157], v[102:105]
	v_mfma_f32_16x16x32_bf16 v[98:101], v[202:205], v[154:157], v[98:101]
	v_mfma_f32_16x16x32_bf16 v[80:83], v[194:197], v[172:175], v[80:83]
	v_mfma_f32_16x16x32_bf16 v[72:75], v[202:205], v[172:175], v[72:75]
	v_mfma_f32_16x16x32_bf16 v[68:71], v[194:197], v[180:183], v[68:71]
	v_mfma_f32_16x16x32_bf16 v[64:67], v[202:205], v[180:183], v[64:67]
	v_mfma_f32_16x16x32_bf16 v[110:113], v[198:201], v[150:153], v[110:113]
	v_mfma_f32_16x16x32_bf16 v[106:109], v[206:209], v[150:153], v[106:109]
	v_mfma_f32_16x16x32_bf16 v[102:105], v[198:201], v[158:161], v[102:105]
	v_mfma_f32_16x16x32_bf16 v[98:101], v[206:209], v[158:161], v[98:101]
	v_mfma_f32_16x16x32_bf16 v[80:83], v[198:201], v[176:179], v[80:83]
	v_mfma_f32_16x16x32_bf16 v[72:75], v[206:209], v[176:179], v[72:75]
	v_mfma_f32_16x16x32_bf16 v[68:71], v[198:201], v[190:193], v[68:71]
	v_mfma_f32_16x16x32_bf16 v[64:67], v[206:209], v[190:193], v[64:67]
	s_mov_b32 m0, s30
	v_lshl_add_u64 v[212:213], s[18:19], 0, v[162:163]
	s_barrier
	ds_read_b128 v[146:149], v189 offset:16384
	ds_read_b128 v[150:153], v189 offset:17408
	ds_read_b128 v[154:157], v189 offset:18432
	ds_read_b128 v[158:161], v189 offset:19456
	ds_read_b128 v[172:175], v189 offset:20480
	ds_read_b128 v[176:179], v189 offset:21504
	ds_read_b128 v[180:183], v189 offset:22528
	ds_read_b128 v[190:193], v189 offset:23552
	global_load_lds_dwordx4 v[212:213], off
	v_lshl_add_u64 v[214:215], s[18:19], 0, v[164:165]
	s_mov_b32 m0, s31
	s_nop 0
	global_load_lds_dwordx4 v[214:215], off
	s_barrier
	s_waitcnt lgkmcnt(0)
	s_waitcnt lgkmcnt(0)
	v_mfma_f32_16x16x32_bf16 v[60:63], v[130:133], v[146:149], v[60:63]
	v_mfma_f32_16x16x32_bf16 v[56:59], v[138:141], v[146:149], v[56:59]
	v_mfma_f32_16x16x32_bf16 v[48:51], v[130:133], v[154:157], v[48:51]
	v_mfma_f32_16x16x32_bf16 v[40:43], v[138:141], v[154:157], v[40:43]
	v_mfma_f32_16x16x32_bf16 v[28:31], v[130:133], v[172:175], v[28:31]
	v_mfma_f32_16x16x32_bf16 v[24:27], v[138:141], v[172:175], v[24:27]
	v_mfma_f32_16x16x32_bf16 v[16:19], v[130:133], v[180:183], v[16:19]
	v_mfma_f32_16x16x32_bf16 v[8:11], v[138:141], v[180:183], v[8:11]
	v_mfma_f32_16x16x32_bf16 v[60:63], v[134:137], v[150:153], v[60:63]
	v_mfma_f32_16x16x32_bf16 v[56:59], v[142:145], v[150:153], v[56:59]
	v_mfma_f32_16x16x32_bf16 v[48:51], v[134:137], v[158:161], v[48:51]
	v_mfma_f32_16x16x32_bf16 v[40:43], v[142:145], v[158:161], v[40:43]
	v_mfma_f32_16x16x32_bf16 v[28:31], v[134:137], v[176:179], v[28:31]
	v_mfma_f32_16x16x32_bf16 v[24:27], v[142:145], v[176:179], v[24:27]
	v_mfma_f32_16x16x32_bf16 v[16:19], v[134:137], v[190:193], v[16:19]
	v_mfma_f32_16x16x32_bf16 v[8:11], v[142:145], v[190:193], v[8:11]
	s_barrier
; #define PG8_STAGE(bufoff, gbase, voff) do { _Pragma("unroll") for (int _i = 0; _i < 2; ++_i) \
;     __builtin_amdgcn_global_load_lds((const unsigned*)((const char*)(gbase) + (voff)[_i]), (LAS unsigned*)(lds + (bufoff) + ldsw + _i * 8192), 16, 0, 0); } while (0)
; #define PG8_LDA(dst, b, h) do { _Pragma("unroll") for (int m = 0; m < 4; ++m) _Pragma("unroll") for (int k = 0; k < 2; ++k) dst[m][k] = *(const LAS bf16x8*)(lds + PG8_SA(b, h) + aoff + m * 2048 + k * 1024); } while (0)
; #define PG8_LDB(dst, b, h) do { _Pragma("unroll") for (int n = 0; n < 2; ++n) _Pragma("unroll") for (int k = 0; k < 2; ++k) dst[n][k] = *(const LAS bf16x8*)(lds + PG8_SB(b, h) + boff + n * 2048 + k * 1024); } while (0)
; #define PG8_MMA(ai, bj, At, Bt) do { __builtin_amdgcn_s_setprio(1); _Pragma("unroll") for (int m = 0; m < 4; ++m) _Pragma("unroll") for (int n = 0; n < 2; ++n) _Pragma("unroll") for (int k = 0; k < 2; ++k) \
;     acc[ai][bj][m][n] = __builtin_amdgcn_mfma_f32_16x16x32_bf16(Bt[n][k], At[m][k], acc[ai][bj][m][n], 0, 0, 0); __builtin_amdgcn_s_setprio(0); } while (0)
; #define PG8_WAIT_V(n) asm volatile("s_waitcnt vmcnt(" #n ")" ::: "memory")
; #define PG8_WAIT_L(n) asm volatile("s_waitcnt lgkmcnt(" #n ")" ::: "memory")
; #define PG8_BAR __builtin_amdgcn_s_barrier()
; #define PG8_SCHED __builtin_amdgcn_sched_barrier(0)
; template <class Epi>
; __device__ __forceinline__ void gemm_phase(LAS unsigned char* lds, const Gemm g, const StaticOrder& S, const Epi& E, int wv0) {
;     ...
;       PG8_STAGE(PG8_SB(0, 1), b2 + hstepB, voffB);
;       PG8_WAIT_V(6); PG8_BAR; PG8_MMA(1, 1, At, B1); PG8_BAR;
;       PG8_LDB(B0, 1, 0); PG8_SCHED; PG8_LDA(At, 1, 0); PG8_STAGE(PG8_SA(0, 1), a2 + hstepA, voffA);
;       PG8_WAIT_L(8); PG8_BAR; PG8_WAIT_L(0); PG8_MMA(0, 0, At, B0); PG8_BAR; PG8_SCHED;
;       PG8_LDB(B1, 1, 1); PG8_STAGE(PG8_SB(1, 0), b3, voffB);
;       PG8_BAR; PG8_WAIT_L(0); PG8_MMA(0, 1, At, B1); PG8_BAR;
;       PG8_LDA(At, 1, 1); PG8_STAGE(PG8_SA(1, 0), a3, voffA);
;       PG8_BAR; PG8_WAIT_L(0); PG8_MMA(1, 0, At, B0); PG8_BAR; PG8_SCHED;
	s_add_u32 s12, s16, 0x160000
	s_addc_u32 s13, s17, 0
	s_add_i32 s0, s46, s29
	v_lshl_add_u64 v[130:131], s[12:13], 0, v[96:97]
	s_mov_b32 m0, s0
	s_nop 0
	global_load_lds_dwordx4 v[130:131], off
	v_lshl_add_u64 v[130:131], s[12:13], 0, v[166:167]
	s_add_i32 m0, s0, 0x2000
	s_nop 0
	global_load_lds_dwordx4 v[130:131], off
	s_waitcnt vmcnt(6)
	s_barrier
	v_mfma_f32_16x16x32_bf16 v[52:55], v[194:197], v[146:149], v[52:55]
	v_mfma_f32_16x16x32_bf16 v[44:47], v[202:205], v[146:149], v[44:47]
	v_mfma_f32_16x16x32_bf16 v[36:39], v[194:197], v[154:157], v[36:39]
	v_mfma_f32_16x16x32_bf16 v[32:35], v[202:205], v[154:157], v[32:35]
	v_mfma_f32_16x16x32_bf16 v[20:23], v[194:197], v[172:175], v[20:23]
	v_mfma_f32_16x16x32_bf16 v[12:15], v[202:205], v[172:175], v[12:15]
	v_mfma_f32_16x16x32_bf16 v[4:7], v[194:197], v[180:183], v[4:7]
	v_mfma_f32_16x16x32_bf16 v[0:3], v[202:205], v[180:183], v[0:3]
	v_mfma_f32_16x16x32_bf16 v[52:55], v[198:201], v[150:153], v[52:55]
	v_mfma_f32_16x16x32_bf16 v[44:47], v[206:209], v[150:153], v[44:47]
	v_mfma_f32_16x16x32_bf16 v[36:39], v[198:201], v[158:161], v[36:39]
	v_mfma_f32_16x16x32_bf16 v[32:35], v[206:209], v[158:161], v[32:35]
	v_mfma_f32_16x16x32_bf16 v[20:23], v[198:201], v[176:179], v[20:23]
	v_mfma_f32_16x16x32_bf16 v[12:15], v[206:209], v[176:179], v[12:15]
	v_mfma_f32_16x16x32_bf16 v[4:7], v[198:201], v[190:193], v[4:7]
	v_mfma_f32_16x16x32_bf16 v[0:3], v[206:209], v[190:193], v[0:3]
	s_add_i32 s0, 0, 0x18000
	v_add_u32_e32 v142, s0, v187
	s_barrier
	ds_read_b128 v[130:133], v142
	ds_read_b128 v[134:137], v142 offset:1024
	ds_read_b128 v[138:141], v142 offset:2048
	ds_read_b128 v[142:145], v142 offset:3072
	s_add_u32 s12, s18, 0x160000
	s_addc_u32 s13, s19, 0
	s_mov_b32 m0, s34
	v_lshl_add_u64 v[194:195], s[12:13], 0, v[162:163]
	ds_read_b128 v[146:149], v189 offset:32768
	ds_read_b128 v[150:153], v189 offset:33792
	ds_read_b128 v[154:157], v189 offset:34816
	ds_read_b128 v[158:161], v189 offset:35840
	ds_read_b128 v[172:175], v189 offset:36864
	ds_read_b128 v[176:179], v189 offset:37888
	ds_read_b128 v[180:183], v189 offset:38912
	ds_read_b128 v[190:193], v189 offset:39936
	global_load_lds_dwordx4 v[194:195], off
	v_lshl_add_u64 v[194:195], s[12:13], 0, v[164:165]
	s_mov_b32 m0, s35
	s_nop 0
	global_load_lds_dwordx4 v[194:195], off
	s_waitcnt lgkmcnt(8)
	s_barrier
	s_waitcnt lgkmcnt(0)
	s_waitcnt lgkmcnt(0)
	v_mfma_f32_16x16x32_bf16 v[126:129], v[130:133], v[146:149], v[126:129]
	v_mfma_f32_16x16x32_bf16 v[122:125], v[138:141], v[146:149], v[122:125]
	v_mfma_f32_16x16x32_bf16 v[118:121], v[130:133], v[154:157], v[118:121]
	v_mfma_f32_16x16x32_bf16 v[114:117], v[138:141], v[154:157], v[114:117]
	v_mfma_f32_16x16x32_bf16 v[92:95], v[130:133], v[172:175], v[92:95]
	v_mfma_f32_16x16x32_bf16 v[88:91], v[138:141], v[172:175], v[88:91]
	v_mfma_f32_16x16x32_bf16 v[84:87], v[130:133], v[180:183], v[84:87]
	v_mfma_f32_16x16x32_bf16 v[76:79], v[138:141], v[180:183], v[76:79]
	v_mfma_f32_16x16x32_bf16 v[126:129], v[134:137], v[150:153], v[126:129]
	v_mfma_f32_16x16x32_bf16 v[122:125], v[142:145], v[150:153], v[122:125]
	v_mfma_f32_16x16x32_bf16 v[118:121], v[134:137], v[158:161], v[118:121]
	v_mfma_f32_16x16x32_bf16 v[114:117], v[142:145], v[158:161], v[114:117]
	v_mfma_f32_16x16x32_bf16 v[92:95], v[134:137], v[176:179], v[92:95]
	v_mfma_f32_16x16x32_bf16 v[88:91], v[142:145], v[176:179], v[88:91]
	v_mfma_f32_16x16x32_bf16 v[84:87], v[134:137], v[190:193], v[84:87]
	v_mfma_f32_16x16x32_bf16 v[76:79], v[142:145], v[190:193], v[76:79]
	s_barrier
	s_add_i32 s18, 0, 0x1c000
	s_add_i32 s0, s0, s29
	v_add_u32_e32 v206, s18, v187
	v_lshl_add_u64 v[184:185], v[184:185], 0, s[72:73]
	s_mov_b32 m0, s0
	ds_read_b128 v[194:197], v206
	ds_read_b128 v[198:201], v206 offset:1024
	ds_read_b128 v[202:205], v206 offset:2048
	ds_read_b128 v[206:209], v206 offset:3072
	global_load_lds_dwordx4 v[184:185], off
	v_lshl_add_u64 v[184:185], v[210:211], 0, s[72:73]
	s_add_i32 m0, s0, 0x2000
	s_nop 0
	global_load_lds_dwordx4 v[184:185], off
	s_barrier
	s_waitcnt lgkmcnt(0)
	s_waitcnt lgkmcnt(0)
	v_mfma_f32_16x16x32_bf16 v[110:113], v[194:197], v[146:149], v[110:113]
	v_mfma_f32_16x16x32_bf16 v[106:109], v[202:205], v[146:149], v[106:109]
	v_mfma_f32_16x16x32_bf16 v[102:105], v[194:197], v[154:157], v[102:105]
	v_mfma_f32_16x16x32_bf16 v[98:101], v[202:205], v[154:157], v[98:101]
	v_mfma_f32_16x16x32_bf16 v[80:83], v[194:197], v[172:175], v[80:83]
	v_mfma_f32_16x16x32_bf16 v[72:75], v[202:205], v[172:175], v[72:75]
	v_mfma_f32_16x16x32_bf16 v[68:71], v[194:197], v[180:183], v[68:71]
	v_mfma_f32_16x16x32_bf16 v[64:67], v[202:205], v[180:183], v[64:67]
	v_mfma_f32_16x16x32_bf16 v[110:113], v[198:201], v[150:153], v[110:113]
	v_mfma_f32_16x16x32_bf16 v[106:109], v[206:209], v[150:153], v[106:109]
	v_mfma_f32_16x16x32_bf16 v[102:105], v[198:201], v[158:161], v[102:105]
	v_mfma_f32_16x16x32_bf16 v[98:101], v[206:209], v[158:161], v[98:101]
	v_mfma_f32_16x16x32_bf16 v[80:83], v[198:201], v[176:179], v[80:83]
	v_mfma_f32_16x16x32_bf16 v[72:75], v[206:209], v[176:179], v[72:75]
	v_mfma_f32_16x16x32_bf16 v[68:71], v[198:201], v[190:193], v[68:71]
	v_mfma_f32_16x16x32_bf16 v[64:67], v[206:209], v[190:193], v[64:67]
	s_mov_b32 m0, s36
	v_lshl_add_u64 v[184:185], v[212:213], 0, s[72:73]
	s_barrier
	ds_read_b128 v[146:149], v189 offset:49152
	ds_read_b128 v[150:153], v189 offset:50176
	ds_read_b128 v[154:157], v189 offset:51200
	ds_read_b128 v[158:161], v189 offset:52224
	ds_read_b128 v[172:175], v189 offset:53248
	ds_read_b128 v[176:179], v189 offset:54272
	ds_read_b128 v[180:183], v189 offset:55296
	ds_read_b128 v[190:193], v189 offset:56320
	global_load_lds_dwordx4 v[184:185], off
	v_lshl_add_u64 v[184:185], v[214:215], 0, s[72:73]
	s_mov_b32 m0, s37
	s_nop 0
	global_load_lds_dwordx4 v[184:185], off
	s_barrier
; #define PG8_STAGE(bufoff, gbase, voff) do { _Pragma("unroll") for (int _i = 0; _i < 2; ++_i) \
;     __builtin_amdgcn_global_load_lds((const unsigned*)((const char*)(gbase) + (voff)[_i]), (LAS unsigned*)(lds + (bufoff) + ldsw + _i * 8192), 16, 0, 0); } while (0)
; #define PG8_MMA(ai, bj, At, Bt) do { __builtin_amdgcn_s_setprio(1); _Pragma("unroll") for (int m = 0; m < 4; ++m) _Pragma("unroll") for (int n = 0; n < 2; ++n) _Pragma("unroll") for (int k = 0; k < 2; ++k) \
;     acc[ai][bj][m][n] = __builtin_amdgcn_mfma_f32_16x16x32_bf16(Bt[n][k], At[m][k], acc[ai][bj][m][n], 0, 0, 0); __builtin_amdgcn_s_setprio(0); } while (0)
; #define PG8_WAIT_V(n) asm volatile("s_waitcnt vmcnt(" #n ")" ::: "memory")
; #define PG8_WAIT_L(n) asm volatile("s_waitcnt lgkmcnt(" #n ")" ::: "memory")
; #define PG8_BAR __builtin_amdgcn_s_barrier()
; #define PG8_SCHED __builtin_amdgcn_sched_barrier(0)
; template <class Epi>
; __device__ __forceinline__ void gemm_phase(LAS unsigned char* lds, const Gemm g, const StaticOrder& S, const Epi& E, int wv0) {
;     ...
;       PG8_BAR; PG8_WAIT_L(0); PG8_MMA(1, 0, At, B0); PG8_BAR; PG8_SCHED;
;       PG8_STAGE(PG8_SB(1, 1), b3 + hstepB, voffB);
;       PG8_WAIT_V(6); PG8_BAR; PG8_MMA(1, 1, At, B1); PG8_BAR;
;     }
;     E(acc, cur, wr, wc, fr, fq);
;   __device__ __forceinline__ void emit(const EpiPre& q0, int row, int col, f32x4 a, f32x4 b, const f32x4 (&hb)[2][2], const float (&hs)[2][4], int ai_, int m_, int bj_) const {
;     ...
;     } else if (MODE == E_RES) {
;       const f32x4 r0 = q.a0, r1 = q.a1;
;       float* o = (float*)e.out + (size_t)row * DM + col;
;       *(f32x4*)o = (f32x4){ALPHA * r0[0] + v[0], ALPHA * r0[1] + v[1], ALPHA * r0[2] + v[2], ALPHA * r0[3] + v[3]};
;       *(f32x4*)(o + 4) = (f32x4){ALPHA * r1[0] + v[4], ALPHA * r1[1] + v[5], ALPHA * r1[2] + v[6], ALPHA * r1[3] + v[7]};
	s_waitcnt lgkmcnt(0)
	s_waitcnt lgkmcnt(0)
	v_mfma_f32_16x16x32_bf16 v[60:63], v[130:133], v[146:149], v[60:63]
	v_mfma_f32_16x16x32_bf16 v[56:59], v[138:141], v[146:149], v[56:59]
	v_mfma_f32_16x16x32_bf16 v[48:51], v[130:133], v[154:157], v[48:51]
	v_mfma_f32_16x16x32_bf16 v[40:43], v[138:141], v[154:157], v[40:43]
	v_mfma_f32_16x16x32_bf16 v[28:31], v[130:133], v[172:175], v[28:31]
	v_mfma_f32_16x16x32_bf16 v[24:27], v[138:141], v[172:175], v[24:27]
	v_mfma_f32_16x16x32_bf16 v[16:19], v[130:133], v[180:183], v[16:19]
	v_mfma_f32_16x16x32_bf16 v[8:11], v[138:141], v[180:183], v[8:11]
	v_mfma_f32_16x16x32_bf16 v[60:63], v[134:137], v[150:153], v[60:63]
	v_mfma_f32_16x16x32_bf16 v[56:59], v[142:145], v[150:153], v[56:59]
	v_mfma_f32_16x16x32_bf16 v[48:51], v[134:137], v[158:161], v[48:51]
	v_mfma_f32_16x16x32_bf16 v[40:43], v[142:145], v[158:161], v[40:43]
	v_mfma_f32_16x16x32_bf16 v[28:31], v[134:137], v[176:179], v[28:31]
	v_mfma_f32_16x16x32_bf16 v[24:27], v[142:145], v[176:179], v[24:27]
	v_mfma_f32_16x16x32_bf16 v[16:19], v[134:137], v[190:193], v[16:19]
	v_mfma_f32_16x16x32_bf16 v[8:11], v[142:145], v[190:193], v[8:11]
	s_barrier
	s_add_u32 s12, s16, 0x160080
	s_addc_u32 s13, s17, 0
	s_add_i32 s0, s18, s29
	v_lshl_add_u64 v[130:131], s[12:13], 0, v[96:97]
	s_mov_b32 m0, s0
	s_nop 0
	global_load_lds_dwordx4 v[130:131], off
	v_lshl_add_u64 v[130:131], s[12:13], 0, v[166:167]
	s_add_i32 m0, s0, 0x2000
	s_nop 0
	global_load_lds_dwordx4 v[130:131], off
	s_waitcnt vmcnt(6)
	s_barrier
	v_mfma_f32_16x16x32_bf16 v[52:55], v[194:197], v[146:149], v[52:55]
	v_mfma_f32_16x16x32_bf16 v[44:47], v[202:205], v[146:149], v[44:47]
	v_mfma_f32_16x16x32_bf16 v[36:39], v[194:197], v[154:157], v[36:39]
	v_mfma_f32_16x16x32_bf16 v[32:35], v[202:205], v[154:157], v[32:35]
	v_mfma_f32_16x16x32_bf16 v[20:23], v[194:197], v[172:175], v[20:23]
	v_mfma_f32_16x16x32_bf16 v[12:15], v[202:205], v[172:175], v[12:15]
	v_mfma_f32_16x16x32_bf16 v[4:7], v[194:197], v[180:183], v[4:7]
	v_mfma_f32_16x16x32_bf16 v[0:3], v[202:205], v[180:183], v[0:3]
	v_mfma_f32_16x16x32_bf16 v[52:55], v[198:201], v[150:153], v[52:55]
	v_mfma_f32_16x16x32_bf16 v[44:47], v[206:209], v[150:153], v[44:47]
	v_mfma_f32_16x16x32_bf16 v[36:39], v[198:201], v[158:161], v[36:39]
	v_mfma_f32_16x16x32_bf16 v[32:35], v[206:209], v[158:161], v[32:35]
	v_mfma_f32_16x16x32_bf16 v[20:23], v[198:201], v[176:179], v[20:23]
	v_mfma_f32_16x16x32_bf16 v[12:15], v[206:209], v[176:179], v[12:15]
	v_mfma_f32_16x16x32_bf16 v[4:7], v[198:201], v[190:193], v[4:7]
	v_mfma_f32_16x16x32_bf16 v[0:3], v[206:209], v[190:193], v[0:3]
	s_add_i32 s45, s45, 2
	s_add_u32 s43, s43, 0x100
	s_addc_u32 s44, s44, 0
	s_cmpk_gt_u32 s45, 0x55
	s_mov_b64 s[12:13], s[14:15]
	s_barrier
	s_cbranch_scc0 .LBB0_1429
	s_setprio 0
	s_load_dwordx4 s[16:19], s[54:55], 0x88
	v_lshl_add_u32 v252, s1, 8, v186
	v_lshl_or_b32 v218, s42, 8, v188
	v_lshlrev_b32_e32 v247, 13, v252
	v_lshlrev_b32_e32 v218, 2, v218
	v_lshlrev_b32_e32 v252, 3, v252
	v_add_u32_e32 v247, v247, v218
	s_add_u32 s12, s8, 0x27700000
	s_addc_u32 s13, s9, 0
	s_add_u32 s14, s10, 0x0
	s_addc_u32 s15, s11, 0
	global_load_dwordx2 v[184:185], v252, s[12:13] offset:0
	global_load_dwordx4 v[130:133], v247, s[14:15]
	global_load_dwordx4 v[134:137], v247, s[14:15] offset:16
	global_load_dwordx4 v[138:141], v247, s[14:15] offset:512
	global_load_dwordx4 v[142:145], v247, s[14:15] offset:528
	s_add_u32 s44, s10, 0x20000
	s_addc_u32 s45, s11, 0
	global_load_dwordx2 v[242:243], v252, s[12:13] offset:128
	global_load_dwordx4 v[146:149], v247, s[44:45]
	global_load_dwordx4 v[150:153], v247, s[44:45] offset:16
	global_load_dwordx4 v[154:157], v247, s[44:45] offset:512
	global_load_dwordx4 v[158:161], v247, s[44:45] offset:528
	s_add_u32 s46, s10, 0x40000
	s_addc_u32 s47, s11, 0
	global_load_dwordx2 v[248:249], v252, s[12:13] offset:256
	global_load_dwordx4 v[172:175], v247, s[46:47]
	global_load_dwordx4 v[176:179], v247, s[46:47] offset:16
	global_load_dwordx4 v[180:183], v247, s[46:47] offset:512
	global_load_dwordx4 v[238:241], v247, s[46:47] offset:528
	s_lshl_b32 s0, s66, 13
	s_waitcnt lgkmcnt(0)
	s_add_u32 s16, s16, s0
	s_addc_u32 s17, s17, 0
	s_add_u32 s18, s18, s0
	s_addc_u32 s19, s19, 0
	global_load_dwordx4 v[190:193], v218, s[16:17]
	global_load_dwordx4 v[194:197], v218, s[16:17] offset:16
	global_load_dwordx4 v[198:201], v218, s[16:17] offset:512
	global_load_dwordx4 v[202:205], v218, s[16:17] offset:528
	global_load_dwordx4 v[206:209], v218, s[18:19]
	global_load_dwordx4 v[210:213], v218, s[18:19] offset:16
	global_load_dwordx4 v[214:217], v218, s[18:19] offset:512
	global_load_dwordx4 v[234:237], v218, s[18:19] offset:528
	s_waitcnt vmcnt(0)
;   __device__ __forceinline__ void emit(const EpiPre& q0, int row, int col, f32x4 a, f32x4 b, const f32x4 (&hb)[2][2], const float (&hs)[2][4], int ai_, int m_, int bj_) const {
;     ...
;     } else if (MODE == E_RES) {
;       const f32x4 r0 = q.a0, r1 = q.a1;
;       float* o = (float*)e.out + (size_t)row * DM + col;
;       *(f32x4*)o = (f32x4){ALPHA * r0[0] + v[0], ALPHA * r0[1] + v[1], ALPHA * r0[2] + v[2], ALPHA * r0[3] + v[3]};
;       *(f32x4*)(o + 4) = (f32x4){ALPHA * r1[0] + v[4], ALPHA * r1[1] + v[5], ALPHA * r1[2] + v[6], ALPHA * r1[3] + v[7]};
	v_pk_add_f32 v[130:131], v[130:131], v[184:185] op_sel_hi:[1,0]
	v_pk_add_f32 v[132:133], v[132:133], v[184:185] op_sel_hi:[1,0]
	v_pk_add_f32 v[134:135], v[134:135], v[184:185] op_sel_hi:[1,0]
	v_pk_add_f32 v[136:137], v[136:137], v[184:185] op_sel_hi:[1,0]
	v_pk_add_f32 v[138:139], v[138:139], v[184:185] op_sel_hi:[1,0]
	v_pk_add_f32 v[140:141], v[140:141], v[184:185] op_sel_hi:[1,0]
	v_pk_add_f32 v[142:143], v[142:143], v[184:185] op_sel_hi:[1,0]
	v_pk_add_f32 v[144:145], v[144:145], v[184:185] op_sel_hi:[1,0]
	v_pk_mul_f32 v[130:131], v[130:131], v[184:185] op_sel:[0,1] op_sel_hi:[1,1]
	v_pk_mul_f32 v[132:133], v[132:133], v[184:185] op_sel:[0,1] op_sel_hi:[1,1]
	v_pk_mul_f32 v[134:135], v[134:135], v[184:185] op_sel:[0,1] op_sel_hi:[1,1]
	v_pk_mul_f32 v[136:137], v[136:137], v[184:185] op_sel:[0,1] op_sel_hi:[1,1]
	v_pk_mul_f32 v[138:139], v[138:139], v[184:185] op_sel:[0,1] op_sel_hi:[1,1]
	v_pk_mul_f32 v[140:141], v[140:141], v[184:185] op_sel:[0,1] op_sel_hi:[1,1]
	v_pk_mul_f32 v[142:143], v[142:143], v[184:185] op_sel:[0,1] op_sel_hi:[1,1]
	v_pk_mul_f32 v[144:145], v[144:145], v[184:185] op_sel:[0,1] op_sel_hi:[1,1]
	v_pk_fma_f32 v[130:131], v[190:191], v[130:131], v[206:207]
	v_pk_fma_f32 v[132:133], v[192:193], v[132:133], v[208:209]
	v_pk_fma_f32 v[134:135], v[194:195], v[134:135], v[210:211]
	v_pk_fma_f32 v[136:137], v[196:197], v[136:137], v[212:213]
	v_pk_fma_f32 v[138:139], v[198:199], v[138:139], v[214:215]
	v_pk_fma_f32 v[140:141], v[200:201], v[140:141], v[216:217]
	v_pk_fma_f32 v[142:143], v[202:203], v[142:143], v[234:235]
	v_pk_fma_f32 v[144:145], v[204:205], v[144:145], v[236:237]
	v_pk_fma_f32 v[126:127], v[130:131], s[90:91], v[126:127] op_sel_hi:[1,0,1]
	v_pk_fma_f32 v[128:129], v[132:133], s[90:91], v[128:129] op_sel_hi:[1,0,1]
	v_pk_fma_f32 v[122:123], v[134:135], s[90:91], v[122:123] op_sel_hi:[1,0,1]
	v_pk_fma_f32 v[124:125], v[136:137], s[90:91], v[124:125] op_sel_hi:[1,0,1]
	v_pk_fma_f32 v[110:111], v[138:139], s[90:91], v[110:111] op_sel_hi:[1,0,1]
	v_pk_fma_f32 v[112:113], v[140:141], s[90:91], v[112:113] op_sel_hi:[1,0,1]
	v_pk_fma_f32 v[106:107], v[142:143], s[90:91], v[106:107] op_sel_hi:[1,0,1]
	v_pk_fma_f32 v[108:109], v[144:145], s[90:91], v[108:109] op_sel_hi:[1,0,1]
	s_add_u32 s48, s10, 0x60000
	s_addc_u32 s49, s11, 0
	global_load_dwordx2 v[184:185], v252, s[12:13] offset:384
	global_load_dwordx4 v[130:133], v247, s[48:49]
	global_load_dwordx4 v[134:137], v247, s[48:49] offset:16
	global_load_dwordx4 v[138:141], v247, s[48:49] offset:512
	global_load_dwordx4 v[142:145], v247, s[48:49] offset:528
	s_waitcnt vmcnt(18)
	v_pk_add_f32 v[146:147], v[146:147], v[242:243] op_sel_hi:[1,0]
	v_pk_add_f32 v[148:149], v[148:149], v[242:243] op_sel_hi:[1,0]
	v_pk_add_f32 v[150:151], v[150:151], v[242:243] op_sel_hi:[1,0]
	v_pk_add_f32 v[152:153], v[152:153], v[242:243] op_sel_hi:[1,0]
	v_pk_add_f32 v[154:155], v[154:155], v[242:243] op_sel_hi:[1,0]
	v_pk_add_f32 v[156:157], v[156:157], v[242:243] op_sel_hi:[1,0]
	v_pk_add_f32 v[158:159], v[158:159], v[242:243] op_sel_hi:[1,0]
	v_pk_add_f32 v[160:161], v[160:161], v[242:243] op_sel_hi:[1,0]
	v_pk_mul_f32 v[146:147], v[146:147], v[242:243] op_sel:[0,1] op_sel_hi:[1,1]
	v_pk_mul_f32 v[148:149], v[148:149], v[242:243] op_sel:[0,1] op_sel_hi:[1,1]
	v_pk_mul_f32 v[150:151], v[150:151], v[242:243] op_sel:[0,1] op_sel_hi:[1,1]
	v_pk_mul_f32 v[152:153], v[152:153], v[242:243] op_sel:[0,1] op_sel_hi:[1,1]
	v_pk_mul_f32 v[154:155], v[154:155], v[242:243] op_sel:[0,1] op_sel_hi:[1,1]
	v_pk_mul_f32 v[156:157], v[156:157], v[242:243] op_sel:[0,1] op_sel_hi:[1,1]
	v_pk_mul_f32 v[158:159], v[158:159], v[242:243] op_sel:[0,1] op_sel_hi:[1,1]
	v_pk_mul_f32 v[160:161], v[160:161], v[242:243] op_sel:[0,1] op_sel_hi:[1,1]
	v_pk_fma_f32 v[146:147], v[190:191], v[146:147], v[206:207]
	v_pk_fma_f32 v[148:149], v[192:193], v[148:149], v[208:209]
	v_pk_fma_f32 v[150:151], v[194:195], v[150:151], v[210:211]
	v_pk_fma_f32 v[152:153], v[196:197], v[152:153], v[212:213]
	v_pk_fma_f32 v[154:155], v[198:199], v[154:155], v[214:215]
	v_pk_fma_f32 v[156:157], v[200:201], v[156:157], v[216:217]
	v_pk_fma_f32 v[158:159], v[202:203], v[158:159], v[234:235]
	v_pk_fma_f32 v[160:161], v[204:205], v[160:161], v[236:237]
	v_pk_fma_f32 v[118:119], v[146:147], s[90:91], v[118:119] op_sel_hi:[1,0,1]
	v_pk_fma_f32 v[120:121], v[148:149], s[90:91], v[120:121] op_sel_hi:[1,0,1]
	v_pk_fma_f32 v[114:115], v[150:151], s[90:91], v[114:115] op_sel_hi:[1,0,1]
	v_pk_fma_f32 v[116:117], v[152:153], s[90:91], v[116:117] op_sel_hi:[1,0,1]
	v_pk_fma_f32 v[102:103], v[154:155], s[90:91], v[102:103] op_sel_hi:[1,0,1]
	v_pk_fma_f32 v[104:105], v[156:157], s[90:91], v[104:105] op_sel_hi:[1,0,1]
	v_pk_fma_f32 v[98:99], v[158:159], s[90:91], v[98:99] op_sel_hi:[1,0,1]
	v_pk_fma_f32 v[100:101], v[160:161], s[90:91], v[100:101] op_sel_hi:[1,0,1]
	s_add_u32 s16, s10, 0x100000
	s_addc_u32 s17, s11, 0
	global_load_dwordx2 v[242:243], v252, s[12:13] offset:1024
	global_load_dwordx4 v[146:149], v247, s[16:17]
	global_load_dwordx4 v[150:153], v247, s[16:17] offset:16
	global_load_dwordx4 v[154:157], v247, s[16:17] offset:512
	global_load_dwordx4 v[158:161], v247, s[16:17] offset:528
	s_waitcnt vmcnt(18)
;   __device__ __forceinline__ void emit(const EpiPre& q0, int row, int col, f32x4 a, f32x4 b, const f32x4 (&hb)[2][2], const float (&hs)[2][4], int ai_, int m_, int bj_) const {
;     ...
;     } else if (MODE == E_RES) {
;       const f32x4 r0 = q.a0, r1 = q.a1;
;       float* o = (float*)e.out + (size_t)row * DM + col;
;       *(f32x4*)o = (f32x4){ALPHA * r0[0] + v[0], ALPHA * r0[1] + v[1], ALPHA * r0[2] + v[2], ALPHA * r0[3] + v[3]};
;       *(f32x4*)(o + 4) = (f32x4){ALPHA * r1[0] + v[4], ALPHA * r1[1] + v[5], ALPHA * r1[2] + v[6], ALPHA * r1[3] + v[7]};
;   __device__ __forceinline__ void operator()(const f32x4 (&acc)[2][2][4][2], const pg8::Unit& u, int wr, int wc, int fr, int fq) const {
;     ...
;     for (int gi = 0; gi < 4; ++gi) {
;       const int ai = gi >> 1, mp = gi & 1;
;       if (gi + 1 < 4) { const int ai2 = (gi + 1) >> 1, mp2 = (gi + 1) & 1;
; #pragma unroll
;         for (int i = 0; i < 4; ++i) preload(q[(gi + 1) & 1][i], row0 + ai2 * 128 + (2 * mp2 + (i >> 1)) * 16, col0 + (i & 1) * 128); }
;       asm volatile("" ::: "memory");
; #pragma unroll
;       for (int i = 0; i < 4; ++i) { const int m = 2 * mp + (i >> 1), bj = i & 1; emit(q[gi & 1][i], row0 + ai * 128 + m * 16, col0 + bj * 128, acc[ai][bj][m][0], acc[ai][bj][m][1], hb, hs, ai, m, bj); }
;       asm volatile("" ::: "memory");
;     }
	v_pk_add_f32 v[172:173], v[172:173], v[248:249] op_sel_hi:[1,0]
	v_pk_add_f32 v[174:175], v[174:175], v[248:249] op_sel_hi:[1,0]
	v_pk_add_f32 v[176:177], v[176:177], v[248:249] op_sel_hi:[1,0]
	v_pk_add_f32 v[178:179], v[178:179], v[248:249] op_sel_hi:[1,0]
	v_pk_add_f32 v[180:181], v[180:181], v[248:249] op_sel_hi:[1,0]
	v_pk_add_f32 v[182:183], v[182:183], v[248:249] op_sel_hi:[1,0]
	v_pk_add_f32 v[238:239], v[238:239], v[248:249] op_sel_hi:[1,0]
	v_pk_add_f32 v[240:241], v[240:241], v[248:249] op_sel_hi:[1,0]
	v_pk_mul_f32 v[172:173], v[172:173], v[248:249] op_sel:[0,1] op_sel_hi:[1,1]
	v_pk_mul_f32 v[174:175], v[174:175], v[248:249] op_sel:[0,1] op_sel_hi:[1,1]
	v_pk_mul_f32 v[176:177], v[176:177], v[248:249] op_sel:[0,1] op_sel_hi:[1,1]
	v_pk_mul_f32 v[178:179], v[178:179], v[248:249] op_sel:[0,1] op_sel_hi:[1,1]
	v_pk_mul_f32 v[180:181], v[180:181], v[248:249] op_sel:[0,1] op_sel_hi:[1,1]
	v_pk_mul_f32 v[182:183], v[182:183], v[248:249] op_sel:[0,1] op_sel_hi:[1,1]
	v_pk_mul_f32 v[238:239], v[238:239], v[248:249] op_sel:[0,1] op_sel_hi:[1,1]
	v_pk_mul_f32 v[240:241], v[240:241], v[248:249] op_sel:[0,1] op_sel_hi:[1,1]
	v_pk_fma_f32 v[172:173], v[190:191], v[172:173], v[206:207]
	v_pk_fma_f32 v[174:175], v[192:193], v[174:175], v[208:209]
	v_pk_fma_f32 v[176:177], v[194:195], v[176:177], v[210:211]
	v_pk_fma_f32 v[178:179], v[196:197], v[178:179], v[212:213]
	v_pk_fma_f32 v[180:181], v[198:199], v[180:181], v[214:215]
	v_pk_fma_f32 v[182:183], v[200:201], v[182:183], v[216:217]
	v_pk_fma_f32 v[238:239], v[202:203], v[238:239], v[234:235]
	v_pk_fma_f32 v[240:241], v[204:205], v[240:241], v[236:237]
	v_pk_fma_f32 v[92:93], v[172:173], s[90:91], v[92:93] op_sel_hi:[1,0,1]
	v_pk_fma_f32 v[94:95], v[174:175], s[90:91], v[94:95] op_sel_hi:[1,0,1]
	v_pk_fma_f32 v[88:89], v[176:177], s[90:91], v[88:89] op_sel_hi:[1,0,1]
	v_pk_fma_f32 v[90:91], v[178:179], s[90:91], v[90:91] op_sel_hi:[1,0,1]
	v_pk_fma_f32 v[80:81], v[180:181], s[90:91], v[80:81] op_sel_hi:[1,0,1]
	v_pk_fma_f32 v[82:83], v[182:183], s[90:91], v[82:83] op_sel_hi:[1,0,1]
	v_pk_fma_f32 v[72:73], v[238:239], s[90:91], v[72:73] op_sel_hi:[1,0,1]
	v_pk_fma_f32 v[74:75], v[240:241], s[90:91], v[74:75] op_sel_hi:[1,0,1]
	s_add_u32 s18, s10, 0x120000
	s_addc_u32 s19, s11, 0
	global_load_dwordx2 v[248:249], v252, s[12:13] offset:1152
	global_load_dwordx4 v[172:175], v247, s[18:19]
	global_load_dwordx4 v[176:179], v247, s[18:19] offset:16
	global_load_dwordx4 v[180:183], v247, s[18:19] offset:512
	global_load_dwordx4 v[238:241], v247, s[18:19] offset:528
	global_store_dwordx4 v247, v[126:129], s[14:15]
	global_store_dwordx4 v247, v[122:125], s[14:15] offset:16
	global_store_dwordx4 v247, v[110:113], s[14:15] offset:512
	global_store_dwordx4 v247, v[106:109], s[14:15] offset:528
	global_store_dwordx4 v247, v[118:121], s[44:45]
	global_store_dwordx4 v247, v[114:117], s[44:45] offset:16
	global_store_dwordx4 v247, v[102:105], s[44:45] offset:512
	global_store_dwordx4 v247, v[98:101], s[44:45] offset:528
	global_store_dwordx4 v247, v[92:95], s[46:47]
	global_store_dwordx4 v247, v[88:91], s[46:47] offset:16
	global_store_dwordx4 v247, v[80:83], s[46:47] offset:512
	global_store_dwordx4 v247, v[72:75], s[46:47] offset:528
	s_add_u32 s14, s10, 0x140000
	s_addc_u32 s15, s11, 0
	global_load_dwordx2 v[92:93], v252, s[12:13] offset:1280
	global_load_dwordx4 v[126:129], v247, s[14:15]
	global_load_dwordx4 v[122:125], v247, s[14:15] offset:16
	global_load_dwordx4 v[110:113], v247, s[14:15] offset:512
	global_load_dwordx4 v[106:109], v247, s[14:15] offset:528
	s_add_u32 s44, s10, 0x160000
	s_addc_u32 s45, s11, 0
	global_load_dwordx2 v[88:89], v252, s[12:13] offset:1408
	global_load_dwordx4 v[118:121], v247, s[44:45]
	global_load_dwordx4 v[114:117], v247, s[44:45] offset:16
	global_load_dwordx4 v[102:105], v247, s[44:45] offset:512
	global_load_dwordx4 v[98:101], v247, s[44:45] offset:528
	s_waitcnt vmcnt(32)
	v_pk_add_f32 v[130:131], v[130:131], v[184:185] op_sel_hi:[1,0]
	v_pk_add_f32 v[132:133], v[132:133], v[184:185] op_sel_hi:[1,0]
	v_pk_add_f32 v[134:135], v[134:135], v[184:185] op_sel_hi:[1,0]
	v_pk_add_f32 v[136:137], v[136:137], v[184:185] op_sel_hi:[1,0]
	v_pk_add_f32 v[138:139], v[138:139], v[184:185] op_sel_hi:[1,0]
	v_pk_add_f32 v[140:141], v[140:141], v[184:185] op_sel_hi:[1,0]
	v_pk_add_f32 v[142:143], v[142:143], v[184:185] op_sel_hi:[1,0]
	v_pk_add_f32 v[144:145], v[144:145], v[184:185] op_sel_hi:[1,0]
	v_pk_mul_f32 v[130:131], v[130:131], v[184:185] op_sel:[0,1] op_sel_hi:[1,1]
	v_pk_mul_f32 v[132:133], v[132:133], v[184:185] op_sel:[0,1] op_sel_hi:[1,1]
	v_pk_mul_f32 v[134:135], v[134:135], v[184:185] op_sel:[0,1] op_sel_hi:[1,1]
	v_pk_mul_f32 v[136:137], v[136:137], v[184:185] op_sel:[0,1] op_sel_hi:[1,1]
	v_pk_mul_f32 v[138:139], v[138:139], v[184:185] op_sel:[0,1] op_sel_hi:[1,1]
	v_pk_mul_f32 v[140:141], v[140:141], v[184:185] op_sel:[0,1] op_sel_hi:[1,1]
	v_pk_mul_f32 v[142:143], v[142:143], v[184:185] op_sel:[0,1] op_sel_hi:[1,1]
	v_pk_mul_f32 v[144:145], v[144:145], v[184:185] op_sel:[0,1] op_sel_hi:[1,1]
	v_pk_fma_f32 v[130:131], v[190:191], v[130:131], v[206:207]
	v_pk_fma_f32 v[132:133], v[192:193], v[132:133], v[208:209]
	v_pk_fma_f32 v[134:135], v[194:195], v[134:135], v[210:211]
	v_pk_fma_f32 v[136:137], v[196:197], v[136:137], v[212:213]
	v_pk_fma_f32 v[138:139], v[198:199], v[138:139], v[214:215]
	v_pk_fma_f32 v[140:141], v[200:201], v[140:141], v[216:217]
	v_pk_fma_f32 v[142:143], v[202:203], v[142:143], v[234:235]
	v_pk_fma_f32 v[144:145], v[204:205], v[144:145], v[236:237]
	v_pk_fma_f32 v[84:85], v[130:131], s[90:91], v[84:85] op_sel_hi:[1,0,1]
	v_pk_fma_f32 v[86:87], v[132:133], s[90:91], v[86:87] op_sel_hi:[1,0,1]
	v_pk_fma_f32 v[76:77], v[134:135], s[90:91], v[76:77] op_sel_hi:[1,0,1]
	v_pk_fma_f32 v[78:79], v[136:137], s[90:91], v[78:79] op_sel_hi:[1,0,1]
	v_pk_fma_f32 v[68:69], v[138:139], s[90:91], v[68:69] op_sel_hi:[1,0,1]
	v_pk_fma_f32 v[70:71], v[140:141], s[90:91], v[70:71] op_sel_hi:[1,0,1]
	v_pk_fma_f32 v[64:65], v[142:143], s[90:91], v[64:65] op_sel_hi:[1,0,1]
	v_pk_fma_f32 v[66:67], v[144:145], s[90:91], v[66:67] op_sel_hi:[1,0,1]
	global_store_dwordx4 v247, v[84:87], s[48:49]
	global_store_dwordx4 v247, v[76:79], s[48:49] offset:16
	global_store_dwordx4 v247, v[68:71], s[48:49] offset:512
	global_store_dwordx4 v247, v[64:67], s[48:49] offset:528
	s_waitcnt vmcnt(31)
;   __device__ __forceinline__ void emit(const EpiPre& q0, int row, int col, f32x4 a, f32x4 b, const f32x4 (&hb)[2][2], const float (&hs)[2][4], int ai_, int m_, int bj_) const {
;     ...
;     } else if (MODE == E_RES) {
;       const f32x4 r0 = q.a0, r1 = q.a1;
;       float* o = (float*)e.out + (size_t)row * DM + col;
;       *(f32x4*)o = (f32x4){ALPHA * r0[0] + v[0], ALPHA * r0[1] + v[1], ALPHA * r0[2] + v[2], ALPHA * r0[3] + v[3]};
;       *(f32x4*)(o + 4) = (f32x4){ALPHA * r1[0] + v[4], ALPHA * r1[1] + v[5], ALPHA * r1[2] + v[6], ALPHA * r1[3] + v[7]};
;   __device__ __forceinline__ void operator()(const f32x4 (&acc)[2][2][4][2], const pg8::Unit& u, int wr, int wc, int fr, int fq) const {
;     ...
;     for (int gi = 0; gi < 4; ++gi) {
;       const int ai = gi >> 1, mp = gi & 1;
;       if (gi + 1 < 4) { const int ai2 = (gi + 1) >> 1, mp2 = (gi + 1) & 1;
; #pragma unroll
;         for (int i = 0; i < 4; ++i) preload(q[(gi + 1) & 1][i], row0 + ai2 * 128 + (2 * mp2 + (i >> 1)) * 16, col0 + (i & 1) * 128); }
;       asm volatile("" ::: "memory");
; #pragma unroll
;       for (int i = 0; i < 4; ++i) { const int m = 2 * mp + (i >> 1), bj = i & 1; emit(q[gi & 1][i], row0 + ai * 128 + m * 16, col0 + bj * 128, acc[ai][bj][m][0], acc[ai][bj][m][1], hb, hs, ai, m, bj); }
;       asm volatile("" ::: "memory");
;     }
	v_pk_add_f32 v[146:147], v[146:147], v[242:243] op_sel_hi:[1,0]
	v_pk_add_f32 v[148:149], v[148:149], v[242:243] op_sel_hi:[1,0]
	v_pk_add_f32 v[150:151], v[150:151], v[242:243] op_sel_hi:[1,0]
	v_pk_add_f32 v[152:153], v[152:153], v[242:243] op_sel_hi:[1,0]
	v_pk_add_f32 v[154:155], v[154:155], v[242:243] op_sel_hi:[1,0]
	v_pk_add_f32 v[156:157], v[156:157], v[242:243] op_sel_hi:[1,0]
	v_pk_add_f32 v[158:159], v[158:159], v[242:243] op_sel_hi:[1,0]
	v_pk_add_f32 v[160:161], v[160:161], v[242:243] op_sel_hi:[1,0]
	v_pk_mul_f32 v[146:147], v[146:147], v[242:243] op_sel:[0,1] op_sel_hi:[1,1]
	v_pk_mul_f32 v[148:149], v[148:149], v[242:243] op_sel:[0,1] op_sel_hi:[1,1]
	v_pk_mul_f32 v[150:151], v[150:151], v[242:243] op_sel:[0,1] op_sel_hi:[1,1]
	v_pk_mul_f32 v[152:153], v[152:153], v[242:243] op_sel:[0,1] op_sel_hi:[1,1]
	v_pk_mul_f32 v[154:155], v[154:155], v[242:243] op_sel:[0,1] op_sel_hi:[1,1]
	v_pk_mul_f32 v[156:157], v[156:157], v[242:243] op_sel:[0,1] op_sel_hi:[1,1]
	v_pk_mul_f32 v[158:159], v[158:159], v[242:243] op_sel:[0,1] op_sel_hi:[1,1]
	v_pk_mul_f32 v[160:161], v[160:161], v[242:243] op_sel:[0,1] op_sel_hi:[1,1]
	v_pk_fma_f32 v[146:147], v[190:191], v[146:147], v[206:207]
	v_pk_fma_f32 v[148:149], v[192:193], v[148:149], v[208:209]
	v_pk_fma_f32 v[150:151], v[194:195], v[150:151], v[210:211]
	v_pk_fma_f32 v[152:153], v[196:197], v[152:153], v[212:213]
	v_pk_fma_f32 v[154:155], v[198:199], v[154:155], v[214:215]
	v_pk_fma_f32 v[156:157], v[200:201], v[156:157], v[216:217]
	v_pk_fma_f32 v[158:159], v[202:203], v[158:159], v[234:235]
	v_pk_fma_f32 v[160:161], v[204:205], v[160:161], v[236:237]
	v_pk_fma_f32 v[60:61], v[146:147], s[90:91], v[60:61] op_sel_hi:[1,0,1]
	v_pk_fma_f32 v[62:63], v[148:149], s[90:91], v[62:63] op_sel_hi:[1,0,1]
	v_pk_fma_f32 v[56:57], v[150:151], s[90:91], v[56:57] op_sel_hi:[1,0,1]
	v_pk_fma_f32 v[58:59], v[152:153], s[90:91], v[58:59] op_sel_hi:[1,0,1]
	v_pk_fma_f32 v[52:53], v[154:155], s[90:91], v[52:53] op_sel_hi:[1,0,1]
	v_pk_fma_f32 v[54:55], v[156:157], s[90:91], v[54:55] op_sel_hi:[1,0,1]
	v_pk_fma_f32 v[44:45], v[158:159], s[90:91], v[44:45] op_sel_hi:[1,0,1]
	v_pk_fma_f32 v[46:47], v[160:161], s[90:91], v[46:47] op_sel_hi:[1,0,1]
	global_store_dwordx4 v247, v[60:63], s[16:17]
	global_store_dwordx4 v247, v[56:59], s[16:17] offset:16
	global_store_dwordx4 v247, v[52:55], s[16:17] offset:512
	global_store_dwordx4 v247, v[44:47], s[16:17] offset:528
	s_waitcnt vmcnt(30)
	v_pk_add_f32 v[172:173], v[172:173], v[248:249] op_sel_hi:[1,0]
	v_pk_add_f32 v[174:175], v[174:175], v[248:249] op_sel_hi:[1,0]
	v_pk_add_f32 v[176:177], v[176:177], v[248:249] op_sel_hi:[1,0]
	v_pk_add_f32 v[178:179], v[178:179], v[248:249] op_sel_hi:[1,0]
	v_pk_add_f32 v[180:181], v[180:181], v[248:249] op_sel_hi:[1,0]
	v_pk_add_f32 v[182:183], v[182:183], v[248:249] op_sel_hi:[1,0]
	v_pk_add_f32 v[238:239], v[238:239], v[248:249] op_sel_hi:[1,0]
	v_pk_add_f32 v[240:241], v[240:241], v[248:249] op_sel_hi:[1,0]
	v_pk_mul_f32 v[172:173], v[172:173], v[248:249] op_sel:[0,1] op_sel_hi:[1,1]
	v_pk_mul_f32 v[174:175], v[174:175], v[248:249] op_sel:[0,1] op_sel_hi:[1,1]
	v_pk_mul_f32 v[176:177], v[176:177], v[248:249] op_sel:[0,1] op_sel_hi:[1,1]
	v_pk_mul_f32 v[178:179], v[178:179], v[248:249] op_sel:[0,1] op_sel_hi:[1,1]
	v_pk_mul_f32 v[180:181], v[180:181], v[248:249] op_sel:[0,1] op_sel_hi:[1,1]
	v_pk_mul_f32 v[182:183], v[182:183], v[248:249] op_sel:[0,1] op_sel_hi:[1,1]
	v_pk_mul_f32 v[238:239], v[238:239], v[248:249] op_sel:[0,1] op_sel_hi:[1,1]
	v_pk_mul_f32 v[240:241], v[240:241], v[248:249] op_sel:[0,1] op_sel_hi:[1,1]
	v_pk_fma_f32 v[172:173], v[190:191], v[172:173], v[206:207]
	v_pk_fma_f32 v[174:175], v[192:193], v[174:175], v[208:209]
	v_pk_fma_f32 v[176:177], v[194:195], v[176:177], v[210:211]
	v_pk_fma_f32 v[178:179], v[196:197], v[178:179], v[212:213]
	v_pk_fma_f32 v[180:181], v[198:199], v[180:181], v[214:215]
	v_pk_fma_f32 v[182:183], v[200:201], v[182:183], v[216:217]
	v_pk_fma_f32 v[238:239], v[202:203], v[238:239], v[234:235]
	v_pk_fma_f32 v[240:241], v[204:205], v[240:241], v[236:237]
	v_pk_fma_f32 v[48:49], v[172:173], s[90:91], v[48:49] op_sel_hi:[1,0,1]
	v_pk_fma_f32 v[50:51], v[174:175], s[90:91], v[50:51] op_sel_hi:[1,0,1]
	v_pk_fma_f32 v[40:41], v[176:177], s[90:91], v[40:41] op_sel_hi:[1,0,1]
	v_pk_fma_f32 v[42:43], v[178:179], s[90:91], v[42:43] op_sel_hi:[1,0,1]
	v_pk_fma_f32 v[36:37], v[180:181], s[90:91], v[36:37] op_sel_hi:[1,0,1]
	v_pk_fma_f32 v[38:39], v[182:183], s[90:91], v[38:39] op_sel_hi:[1,0,1]
	v_pk_fma_f32 v[32:33], v[238:239], s[90:91], v[32:33] op_sel_hi:[1,0,1]
	v_pk_fma_f32 v[34:35], v[240:241], s[90:91], v[34:35] op_sel_hi:[1,0,1]
	global_store_dwordx4 v247, v[48:51], s[18:19]
	global_store_dwordx4 v247, v[40:43], s[18:19] offset:16
	global_store_dwordx4 v247, v[36:39], s[18:19] offset:512
	global_store_dwordx4 v247, v[32:35], s[18:19] offset:528
	s_waitcnt vmcnt(17)
; #define PG8_WAIT_V(n) asm volatile("s_waitcnt vmcnt(" #n ")" ::: "memory")
; #define PG8_BAR __builtin_amdgcn_s_barrier()
; template <class Epi>
; __device__ __forceinline__ void gemm_phase(LAS unsigned char* lds, const Gemm g, const StaticOrder& S, const Epi& E, int wv0) {
;     ...
;     E(acc, cur, wr, wc, fr, fq);
;     if (!has_next) break;
; #pragma unroll
;     for (int a = 0; a < 2; ++a)
; #pragma unroll
;       for (int b = 0; b < 2; ++b)
; #pragma unroll
;         for (int m = 0; m < 4; ++m)
; #pragma unroll
;           for (int n = 0; n < 2; ++n) acc[a][b][m][n] = (f32x4){0.f, 0.f, 0.f, 0.f};
;     cur = nxt; cA = nA; cB = nB; ++ui;
;   }
;   PG8_WAIT_V(0);
;   if (wr == 0) PG8_BAR;
;   PG8_BAR;
;   __device__ __forceinline__ void emit(const EpiPre& q0, int row, int col, f32x4 a, f32x4 b, const f32x4 (&hb)[2][2], const float (&hs)[2][4], int ai_, int m_, int bj_) const {
;     ...
;     } else if (MODE == E_RES) {
;       const f32x4 r0 = q.a0, r1 = q.a1;
;       float* o = (float*)e.out + (size_t)row * DM + col;
;       *(f32x4*)o = (f32x4){ALPHA * r0[0] + v[0], ALPHA * r0[1] + v[1], ALPHA * r0[2] + v[2], ALPHA * r0[3] + v[3]};
;       *(f32x4*)(o + 4) = (f32x4){ALPHA * r1[0] + v[4], ALPHA * r1[1] + v[5], ALPHA * r1[2] + v[6], ALPHA * r1[3] + v[7]};
	v_pk_add_f32 v[126:127], v[126:127], v[92:93] op_sel_hi:[1,0]
	v_pk_add_f32 v[128:129], v[128:129], v[92:93] op_sel_hi:[1,0]
	v_pk_add_f32 v[122:123], v[122:123], v[92:93] op_sel_hi:[1,0]
	v_pk_add_f32 v[124:125], v[124:125], v[92:93] op_sel_hi:[1,0]
	v_pk_add_f32 v[110:111], v[110:111], v[92:93] op_sel_hi:[1,0]
	v_pk_add_f32 v[112:113], v[112:113], v[92:93] op_sel_hi:[1,0]
	v_pk_add_f32 v[106:107], v[106:107], v[92:93] op_sel_hi:[1,0]
	v_pk_add_f32 v[108:109], v[108:109], v[92:93] op_sel_hi:[1,0]
	v_pk_mul_f32 v[126:127], v[126:127], v[92:93] op_sel:[0,1] op_sel_hi:[1,1]
	v_pk_mul_f32 v[128:129], v[128:129], v[92:93] op_sel:[0,1] op_sel_hi:[1,1]
	v_pk_mul_f32 v[122:123], v[122:123], v[92:93] op_sel:[0,1] op_sel_hi:[1,1]
	v_pk_mul_f32 v[124:125], v[124:125], v[92:93] op_sel:[0,1] op_sel_hi:[1,1]
	v_pk_mul_f32 v[110:111], v[110:111], v[92:93] op_sel:[0,1] op_sel_hi:[1,1]
	v_pk_mul_f32 v[112:113], v[112:113], v[92:93] op_sel:[0,1] op_sel_hi:[1,1]
	v_pk_mul_f32 v[106:107], v[106:107], v[92:93] op_sel:[0,1] op_sel_hi:[1,1]
	v_pk_mul_f32 v[108:109], v[108:109], v[92:93] op_sel:[0,1] op_sel_hi:[1,1]
	v_pk_fma_f32 v[126:127], v[190:191], v[126:127], v[206:207]
	v_pk_fma_f32 v[128:129], v[192:193], v[128:129], v[208:209]
	v_pk_fma_f32 v[122:123], v[194:195], v[122:123], v[210:211]
	v_pk_fma_f32 v[124:125], v[196:197], v[124:125], v[212:213]
	v_pk_fma_f32 v[110:111], v[198:199], v[110:111], v[214:215]
	v_pk_fma_f32 v[112:113], v[200:201], v[112:113], v[216:217]
	v_pk_fma_f32 v[106:107], v[202:203], v[106:107], v[234:235]
	v_pk_fma_f32 v[108:109], v[204:205], v[108:109], v[236:237]
	v_pk_fma_f32 v[28:29], v[126:127], s[90:91], v[28:29] op_sel_hi:[1,0,1]
	v_pk_fma_f32 v[30:31], v[128:129], s[90:91], v[30:31] op_sel_hi:[1,0,1]
	v_pk_fma_f32 v[24:25], v[122:123], s[90:91], v[24:25] op_sel_hi:[1,0,1]
	v_pk_fma_f32 v[26:27], v[124:125], s[90:91], v[26:27] op_sel_hi:[1,0,1]
	v_pk_fma_f32 v[20:21], v[110:111], s[90:91], v[20:21] op_sel_hi:[1,0,1]
	v_pk_fma_f32 v[22:23], v[112:113], s[90:91], v[22:23] op_sel_hi:[1,0,1]
	v_pk_fma_f32 v[12:13], v[106:107], s[90:91], v[12:13] op_sel_hi:[1,0,1]
	v_pk_fma_f32 v[14:15], v[108:109], s[90:91], v[14:15] op_sel_hi:[1,0,1]
	global_store_dwordx4 v247, v[28:31], s[14:15]
	global_store_dwordx4 v247, v[24:27], s[14:15] offset:16
	global_store_dwordx4 v247, v[20:23], s[14:15] offset:512
	global_store_dwordx4 v247, v[12:15], s[14:15] offset:528
	s_waitcnt vmcnt(16)
	v_pk_add_f32 v[118:119], v[118:119], v[88:89] op_sel_hi:[1,0]
	v_pk_add_f32 v[120:121], v[120:121], v[88:89] op_sel_hi:[1,0]
	v_pk_add_f32 v[114:115], v[114:115], v[88:89] op_sel_hi:[1,0]
	v_pk_add_f32 v[116:117], v[116:117], v[88:89] op_sel_hi:[1,0]
	v_pk_add_f32 v[102:103], v[102:103], v[88:89] op_sel_hi:[1,0]
	v_pk_add_f32 v[104:105], v[104:105], v[88:89] op_sel_hi:[1,0]
	v_pk_add_f32 v[98:99], v[98:99], v[88:89] op_sel_hi:[1,0]
	v_pk_add_f32 v[100:101], v[100:101], v[88:89] op_sel_hi:[1,0]
	v_pk_mul_f32 v[118:119], v[118:119], v[88:89] op_sel:[0,1] op_sel_hi:[1,1]
	v_pk_mul_f32 v[120:121], v[120:121], v[88:89] op_sel:[0,1] op_sel_hi:[1,1]
	v_pk_mul_f32 v[114:115], v[114:115], v[88:89] op_sel:[0,1] op_sel_hi:[1,1]
	v_pk_mul_f32 v[116:117], v[116:117], v[88:89] op_sel:[0,1] op_sel_hi:[1,1]
	v_pk_mul_f32 v[102:103], v[102:103], v[88:89] op_sel:[0,1] op_sel_hi:[1,1]
	v_pk_mul_f32 v[104:105], v[104:105], v[88:89] op_sel:[0,1] op_sel_hi:[1,1]
	v_pk_mul_f32 v[98:99], v[98:99], v[88:89] op_sel:[0,1] op_sel_hi:[1,1]
	v_pk_mul_f32 v[100:101], v[100:101], v[88:89] op_sel:[0,1] op_sel_hi:[1,1]
	v_pk_fma_f32 v[118:119], v[190:191], v[118:119], v[206:207]
	v_pk_fma_f32 v[120:121], v[192:193], v[120:121], v[208:209]
	v_pk_fma_f32 v[114:115], v[194:195], v[114:115], v[210:211]
	v_pk_fma_f32 v[116:117], v[196:197], v[116:117], v[212:213]
	v_pk_fma_f32 v[102:103], v[198:199], v[102:103], v[214:215]
	v_pk_fma_f32 v[104:105], v[200:201], v[104:105], v[216:217]
	v_pk_fma_f32 v[98:99], v[202:203], v[98:99], v[234:235]
	v_pk_fma_f32 v[100:101], v[204:205], v[100:101], v[236:237]
	v_pk_fma_f32 v[16:17], v[118:119], s[90:91], v[16:17] op_sel_hi:[1,0,1]
	v_pk_fma_f32 v[18:19], v[120:121], s[90:91], v[18:19] op_sel_hi:[1,0,1]
	v_pk_fma_f32 v[8:9], v[114:115], s[90:91], v[8:9] op_sel_hi:[1,0,1]
	v_pk_fma_f32 v[10:11], v[116:117], s[90:91], v[10:11] op_sel_hi:[1,0,1]
	v_pk_fma_f32 v[4:5], v[102:103], s[90:91], v[4:5] op_sel_hi:[1,0,1]
	v_pk_fma_f32 v[6:7], v[104:105], s[90:91], v[6:7] op_sel_hi:[1,0,1]
	v_pk_fma_f32 v[0:1], v[98:99], s[90:91], v[0:1] op_sel_hi:[1,0,1]
	v_pk_fma_f32 v[2:3], v[100:101], s[90:91], v[2:3] op_sel_hi:[1,0,1]
	global_store_dwordx4 v247, v[16:19], s[44:45]
	global_store_dwordx4 v247, v[8:11], s[44:45] offset:16
	global_store_dwordx4 v247, v[4:7], s[44:45] offset:512
	global_store_dwordx4 v247, v[0:3], s[44:45] offset:528
	s_mov_b64 s[0:1], 0x100000
	s_mov_b32 s42, s40
	s_mov_b64 s[14:15], s[6:7]
	s_mov_b64 s[12:13], s[4:5]
	s_and_b64 vcc, exec, s[2:3]
	s_mov_b32 s1, s41
	s_cbranch_vccz .LBB0_1418
	s_waitcnt vmcnt(0)
	s_cmpk_gt_u32 s23, 0xff
	s_cbranch_scc1 .LBB0_1433
	s_barrier
